# wave all-reduce sums (norm rows, g3 rmsnorm, softmax sums): xor 1/2/4/8 butterfly steps via v_add_f32_dpp instead of ds_bpermute_b32, counted LDS waits after removed shuffles made full
# speedup vs baseline: 1.0075x; 1.0047x over previous
.LBB0_730:
	v_pk_mul_f32 v[24:25], v[80:81], v[80:81]
	v_pk_mul_f32 v[26:27], v[78:79], v[78:79]
	s_ashr_i32 s27, s10, 13
	v_pk_mov_b32 v[28:29], v[26:27], v[24:25] op_sel:[1,0]
	v_mov_b32_e32 v27, v25
	v_pk_add_f32 v[24:25], v[28:29], v[26:27]
	v_pk_mul_f32 v[26:27], v[76:77], v[76:77]
	v_pk_mul_f32 v[28:29], v[74:75], v[74:75]
	s_and_b64 s[6:7], s[6:7], exec
	v_pk_mov_b32 v[34:35], v[28:29], v[26:27] op_sel:[1,0]
	v_mov_b32_e32 v29, v27
	v_pk_add_f32 v[26:27], v[34:35], v[28:29]
	v_mul_f32_e32 v28, v66, v66
	v_mul_f32_e32 v29, v67, v67
	v_pk_add_f32 v[24:25], v[24:25], v[24:25] op_sel:[0,1] op_sel_hi:[1,0]
	v_pk_add_f32 v[26:27], v[26:27], v[26:27] op_sel:[0,1] op_sel_hi:[1,0]
	s_cselect_b32 s6, s27, s28
	v_mov_b32_e32 v25, v28
	v_mov_b32_e32 v27, v29
	s_mul_hi_i32 s7, s6, 0x9000
	s_mul_i32 s6, s6, 0x9000
	v_pk_add_f32 v[24:25], v[24:25], v[26:27]
	v_mul_f32_e32 v26, v71, v71
	v_mul_f32_e32 v28, v73, v73
	s_add_u32 s6, s42, s6
	v_mul_f32_e32 v34, v68, v68
	v_mul_f32_e32 v35, v69, v69
	v_pk_fma_f32 v[26:27], v[70:71], v[70:71], v[26:27] op_sel_hi:[1,1,0]
	v_pk_fma_f32 v[28:29], v[72:73], v[72:73], v[28:29] op_sel_hi:[1,1,0]
	s_addc_u32 s7, s43, s7
	v_mov_b32_e32 v27, v34
	v_mov_b32_e32 v29, v35
	s_add_u32 s50, s6, 0x1000
	v_mov_b32_e32 v89, v83
	v_pk_add_f32 v[26:27], v[26:27], v[28:29]
	s_addc_u32 s51, s7, 0
	v_lshl_add_u64 v[112:113], s[6:7], 0, v[88:89]
	v_pk_add_f32 v[24:25], v[24:25], v[26:27]
	v_lshl_add_u64 v[26:27], s[50:51], 0, v[88:89]
	global_load_dwordx4 v[104:107], v[112:113], off
	global_load_dwordx4 v[108:111], v[26:27], off
	v_add_f32_e32 v24, v24, v25
	v_lshl_add_u64 v[22:23], v[22:23], 0, v[82:83]
	v_mul_f32_e32 v116, v53, v53
	s_waitcnt lgkmcnt(0)
	s_nop 1
	v_add_f32_dpp v24, v24, v24 quad_perm:[1,0,3,2] row_mask:0xf bank_mask:0xf
	s_waitcnt lgkmcnt(0)
	s_nop 1
	v_add_f32_dpp v24, v24, v24 quad_perm:[2,3,0,1] row_mask:0xf bank_mask:0xf
	s_waitcnt lgkmcnt(0)
	s_nop 1
	v_add_f32_dpp v24, v24, v24 row_half_mirror row_mask:0xf bank_mask:0xf
	s_waitcnt lgkmcnt(0)
	s_nop 1
	v_add_f32_dpp v24, v24, v24 row_mirror row_mask:0xf bank_mask:0xf
	ds_bpermute_b32 v25, v100, v24
	s_waitcnt lgkmcnt(0)
	v_add_f32_e32 v24, v24, v25
	ds_bpermute_b32 v25, v101, v24
	s_waitcnt lgkmcnt(0)
	v_add_f32_e32 v24, v24, v25
	v_fmamk_f32 v24, v24, 0x3a800000, v102
	v_mul_f32_e32 v25, 0x4f800000, v24
	v_cmp_gt_f32_e32 vcc, s4, v24
	s_waitcnt vmcnt(0)
	v_pk_add_f32 v[108:109], v[108:109], 1.0 op_sel_hi:[1,0]
	v_cndmask_b32_e32 v24, v24, v25, vcc
	v_sqrt_f32_e32 v25, v24
	v_pk_add_f32 v[110:111], v[110:111], 1.0 op_sel_hi:[1,0]
	v_add_u32_e32 v26, -1, v25
	v_fma_f32 v27, -v26, v25, v24
	v_cmp_ge_f32_e64 s[6:7], 0, v27
	v_add_u32_e32 v27, 1, v25
	s_nop 0
	v_cndmask_b32_e64 v26, v25, v26, s[6:7]
	v_fma_f32 v25, -v27, v25, v24
	v_cmp_lt_f32_e64 s[6:7], 0, v25
	s_nop 1
	v_cndmask_b32_e64 v25, v26, v27, s[6:7]
	v_mul_f32_e32 v26, 0x37800000, v25
	v_cndmask_b32_e32 v25, v25, v26, vcc
	v_cmp_class_f32_e32 vcc, v24, v103
	s_and_b64 s[6:7], s[48:49], exec
	s_nop 0
	v_cndmask_b32_e32 v91, v25, v24, vcc
	v_div_scale_f32 v93, s[6:7], v91, v91, 1.0
	v_rcp_f32_e32 v95, v93
	global_load_dwordx4 v[42:45], v[22:23], off
	global_load_dwordx4 v[34:37], v[22:23], off offset:1024
	global_load_dwordx4 v[26:29], v[22:23], off offset:2048
	s_nop 0
	global_load_dwordx4 v[22:25], v[22:23], off offset:3072
	s_cselect_b32 s6, s27, s14
	s_mul_hi_i32 s7, s6, 0x9000
	v_fma_f32 v96, -v93, v95, 1.0
	v_fmac_f32_e32 v95, v96, v95
	v_div_scale_f32 v96, vcc, 1.0, v91, 1.0
	v_mul_f32_e32 v114, v96, v95
	v_fma_f32 v115, -v93, v114, v96
	v_fmac_f32_e32 v114, v115, v95
	v_fma_f32 v93, -v93, v114, v96
	v_div_fmas_f32 v93, v93, v95, v114
	v_div_fixup_f32 v96, v93, v91, 1.0
	v_pk_mul_f32 v[78:79], v[78:79], v[96:97] op_sel_hi:[1,0]
	v_pk_mul_f32 v[80:81], v[80:81], v[96:97] op_sel_hi:[1,0]
	v_pk_mul_f32 v[78:79], v[2:3], v[78:79]
	v_pk_mul_f32 v[80:81], v[4:5], v[80:81]
	v_pk_fma_f32 v[78:79], v[108:109], v[78:79], v[104:105]
	v_pk_fma_f32 v[80:81], v[110:111], v[80:81], v[106:107]
	v_cvt_pk_bf16_f32 v78, v78, v79
	v_cvt_pk_bf16_f32 v79, v80, v81
	v_mov_b32_e32 v91, v83
	global_store_dwordx2 v[86:87], v[78:79], off
	v_lshl_add_u64 v[78:79], s[50:51], 0, v[90:91]
	global_load_dwordx4 v[78:81], v[78:79], off
	s_nop 0
	global_load_dwordx4 v[104:107], v[112:113], off offset:1024
	v_pk_mul_f32 v[76:77], v[76:77], v[96:97] op_sel_hi:[1,0]
	v_pk_mul_f32 v[74:75], v[74:75], v[96:97] op_sel_hi:[1,0]
	v_pk_mul_f32 v[76:77], v[8:9], v[76:77]
	v_pk_mul_f32 v[74:75], v[6:7], v[74:75]
	v_mov_b32_e32 v93, v83
	v_lshl_add_u64 v[108:109], s[50:51], 0, v[92:93]
	v_pk_mul_f32 v[72:73], v[72:73], v[96:97] op_sel_hi:[1,0]
	v_pk_mul_f32 v[70:71], v[70:71], v[96:97] op_sel_hi:[1,0]
	v_pk_mul_f32 v[72:73], v[12:13], v[72:73]
	v_pk_mul_f32 v[70:71], v[10:11], v[70:71]
	v_mov_b32_e32 v95, v83
	v_pk_mul_f32 v[68:69], v[68:69], v[96:97] op_sel_hi:[1,0]
	v_pk_mul_f32 v[66:67], v[66:67], v[96:97] op_sel_hi:[1,0]
	v_pk_mul_f32 v[68:69], v[68:69], v[16:17]
	v_pk_mul_f32 v[66:67], v[66:67], v[14:15]
	s_mul_i32 s6, s6, 0x9000
	s_add_u32 s6, s42, s6
	v_mul_f32_e32 v111, v50, v50
	v_mul_f32_e32 v110, v57, v57
	s_addc_u32 s7, s43, s7
	v_mul_f32_e32 v115, v52, v52
	s_add_u32 s48, s6, 0x1000
	s_addc_u32 s49, s7, 0
	v_mul_f32_e32 v114, v51, v51
	s_add_i32 s14, s10, 0xffffc004
	s_waitcnt vmcnt(0) lgkmcnt(0)
	v_pk_add_f32 v[80:81], v[80:81], 1.0 op_sel_hi:[1,0]
	v_pk_add_f32 v[78:79], v[78:79], 1.0 op_sel_hi:[1,0]
	v_pk_fma_f32 v[76:77], v[80:81], v[76:77], v[106:107]
	v_pk_fma_f32 v[74:75], v[78:79], v[74:75], v[104:105]
	v_cvt_pk_bf16_f32 v74, v74, v75
	v_cvt_pk_bf16_f32 v75, v76, v77
	global_store_dwordx2 v[86:87], v[74:75], off offset:512
	global_load_dwordx4 v[74:77], v[108:109], off
	s_nop 0
	global_load_dwordx4 v[78:81], v[112:113], off offset:2048
	v_lshl_add_u64 v[104:105], s[50:51], 0, v[94:95]
	v_pk_mul_f32 v[106:107], v[58:59], v[58:59]
	v_mul_f32_e32 v108, v55, v55
	s_waitcnt vmcnt(0) lgkmcnt(0)
	v_pk_add_f32 v[76:77], v[76:77], 1.0 op_sel_hi:[1,0]
	v_pk_add_f32 v[74:75], v[74:75], 1.0 op_sel_hi:[1,0]
	v_pk_fma_f32 v[72:73], v[72:73], v[76:77], v[80:81]
	v_pk_fma_f32 v[70:71], v[70:71], v[74:75], v[78:79]
	v_cvt_pk_bf16_f32 v70, v70, v71
	v_cvt_pk_bf16_f32 v71, v72, v73
	global_store_dwordx2 v[86:87], v[70:71], off offset:1024
	global_load_dwordx4 v[70:73], v[104:105], off
	s_nop 0
	global_load_dwordx4 v[74:77], v[112:113], off offset:3072
	v_pk_mul_f32 v[78:79], v[64:65], v[64:65]
	v_pk_mul_f32 v[80:81], v[62:63], v[62:63]
	v_pk_mul_f32 v[104:105], v[60:61], v[60:61]
	v_pk_mov_b32 v[112:113], v[80:81], v[78:79] op_sel:[1,0]
	v_mov_b32_e32 v81, v79
	v_pk_mov_b32 v[78:79], v[106:107], v[104:105] op_sel:[1,0]
	v_mov_b32_e32 v107, v105
	v_pk_fma_f32 v[104:105], v[54:55], v[54:55], v[108:109] op_sel_hi:[1,1,0]
	v_pk_fma_f32 v[108:109], v[56:57], v[56:57], v[110:111] op_sel_hi:[1,1,0]
	v_pk_add_f32 v[78:79], v[78:79], v[106:107]
	v_mov_b32_e32 v105, v115
	v_mov_b32_e32 v109, v116
	v_lshl_add_u64 v[106:107], s[6:7], 0, v[88:89]
	v_pk_add_f32 v[104:105], v[104:105], v[108:109]
	v_lshl_add_u64 v[108:109], s[48:49], 0, v[88:89]
	v_pk_add_f32 v[80:81], v[112:113], v[80:81]
	v_pk_add_f32 v[78:79], v[78:79], v[78:79] op_sel:[0,1] op_sel_hi:[1,0]
	v_pk_add_f32 v[80:81], v[80:81], v[80:81] op_sel:[0,1] op_sel_hi:[1,0]
	v_mov_b32_e32 v79, v114
	v_mov_b32_e32 v81, v111
	s_waitcnt vmcnt(0) lgkmcnt(0)
	v_pk_add_f32 v[72:73], v[72:73], 1.0 op_sel_hi:[1,0]
	v_pk_add_f32 v[70:71], v[70:71], 1.0 op_sel_hi:[1,0]
	v_pk_fma_f32 v[68:69], v[68:69], v[72:73], v[76:77]
	v_pk_fma_f32 v[66:67], v[66:67], v[70:71], v[74:75]
	v_cvt_pk_bf16_f32 v66, v66, v67
	v_cvt_pk_bf16_f32 v67, v68, v69
	global_store_dwordx2 v[86:87], v[66:67], off offset:1536
	global_load_dwordx4 v[66:69], v[106:107], off
	s_nop 0
	global_load_dwordx4 v[70:73], v[108:109], off
	v_pk_add_f32 v[74:75], v[80:81], v[78:79]
	s_waitcnt vmcnt(0) lgkmcnt(0)
	v_pk_add_f32 v[72:73], v[72:73], 1.0 op_sel_hi:[1,0]
	v_pk_add_f32 v[74:75], v[74:75], v[104:105]
	v_pk_add_f32 v[70:71], v[70:71], 1.0 op_sel_hi:[1,0]
	v_add_f32_e32 v74, v74, v75
	s_waitcnt lgkmcnt(0)
	s_nop 1
	v_add_f32_dpp v74, v74, v74 quad_perm:[1,0,3,2] row_mask:0xf bank_mask:0xf
	s_waitcnt lgkmcnt(0)
	s_nop 1
	v_add_f32_dpp v74, v74, v74 quad_perm:[2,3,0,1] row_mask:0xf bank_mask:0xf
	s_waitcnt lgkmcnt(0)
	s_nop 1
	v_add_f32_dpp v74, v74, v74 row_half_mirror row_mask:0xf bank_mask:0xf
	s_waitcnt lgkmcnt(0)
	s_nop 1
	v_add_f32_dpp v74, v74, v74 row_mirror row_mask:0xf bank_mask:0xf
	ds_bpermute_b32 v75, v100, v74
	s_waitcnt lgkmcnt(0)
	v_add_f32_e32 v74, v74, v75
	ds_bpermute_b32 v75, v101, v74
	s_waitcnt lgkmcnt(0)
	v_add_f32_e32 v74, v74, v75
	v_fmamk_f32 v74, v74, 0x3a800000, v102
	v_mul_f32_e32 v75, 0x4f800000, v74
	v_cmp_gt_f32_e32 vcc, s4, v74
	s_nop 1
	v_cndmask_b32_e32 v74, v74, v75, vcc
	v_sqrt_f32_e32 v75, v74
	s_nop 0
	v_add_u32_e32 v76, -1, v75
	v_add_u32_e32 v77, 1, v75
	v_fma_f32 v78, -v76, v75, v74
	v_fma_f32 v79, -v77, v75, v74
	v_cmp_ge_f32_e64 s[6:7], 0, v78
	s_nop 1
	v_cndmask_b32_e64 v75, v75, v76, s[6:7]
	v_cmp_lt_f32_e64 s[6:7], 0, v79
	s_nop 1
	v_cndmask_b32_e64 v75, v75, v77, s[6:7]
	v_mul_f32_e32 v76, 0x37800000, v75
	v_cndmask_b32_e32 v75, v75, v76, vcc
	v_cmp_class_f32_e32 vcc, v74, v103
	s_and_b64 s[6:7], s[46:47], exec
	s_nop 0
	v_cndmask_b32_e32 v76, v75, v74, vcc
	v_div_scale_f32 v77, s[6:7], v76, v76, 1.0
	v_rcp_f32_e32 v78, v77
	v_div_scale_f32 v79, vcc, 1.0, v76, 1.0
	v_lshl_add_u64 v[74:75], s[48:49], 0, v[90:91]
	v_fma_f32 v80, -v77, v78, 1.0
	v_fmac_f32_e32 v78, v80, v78
	v_mul_f32_e32 v80, v79, v78
	v_fma_f32 v81, -v77, v80, v79
	v_fmac_f32_e32 v80, v81, v78
	v_fma_f32 v77, -v77, v80, v79
	v_div_fmas_f32 v77, v77, v78, v80
	v_div_fixup_f32 v76, v77, v76, 1.0
	v_pk_mul_f32 v[64:65], v[64:65], v[76:77] op_sel_hi:[1,0]
	v_pk_mul_f32 v[62:63], v[62:63], v[76:77] op_sel_hi:[1,0]
	v_pk_mul_f32 v[64:65], v[4:5], v[64:65]
	v_pk_mul_f32 v[62:63], v[2:3], v[62:63]
	v_pk_fma_f32 v[64:65], v[72:73], v[64:65], v[68:69]
	v_pk_fma_f32 v[62:63], v[70:71], v[62:63], v[66:67]
	v_cvt_pk_bf16_f32 v62, v62, v63
	v_cvt_pk_bf16_f32 v63, v64, v65
	global_store_dwordx2 v[86:87], v[62:63], off offset:2048
	global_load_dwordx4 v[62:65], v[74:75], off
	s_nop 0
	global_load_dwordx4 v[66:69], v[106:107], off offset:1024
	v_pk_mul_f32 v[60:61], v[60:61], v[76:77] op_sel_hi:[1,0]
	v_pk_mul_f32 v[58:59], v[58:59], v[76:77] op_sel_hi:[1,0]
	v_pk_mul_f32 v[60:61], v[8:9], v[60:61]
	v_pk_mul_f32 v[58:59], v[6:7], v[58:59]
	v_lshl_add_u64 v[70:71], s[48:49], 0, v[92:93]
	v_pk_mul_f32 v[56:57], v[56:57], v[76:77] op_sel_hi:[1,0]
	v_pk_mul_f32 v[54:55], v[54:55], v[76:77] op_sel_hi:[1,0]
	v_pk_mul_f32 v[56:57], v[12:13], v[56:57]
	v_pk_mul_f32 v[54:55], v[10:11], v[54:55]
	v_mul_f32_e32 v77, v19, v19
	v_pk_mul_f32 v[52:53], v[52:53], v[76:77] op_sel_hi:[1,0]
	v_pk_mul_f32 v[50:51], v[50:51], v[76:77] op_sel_hi:[1,0]
	v_pk_mul_f32 v[52:53], v[16:17], v[52:53]
	v_pk_mul_f32 v[50:51], v[14:15], v[50:51]
	s_cselect_b32 s6, s27, s14
	s_mul_hi_i32 s7, s6, 0x9000
	s_mul_i32 s6, s6, 0x9000
	s_add_u32 s6, s42, s6
	v_mul_f32_e32 v73, v18, v18
	v_mul_f32_e32 v72, v33, v33
	s_addc_u32 s7, s43, s7
	v_mul_f32_e32 v78, v20, v20
	v_mul_f32_e32 v79, v21, v21
	s_add_u32 s46, s6, 0x1000
	s_addc_u32 s47, s7, 0
	s_add_i32 s14, s10, 0xffffc005
	s_waitcnt vmcnt(0) lgkmcnt(0)
	v_pk_add_f32 v[64:65], v[64:65], 1.0 op_sel_hi:[1,0]
	v_pk_add_f32 v[62:63], v[62:63], 1.0 op_sel_hi:[1,0]
	v_pk_fma_f32 v[60:61], v[64:65], v[60:61], v[68:69]
	v_pk_fma_f32 v[58:59], v[62:63], v[58:59], v[66:67]
	v_cvt_pk_bf16_f32 v58, v58, v59
	v_cvt_pk_bf16_f32 v59, v60, v61
	global_store_dwordx2 v[86:87], v[58:59], off offset:2560
	global_load_dwordx4 v[58:61], v[70:71], off
	s_nop 0
	global_load_dwordx4 v[62:65], v[106:107], off offset:2048
	v_lshl_add_u64 v[66:67], s[48:49], 0, v[94:95]
	v_pk_mul_f32 v[68:69], v[38:39], v[38:39]
	v_mul_f32_e32 v70, v31, v31
	s_waitcnt vmcnt(0) lgkmcnt(0)
	v_pk_add_f32 v[60:61], v[60:61], 1.0 op_sel_hi:[1,0]
	v_pk_add_f32 v[58:59], v[58:59], 1.0 op_sel_hi:[1,0]
	v_pk_fma_f32 v[56:57], v[60:61], v[56:57], v[64:65]
	v_pk_fma_f32 v[54:55], v[58:59], v[54:55], v[62:63]
	v_cvt_pk_bf16_f32 v54, v54, v55
	v_cvt_pk_bf16_f32 v55, v56, v57
	global_store_dwordx2 v[86:87], v[54:55], off offset:3072
	global_load_dwordx4 v[54:57], v[66:67], off
	s_nop 0
	global_load_dwordx4 v[58:61], v[106:107], off offset:3072
	v_pk_mul_f32 v[62:63], v[48:49], v[48:49]
	v_pk_mul_f32 v[64:65], v[46:47], v[46:47]
	v_pk_mul_f32 v[66:67], v[40:41], v[40:41]
	v_pk_mov_b32 v[74:75], v[64:65], v[62:63] op_sel:[1,0]
	v_mov_b32_e32 v65, v63
	v_pk_mov_b32 v[62:63], v[68:69], v[66:67] op_sel:[1,0]
	v_mov_b32_e32 v69, v67
	v_pk_fma_f32 v[66:67], v[30:31], v[30:31], v[70:71] op_sel_hi:[1,1,0]
	v_pk_fma_f32 v[70:71], v[32:33], v[32:33], v[72:73] op_sel_hi:[1,1,0]
	v_pk_add_f32 v[62:63], v[62:63], v[68:69]
	v_mov_b32_e32 v67, v78
	v_mov_b32_e32 v71, v79
	v_lshl_add_u64 v[68:69], s[6:7], 0, v[88:89]
	v_pk_add_f32 v[66:67], v[66:67], v[70:71]
	v_lshl_add_u64 v[70:71], s[46:47], 0, v[88:89]
	v_pk_add_f32 v[64:65], v[74:75], v[64:65]
	v_pk_add_f32 v[62:63], v[62:63], v[62:63] op_sel:[0,1] op_sel_hi:[1,0]
	v_pk_add_f32 v[64:65], v[64:65], v[64:65] op_sel:[0,1] op_sel_hi:[1,0]
	v_mov_b32_e32 v63, v77
	v_mov_b32_e32 v65, v73
	s_waitcnt vmcnt(0) lgkmcnt(0)
	v_pk_add_f32 v[56:57], v[56:57], 1.0 op_sel_hi:[1,0]
	v_pk_add_f32 v[54:55], v[54:55], 1.0 op_sel_hi:[1,0]
	v_pk_fma_f32 v[52:53], v[52:53], v[56:57], v[60:61]
	v_pk_fma_f32 v[50:51], v[50:51], v[54:55], v[58:59]
	v_cvt_pk_bf16_f32 v50, v50, v51
	v_cvt_pk_bf16_f32 v51, v52, v53
	global_store_dwordx2 v[86:87], v[50:51], off offset:3584
	global_load_dwordx4 v[52:55], v[68:69], off
	global_load_dwordx4 v[56:59], v[70:71], off
	v_pk_add_f32 v[50:51], v[64:65], v[62:63]
	s_waitcnt vmcnt(0) lgkmcnt(0)
	v_pk_add_f32 v[58:59], v[58:59], 1.0 op_sel_hi:[1,0]
	v_pk_add_f32 v[50:51], v[50:51], v[66:67]
	v_pk_add_f32 v[56:57], v[56:57], 1.0 op_sel_hi:[1,0]
	v_add_f32_e32 v50, v50, v51
	s_waitcnt lgkmcnt(0)
	s_nop 1
	v_add_f32_dpp v50, v50, v50 quad_perm:[1,0,3,2] row_mask:0xf bank_mask:0xf
	s_waitcnt lgkmcnt(0)
	s_nop 1
	v_add_f32_dpp v50, v50, v50 quad_perm:[2,3,0,1] row_mask:0xf bank_mask:0xf
	s_waitcnt lgkmcnt(0)
	s_nop 1
	v_add_f32_dpp v50, v50, v50 row_half_mirror row_mask:0xf bank_mask:0xf
	s_waitcnt lgkmcnt(0)
	s_nop 1
	v_add_f32_dpp v50, v50, v50 row_mirror row_mask:0xf bank_mask:0xf
	ds_bpermute_b32 v51, v100, v50
	s_waitcnt lgkmcnt(0)
	v_add_f32_e32 v50, v50, v51
	ds_bpermute_b32 v51, v101, v50
	s_waitcnt lgkmcnt(0)
	v_add_f32_e32 v50, v50, v51
	v_fmamk_f32 v50, v50, 0x3a800000, v102
	v_mul_f32_e32 v51, 0x4f800000, v50
	v_cmp_gt_f32_e32 vcc, s4, v50
	s_nop 1
	v_cndmask_b32_e32 v60, v50, v51, vcc
	v_sqrt_f32_e32 v61, v60
	v_add_co_u32_e64 v50, s[6:7], s26, v86
	v_add_u32_e32 v62, -1, v61
	s_nop 0
	v_addc_co_u32_e64 v51, s[6:7], 0, v87, s[6:7]
	v_add_u32_e32 v63, 1, v61
	v_fma_f32 v64, -v62, v61, v60
	v_fma_f32 v65, -v63, v61, v60
	v_cmp_ge_f32_e64 s[6:7], 0, v64
	v_lshl_add_u64 v[86:87], v[86:87], 0, s[18:19]
	s_nop 0
	v_cndmask_b32_e64 v61, v61, v62, s[6:7]
	v_cmp_lt_f32_e64 s[6:7], 0, v65
	s_nop 1
	v_cndmask_b32_e64 v61, v61, v63, s[6:7]
	v_mul_f32_e32 v62, 0x37800000, v61
	v_cndmask_b32_e32 v61, v61, v62, vcc
	v_cmp_class_f32_e32 vcc, v60, v103
	s_and_b64 s[6:7], exec, s[24:25]
	s_nop 0
	v_cndmask_b32_e32 v62, v61, v60, vcc
	v_div_scale_f32 v63, s[6:7], v62, v62, 1.0
	v_rcp_f32_e32 v64, v63
	v_div_scale_f32 v65, vcc, 1.0, v62, 1.0
	v_lshl_add_u64 v[60:61], s[46:47], 0, v[90:91]
	v_fma_f32 v66, -v63, v64, 1.0
	v_fmac_f32_e32 v64, v66, v64
	v_mul_f32_e32 v66, v65, v64
	v_fma_f32 v67, -v63, v66, v65
	v_fmac_f32_e32 v66, v67, v64
	v_fma_f32 v63, -v63, v66, v65
	v_div_fmas_f32 v63, v63, v64, v66
	v_div_fixup_f32 v62, v63, v62, 1.0
	v_pk_mul_f32 v[48:49], v[48:49], v[62:63] op_sel_hi:[1,0]
	v_pk_mul_f32 v[46:47], v[46:47], v[62:63] op_sel_hi:[1,0]
	v_pk_mul_f32 v[48:49], v[4:5], v[48:49]
	v_pk_mul_f32 v[46:47], v[2:3], v[46:47]
	v_pk_fma_f32 v[48:49], v[58:59], v[48:49], v[54:55]
	v_pk_fma_f32 v[46:47], v[56:57], v[46:47], v[52:53]
	v_cvt_pk_bf16_f32 v46, v46, v47
	v_cvt_pk_bf16_f32 v47, v48, v49
	global_store_dwordx2 v[50:51], v[46:47], off
	global_load_dwordx4 v[46:49], v[60:61], off
	s_nop 0
	global_load_dwordx4 v[52:55], v[68:69], off offset:1024
	v_pk_mul_f32 v[40:41], v[40:41], v[62:63] op_sel_hi:[1,0]
	v_pk_mul_f32 v[38:39], v[38:39], v[62:63] op_sel_hi:[1,0]
	v_pk_mul_f32 v[40:41], v[8:9], v[40:41]
	v_pk_mul_f32 v[38:39], v[6:7], v[38:39]
	v_lshl_add_u64 v[56:57], s[46:47], 0, v[92:93]
	v_pk_mul_f32 v[32:33], v[32:33], v[62:63] op_sel_hi:[1,0]
	v_pk_mul_f32 v[30:31], v[30:31], v[62:63] op_sel_hi:[1,0]
	v_pk_mul_f32 v[32:33], v[12:13], v[32:33]
	v_pk_mul_f32 v[30:31], v[10:11], v[30:31]
	v_pk_mul_f32 v[20:21], v[20:21], v[62:63] op_sel_hi:[1,0]
	v_pk_mul_f32 v[18:19], v[18:19], v[62:63] op_sel_hi:[1,0]
	v_pk_mul_f32 v[20:21], v[16:17], v[20:21]
	v_pk_mul_f32 v[18:19], v[14:15], v[18:19]
	s_cselect_b32 s6, s27, s14
	s_mul_hi_i32 s7, s6, 0x9000
	s_mul_i32 s6, s6, 0x9000
	s_add_u32 s6, s42, s6
	s_addc_u32 s7, s43, s7
	s_lshl_b64 s[28:29], s[44:45], 11
	s_add_u32 s24, s6, 0x1000
	s_addc_u32 s25, s7, 0
	v_pk_mul_f32 v[58:59], v[34:35], v[34:35]
	v_mul_f32_e32 v63, v22, v22
	v_mul_f32_e32 v60, v27, v27
	v_mul_f32_e32 v62, v29, v29
	v_mul_f32_e32 v66, v23, v23
	v_mul_f32_e32 v67, v24, v24
	s_add_u32 s10, s10, s16
	s_addc_u32 s11, s11, s17
	s_add_u32 s20, s20, s22
	s_addc_u32 s21, s21, s23
	s_cmpk_lt_i32 s10, 0x4080
	s_waitcnt vmcnt(0) lgkmcnt(0)
	v_pk_add_f32 v[48:49], v[48:49], 1.0 op_sel_hi:[1,0]
	v_pk_add_f32 v[46:47], v[46:47], 1.0 op_sel_hi:[1,0]
	v_pk_fma_f32 v[40:41], v[48:49], v[40:41], v[54:55]
	v_pk_fma_f32 v[38:39], v[46:47], v[38:39], v[52:53]
	v_cvt_pk_bf16_f32 v38, v38, v39
	v_cvt_pk_bf16_f32 v39, v40, v41
	global_store_dwordx2 v[50:51], v[38:39], off offset:512
	global_load_dwordx4 v[38:41], v[56:57], off
	s_nop 0
	global_load_dwordx4 v[46:49], v[68:69], off offset:2048
	v_lshl_add_u64 v[52:53], s[46:47], 0, v[94:95]
	v_pk_mul_f32 v[54:55], v[42:43], v[42:43]
	v_pk_mul_f32 v[56:57], v[36:37], v[36:37]
	s_waitcnt vmcnt(0) lgkmcnt(0)
	v_pk_add_f32 v[40:41], v[40:41], 1.0 op_sel_hi:[1,0]
	v_pk_add_f32 v[38:39], v[38:39], 1.0 op_sel_hi:[1,0]
	v_pk_fma_f32 v[32:33], v[40:41], v[32:33], v[48:49]
	v_pk_fma_f32 v[30:31], v[38:39], v[30:31], v[46:47]
	v_cvt_pk_bf16_f32 v30, v30, v31
	v_cvt_pk_bf16_f32 v31, v32, v33
	global_store_dwordx2 v[50:51], v[30:31], off offset:1024
	global_load_dwordx4 v[38:41], v[52:53], off
	global_load_dwordx4 v[46:49], v[68:69], off offset:3072
	v_lshl_add_u64 v[30:31], s[6:7], 0, v[88:89]
	v_lshl_add_u64 v[32:33], s[24:25], 0, v[88:89]
	v_pk_mul_f32 v[52:53], v[44:45], v[44:45]
	v_mul_f32_e32 v68, v25, v25
	v_pk_mov_b32 v[64:65], v[54:55], v[52:53] op_sel:[1,0]
	v_mov_b32_e32 v55, v53
	v_pk_mov_b32 v[52:53], v[58:59], v[56:57] op_sel:[1,0]
	v_mov_b32_e32 v59, v57
	v_pk_add_f32 v[54:55], v[64:65], v[54:55]
	v_pk_add_f32 v[52:53], v[52:53], v[58:59]
	v_pk_fma_f32 v[56:57], v[26:27], v[26:27], v[60:61] op_sel_hi:[1,1,0]
	v_pk_fma_f32 v[60:61], v[28:29], v[28:29], v[62:63] op_sel_hi:[1,1,0]
	v_pk_add_f32 v[54:55], v[54:55], v[54:55] op_sel:[0,1] op_sel_hi:[1,0]
	v_pk_add_f32 v[52:53], v[52:53], v[52:53] op_sel:[0,1] op_sel_hi:[1,0]
	v_mov_b32_e32 v57, v67
	v_mov_b32_e32 v61, v68
	v_mov_b32_e32 v55, v63
	v_mov_b32_e32 v53, v66
	v_pk_add_f32 v[56:57], v[56:57], v[60:61]
	s_waitcnt vmcnt(0) lgkmcnt(0)
	v_pk_add_f32 v[40:41], v[40:41], 1.0 op_sel_hi:[1,0]
	v_pk_add_f32 v[38:39], v[38:39], 1.0 op_sel_hi:[1,0]
	v_pk_fma_f32 v[20:21], v[20:21], v[40:41], v[48:49]
	v_pk_fma_f32 v[18:19], v[18:19], v[38:39], v[46:47]
	v_cvt_pk_bf16_f32 v18, v18, v19
	v_cvt_pk_bf16_f32 v19, v20, v21
	global_store_dwordx2 v[50:51], v[18:19], off offset:1536
	global_load_dwordx4 v[18:21], v[30:31], off
	s_nop 0
	global_load_dwordx4 v[38:41], v[32:33], off
	v_pk_add_f32 v[32:33], v[54:55], v[52:53]
	v_lshl_add_u64 v[46:47], v[84:85], 0, s[28:29]
	v_pk_add_f32 v[32:33], v[32:33], v[56:57]
	s_waitcnt vmcnt(0) lgkmcnt(0)
	v_pk_add_f32 v[40:41], v[40:41], 1.0 op_sel_hi:[1,0]
	v_add_f32_e32 v32, v32, v33
	v_pk_add_f32 v[38:39], v[38:39], 1.0 op_sel_hi:[1,0]
	s_waitcnt lgkmcnt(0)
	s_nop 1
	v_add_f32_dpp v32, v32, v32 quad_perm:[1,0,3,2] row_mask:0xf bank_mask:0xf
	s_waitcnt lgkmcnt(0)
	s_nop 1
	v_add_f32_dpp v32, v32, v32 quad_perm:[2,3,0,1] row_mask:0xf bank_mask:0xf
	s_waitcnt lgkmcnt(0)
	s_nop 1
	v_add_f32_dpp v32, v32, v32 row_half_mirror row_mask:0xf bank_mask:0xf
	s_waitcnt lgkmcnt(0)
	s_nop 1
	v_add_f32_dpp v32, v32, v32 row_mirror row_mask:0xf bank_mask:0xf
	ds_bpermute_b32 v33, v100, v32
	s_waitcnt lgkmcnt(0)
	v_add_f32_e32 v32, v32, v33
	ds_bpermute_b32 v33, v101, v32
	s_waitcnt lgkmcnt(0)
	v_add_f32_e32 v32, v32, v33
	v_fmamk_f32 v32, v32, 0x3a800000, v102
	v_mul_f32_e32 v33, 0x4f800000, v32
	v_cmp_gt_f32_e32 vcc, s4, v32
	s_nop 1
	v_cndmask_b32_e32 v32, v32, v33, vcc
	v_sqrt_f32_e32 v33, v32
	s_nop 0
	v_add_u32_e32 v48, -1, v33
	v_add_u32_e32 v49, 1, v33
	v_fma_f32 v50, -v48, v33, v32
	v_fma_f32 v51, -v49, v33, v32
	v_cmp_ge_f32_e64 s[6:7], 0, v50
	s_nop 1
	v_cndmask_b32_e64 v33, v33, v48, s[6:7]
	v_cmp_lt_f32_e64 s[6:7], 0, v51
	s_nop 1
	v_cndmask_b32_e64 v33, v33, v49, s[6:7]
	v_mul_f32_e32 v48, 0x37800000, v33
	v_cndmask_b32_e32 v33, v33, v48, vcc
	v_cmp_class_f32_e32 vcc, v32, v103
	s_nop 1
	v_cndmask_b32_e32 v48, v33, v32, vcc
	v_div_scale_f32 v49, s[6:7], v48, v48, 1.0
	v_rcp_f32_e32 v50, v49
	v_div_scale_f32 v51, vcc, 1.0, v48, 1.0
	v_lshl_add_u64 v[32:33], s[24:25], 0, v[90:91]
	v_fma_f32 v52, -v49, v50, 1.0
	v_fmac_f32_e32 v50, v52, v50
	v_mul_f32_e32 v52, v51, v50
	v_fma_f32 v53, -v49, v52, v51
	v_fmac_f32_e32 v52, v53, v50
	v_fma_f32 v49, -v49, v52, v51
	v_div_fmas_f32 v49, v49, v50, v52
	v_div_fixup_f32 v48, v49, v48, 1.0
	v_pk_mul_f32 v[44:45], v[44:45], v[48:49] op_sel_hi:[1,0]
	v_pk_mul_f32 v[42:43], v[42:43], v[48:49] op_sel_hi:[1,0]
	v_pk_mul_f32 v[44:45], v[4:5], v[44:45]
	v_pk_mul_f32 v[42:43], v[2:3], v[42:43]
	v_pk_fma_f32 v[20:21], v[40:41], v[44:45], v[20:21]
	v_pk_fma_f32 v[18:19], v[38:39], v[42:43], v[18:19]
	v_cvt_pk_bf16_f32 v18, v18, v19
	v_cvt_pk_bf16_f32 v19, v20, v21
	global_store_dwordx2 v[46:47], v[18:19], off
	global_load_dwordx4 v[18:21], v[32:33], off
	s_nop 0
	global_load_dwordx4 v[38:41], v[30:31], off offset:1024
	v_pk_mul_f32 v[32:33], v[36:37], v[48:49] op_sel_hi:[1,0]
	v_pk_mul_f32 v[34:35], v[34:35], v[48:49] op_sel_hi:[1,0]
	v_pk_mul_f32 v[32:33], v[8:9], v[32:33]
	v_pk_mul_f32 v[34:35], v[6:7], v[34:35]
	v_lshl_add_u64 v[42:43], s[24:25], 0, v[92:93]
	v_pk_mul_f32 v[28:29], v[28:29], v[48:49] op_sel_hi:[1,0]
	v_pk_mul_f32 v[26:27], v[26:27], v[48:49] op_sel_hi:[1,0]
	v_pk_mul_f32 v[28:29], v[12:13], v[28:29]
	v_pk_mul_f32 v[26:27], v[10:11], v[26:27]
	v_lshl_add_u64 v[36:37], s[24:25], 0, v[94:95]
	v_pk_mul_f32 v[24:25], v[24:25], v[48:49] op_sel_hi:[1,0]
	v_pk_mul_f32 v[22:23], v[22:23], v[48:49] op_sel_hi:[1,0]
	v_pk_mul_f32 v[24:25], v[16:17], v[24:25]
	v_pk_mul_f32 v[22:23], v[14:15], v[22:23]
	s_waitcnt vmcnt(0) lgkmcnt(0)
	v_pk_add_f32 v[20:21], v[20:21], 1.0 op_sel_hi:[1,0]
	v_pk_add_f32 v[18:19], v[18:19], 1.0 op_sel_hi:[1,0]
	v_pk_fma_f32 v[20:21], v[20:21], v[32:33], v[40:41]
	v_pk_fma_f32 v[18:19], v[18:19], v[34:35], v[38:39]
	v_cvt_pk_bf16_f32 v18, v18, v19
	v_cvt_pk_bf16_f32 v19, v20, v21
	global_store_dwordx2 v[46:47], v[18:19], off offset:512
	global_load_dwordx4 v[18:21], v[42:43], off
	s_nop 0
	global_load_dwordx4 v[32:35], v[30:31], off offset:2048
	s_waitcnt vmcnt(0) lgkmcnt(0)
	v_pk_add_f32 v[20:21], v[20:21], 1.0 op_sel_hi:[1,0]
	v_pk_add_f32 v[18:19], v[18:19], 1.0 op_sel_hi:[1,0]
	v_pk_fma_f32 v[20:21], v[20:21], v[28:29], v[34:35]
	v_pk_fma_f32 v[18:19], v[18:19], v[26:27], v[32:33]
	v_cvt_pk_bf16_f32 v18, v18, v19
	v_cvt_pk_bf16_f32 v19, v20, v21
	global_store_dwordx2 v[46:47], v[18:19], off offset:1024
	global_load_dwordx4 v[18:21], v[36:37], off
	s_nop 0
	global_load_dwordx4 v[26:29], v[30:31], off offset:3072
	s_waitcnt vmcnt(0) lgkmcnt(0)
	v_pk_add_f32 v[20:21], v[20:21], 1.0 op_sel_hi:[1,0]
	v_pk_add_f32 v[18:19], v[18:19], 1.0 op_sel_hi:[1,0]
	v_pk_fma_f32 v[20:21], v[24:25], v[20:21], v[28:29]
	v_pk_fma_f32 v[18:19], v[22:23], v[18:19], v[26:27]
	v_cvt_pk_bf16_f32 v18, v18, v19
	v_cvt_pk_bf16_f32 v19, v20, v21
	global_store_dwordx2 v[46:47], v[18:19], off offset:1536
	s_cbranch_scc0 .LBB0_735

.LBB0_842:
	v_lshl_add_u64 v[18:19], s[38:39], 0, v[94:95]
	v_lshl_add_u64 v[22:23], s[38:39], 0, v[92:93]
	v_add_co_u32_e32 v20, vcc, 0x7800000, v18
	v_add_co_u32_e64 v102, s[6:7], s31, v22
	s_nop 0
	v_addc_co_u32_e32 v21, vcc, 0, v19, vcc
	v_addc_co_u32_e64 v103, s[6:7], 0, v23, s[6:7]
	v_add_co_u32_e64 v104, s[6:7], s33, v22
	v_add_co_u32_e32 v22, vcc, 0x7801000, v18
	s_nop 0
	v_addc_co_u32_e64 v105, s[6:7], 0, v23, s[6:7]
	global_load_dwordx4 v[78:81], v[20:21], off
	global_load_dwordx4 v[74:77], v[20:21], off offset:1024
	global_load_dwordx4 v[70:73], v[20:21], off offset:2048
	global_load_dwordx4 v[66:69], v[20:21], off offset:3072
	v_addc_co_u32_e32 v23, vcc, 0, v19, vcc
	v_add_co_u32_e32 v20, vcc, 0x7802000, v18
	global_load_dwordx4 v[62:65], v[22:23], off
	global_load_dwordx4 v[58:61], v[22:23], off offset:1024
	global_load_dwordx4 v[54:57], v[22:23], off offset:2048
	global_load_dwordx4 v[50:53], v[22:23], off offset:3072
	v_addc_co_u32_e32 v21, vcc, 0, v19, vcc
	global_load_dwordx4 v[46:49], v[20:21], off
	global_load_dwordx4 v[42:45], v[20:21], off offset:1024
	global_load_dwordx4 v[38:41], v[20:21], off offset:2048
	global_load_dwordx4 v[34:37], v[20:21], off offset:3072
	v_add_co_u32_e32 v18, vcc, 0x7803000, v18
	s_ashr_i32 s8, s18, 13
	s_nop 0
	v_addc_co_u32_e32 v19, vcc, 0, v19, vcc
	global_load_dwordx4 v[30:33], v[18:19], off
	global_load_dwordx4 v[26:29], v[18:19], off offset:1024
	global_load_dwordx4 v[22:25], v[18:19], off offset:2048
	s_nop 0
	global_load_dwordx4 v[18:21], v[18:19], off offset:3072
	s_add_i32 s9, s18, 0xffffc002
	s_cmpk_lt_i32 s18, 0x4000
	s_cselect_b32 s6, s8, s9
	s_mul_hi_i32 s7, s6, 0x9000
	s_mul_i32 s6, s6, 0x9000
	s_add_u32 s6, s27, s6
	s_addc_u32 s7, s28, s7
	s_add_u32 s10, s6, 0x1000
	s_addc_u32 s11, s7, 0
	v_lshl_add_u64 v[122:123], s[6:7], 0, v[90:91]
	v_lshl_add_u64 v[86:87], s[10:11], 0, v[90:91]
	global_load_dwordx4 v[82:85], v[122:123], off
	s_add_i32 s6, s18, 0xffffc003
	global_load_dwordx4 v[86:89], v[86:87], off
	s_cmpk_lt_i32 s18, 0x3fff
	s_cselect_b32 s6, s8, s6
	s_mul_hi_i32 s7, s6, 0x9000
	s_mul_i32 s6, s6, 0x9000
	s_add_u32 s6, s27, s6
	s_addc_u32 s7, s28, s7
	v_lshl_add_u64 v[142:143], s[10:11], 0, v[96:97]
	v_lshl_add_u64 v[138:139], s[10:11], 0, v[98:99]
	v_lshl_add_u64 v[128:129], s[10:11], 0, v[100:101]
	s_add_u32 s10, s6, 0x1000
	v_lshl_add_u64 v[110:111], s[6:7], 0, v[90:91]
	s_addc_u32 s11, s7, 0
	s_add_i32 s6, s18, 0xffffc004
	s_cmpk_lt_i32 s18, 0x3ffe
	s_cselect_b32 s6, s8, s6
	s_mul_hi_i32 s7, s6, 0x9000
	s_mul_i32 s6, s6, 0x9000
	v_lshl_add_u64 v[124:125], s[10:11], 0, v[90:91]
	v_lshl_add_u64 v[118:119], s[10:11], 0, v[96:97]
	v_lshl_add_u64 v[114:115], s[10:11], 0, v[98:99]
	v_lshl_add_u64 v[112:113], s[10:11], 0, v[100:101]
	s_add_u32 s10, s27, s6
	s_addc_u32 s11, s28, s7
	s_add_u32 s6, s10, 0x1000
	s_addc_u32 s7, s11, 0
	s_add_i32 s9, s18, 0xffffc005
	s_cmpk_lt_i32 s18, 0x3ffd
	v_lshl_add_u64 v[146:147], s[6:7], 0, v[90:91]
	v_lshl_add_u64 v[144:145], s[6:7], 0, v[96:97]
	v_lshl_add_u64 v[140:141], s[6:7], 0, v[98:99]
	v_lshl_add_u64 v[126:127], s[6:7], 0, v[100:101]
	s_cselect_b32 s6, s8, s9
	s_mul_hi_i32 s7, s6, 0x9000
	s_mul_i32 s6, s6, 0x9000
	s_add_u32 s6, s27, s6
	s_addc_u32 s7, s28, s7
	s_add_u32 s24, s6, 0x1000
	v_lshl_add_u64 v[106:107], s[6:7], 0, v[90:91]
	s_addc_u32 s25, s7, 0
	v_lshl_add_u64 v[108:109], s[10:11], 0, v[90:91]
	v_lshl_add_u64 v[120:121], s[24:25], 0, v[90:91]
	v_lshl_add_u64 v[116:117], s[24:25], 0, v[96:97]
	s_add_i32 s18, s18, 32
	v_lshl_add_u64 v[92:93], v[92:93], 0, s[20:21]
	v_lshl_add_u64 v[94:95], v[94:95], 0, s[22:23]
	s_cmp_lt_i32 s18, s26
	s_waitcnt vmcnt(0) lgkmcnt(0)
	v_pk_mul_f32 v[148:149], v[80:81], v[80:81]
	v_pk_mul_f32 v[150:151], v[78:79], v[78:79]
	v_pk_mul_f32 v[152:153], v[76:77], v[76:77]
	v_pk_mul_f32 v[154:155], v[74:75], v[74:75]
	v_mul_f32_e32 v164, v71, v71
	v_mul_f32_e32 v166, v73, v73
	v_pk_mov_b32 v[168:169], v[150:151], v[148:149] op_sel:[1,0]
	v_mov_b32_e32 v151, v149
	v_pk_mov_b32 v[148:149], v[154:155], v[152:153] op_sel:[1,0]
	v_mov_b32_e32 v155, v153
	v_mul_f32_e32 v177, v68, v68
	v_mul_f32_e32 v179, v69, v69
	v_pk_fma_f32 v[152:153], v[70:71], v[70:71], v[164:165] op_sel_hi:[1,1,0]
	v_pk_fma_f32 v[164:165], v[72:73], v[72:73], v[166:167] op_sel_hi:[1,1,0]
	v_pk_mul_f32 v[166:167], v[64:65], v[64:65]
	v_pk_mul_f32 v[170:171], v[62:63], v[62:63]
	v_pk_mul_f32 v[172:173], v[60:61], v[60:61]
	v_pk_mul_f32 v[174:175], v[58:59], v[58:59]
	v_mul_f32_e32 v176, v55, v55
	v_mul_f32_e32 v178, v57, v57
	v_pk_add_f32 v[150:151], v[168:169], v[150:151]
	v_pk_add_f32 v[148:149], v[148:149], v[154:155]
	v_mul_f32_e32 v163, v66, v66
	v_mul_f32_e32 v187, v67, v67
	v_mov_b32_e32 v153, v177
	v_mov_b32_e32 v165, v179
	v_pk_mov_b32 v[154:155], v[170:171], v[166:167] op_sel:[1,0]
	v_mov_b32_e32 v171, v167
	v_pk_mov_b32 v[166:167], v[174:175], v[172:173] op_sel:[1,0]
	v_mov_b32_e32 v175, v173
	v_pk_fma_f32 v[168:169], v[54:55], v[54:55], v[176:177] op_sel_hi:[1,1,0]
	v_pk_fma_f32 v[172:173], v[56:57], v[56:57], v[178:179] op_sel_hi:[1,1,0]
	v_pk_mul_f32 v[176:177], v[48:49], v[48:49]
	v_pk_mul_f32 v[178:179], v[46:47], v[46:47]
	v_pk_add_f32 v[188:189], v[150:151], v[150:151] op_sel:[0,1] op_sel_hi:[1,0]
	v_pk_add_f32 v[190:191], v[148:149], v[148:149] op_sel:[0,1] op_sel_hi:[1,0]
	v_mul_f32_e32 v185, v52, v52
	v_pk_mul_f32 v[180:181], v[44:45], v[44:45]
	v_pk_mul_f32 v[182:183], v[42:43], v[42:43]
	v_mul_f32_e32 v184, v39, v39
	v_mul_f32_e32 v186, v41, v41
	v_pk_add_f32 v[164:165], v[152:153], v[164:165]
	v_pk_add_f32 v[148:149], v[154:155], v[170:171]
	v_pk_add_f32 v[150:151], v[166:167], v[174:175]
	v_pk_mov_b32 v[152:153], v[178:179], v[176:177] op_sel:[1,0]
	v_mov_b32_e32 v179, v177
	v_mov_b32_e32 v189, v163
	v_mov_b32_e32 v191, v187
	v_mul_f32_e32 v193, v50, v50
	v_mul_f32_e32 v198, v51, v51
	v_mul_f32_e32 v192, v53, v53
	v_mul_f32_e32 v201, v36, v36
	v_mul_f32_e32 v202, v37, v37
	v_pk_mov_b32 v[154:155], v[182:183], v[180:181] op_sel:[1,0]
	v_mov_b32_e32 v183, v181
	v_pk_fma_f32 v[166:167], v[38:39], v[38:39], v[184:185] op_sel_hi:[1,1,0]
	v_pk_fma_f32 v[170:171], v[40:41], v[40:41], v[186:187] op_sel_hi:[1,1,0]
	v_pk_add_f32 v[194:195], v[148:149], v[148:149] op_sel:[0,1] op_sel_hi:[1,0]
	v_pk_add_f32 v[196:197], v[150:151], v[150:151] op_sel:[0,1] op_sel_hi:[1,0]
	v_pk_add_f32 v[152:153], v[152:153], v[178:179]
	v_pk_add_f32 v[178:179], v[188:189], v[190:191]
	v_mov_b32_e32 v169, v185
	v_mov_b32_e32 v173, v192
	v_pk_mul_f32 v[174:175], v[32:33], v[32:33]
	v_pk_mul_f32 v[176:177], v[30:31], v[30:31]
	v_pk_mul_f32 v[180:181], v[28:29], v[28:29]
	v_pk_mul_f32 v[184:185], v[26:27], v[26:27]
	v_pk_add_f32 v[154:155], v[154:155], v[182:183]
	v_mov_b32_e32 v167, v201
	v_mov_b32_e32 v171, v202
	v_mov_b32_e32 v195, v193
	v_mov_b32_e32 v197, v198
	v_pk_add_f32 v[164:165], v[178:179], v[164:165]
	v_mul_f32_e32 v199, v34, v34
	v_mul_f32_e32 v200, v35, v35
	v_pk_add_f32 v[168:169], v[168:169], v[172:173]
	v_pk_mov_b32 v[172:173], v[176:177], v[174:175] op_sel:[1,0]
	v_mov_b32_e32 v177, v175
	v_pk_mov_b32 v[174:175], v[184:185], v[180:181] op_sel:[1,0]
	v_mov_b32_e32 v185, v181
	v_pk_add_f32 v[180:181], v[152:153], v[152:153] op_sel:[0,1] op_sel_hi:[1,0]
	v_pk_add_f32 v[182:183], v[154:155], v[154:155] op_sel:[0,1] op_sel_hi:[1,0]
	v_pk_add_f32 v[166:167], v[166:167], v[170:171]
	v_pk_add_f32 v[170:171], v[194:195], v[196:197]
	v_add_f32_e32 v163, v164, v165
	v_mov_b32_e32 v181, v199
	v_mov_b32_e32 v183, v200
	v_pk_add_f32 v[164:165], v[170:171], v[168:169]
	ds_bpermute_b32 v171, v133, v163
	v_pk_add_f32 v[168:169], v[180:181], v[182:183]
	v_add_f32_e32 v170, v164, v165
	v_pk_add_f32 v[164:165], v[168:169], v[166:167]
	v_add_f32_e32 v164, v164, v165
	s_waitcnt lgkmcnt(0)
	v_add_f32_e32 v163, v163, v171
	s_waitcnt lgkmcnt(0)
	s_nop 1
	v_add_f32_dpp v166, v170, v170 quad_perm:[1,0,3,2] row_mask:0xf bank_mask:0xf
	s_waitcnt lgkmcnt(0)
	s_nop 1
	v_add_f32_dpp v164, v164, v164 quad_perm:[1,0,3,2] row_mask:0xf bank_mask:0xf
	s_waitcnt lgkmcnt(0)
	s_nop 1
	v_add_f32_dpp v163, v163, v163 quad_perm:[2,3,0,1] row_mask:0xf bank_mask:0xf
	ds_bpermute_b32 v167, v157, v163
	s_waitcnt lgkmcnt(2)
	s_nop 1
	v_add_f32_dpp v166, v166, v166 quad_perm:[2,3,0,1] row_mask:0xf bank_mask:0xf
	s_waitcnt lgkmcnt(0)
	s_nop 1
	v_add_f32_dpp v164, v164, v164 quad_perm:[2,3,0,1] row_mask:0xf bank_mask:0xf
	s_waitcnt lgkmcnt(0)
	v_add_f32_e32 v163, v163, v167
	ds_bpermute_b32 v167, v158, v163
	s_waitcnt lgkmcnt(2)
	s_nop 1
	v_add_f32_dpp v166, v166, v166 row_half_mirror row_mask:0xf bank_mask:0xf
	s_waitcnt lgkmcnt(0)
	s_nop 1
	v_add_f32_dpp v164, v164, v164 row_half_mirror row_mask:0xf bank_mask:0xf
	s_waitcnt lgkmcnt(0)
	v_add_f32_e32 v163, v163, v167
	ds_bpermute_b32 v167, v159, v163
	s_waitcnt lgkmcnt(2)
	s_nop 1
	v_add_f32_dpp v166, v166, v166 row_mirror row_mask:0xf bank_mask:0xf
	ds_bpermute_b32 v168, v159, v166
	s_waitcnt lgkmcnt(2)
	s_nop 1
	v_add_f32_dpp v164, v164, v164 row_mirror row_mask:0xf bank_mask:0xf
	ds_bpermute_b32 v165, v159, v164
	s_waitcnt lgkmcnt(2)
	v_add_f32_e32 v163, v163, v167
	ds_bpermute_b32 v167, v160, v163
	s_waitcnt lgkmcnt(2)
	v_add_f32_e32 v166, v166, v168
	ds_bpermute_b32 v168, v160, v166
	s_waitcnt lgkmcnt(2)
	v_add_f32_e32 v164, v164, v165
	ds_bpermute_b32 v165, v160, v164
	s_waitcnt lgkmcnt(2)
	v_add_f32_e32 v163, v163, v167
	v_fmamk_f32 v163, v163, 0x3a800000, v161
	s_waitcnt lgkmcnt(1)
	v_add_f32_e32 v166, v166, v168
	v_mul_f32_e32 v167, 0x4f800000, v163
	v_cmp_gt_f32_e32 vcc, s19, v163
	v_fmamk_f32 v166, v166, 0x3a800000, v161
	s_waitcnt lgkmcnt(0)
	v_add_f32_e32 v164, v164, v165
	v_cndmask_b32_e32 v163, v163, v167, vcc
	v_mul_f32_e32 v165, 0x4f800000, v166
	v_cmp_gt_f32_e64 s[6:7], s19, v166
	v_sqrt_f32_e32 v167, v163
	v_fmamk_f32 v164, v164, 0x3a800000, v161
	v_cndmask_b32_e64 v165, v166, v165, s[6:7]
	v_mul_f32_e32 v166, 0x4f800000, v164
	v_cmp_gt_f32_e64 s[8:9], s19, v164
	v_sqrt_f32_e32 v168, v165
	v_add_u32_e32 v169, -1, v167
	v_cndmask_b32_e64 v164, v164, v166, s[8:9]
	v_sqrt_f32_e32 v166, v164
	v_add_u32_e32 v170, 1, v167
	v_fma_f32 v171, -v169, v167, v163
	v_pk_add_f32 v[152:153], v[172:173], v[176:177]
	v_fma_f32 v172, -v170, v167, v163
	v_add_u32_e32 v173, -1, v168
	v_cmp_ge_f32_e64 s[10:11], 0, v171
	v_pk_add_f32 v[154:155], v[174:175], v[184:185]
	v_add_u32_e32 v174, 1, v168
	v_cndmask_b32_e64 v167, v167, v169, s[10:11]
	v_fma_f32 v169, -v173, v168, v165
	v_cmp_lt_f32_e64 s[10:11], 0, v172
	v_fma_f32 v171, -v174, v168, v165
	v_add_u32_e32 v175, -1, v166
	v_cndmask_b32_e64 v167, v167, v170, s[10:11]
	v_cmp_ge_f32_e64 s[10:11], 0, v169
	v_add_u32_e32 v176, 1, v166
	v_fma_f32 v169, -v175, v166, v164
	v_cndmask_b32_e64 v168, v168, v173, s[10:11]
	v_cmp_lt_f32_e64 s[10:11], 0, v171
	v_fma_f32 v170, -v176, v166, v164
	v_mul_f32_e32 v171, 0x37800000, v167
	v_cndmask_b32_e64 v168, v168, v174, s[10:11]
	v_cmp_ge_f32_e64 s[10:11], 0, v169
	v_cndmask_b32_e32 v167, v167, v171, vcc
	v_cmp_class_f32_e32 vcc, v163, v162
	v_cndmask_b32_e64 v166, v166, v175, s[10:11]
	v_cmp_lt_f32_e64 s[10:11], 0, v170
	v_mul_f32_e32 v169, 0x37800000, v168
	v_cndmask_b32_e32 v163, v167, v163, vcc
	v_cndmask_b32_e64 v166, v166, v176, s[10:11]
	v_cndmask_b32_e64 v167, v168, v169, s[6:7]
	v_cmp_class_f32_e32 vcc, v165, v162
	v_mul_f32_e32 v168, 0x37800000, v166
	v_div_scale_f32 v169, s[6:7], v163, v163, 1.0
	v_cndmask_b32_e32 v165, v167, v165, vcc
	v_cndmask_b32_e64 v166, v166, v168, s[8:9]
	v_cmp_class_f32_e32 vcc, v164, v162
	v_rcp_f32_e32 v167, v169
	v_div_scale_f32 v168, s[8:9], v165, v165, 1.0
	v_cndmask_b32_e32 v166, v166, v164, vcc
	v_rcp_f32_e32 v172, v168
	v_div_scale_f32 v173, s[10:11], v166, v166, 1.0
	v_rcp_f32_e32 v175, v173
	v_fma_f32 v164, -v169, v167, 1.0
	v_div_scale_f32 v170, s[6:7], 1.0, v163, 1.0
	v_fmac_f32_e32 v167, v164, v167
	v_fma_f32 v164, -v168, v172, 1.0
	v_mul_f32_e32 v176, v170, v167
	v_div_scale_f32 v171, s[8:9], 1.0, v165, 1.0
	v_fmac_f32_e32 v172, v164, v172
	v_fma_f32 v164, -v173, v175, 1.0
	v_fma_f32 v177, -v169, v176, v170
	v_div_scale_f32 v174, s[10:11], 1.0, v166, 1.0
	v_mul_f32_e32 v178, v171, v172
	v_fmac_f32_e32 v175, v164, v175
	v_fmac_f32_e32 v176, v177, v167
	v_fma_f32 v164, -v168, v178, v171
	v_mul_f32_e32 v177, v174, v175
	v_fma_f32 v169, -v169, v176, v170
	s_mov_b64 vcc, s[6:7]
	v_fmac_f32_e32 v178, v164, v172
	v_fma_f32 v164, -v173, v177, v174
	v_div_fmas_f32 v167, v169, v167, v176
	v_fma_f32 v168, -v168, v178, v171
	v_fmac_f32_e32 v177, v164, v175
	v_div_fixup_f32 v164, v167, v163, 1.0
	s_mov_b64 vcc, s[8:9]
	v_div_fmas_f32 v163, v168, v172, v178
	v_fma_f32 v167, -v173, v177, v174
	v_pk_mul_f32 v[80:81], v[80:81], v[164:165] op_sel_hi:[1,0]
	v_pk_mul_f32 v[78:79], v[78:79], v[164:165] op_sel_hi:[1,0]
	s_mov_b64 vcc, s[10:11]
	v_pk_add_f32 v[88:89], v[88:89], 1.0 op_sel_hi:[1,0]
	v_pk_add_f32 v[86:87], v[86:87], 1.0 op_sel_hi:[1,0]
	v_pk_mul_f32 v[76:77], v[76:77], v[164:165] op_sel_hi:[1,0]
	v_pk_mul_f32 v[74:75], v[74:75], v[164:165] op_sel_hi:[1,0]
	v_pk_mul_f32 v[72:73], v[72:73], v[164:165] op_sel_hi:[1,0]
	v_pk_mul_f32 v[70:71], v[70:71], v[164:165] op_sel_hi:[1,0]
	v_pk_mul_f32 v[68:69], v[68:69], v[164:165] op_sel_hi:[1,0]
	v_pk_mul_f32 v[66:67], v[66:67], v[164:165] op_sel_hi:[1,0]
	v_div_fixup_f32 v164, v163, v165, 1.0
	v_div_fmas_f32 v163, v167, v175, v177
	v_pk_mul_f32 v[78:79], v[78:79], v[2:3]
	v_pk_mul_f32 v[80:81], v[80:81], v[4:5]
	v_pk_mul_f32 v[64:65], v[64:65], v[164:165] op_sel_hi:[1,0]
	v_pk_mul_f32 v[62:63], v[62:63], v[164:165] op_sel_hi:[1,0]
	v_pk_mul_f32 v[60:61], v[60:61], v[164:165] op_sel_hi:[1,0]
	v_pk_mul_f32 v[58:59], v[58:59], v[164:165] op_sel_hi:[1,0]
	v_pk_mul_f32 v[56:57], v[56:57], v[164:165] op_sel_hi:[1,0]
	v_pk_mul_f32 v[54:55], v[54:55], v[164:165] op_sel_hi:[1,0]
	v_pk_mul_f32 v[52:53], v[52:53], v[164:165] op_sel_hi:[1,0]
	v_pk_mul_f32 v[50:51], v[50:51], v[164:165] op_sel_hi:[1,0]
	v_div_fixup_f32 v164, v163, v166, 1.0
	v_pk_fma_f32 v[80:81], v[80:81], v[88:89], v[84:85]
	v_pk_fma_f32 v[78:79], v[78:79], v[86:87], v[82:83]
	v_pk_mul_f32 v[82:83], v[50:51], v[14:15]
	v_pk_mul_f32 v[84:85], v[52:53], v[16:17]
	v_pk_mul_f32 v[48:49], v[48:49], v[164:165] op_sel_hi:[1,0]
	v_pk_mul_f32 v[46:47], v[46:47], v[164:165] op_sel_hi:[1,0]
	v_pk_mul_f32 v[86:87], v[46:47], v[2:3]
	v_pk_mul_f32 v[88:89], v[48:49], v[4:5]
	v_cvt_pk_bf16_f32 v46, v78, v79
	v_cvt_pk_bf16_f32 v47, v80, v81
	global_store_dwordx2 v[102:103], v[46:47], off
	global_load_dwordx4 v[46:49], v[142:143], off
	s_nop 0
	global_load_dwordx4 v[50:53], v[122:123], off offset:1024
	v_pk_mul_f32 v[74:75], v[74:75], v[6:7]
	v_pk_mul_f32 v[76:77], v[76:77], v[8:9]
	v_pk_mul_f32 v[70:71], v[70:71], v[10:11]
	v_pk_mul_f32 v[72:73], v[72:73], v[12:13]
	v_pk_mul_f32 v[66:67], v[66:67], v[14:15]
	v_pk_mul_f32 v[68:69], v[68:69], v[16:17]
	v_pk_mul_f32 v[62:63], v[62:63], v[2:3]
	v_pk_mul_f32 v[64:65], v[64:65], v[4:5]
	v_pk_mul_f32 v[58:59], v[58:59], v[6:7]
	v_pk_mul_f32 v[60:61], v[60:61], v[8:9]
	v_pk_mul_f32 v[54:55], v[54:55], v[10:11]
	v_pk_mul_f32 v[56:57], v[56:57], v[12:13]
	v_pk_mul_f32 v[44:45], v[44:45], v[164:165] op_sel_hi:[1,0]
	v_pk_mul_f32 v[42:43], v[42:43], v[164:165] op_sel_hi:[1,0]
	v_pk_mul_f32 v[44:45], v[44:45], v[8:9]
	v_pk_mul_f32 v[42:43], v[42:43], v[6:7]
	v_pk_mul_f32 v[40:41], v[40:41], v[164:165] op_sel_hi:[1,0]
	v_pk_mul_f32 v[38:39], v[38:39], v[164:165] op_sel_hi:[1,0]
	v_pk_mul_f32 v[40:41], v[40:41], v[12:13]
	v_pk_mul_f32 v[38:39], v[38:39], v[10:11]
	v_pk_mul_f32 v[36:37], v[36:37], v[164:165] op_sel_hi:[1,0]
	v_pk_mul_f32 v[34:35], v[34:35], v[164:165] op_sel_hi:[1,0]
	v_pk_mul_f32 v[36:37], v[36:37], v[16:17]
	v_pk_mul_f32 v[34:35], v[34:35], v[14:15]
	v_mul_f32_e32 v186, v23, v23
	v_mul_f32_e32 v192, v25, v25
	v_mul_f32_e32 v203, v18, v18
	v_mul_f32_e32 v204, v19, v19
	v_mul_f32_e32 v205, v20, v20
	v_mul_f32_e32 v206, v21, v21
	v_pk_fma_f32 v[148:149], v[22:23], v[22:23], v[186:187] op_sel_hi:[1,1,0]
	v_pk_fma_f32 v[150:151], v[24:25], v[24:25], v[192:193] op_sel_hi:[1,1,0]
	v_mov_b32_e32 v149, v205
	v_mov_b32_e32 v151, v206
	s_waitcnt vmcnt(0) lgkmcnt(0)
	v_pk_add_f32 v[48:49], v[48:49], 1.0 op_sel_hi:[1,0]
	v_pk_add_f32 v[46:47], v[46:47], 1.0 op_sel_hi:[1,0]
	v_pk_fma_f32 v[48:49], v[76:77], v[48:49], v[52:53]
	v_pk_fma_f32 v[46:47], v[74:75], v[46:47], v[50:51]
	v_cvt_pk_bf16_f32 v46, v46, v47
	v_cvt_pk_bf16_f32 v47, v48, v49
	global_store_dwordx2 v[102:103], v[46:47], off offset:512
	global_load_dwordx4 v[46:49], v[138:139], off
	s_nop 0
	global_load_dwordx4 v[50:53], v[122:123], off offset:2048
	s_waitcnt vmcnt(0) lgkmcnt(0)
	v_pk_add_f32 v[48:49], v[48:49], 1.0 op_sel_hi:[1,0]
	v_pk_add_f32 v[46:47], v[46:47], 1.0 op_sel_hi:[1,0]
	v_pk_fma_f32 v[48:49], v[72:73], v[48:49], v[52:53]
	v_pk_fma_f32 v[46:47], v[70:71], v[46:47], v[50:51]
	v_cvt_pk_bf16_f32 v46, v46, v47
	v_cvt_pk_bf16_f32 v47, v48, v49
	global_store_dwordx2 v[102:103], v[46:47], off offset:1024
	global_load_dwordx4 v[46:49], v[128:129], off
	s_nop 0
	global_load_dwordx4 v[50:53], v[122:123], off offset:3072
	s_waitcnt vmcnt(0) lgkmcnt(0)
	v_pk_add_f32 v[48:49], v[48:49], 1.0 op_sel_hi:[1,0]
	v_pk_add_f32 v[46:47], v[46:47], 1.0 op_sel_hi:[1,0]
	v_pk_fma_f32 v[48:49], v[68:69], v[48:49], v[52:53]
	v_pk_fma_f32 v[46:47], v[66:67], v[46:47], v[50:51]
	v_cvt_pk_bf16_f32 v46, v46, v47
	v_cvt_pk_bf16_f32 v47, v48, v49
	global_store_dwordx2 v[102:103], v[46:47], off offset:1536
	global_load_dwordx4 v[46:49], v[124:125], off
	s_nop 0
	global_load_dwordx4 v[50:53], v[110:111], off
	s_waitcnt vmcnt(0) lgkmcnt(0)
	v_pk_add_f32 v[48:49], v[48:49], 1.0 op_sel_hi:[1,0]
	v_pk_add_f32 v[46:47], v[46:47], 1.0 op_sel_hi:[1,0]
	v_pk_fma_f32 v[48:49], v[64:65], v[48:49], v[52:53]
	v_pk_fma_f32 v[46:47], v[62:63], v[46:47], v[50:51]
	v_cvt_pk_bf16_f32 v46, v46, v47
	v_cvt_pk_bf16_f32 v47, v48, v49
	global_store_dwordx2 v[102:103], v[46:47], off offset:2048
	global_load_dwordx4 v[46:49], v[118:119], off
	s_nop 0
	global_load_dwordx4 v[50:53], v[110:111], off offset:1024
	s_waitcnt vmcnt(0) lgkmcnt(0)
	v_pk_add_f32 v[48:49], v[48:49], 1.0 op_sel_hi:[1,0]
	v_pk_add_f32 v[46:47], v[46:47], 1.0 op_sel_hi:[1,0]
	v_pk_fma_f32 v[48:49], v[60:61], v[48:49], v[52:53]
	v_pk_fma_f32 v[46:47], v[58:59], v[46:47], v[50:51]
	v_cvt_pk_bf16_f32 v46, v46, v47
	v_cvt_pk_bf16_f32 v47, v48, v49
	global_store_dwordx2 v[102:103], v[46:47], off offset:2560
	global_load_dwordx4 v[46:49], v[114:115], off
	s_nop 0
	global_load_dwordx4 v[50:53], v[110:111], off offset:2048
	v_pk_add_f32 v[58:59], v[148:149], v[150:151]
	s_waitcnt vmcnt(0) lgkmcnt(0)
	v_pk_add_f32 v[48:49], v[48:49], 1.0 op_sel_hi:[1,0]
	v_pk_add_f32 v[46:47], v[46:47], 1.0 op_sel_hi:[1,0]
	v_pk_fma_f32 v[48:49], v[56:57], v[48:49], v[52:53]
	v_pk_fma_f32 v[46:47], v[54:55], v[46:47], v[50:51]
	v_cvt_pk_bf16_f32 v46, v46, v47
	v_cvt_pk_bf16_f32 v47, v48, v49
	global_store_dwordx2 v[102:103], v[46:47], off offset:3072
	global_load_dwordx4 v[46:49], v[112:113], off
	s_nop 0
	global_load_dwordx4 v[50:53], v[110:111], off offset:3072
	v_pk_add_f32 v[54:55], v[152:153], v[152:153] op_sel:[0,1] op_sel_hi:[1,0]
	v_pk_add_f32 v[56:57], v[154:155], v[154:155] op_sel:[0,1] op_sel_hi:[1,0]
	v_mov_b32_e32 v55, v203
	v_mov_b32_e32 v57, v204
	s_waitcnt vmcnt(0) lgkmcnt(0)
	v_pk_add_f32 v[48:49], v[48:49], 1.0 op_sel_hi:[1,0]
	v_pk_add_f32 v[46:47], v[46:47], 1.0 op_sel_hi:[1,0]
	v_pk_fma_f32 v[48:49], v[84:85], v[48:49], v[52:53]
	v_pk_fma_f32 v[46:47], v[82:83], v[46:47], v[50:51]
	v_cvt_pk_bf16_f32 v46, v46, v47
	v_cvt_pk_bf16_f32 v47, v48, v49
	global_store_dwordx2 v[102:103], v[46:47], off offset:3584
	global_load_dwordx4 v[46:49], v[146:147], off
	s_nop 0
	global_load_dwordx4 v[50:53], v[108:109], off
	s_waitcnt vmcnt(0) lgkmcnt(0)
	v_pk_add_f32 v[48:49], v[48:49], 1.0 op_sel_hi:[1,0]
	v_pk_add_f32 v[46:47], v[46:47], 1.0 op_sel_hi:[1,0]
	v_pk_fma_f32 v[48:49], v[88:89], v[48:49], v[52:53]
	v_pk_fma_f32 v[46:47], v[86:87], v[46:47], v[50:51]
	v_cvt_pk_bf16_f32 v46, v46, v47
	v_cvt_pk_bf16_f32 v47, v48, v49
	global_store_dwordx2 v[104:105], v[46:47], off
	global_load_dwordx4 v[46:49], v[144:145], off
	s_nop 0
	global_load_dwordx4 v[50:53], v[108:109], off offset:1024
	s_waitcnt vmcnt(0) lgkmcnt(0)
	v_pk_add_f32 v[48:49], v[48:49], 1.0 op_sel_hi:[1,0]
	v_pk_add_f32 v[46:47], v[46:47], 1.0 op_sel_hi:[1,0]
	v_pk_fma_f32 v[44:45], v[44:45], v[48:49], v[52:53]
	v_pk_fma_f32 v[42:43], v[42:43], v[46:47], v[50:51]
	v_cvt_pk_bf16_f32 v42, v42, v43
	v_cvt_pk_bf16_f32 v43, v44, v45
	global_store_dwordx2 v[104:105], v[42:43], off offset:512
	global_load_dwordx4 v[42:45], v[140:141], off
	s_nop 0
	global_load_dwordx4 v[46:49], v[108:109], off offset:2048
	v_pk_add_f32 v[50:51], v[54:55], v[56:57]
	s_waitcnt vmcnt(0) lgkmcnt(0)
	v_pk_add_f32 v[44:45], v[44:45], 1.0 op_sel_hi:[1,0]
	v_pk_add_f32 v[42:43], v[42:43], 1.0 op_sel_hi:[1,0]
	v_pk_fma_f32 v[40:41], v[40:41], v[44:45], v[48:49]
	v_pk_fma_f32 v[38:39], v[38:39], v[42:43], v[46:47]
	v_cvt_pk_bf16_f32 v38, v38, v39
	v_cvt_pk_bf16_f32 v39, v40, v41
	global_store_dwordx2 v[104:105], v[38:39], off offset:1024
	global_load_dwordx4 v[38:41], v[126:127], off
	s_nop 0
	global_load_dwordx4 v[42:45], v[108:109], off offset:3072
	v_pk_add_f32 v[50:51], v[50:51], v[58:59]
	s_waitcnt vmcnt(0) lgkmcnt(0)
	v_pk_add_f32 v[40:41], v[40:41], 1.0 op_sel_hi:[1,0]
	v_pk_add_f32 v[38:39], v[38:39], 1.0 op_sel_hi:[1,0]
	v_pk_fma_f32 v[36:37], v[36:37], v[40:41], v[44:45]
	v_pk_fma_f32 v[34:35], v[34:35], v[38:39], v[42:43]
	v_cvt_pk_bf16_f32 v34, v34, v35
	v_cvt_pk_bf16_f32 v35, v36, v37
	global_store_dwordx2 v[104:105], v[34:35], off offset:1536
	global_load_dwordx4 v[34:37], v[120:121], off
	s_nop 0
	global_load_dwordx4 v[38:41], v[106:107], off
	v_add_f32_e32 v50, v50, v51
	s_waitcnt lgkmcnt(0)
	s_nop 1
	v_add_f32_dpp v50, v50, v50 quad_perm:[1,0,3,2] row_mask:0xf bank_mask:0xf
	ds_bpermute_b32 v51, v156, v50
	s_waitcnt lgkmcnt(0)
	v_add_f32_e32 v50, v50, v51
	ds_bpermute_b32 v46, v157, v50
	s_waitcnt lgkmcnt(0)
	v_add_f32_e32 v46, v50, v46
	ds_bpermute_b32 v47, v158, v46
	s_waitcnt lgkmcnt(0)
	v_add_f32_e32 v46, v46, v47
	ds_bpermute_b32 v47, v159, v46
	s_waitcnt lgkmcnt(0)
	v_add_f32_e32 v46, v46, v47
	ds_bpermute_b32 v47, v160, v46
	s_waitcnt lgkmcnt(0)
	v_add_f32_e32 v46, v46, v47
	v_fmamk_f32 v46, v46, 0x3a800000, v161
	v_mul_f32_e32 v47, 0x4f800000, v46
	v_cmp_gt_f32_e32 vcc, s19, v46
	s_waitcnt vmcnt(0)
	v_pk_add_f32 v[36:37], v[36:37], 1.0 op_sel_hi:[1,0]
	v_cndmask_b32_e32 v42, v46, v47, vcc
	v_sqrt_f32_e32 v43, v42
	v_pk_add_f32 v[34:35], v[34:35], 1.0 op_sel_hi:[1,0]
	v_add_u32_e32 v44, -1, v43
	v_add_u32_e32 v45, 1, v43
	v_fma_f32 v46, -v44, v43, v42
	v_fma_f32 v47, -v45, v43, v42
	v_cmp_ge_f32_e64 s[6:7], 0, v46
	s_nop 1
	v_cndmask_b32_e64 v43, v43, v44, s[6:7]
	v_cmp_lt_f32_e64 s[6:7], 0, v47
	s_nop 1
	v_cndmask_b32_e64 v43, v43, v45, s[6:7]
	v_mul_f32_e32 v44, 0x37800000, v43
	v_cndmask_b32_e32 v43, v43, v44, vcc
	v_cmp_class_f32_e32 vcc, v42, v162
	s_nop 1
	v_cndmask_b32_e32 v42, v43, v42, vcc
	v_div_scale_f32 v43, s[6:7], v42, v42, 1.0
	v_rcp_f32_e32 v45, v43
	v_div_scale_f32 v44, vcc, 1.0, v42, 1.0
	v_fma_f32 v46, -v43, v45, 1.0
	v_fmac_f32_e32 v45, v46, v45
	v_mul_f32_e32 v46, v44, v45
	v_fma_f32 v47, -v43, v46, v44
	v_fmac_f32_e32 v46, v47, v45
	v_fma_f32 v43, -v43, v46, v44
	v_div_fmas_f32 v43, v43, v45, v46
	v_div_fixup_f32 v42, v43, v42, 1.0
	v_pk_mul_f32 v[32:33], v[32:33], v[42:43] op_sel_hi:[1,0]
	v_pk_mul_f32 v[30:31], v[30:31], v[42:43] op_sel_hi:[1,0]
	v_pk_mul_f32 v[32:33], v[32:33], v[4:5]
	v_pk_mul_f32 v[30:31], v[30:31], v[2:3]
	v_pk_fma_f32 v[32:33], v[32:33], v[36:37], v[40:41]
	v_pk_fma_f32 v[30:31], v[30:31], v[34:35], v[38:39]
	v_cvt_pk_bf16_f32 v30, v30, v31
	v_cvt_pk_bf16_f32 v31, v32, v33
	global_store_dwordx2 v[104:105], v[30:31], off offset:2048
	global_load_dwordx4 v[30:33], v[116:117], off
	s_nop 0
	global_load_dwordx4 v[34:37], v[106:107], off offset:1024
	v_pk_mul_f32 v[28:29], v[28:29], v[42:43] op_sel_hi:[1,0]
	v_pk_mul_f32 v[26:27], v[26:27], v[42:43] op_sel_hi:[1,0]
	v_pk_mul_f32 v[28:29], v[28:29], v[8:9]
	v_pk_mul_f32 v[26:27], v[26:27], v[6:7]
	v_lshl_add_u64 v[38:39], s[24:25], 0, v[98:99]
	v_pk_mul_f32 v[24:25], v[24:25], v[42:43] op_sel_hi:[1,0]
	v_pk_mul_f32 v[22:23], v[22:23], v[42:43] op_sel_hi:[1,0]
	v_pk_mul_f32 v[24:25], v[24:25], v[12:13]
	v_pk_mul_f32 v[22:23], v[22:23], v[10:11]
	v_pk_mul_f32 v[20:21], v[20:21], v[42:43] op_sel_hi:[1,0]
	v_pk_mul_f32 v[18:19], v[18:19], v[42:43] op_sel_hi:[1,0]
	v_pk_mul_f32 v[20:21], v[20:21], v[16:17]
	v_pk_mul_f32 v[18:19], v[18:19], v[14:15]
	s_waitcnt vmcnt(0) lgkmcnt(0)
	v_pk_add_f32 v[32:33], v[32:33], 1.0 op_sel_hi:[1,0]
	v_pk_add_f32 v[30:31], v[30:31], 1.0 op_sel_hi:[1,0]
	v_pk_fma_f32 v[28:29], v[28:29], v[32:33], v[36:37]
	v_pk_fma_f32 v[26:27], v[26:27], v[30:31], v[34:35]
	v_cvt_pk_bf16_f32 v26, v26, v27
	v_cvt_pk_bf16_f32 v27, v28, v29
	global_store_dwordx2 v[104:105], v[26:27], off offset:2560
	global_load_dwordx4 v[26:29], v[38:39], off
	s_nop 0
	global_load_dwordx4 v[30:33], v[106:107], off offset:2048
	v_lshl_add_u64 v[34:35], s[24:25], 0, v[100:101]
	s_waitcnt vmcnt(0) lgkmcnt(0)
	v_pk_add_f32 v[28:29], v[28:29], 1.0 op_sel_hi:[1,0]
	v_pk_add_f32 v[26:27], v[26:27], 1.0 op_sel_hi:[1,0]
	v_pk_fma_f32 v[24:25], v[24:25], v[28:29], v[32:33]
	v_pk_fma_f32 v[22:23], v[22:23], v[26:27], v[30:31]
	v_cvt_pk_bf16_f32 v22, v22, v23
	v_cvt_pk_bf16_f32 v23, v24, v25
	global_store_dwordx2 v[104:105], v[22:23], off offset:3072
	global_load_dwordx4 v[22:25], v[34:35], off
	s_nop 0
	global_load_dwordx4 v[26:29], v[106:107], off offset:3072
	s_waitcnt vmcnt(0) lgkmcnt(0)
	v_pk_add_f32 v[24:25], v[24:25], 1.0 op_sel_hi:[1,0]
	v_pk_add_f32 v[22:23], v[22:23], 1.0 op_sel_hi:[1,0]
	v_pk_fma_f32 v[20:21], v[20:21], v[24:25], v[28:29]
	v_pk_fma_f32 v[18:19], v[18:19], v[22:23], v[26:27]
	v_cvt_pk_bf16_f32 v18, v18, v19
	v_cvt_pk_bf16_f32 v19, v20, v21
	global_store_dwordx2 v[104:105], v[18:19], off offset:3584
	s_cbranch_scc1 .LBB0_842

.LBB0_1004:
	v_lshl_add_u64 v[18:19], s[38:39], 0, v[94:95]
	v_lshl_add_u64 v[22:23], s[38:39], 0, v[92:93]
	v_add_co_u32_e32 v20, vcc, 0x7800000, v18
	v_add_co_u32_e64 v102, s[6:7], s24, v22
	s_nop 0
	v_addc_co_u32_e32 v21, vcc, 0, v19, vcc
	v_addc_co_u32_e64 v103, s[6:7], 0, v23, s[6:7]
	v_add_co_u32_e64 v104, s[6:7], s25, v22
	v_add_co_u32_e32 v22, vcc, 0x7801000, v18
	s_nop 0
	v_addc_co_u32_e64 v105, s[6:7], 0, v23, s[6:7]
	global_load_dwordx4 v[78:81], v[20:21], off
	global_load_dwordx4 v[74:77], v[20:21], off offset:1024
	global_load_dwordx4 v[70:73], v[20:21], off offset:2048
	global_load_dwordx4 v[66:69], v[20:21], off offset:3072
	v_addc_co_u32_e32 v23, vcc, 0, v19, vcc
	v_add_co_u32_e32 v20, vcc, 0x7802000, v18
	global_load_dwordx4 v[62:65], v[22:23], off
	global_load_dwordx4 v[58:61], v[22:23], off offset:1024
	global_load_dwordx4 v[54:57], v[22:23], off offset:2048
	global_load_dwordx4 v[50:53], v[22:23], off offset:3072
	v_addc_co_u32_e32 v21, vcc, 0, v19, vcc
	global_load_dwordx4 v[46:49], v[20:21], off
	global_load_dwordx4 v[42:45], v[20:21], off offset:1024
	global_load_dwordx4 v[38:41], v[20:21], off offset:2048
	global_load_dwordx4 v[34:37], v[20:21], off offset:3072
	v_add_co_u32_e32 v82, vcc, 0x7803000, v18
	s_add_i32 s26, s8, 32
	s_nop 0
	v_addc_co_u32_e32 v83, vcc, 0, v19, vcc
	global_load_dwordx4 v[30:33], v[82:83], off
	global_load_dwordx4 v[26:29], v[82:83], off offset:1024
	global_load_dwordx4 v[22:25], v[82:83], off offset:2048
	global_load_dwordx4 v[18:21], v[82:83], off offset:3072
	s_add_i32 s10, s8, 0xffffc022
	s_ashr_i32 s9, s26, 13
	s_cmpk_lt_i32 s26, 0x4000
	s_cselect_b32 s6, s9, s10
	s_mul_hi_i32 s7, s6, 0x9000
	s_mul_i32 s6, s6, 0x9000
	s_add_u32 s6, s2, s6
	s_addc_u32 s7, s13, s7
	s_add_u32 s10, s6, 0x1000
	s_addc_u32 s11, s7, 0
	v_lshl_add_u64 v[124:125], s[6:7], 0, v[90:91]
	v_lshl_add_u64 v[86:87], s[10:11], 0, v[90:91]
	global_load_dwordx4 v[82:85], v[124:125], off
	s_add_i32 s6, s8, 0xffffc023
	global_load_dwordx4 v[86:89], v[86:87], off
	s_cmpk_lt_i32 s26, 0x3fff
	s_cselect_b32 s6, s9, s6
	s_mul_hi_i32 s7, s6, 0x9000
	s_mul_i32 s6, s6, 0x9000
	s_add_u32 s6, s2, s6
	s_addc_u32 s7, s13, s7
	v_lshl_add_u64 v[138:139], s[10:11], 0, v[96:97]
	v_lshl_add_u64 v[134:135], s[10:11], 0, v[98:99]
	v_lshl_add_u64 v[128:129], s[10:11], 0, v[100:101]
	s_add_u32 s10, s6, 0x1000
	v_lshl_add_u64 v[110:111], s[6:7], 0, v[90:91]
	s_addc_u32 s11, s7, 0
	s_add_i32 s6, s8, 0xffffc024
	s_cmpk_lt_i32 s26, 0x3ffe
	s_cselect_b32 s6, s9, s6
	s_mul_hi_i32 s7, s6, 0x9000
	s_mul_i32 s6, s6, 0x9000
	v_lshl_add_u64 v[126:127], s[10:11], 0, v[90:91]
	v_lshl_add_u64 v[120:121], s[10:11], 0, v[96:97]
	v_lshl_add_u64 v[116:117], s[10:11], 0, v[98:99]
	v_lshl_add_u64 v[112:113], s[10:11], 0, v[100:101]
	s_add_u32 s10, s2, s6
	s_addc_u32 s11, s13, s7
	s_add_u32 s6, s10, 0x1000
	s_addc_u32 s7, s11, 0
	s_addk_i32 s8, 0xc025
	s_cmpk_lt_i32 s26, 0x3ffd
	v_lshl_add_u64 v[142:143], s[6:7], 0, v[90:91]
	v_lshl_add_u64 v[140:141], s[6:7], 0, v[96:97]
	v_lshl_add_u64 v[136:137], s[6:7], 0, v[98:99]
	v_lshl_add_u64 v[122:123], s[6:7], 0, v[100:101]
	s_cselect_b32 s6, s9, s8
	s_mul_hi_i32 s7, s6, 0x9000
	s_mul_i32 s6, s6, 0x9000
	s_add_u32 s6, s2, s6
	s_addc_u32 s7, s13, s7
	s_add_u32 s20, s6, 0x1000
	v_lshl_add_u64 v[106:107], s[6:7], 0, v[90:91]
	s_addc_u32 s21, s7, 0
	v_lshl_add_u64 v[108:109], s[10:11], 0, v[90:91]
	v_lshl_add_u64 v[118:119], s[20:21], 0, v[90:91]
	v_lshl_add_u64 v[114:115], s[20:21], 0, v[96:97]
	v_lshl_add_u64 v[92:93], v[92:93], 0, s[16:17]
	v_lshl_add_u64 v[94:95], v[94:95], 0, s[18:19]
	s_cmp_lt_i32 s26, s22
	s_waitcnt vmcnt(0) lgkmcnt(0)
	v_pk_mul_f32 v[144:145], v[80:81], v[80:81]
	v_pk_mul_f32 v[146:147], v[78:79], v[78:79]
	v_pk_mul_f32 v[148:149], v[76:77], v[76:77]
	v_pk_mul_f32 v[150:151], v[74:75], v[74:75]
	v_mul_f32_e32 v158, v71, v71
	v_mul_f32_e32 v160, v73, v73
	v_pk_mov_b32 v[162:163], v[146:147], v[144:145] op_sel:[1,0]
	v_mov_b32_e32 v147, v145
	v_pk_mov_b32 v[144:145], v[150:151], v[148:149] op_sel:[1,0]
	v_mov_b32_e32 v151, v149
	v_mul_f32_e32 v171, v68, v68
	v_mul_f32_e32 v173, v69, v69
	v_pk_fma_f32 v[148:149], v[70:71], v[70:71], v[158:159] op_sel_hi:[1,1,0]
	v_pk_fma_f32 v[158:159], v[72:73], v[72:73], v[160:161] op_sel_hi:[1,1,0]
	v_pk_mul_f32 v[160:161], v[64:65], v[64:65]
	v_pk_mul_f32 v[164:165], v[62:63], v[62:63]
	v_pk_mul_f32 v[166:167], v[60:61], v[60:61]
	v_pk_mul_f32 v[168:169], v[58:59], v[58:59]
	v_mul_f32_e32 v170, v55, v55
	v_mul_f32_e32 v172, v57, v57
	v_pk_add_f32 v[146:147], v[162:163], v[146:147]
	v_pk_add_f32 v[144:145], v[144:145], v[150:151]
	v_mul_f32_e32 v157, v66, v66
	v_mul_f32_e32 v181, v67, v67
	v_mov_b32_e32 v149, v171
	v_mov_b32_e32 v159, v173
	v_pk_mov_b32 v[150:151], v[164:165], v[160:161] op_sel:[1,0]
	v_mov_b32_e32 v165, v161
	v_pk_mov_b32 v[160:161], v[168:169], v[166:167] op_sel:[1,0]
	v_mov_b32_e32 v169, v167
	v_pk_fma_f32 v[162:163], v[54:55], v[54:55], v[170:171] op_sel_hi:[1,1,0]
	v_pk_fma_f32 v[166:167], v[56:57], v[56:57], v[172:173] op_sel_hi:[1,1,0]
	v_pk_mul_f32 v[170:171], v[48:49], v[48:49]
	v_pk_mul_f32 v[172:173], v[46:47], v[46:47]
	v_pk_add_f32 v[182:183], v[146:147], v[146:147] op_sel:[0,1] op_sel_hi:[1,0]
	v_pk_add_f32 v[184:185], v[144:145], v[144:145] op_sel:[0,1] op_sel_hi:[1,0]
	v_mul_f32_e32 v179, v52, v52
	v_pk_mul_f32 v[174:175], v[44:45], v[44:45]
	v_pk_mul_f32 v[176:177], v[42:43], v[42:43]
	v_mul_f32_e32 v178, v39, v39
	v_mul_f32_e32 v180, v41, v41
	v_pk_add_f32 v[158:159], v[148:149], v[158:159]
	v_pk_add_f32 v[144:145], v[150:151], v[164:165]
	v_pk_add_f32 v[146:147], v[160:161], v[168:169]
	v_pk_mov_b32 v[148:149], v[172:173], v[170:171] op_sel:[1,0]
	v_mov_b32_e32 v173, v171
	v_mov_b32_e32 v183, v157
	v_mov_b32_e32 v185, v181
	v_mul_f32_e32 v187, v50, v50
	v_mul_f32_e32 v192, v51, v51
	v_mul_f32_e32 v186, v53, v53
	v_mul_f32_e32 v195, v36, v36
	v_mul_f32_e32 v196, v37, v37
	v_pk_mov_b32 v[150:151], v[176:177], v[174:175] op_sel:[1,0]
	v_mov_b32_e32 v177, v175
	v_pk_fma_f32 v[160:161], v[38:39], v[38:39], v[178:179] op_sel_hi:[1,1,0]
	v_pk_fma_f32 v[164:165], v[40:41], v[40:41], v[180:181] op_sel_hi:[1,1,0]
	v_pk_add_f32 v[188:189], v[144:145], v[144:145] op_sel:[0,1] op_sel_hi:[1,0]
	v_pk_add_f32 v[190:191], v[146:147], v[146:147] op_sel:[0,1] op_sel_hi:[1,0]
	v_pk_add_f32 v[148:149], v[148:149], v[172:173]
	v_pk_add_f32 v[172:173], v[182:183], v[184:185]
	v_mov_b32_e32 v163, v179
	v_mov_b32_e32 v167, v186
	v_pk_mul_f32 v[168:169], v[32:33], v[32:33]
	v_pk_mul_f32 v[170:171], v[30:31], v[30:31]
	v_pk_mul_f32 v[174:175], v[28:29], v[28:29]
	v_pk_mul_f32 v[178:179], v[26:27], v[26:27]
	v_pk_add_f32 v[150:151], v[150:151], v[176:177]
	v_mov_b32_e32 v161, v195
	v_mov_b32_e32 v165, v196
	v_mov_b32_e32 v189, v187
	v_mov_b32_e32 v191, v192
	v_pk_add_f32 v[158:159], v[172:173], v[158:159]
	v_mul_f32_e32 v193, v34, v34
	v_mul_f32_e32 v194, v35, v35
	v_pk_add_f32 v[162:163], v[162:163], v[166:167]
	v_pk_mov_b32 v[166:167], v[170:171], v[168:169] op_sel:[1,0]
	v_mov_b32_e32 v171, v169
	v_pk_mov_b32 v[168:169], v[178:179], v[174:175] op_sel:[1,0]
	v_mov_b32_e32 v179, v175
	v_pk_add_f32 v[174:175], v[148:149], v[148:149] op_sel:[0,1] op_sel_hi:[1,0]
	v_pk_add_f32 v[176:177], v[150:151], v[150:151] op_sel:[0,1] op_sel_hi:[1,0]
	v_pk_add_f32 v[160:161], v[160:161], v[164:165]
	v_pk_add_f32 v[164:165], v[188:189], v[190:191]
	v_add_f32_e32 v157, v158, v159
	v_mov_b32_e32 v175, v193
	v_mov_b32_e32 v177, v194
	v_pk_add_f32 v[158:159], v[164:165], v[162:163]
	ds_bpermute_b32 v165, v1, v157
	v_pk_add_f32 v[162:163], v[174:175], v[176:177]
	v_add_f32_e32 v164, v158, v159
	v_pk_add_f32 v[158:159], v[162:163], v[160:161]
	v_add_f32_e32 v158, v158, v159
	s_waitcnt lgkmcnt(0)
	v_add_f32_e32 v157, v157, v165
	s_waitcnt lgkmcnt(0)
	s_nop 1
	v_add_f32_dpp v160, v164, v164 quad_perm:[1,0,3,2] row_mask:0xf bank_mask:0xf
	s_waitcnt lgkmcnt(0)
	s_nop 1
	v_add_f32_dpp v158, v158, v158 quad_perm:[1,0,3,2] row_mask:0xf bank_mask:0xf
	s_waitcnt lgkmcnt(0)
	s_nop 1
	v_add_f32_dpp v157, v157, v157 quad_perm:[2,3,0,1] row_mask:0xf bank_mask:0xf
	ds_bpermute_b32 v161, v133, v157
	s_waitcnt lgkmcnt(2)
	s_nop 1
	v_add_f32_dpp v160, v160, v160 quad_perm:[2,3,0,1] row_mask:0xf bank_mask:0xf
	s_waitcnt lgkmcnt(0)
	s_nop 1
	v_add_f32_dpp v158, v158, v158 quad_perm:[2,3,0,1] row_mask:0xf bank_mask:0xf
	s_waitcnt lgkmcnt(0)
	v_add_f32_e32 v157, v157, v161
	ds_bpermute_b32 v161, v152, v157
	s_waitcnt lgkmcnt(2)
	s_nop 1
	v_add_f32_dpp v160, v160, v160 row_half_mirror row_mask:0xf bank_mask:0xf
	s_waitcnt lgkmcnt(0)
	s_nop 1
	v_add_f32_dpp v158, v158, v158 row_half_mirror row_mask:0xf bank_mask:0xf
	s_waitcnt lgkmcnt(0)
	v_add_f32_e32 v157, v157, v161
	ds_bpermute_b32 v161, v153, v157
	s_waitcnt lgkmcnt(2)
	s_nop 1
	v_add_f32_dpp v160, v160, v160 row_mirror row_mask:0xf bank_mask:0xf
	ds_bpermute_b32 v162, v153, v160
	s_waitcnt lgkmcnt(2)
	s_nop 1
	v_add_f32_dpp v158, v158, v158 row_mirror row_mask:0xf bank_mask:0xf
	ds_bpermute_b32 v159, v153, v158
	s_waitcnt lgkmcnt(2)
	v_add_f32_e32 v157, v157, v161
	ds_bpermute_b32 v161, v154, v157
	s_waitcnt lgkmcnt(2)
	v_add_f32_e32 v160, v160, v162
	ds_bpermute_b32 v162, v154, v160
	s_waitcnt lgkmcnt(2)
	v_add_f32_e32 v158, v158, v159
	ds_bpermute_b32 v159, v154, v158
	s_waitcnt lgkmcnt(2)
	v_add_f32_e32 v157, v157, v161
	v_fmamk_f32 v157, v157, 0x3a800000, v155
	s_waitcnt lgkmcnt(1)
	v_add_f32_e32 v160, v160, v162
	v_mul_f32_e32 v161, 0x4f800000, v157
	v_cmp_gt_f32_e32 vcc, s4, v157
	v_fmamk_f32 v160, v160, 0x3a800000, v155
	s_waitcnt lgkmcnt(0)
	v_add_f32_e32 v158, v158, v159
	v_cndmask_b32_e32 v157, v157, v161, vcc
	v_mul_f32_e32 v159, 0x4f800000, v160
	v_cmp_gt_f32_e64 s[6:7], s4, v160
	v_sqrt_f32_e32 v161, v157
	v_fmamk_f32 v158, v158, 0x3a800000, v155
	v_cndmask_b32_e64 v159, v160, v159, s[6:7]
	v_mul_f32_e32 v160, 0x4f800000, v158
	v_cmp_gt_f32_e64 s[8:9], s4, v158
	v_sqrt_f32_e32 v162, v159
	v_add_u32_e32 v163, -1, v161
	v_cndmask_b32_e64 v158, v158, v160, s[8:9]
	v_sqrt_f32_e32 v160, v158
	v_add_u32_e32 v164, 1, v161
	v_fma_f32 v165, -v163, v161, v157
	v_pk_add_f32 v[148:149], v[166:167], v[170:171]
	v_fma_f32 v166, -v164, v161, v157
	v_add_u32_e32 v167, -1, v162
	v_cmp_ge_f32_e64 s[10:11], 0, v165
	v_pk_add_f32 v[150:151], v[168:169], v[178:179]
	v_add_u32_e32 v168, 1, v162
	v_cndmask_b32_e64 v161, v161, v163, s[10:11]
	v_fma_f32 v163, -v167, v162, v159
	v_cmp_lt_f32_e64 s[10:11], 0, v166
	v_fma_f32 v165, -v168, v162, v159
	v_add_u32_e32 v169, -1, v160
	v_cndmask_b32_e64 v161, v161, v164, s[10:11]
	v_cmp_ge_f32_e64 s[10:11], 0, v163
	v_add_u32_e32 v170, 1, v160
	v_fma_f32 v163, -v169, v160, v158
	v_cndmask_b32_e64 v162, v162, v167, s[10:11]
	v_cmp_lt_f32_e64 s[10:11], 0, v165
	v_fma_f32 v164, -v170, v160, v158
	v_mul_f32_e32 v165, 0x37800000, v161
	v_cndmask_b32_e64 v162, v162, v168, s[10:11]
	v_cmp_ge_f32_e64 s[10:11], 0, v163
	v_cndmask_b32_e32 v161, v161, v165, vcc
	v_cmp_class_f32_e32 vcc, v157, v156
	v_cndmask_b32_e64 v160, v160, v169, s[10:11]
	v_cmp_lt_f32_e64 s[10:11], 0, v164
	v_mul_f32_e32 v163, 0x37800000, v162
	v_cndmask_b32_e32 v157, v161, v157, vcc
	v_cndmask_b32_e64 v160, v160, v170, s[10:11]
	v_cndmask_b32_e64 v161, v162, v163, s[6:7]
	v_cmp_class_f32_e32 vcc, v159, v156
	v_mul_f32_e32 v162, 0x37800000, v160
	v_div_scale_f32 v163, s[6:7], v157, v157, 1.0
	v_cndmask_b32_e32 v159, v161, v159, vcc
	v_cndmask_b32_e64 v160, v160, v162, s[8:9]
	v_cmp_class_f32_e32 vcc, v158, v156
	v_rcp_f32_e32 v161, v163
	v_div_scale_f32 v162, s[8:9], v159, v159, 1.0
	v_cndmask_b32_e32 v160, v160, v158, vcc
	v_rcp_f32_e32 v166, v162
	v_div_scale_f32 v167, s[10:11], v160, v160, 1.0
	v_rcp_f32_e32 v169, v167
	v_fma_f32 v158, -v163, v161, 1.0
	v_div_scale_f32 v164, s[6:7], 1.0, v157, 1.0
	v_fmac_f32_e32 v161, v158, v161
	v_fma_f32 v158, -v162, v166, 1.0
	v_mul_f32_e32 v170, v164, v161
	v_div_scale_f32 v165, s[8:9], 1.0, v159, 1.0
	v_fmac_f32_e32 v166, v158, v166
	v_fma_f32 v158, -v167, v169, 1.0
	v_fma_f32 v171, -v163, v170, v164
	v_div_scale_f32 v168, s[10:11], 1.0, v160, 1.0
	v_mul_f32_e32 v172, v165, v166
	v_fmac_f32_e32 v169, v158, v169
	v_fmac_f32_e32 v170, v171, v161
	v_fma_f32 v158, -v162, v172, v165
	v_mul_f32_e32 v171, v168, v169
	v_fma_f32 v163, -v163, v170, v164
	s_mov_b64 vcc, s[6:7]
	v_fmac_f32_e32 v172, v158, v166
	v_fma_f32 v158, -v167, v171, v168
	v_div_fmas_f32 v161, v163, v161, v170
	v_fma_f32 v162, -v162, v172, v165
	v_fmac_f32_e32 v171, v158, v169
	v_div_fixup_f32 v158, v161, v157, 1.0
	s_mov_b64 vcc, s[8:9]
	v_div_fmas_f32 v157, v162, v166, v172
	v_fma_f32 v161, -v167, v171, v168
	v_pk_mul_f32 v[80:81], v[80:81], v[158:159] op_sel_hi:[1,0]
	v_pk_mul_f32 v[78:79], v[78:79], v[158:159] op_sel_hi:[1,0]
	s_mov_b64 vcc, s[10:11]
	v_pk_add_f32 v[88:89], v[88:89], 1.0 op_sel_hi:[1,0]
	v_pk_add_f32 v[86:87], v[86:87], 1.0 op_sel_hi:[1,0]
	v_pk_mul_f32 v[76:77], v[76:77], v[158:159] op_sel_hi:[1,0]
	v_pk_mul_f32 v[74:75], v[74:75], v[158:159] op_sel_hi:[1,0]
	v_pk_mul_f32 v[72:73], v[72:73], v[158:159] op_sel_hi:[1,0]
	v_pk_mul_f32 v[70:71], v[70:71], v[158:159] op_sel_hi:[1,0]
	v_pk_mul_f32 v[68:69], v[68:69], v[158:159] op_sel_hi:[1,0]
	v_pk_mul_f32 v[66:67], v[66:67], v[158:159] op_sel_hi:[1,0]
	v_div_fixup_f32 v158, v157, v159, 1.0
	v_div_fmas_f32 v157, v161, v169, v171
	v_pk_mul_f32 v[78:79], v[78:79], v[2:3]
	v_pk_mul_f32 v[80:81], v[80:81], v[4:5]
	v_pk_mul_f32 v[64:65], v[64:65], v[158:159] op_sel_hi:[1,0]
	v_pk_mul_f32 v[62:63], v[62:63], v[158:159] op_sel_hi:[1,0]
	v_pk_mul_f32 v[60:61], v[60:61], v[158:159] op_sel_hi:[1,0]
	v_pk_mul_f32 v[58:59], v[58:59], v[158:159] op_sel_hi:[1,0]
	v_pk_mul_f32 v[56:57], v[56:57], v[158:159] op_sel_hi:[1,0]
	v_pk_mul_f32 v[54:55], v[54:55], v[158:159] op_sel_hi:[1,0]
	v_pk_mul_f32 v[52:53], v[52:53], v[158:159] op_sel_hi:[1,0]
	v_pk_mul_f32 v[158:159], v[50:51], v[158:159] op_sel_hi:[1,0]
	v_div_fixup_f32 v50, v157, v160, 1.0
	v_pk_fma_f32 v[80:81], v[80:81], v[88:89], v[84:85]
	v_pk_fma_f32 v[78:79], v[78:79], v[86:87], v[82:83]
	v_pk_mul_f32 v[86:87], v[52:53], v[16:17]
	v_pk_mul_f32 v[48:49], v[48:49], v[50:51] op_sel_hi:[1,0]
	v_pk_mul_f32 v[46:47], v[46:47], v[50:51] op_sel_hi:[1,0]
	v_pk_mul_f32 v[82:83], v[54:55], v[10:11]
	v_pk_mul_f32 v[84:85], v[158:159], v[14:15]
	v_pk_mul_f32 v[88:89], v[46:47], v[2:3]
	v_pk_mul_f32 v[158:159], v[48:49], v[4:5]
	v_cvt_pk_bf16_f32 v46, v78, v79
	v_cvt_pk_bf16_f32 v47, v80, v81
	global_store_dwordx2 v[102:103], v[46:47], off
	global_load_dwordx4 v[46:49], v[138:139], off
	s_nop 0
	global_load_dwordx4 v[52:55], v[124:125], off offset:1024
	v_pk_mul_f32 v[74:75], v[74:75], v[6:7]
	v_pk_mul_f32 v[76:77], v[76:77], v[8:9]
	v_pk_mul_f32 v[70:71], v[70:71], v[10:11]
	v_pk_mul_f32 v[72:73], v[72:73], v[12:13]
	v_pk_mul_f32 v[66:67], v[66:67], v[14:15]
	v_pk_mul_f32 v[68:69], v[68:69], v[16:17]
	v_pk_mul_f32 v[62:63], v[62:63], v[2:3]
	v_pk_mul_f32 v[64:65], v[64:65], v[4:5]
	v_pk_mul_f32 v[58:59], v[58:59], v[6:7]
	v_pk_mul_f32 v[60:61], v[60:61], v[8:9]
	v_pk_mul_f32 v[56:57], v[56:57], v[12:13]
	v_mul_f32_e32 v180, v23, v23
	v_mul_f32_e32 v186, v25, v25
	v_mul_f32_e32 v197, v18, v18
	v_mul_f32_e32 v198, v19, v19
	v_mul_f32_e32 v199, v20, v20
	v_mul_f32_e32 v200, v21, v21
	v_pk_fma_f32 v[144:145], v[22:23], v[22:23], v[180:181] op_sel_hi:[1,1,0]
	v_pk_fma_f32 v[146:147], v[24:25], v[24:25], v[186:187] op_sel_hi:[1,1,0]
	v_mov_b32_e32 v145, v199
	v_mov_b32_e32 v147, v200
	s_mov_b32 s8, s26
	s_waitcnt vmcnt(0) lgkmcnt(0)
	v_pk_add_f32 v[48:49], v[48:49], 1.0 op_sel_hi:[1,0]
	v_pk_add_f32 v[46:47], v[46:47], 1.0 op_sel_hi:[1,0]
	v_pk_fma_f32 v[48:49], v[76:77], v[48:49], v[54:55]
	v_pk_fma_f32 v[46:47], v[74:75], v[46:47], v[52:53]
	v_cvt_pk_bf16_f32 v46, v46, v47
	v_cvt_pk_bf16_f32 v47, v48, v49
	global_store_dwordx2 v[102:103], v[46:47], off offset:512
	global_load_dwordx4 v[46:49], v[134:135], off
	s_nop 0
	global_load_dwordx4 v[52:55], v[124:125], off offset:2048
	s_waitcnt vmcnt(0) lgkmcnt(0)
	v_pk_add_f32 v[48:49], v[48:49], 1.0 op_sel_hi:[1,0]
	v_pk_add_f32 v[46:47], v[46:47], 1.0 op_sel_hi:[1,0]
	v_pk_fma_f32 v[48:49], v[72:73], v[48:49], v[54:55]
	v_pk_fma_f32 v[46:47], v[70:71], v[46:47], v[52:53]
	v_cvt_pk_bf16_f32 v46, v46, v47
	v_cvt_pk_bf16_f32 v47, v48, v49
	global_store_dwordx2 v[102:103], v[46:47], off offset:1024
	global_load_dwordx4 v[46:49], v[128:129], off
	s_nop 0
	global_load_dwordx4 v[52:55], v[124:125], off offset:3072
	s_waitcnt vmcnt(0) lgkmcnt(0)
	v_pk_add_f32 v[48:49], v[48:49], 1.0 op_sel_hi:[1,0]
	v_pk_add_f32 v[46:47], v[46:47], 1.0 op_sel_hi:[1,0]
	v_pk_fma_f32 v[48:49], v[68:69], v[48:49], v[54:55]
	v_pk_fma_f32 v[46:47], v[66:67], v[46:47], v[52:53]
	v_cvt_pk_bf16_f32 v46, v46, v47
	v_cvt_pk_bf16_f32 v47, v48, v49
	global_store_dwordx2 v[102:103], v[46:47], off offset:1536
	global_load_dwordx4 v[46:49], v[126:127], off
	s_nop 0
	global_load_dwordx4 v[52:55], v[110:111], off
	s_waitcnt vmcnt(0) lgkmcnt(0)
	v_pk_add_f32 v[48:49], v[48:49], 1.0 op_sel_hi:[1,0]
	v_pk_add_f32 v[46:47], v[46:47], 1.0 op_sel_hi:[1,0]
	v_pk_fma_f32 v[48:49], v[64:65], v[48:49], v[54:55]
	v_pk_fma_f32 v[46:47], v[62:63], v[46:47], v[52:53]
	v_cvt_pk_bf16_f32 v46, v46, v47
	v_cvt_pk_bf16_f32 v47, v48, v49
	global_store_dwordx2 v[102:103], v[46:47], off offset:2048
	global_load_dwordx4 v[46:49], v[120:121], off
	s_nop 0
	global_load_dwordx4 v[52:55], v[110:111], off offset:1024
	s_waitcnt vmcnt(0) lgkmcnt(0)
	v_pk_add_f32 v[48:49], v[48:49], 1.0 op_sel_hi:[1,0]
	v_pk_add_f32 v[46:47], v[46:47], 1.0 op_sel_hi:[1,0]
	v_pk_fma_f32 v[48:49], v[60:61], v[48:49], v[54:55]
	v_pk_fma_f32 v[46:47], v[58:59], v[46:47], v[52:53]
	v_cvt_pk_bf16_f32 v46, v46, v47
	v_cvt_pk_bf16_f32 v47, v48, v49
	global_store_dwordx2 v[102:103], v[46:47], off offset:2560
	global_load_dwordx4 v[46:49], v[116:117], off
	s_nop 0
	global_load_dwordx4 v[52:55], v[110:111], off offset:2048
	v_pk_add_f32 v[58:59], v[150:151], v[150:151] op_sel:[0,1] op_sel_hi:[1,0]
	v_pk_add_f32 v[60:61], v[144:145], v[146:147]
	v_mov_b32_e32 v59, v198
	s_waitcnt vmcnt(0) lgkmcnt(0)
	v_pk_add_f32 v[48:49], v[48:49], 1.0 op_sel_hi:[1,0]
	v_pk_add_f32 v[46:47], v[46:47], 1.0 op_sel_hi:[1,0]
	v_pk_fma_f32 v[48:49], v[56:57], v[48:49], v[54:55]
	v_pk_fma_f32 v[46:47], v[82:83], v[46:47], v[52:53]
	v_cvt_pk_bf16_f32 v46, v46, v47
	v_cvt_pk_bf16_f32 v47, v48, v49
	global_store_dwordx2 v[102:103], v[46:47], off offset:3072
	global_load_dwordx4 v[46:49], v[112:113], off
	s_nop 0
	global_load_dwordx4 v[52:55], v[110:111], off offset:3072
	v_pk_add_f32 v[56:57], v[148:149], v[148:149] op_sel:[0,1] op_sel_hi:[1,0]
	s_waitcnt vmcnt(0) lgkmcnt(0)
	v_pk_add_f32 v[48:49], v[48:49], 1.0 op_sel_hi:[1,0]
	v_pk_add_f32 v[46:47], v[46:47], 1.0 op_sel_hi:[1,0]
	v_pk_fma_f32 v[48:49], v[86:87], v[48:49], v[54:55]
	v_pk_fma_f32 v[46:47], v[84:85], v[46:47], v[52:53]
	v_cvt_pk_bf16_f32 v46, v46, v47
	v_cvt_pk_bf16_f32 v47, v48, v49
	global_store_dwordx2 v[102:103], v[46:47], off offset:3584
	global_load_dwordx4 v[46:49], v[142:143], off
	s_nop 0
	global_load_dwordx4 v[52:55], v[108:109], off
	v_mov_b32_e32 v57, v197
	s_waitcnt vmcnt(0) lgkmcnt(0)
	v_pk_add_f32 v[48:49], v[48:49], 1.0 op_sel_hi:[1,0]
	v_pk_add_f32 v[46:47], v[46:47], 1.0 op_sel_hi:[1,0]
	v_pk_fma_f32 v[48:49], v[158:159], v[48:49], v[54:55]
	v_pk_fma_f32 v[46:47], v[88:89], v[46:47], v[52:53]
	v_bfe_u32 v51, v46, 16, 1
	v_bfe_u32 v52, v47, 16, 1
	v_add3_u32 v46, v46, v51, s5
	v_add3_u32 v47, v47, v52, s5
	v_lshrrev_b32_e32 v46, 16, v46
	v_and_or_b32 v46, v47, s23, v46
	v_cvt_pk_bf16_f32 v47, v48, v49
	global_store_dwordx2 v[104:105], v[46:47], off
	global_load_dwordx4 v[46:49], v[140:141], off
	s_nop 0
	global_load_dwordx4 v[52:55], v[108:109], off offset:1024
	v_pk_mul_f32 v[44:45], v[44:45], v[50:51] op_sel_hi:[1,0]
	v_pk_mul_f32 v[42:43], v[42:43], v[50:51] op_sel_hi:[1,0]
	v_pk_mul_f32 v[44:45], v[44:45], v[8:9]
	v_pk_mul_f32 v[42:43], v[42:43], v[6:7]
	s_waitcnt vmcnt(0) lgkmcnt(0)
	v_pk_add_f32 v[48:49], v[48:49], 1.0 op_sel_hi:[1,0]
	v_pk_add_f32 v[46:47], v[46:47], 1.0 op_sel_hi:[1,0]
	v_pk_fma_f32 v[44:45], v[44:45], v[48:49], v[54:55]
	v_pk_fma_f32 v[42:43], v[42:43], v[46:47], v[52:53]
	v_cvt_pk_bf16_f32 v42, v42, v43
	v_cvt_pk_bf16_f32 v43, v44, v45
	global_store_dwordx2 v[104:105], v[42:43], off offset:512
	global_load_dwordx4 v[42:45], v[136:137], off
	s_nop 0
	global_load_dwordx4 v[46:49], v[108:109], off offset:2048
	v_pk_add_f32 v[52:53], v[56:57], v[58:59]
	s_waitcnt vmcnt(0) lgkmcnt(0)
	v_pk_add_f32 v[44:45], v[44:45], 1.0 op_sel_hi:[1,0]
	v_pk_add_f32 v[52:53], v[52:53], v[60:61]
	v_pk_add_f32 v[42:43], v[42:43], 1.0 op_sel_hi:[1,0]
	v_add_f32_e32 v51, v52, v53
	s_waitcnt lgkmcnt(0)
	s_nop 1
	v_add_f32_dpp v51, v51, v51 quad_perm:[1,0,3,2] row_mask:0xf bank_mask:0xf
	ds_bpermute_b32 v52, v131, v51
	s_waitcnt lgkmcnt(0)
	v_add_f32_e32 v51, v51, v52
	v_pk_mul_f32 v[40:41], v[40:41], v[50:51] op_sel_hi:[1,0]
	v_pk_mul_f32 v[38:39], v[38:39], v[50:51] op_sel_hi:[1,0]
	v_pk_mul_f32 v[40:41], v[40:41], v[12:13]
	v_pk_mul_f32 v[38:39], v[38:39], v[10:11]
	v_pk_fma_f32 v[40:41], v[40:41], v[44:45], v[48:49]
	v_pk_fma_f32 v[38:39], v[38:39], v[42:43], v[46:47]
	v_cvt_pk_bf16_f32 v38, v38, v39
	v_cvt_pk_bf16_f32 v39, v40, v41
	global_store_dwordx2 v[104:105], v[38:39], off offset:1024
	global_load_dwordx4 v[38:41], v[122:123], off
	s_nop 0
	global_load_dwordx4 v[42:45], v[108:109], off offset:3072
	v_pk_mul_f32 v[36:37], v[36:37], v[50:51] op_sel_hi:[1,0]
	v_pk_mul_f32 v[34:35], v[34:35], v[50:51] op_sel_hi:[1,0]
	v_pk_mul_f32 v[36:37], v[36:37], v[16:17]
	v_pk_mul_f32 v[34:35], v[34:35], v[14:15]
	ds_bpermute_b32 v46, v133, v51
	s_waitcnt lgkmcnt(0)
	v_add_f32_e32 v46, v51, v46
	ds_bpermute_b32 v47, v152, v46
	s_waitcnt lgkmcnt(0)
	v_add_f32_e32 v46, v46, v47
	ds_bpermute_b32 v47, v153, v46
	s_waitcnt lgkmcnt(0)
	v_add_f32_e32 v46, v46, v47
	ds_bpermute_b32 v47, v154, v46
	s_waitcnt lgkmcnt(0)
	v_add_f32_e32 v46, v46, v47
	v_fmamk_f32 v46, v46, 0x3a800000, v155
	v_mul_f32_e32 v47, 0x4f800000, v46
	v_cmp_gt_f32_e32 vcc, s4, v46
	s_waitcnt vmcnt(0)
	v_pk_add_f32 v[40:41], v[40:41], 1.0 op_sel_hi:[1,0]
	v_pk_add_f32 v[38:39], v[38:39], 1.0 op_sel_hi:[1,0]
	v_pk_fma_f32 v[36:37], v[36:37], v[40:41], v[44:45]
	v_pk_fma_f32 v[34:35], v[34:35], v[38:39], v[42:43]
	v_cvt_pk_bf16_f32 v34, v34, v35
	v_cvt_pk_bf16_f32 v35, v36, v37
	global_store_dwordx2 v[104:105], v[34:35], off offset:1536
	global_load_dwordx4 v[34:37], v[118:119], off
	s_nop 0
	global_load_dwordx4 v[38:41], v[106:107], off
	v_cndmask_b32_e32 v42, v46, v47, vcc
	v_sqrt_f32_e32 v43, v42
	s_waitcnt vmcnt(0) lgkmcnt(0)
	v_pk_add_f32 v[36:37], v[36:37], 1.0 op_sel_hi:[1,0]
	v_add_u32_e32 v44, -1, v43
	v_add_u32_e32 v45, 1, v43
	v_fma_f32 v46, -v44, v43, v42
	v_fma_f32 v47, -v45, v43, v42
	v_cmp_ge_f32_e64 s[6:7], 0, v46
	v_pk_add_f32 v[34:35], v[34:35], 1.0 op_sel_hi:[1,0]
	s_nop 0
	v_cndmask_b32_e64 v43, v43, v44, s[6:7]
	v_cmp_lt_f32_e64 s[6:7], 0, v47
	s_nop 1
	v_cndmask_b32_e64 v43, v43, v45, s[6:7]
	v_mul_f32_e32 v44, 0x37800000, v43
	v_cndmask_b32_e32 v43, v43, v44, vcc
	v_cmp_class_f32_e32 vcc, v42, v156
	s_nop 1
	v_cndmask_b32_e32 v42, v43, v42, vcc
	v_div_scale_f32 v43, s[6:7], v42, v42, 1.0
	v_rcp_f32_e32 v45, v43
	v_div_scale_f32 v44, vcc, 1.0, v42, 1.0
	v_fma_f32 v46, -v43, v45, 1.0
	v_fmac_f32_e32 v45, v46, v45
	v_mul_f32_e32 v46, v44, v45
	v_fma_f32 v47, -v43, v46, v44
	v_fmac_f32_e32 v46, v47, v45
	v_fma_f32 v43, -v43, v46, v44
	v_div_fmas_f32 v43, v43, v45, v46
	v_div_fixup_f32 v42, v43, v42, 1.0
	v_pk_mul_f32 v[32:33], v[32:33], v[42:43] op_sel_hi:[1,0]
	v_pk_mul_f32 v[30:31], v[30:31], v[42:43] op_sel_hi:[1,0]
	v_pk_mul_f32 v[32:33], v[32:33], v[4:5]
	v_pk_mul_f32 v[30:31], v[30:31], v[2:3]
	v_pk_fma_f32 v[32:33], v[32:33], v[36:37], v[40:41]
	v_pk_fma_f32 v[30:31], v[30:31], v[34:35], v[38:39]
	v_cvt_pk_bf16_f32 v30, v30, v31
	v_cvt_pk_bf16_f32 v31, v32, v33
	global_store_dwordx2 v[104:105], v[30:31], off offset:2048
	global_load_dwordx4 v[30:33], v[114:115], off
	s_nop 0
	global_load_dwordx4 v[34:37], v[106:107], off offset:1024
	v_pk_mul_f32 v[28:29], v[28:29], v[42:43] op_sel_hi:[1,0]
	v_pk_mul_f32 v[26:27], v[26:27], v[42:43] op_sel_hi:[1,0]
	v_pk_mul_f32 v[28:29], v[28:29], v[8:9]
	v_pk_mul_f32 v[26:27], v[26:27], v[6:7]
	v_lshl_add_u64 v[38:39], s[20:21], 0, v[98:99]
	v_pk_mul_f32 v[24:25], v[24:25], v[42:43] op_sel_hi:[1,0]
	v_pk_mul_f32 v[22:23], v[22:23], v[42:43] op_sel_hi:[1,0]
	v_pk_mul_f32 v[24:25], v[24:25], v[12:13]
	v_pk_mul_f32 v[22:23], v[22:23], v[10:11]
	v_pk_mul_f32 v[20:21], v[20:21], v[42:43] op_sel_hi:[1,0]
	v_pk_mul_f32 v[18:19], v[18:19], v[42:43] op_sel_hi:[1,0]
	v_pk_mul_f32 v[20:21], v[20:21], v[16:17]
	v_pk_mul_f32 v[18:19], v[18:19], v[14:15]
	s_waitcnt vmcnt(0) lgkmcnt(0)
	v_pk_add_f32 v[32:33], v[32:33], 1.0 op_sel_hi:[1,0]
	v_pk_add_f32 v[30:31], v[30:31], 1.0 op_sel_hi:[1,0]
	v_pk_fma_f32 v[28:29], v[28:29], v[32:33], v[36:37]
	v_pk_fma_f32 v[26:27], v[26:27], v[30:31], v[34:35]
	v_cvt_pk_bf16_f32 v26, v26, v27
	v_cvt_pk_bf16_f32 v27, v28, v29
	global_store_dwordx2 v[104:105], v[26:27], off offset:2560
	global_load_dwordx4 v[26:29], v[38:39], off
	s_nop 0
	global_load_dwordx4 v[30:33], v[106:107], off offset:2048
	v_lshl_add_u64 v[34:35], s[20:21], 0, v[100:101]
	s_waitcnt vmcnt(0) lgkmcnt(0)
	v_pk_add_f32 v[28:29], v[28:29], 1.0 op_sel_hi:[1,0]
	v_pk_add_f32 v[26:27], v[26:27], 1.0 op_sel_hi:[1,0]
	v_pk_fma_f32 v[24:25], v[24:25], v[28:29], v[32:33]
	v_pk_fma_f32 v[22:23], v[22:23], v[26:27], v[30:31]
	v_cvt_pk_bf16_f32 v22, v22, v23
	v_cvt_pk_bf16_f32 v23, v24, v25
	global_store_dwordx2 v[104:105], v[22:23], off offset:3072
	global_load_dwordx4 v[22:25], v[34:35], off
	s_nop 0
	global_load_dwordx4 v[26:29], v[106:107], off offset:3072
	s_waitcnt vmcnt(0) lgkmcnt(0)
	v_pk_add_f32 v[24:25], v[24:25], 1.0 op_sel_hi:[1,0]
	v_pk_add_f32 v[22:23], v[22:23], 1.0 op_sel_hi:[1,0]
	v_pk_fma_f32 v[20:21], v[20:21], v[24:25], v[28:29]
	v_pk_fma_f32 v[18:19], v[18:19], v[22:23], v[26:27]
	v_cvt_pk_bf16_f32 v18, v18, v19
	v_cvt_pk_bf16_f32 v19, v20, v21
	global_store_dwordx2 v[104:105], v[18:19], off offset:3584
	s_cbranch_scc1 .LBB0_1004

.LBB0_2291:
	s_cmp_lt_i32 s5, 4
	s_cselect_b64 s[20:21], -1, 0
	s_cmp_gt_i32 s5, 3
	s_waitcnt lgkmcnt(0)
	s_barrier
	s_cbranch_scc1 .LBB0_2293
	s_lshl_b32 s6, s5, 9
	s_add_i32 s6, s36, s6
	v_lshl_add_u32 v4, v1, 2, s6
	ds_read2st64_b32 v[2:3], v4 offset0:4 offset1:5
	v_and_b32_e32 v5, 64, v166
	v_xor_b32_e32 v6, 1, v166
	v_add_u32_e32 v5, 64, v5
	v_cmp_lt_i32_e32 vcc, v6, v5
	s_waitcnt lgkmcnt(0)
	v_max_f32_e32 v7, v3, v3
	v_max_f32_e32 v8, v2, v2
	v_cndmask_b32_e32 v6, v166, v6, vcc
	v_max_f32_e32 v7, v8, v7
	v_lshlrev_b32_e32 v6, 2, v6
	ds_bpermute_b32 v8, v6, v7
	v_xor_b32_e32 v9, 2, v166
	v_cmp_lt_i32_e32 vcc, v9, v5
	v_xor_b32_e32 v10, 4, v166
	v_xor_b32_e32 v11, 8, v166
	s_waitcnt lgkmcnt(0)
	v_max_f32_e32 v8, v8, v8
	v_max_f32_e32 v7, v7, v8
	v_cndmask_b32_e32 v8, v166, v9, vcc
	v_lshlrev_b32_e32 v8, 2, v8
	ds_bpermute_b32 v9, v8, v7
	v_cmp_lt_i32_e32 vcc, v10, v5
	v_xor_b32_e32 v12, 16, v166
	v_xor_b32_e32 v13, 32, v166
	s_waitcnt lgkmcnt(0)
	v_max_f32_e32 v9, v9, v9
	v_max_f32_e32 v7, v7, v9
	v_cndmask_b32_e32 v9, v166, v10, vcc
	v_lshlrev_b32_e32 v9, 2, v9
	ds_bpermute_b32 v10, v9, v7
	v_cmp_lt_i32_e32 vcc, v11, v5
	s_waitcnt lgkmcnt(0)
	v_max_f32_e32 v10, v10, v10
	v_max_f32_e32 v7, v7, v10
	v_cndmask_b32_e32 v10, v166, v11, vcc
	v_lshlrev_b32_e32 v10, 2, v10
	ds_bpermute_b32 v11, v10, v7
	v_cmp_lt_i32_e32 vcc, v12, v5
	s_waitcnt lgkmcnt(0)
	v_max_f32_e32 v11, v11, v11
	v_max_f32_e32 v7, v7, v11
	v_cndmask_b32_e32 v11, v166, v12, vcc
	v_lshlrev_b32_e32 v11, 2, v11
	ds_bpermute_b32 v12, v11, v7
	v_cmp_lt_i32_e32 vcc, v13, v5
	s_waitcnt lgkmcnt(0)
	v_max_f32_e32 v12, v12, v12
	v_cndmask_b32_e32 v5, v166, v13, vcc
	v_max_f32_e32 v7, v7, v12
	v_lshlrev_b32_e32 v5, 2, v5
	ds_bpermute_b32 v12, v5, v7
	s_waitcnt lgkmcnt(0)
	v_max_f32_e32 v12, v12, v12
	v_max_f32_e32 v7, v7, v12
	v_sub_f32_e32 v2, v2, v7
	v_sub_f32_e32 v3, v3, v7
	v_mul_f32_e32 v2, 0x3fb8aa3b, v2
	v_mul_f32_e32 v3, 0x3fb8aa3b, v3
	v_exp_f32_e32 v2, v2
	v_exp_f32_e32 v3, v3
	s_nop 0
	v_add_f32_e32 v7, v2, v3
	ds_bpermute_b32 v6, v6, v7
	s_waitcnt lgkmcnt(0)
	v_add_f32_e32 v6, v7, v6
	s_waitcnt lgkmcnt(0)
	s_nop 1
	v_add_f32_dpp v6, v6, v6 quad_perm:[2,3,0,1] row_mask:0xf bank_mask:0xf
	ds_bpermute_b32 v7, v9, v6
	s_waitcnt lgkmcnt(0)
	v_add_f32_e32 v6, v6, v7
	ds_bpermute_b32 v7, v10, v6
	s_waitcnt lgkmcnt(0)
	v_add_f32_e32 v6, v6, v7
	ds_bpermute_b32 v7, v11, v6
	s_waitcnt lgkmcnt(0)
	v_add_f32_e32 v6, v6, v7
	ds_bpermute_b32 v5, v5, v6
	s_waitcnt lgkmcnt(0)
	v_add_f32_e32 v5, v6, v5
	v_max_f32_e32 v5, 0xda24260, v5
	v_div_scale_f32 v6, s[6:7], v5, v5, 1.0
	v_rcp_f32_e32 v7, v6
	v_div_scale_f32 v8, vcc, 1.0, v5, 1.0
	v_fma_f32 v9, -v6, v7, 1.0
	v_fmac_f32_e32 v7, v9, v7
	v_mul_f32_e32 v9, v8, v7
	v_fma_f32 v10, -v6, v9, v8
	v_fmac_f32_e32 v9, v10, v7
	v_fma_f32 v6, -v6, v9, v8
	v_div_fmas_f32 v6, v6, v7, v9
	v_div_fixup_f32 v5, v6, v5, 1.0
	v_mul_f32_e32 v2, v2, v5
	v_mul_f32_e32 v3, v3, v5
	ds_write2st64_b32 v4, v2, v3 offset0:4 offset1:5

.LBB0_2737:
	v_sub_f32_e32 v49, v50, v122
	v_sub_f32_e32 v50, v54, v122
	v_exp_f32_e32 v147, v50
	v_sub_f32_e32 v50, v55, v122
	v_sub_f32_e32 v48, v112, v122
	v_exp_f32_e32 v112, v49
	v_sub_f32_e32 v49, v51, v122
	v_exp_f32_e32 v153, v50
	v_sub_f32_e32 v50, v56, v122
	v_sub_f32_e32 v51, v58, v122
	v_exp_f32_e32 v56, v50
	v_sub_f32_e32 v50, v57, v122
	v_exp_f32_e32 v57, v51
	v_sub_f32_e32 v51, v59, v122
	v_exp_f32_e32 v65, v48
	v_sub_f32_e32 v48, v113, v122
	v_exp_f32_e32 v149, v49
	v_sub_f32_e32 v49, v52, v122
	v_exp_f32_e32 v157, v51
	v_sub_f32_e32 v51, v60, v122
	v_exp_f32_e32 v48, v48
	v_exp_f32_e32 v113, v49
	v_sub_f32_e32 v49, v53, v122
	v_exp_f32_e32 v58, v51
	v_sub_f32_e32 v51, v61, v122
	v_exp_f32_e32 v49, v49
	v_exp_f32_e32 v60, v51
	v_exp_f32_e32 v50, v50
	v_sub_f32_e32 v51, v62, v122
	v_mul_f32_e32 v55, v123, v48
	v_mul_f32_e32 v54, v123, v149
	v_exp_f32_e32 v59, v51
	v_sub_f32_e32 v51, v63, v122
	v_mul_f32_e32 v53, v123, v49
	v_mul_f32_e32 v52, v123, v153
	v_mul_f32_e32 v49, v123, v60
	v_fma_f32 v60, v123, v65, v55
	v_fma_f32 v62, v123, v112, v54
	v_exp_f32_e32 v61, v51
	v_mul_f32_e32 v51, v123, v50
	v_mul_f32_e32 v50, v123, v157
	v_add_f32_e32 v60, v60, v62
	v_fma_f32 v62, v123, v113, v53
	v_fma_f32 v63, v123, v147, v52
	v_add_f32_e32 v151, v62, v63
	v_fma_f32 v62, v123, v56, v51
	v_fma_f32 v63, v123, v57, v50
	v_add_f32_e32 v154, v62, v63
	v_mul_f32_e32 v48, v123, v61
	v_fma_f32 v148, v123, v58, v49
	v_fma_f32 v150, v123, v59, v48
	v_add_f32_e32 v159, v148, v150
	s_waitcnt lgkmcnt(0)
	s_nop 1
	v_add_f32_dpp v63, v60, v60 quad_perm:[1,0,3,2] row_mask:0xf bank_mask:0xf
	ds_bpermute_b32 v62, v118, v54
	ds_bpermute_b32 v150, v118, v52
	ds_bpermute_b32 v155, v118, v50
	ds_bpermute_b32 v158, v118, v48
	s_waitcnt lgkmcnt(0)
	s_nop 1
	v_add_f32_dpp v151, v151, v151 quad_perm:[1,0,3,2] row_mask:0xf bank_mask:0xf
	v_fmac_f32_e32 v62, v123, v149
	v_fmac_f32_e32 v150, v123, v153
	v_fmac_f32_e32 v155, v123, v157
	v_fmac_f32_e32 v158, v123, v61
	s_waitcnt lgkmcnt(0)
	s_nop 1
	v_add_f32_dpp v154, v154, v154 quad_perm:[1,0,3,2] row_mask:0xf bank_mask:0xf
	ds_bpermute_b32 v148, v117, v63
	ds_bpermute_b32 v149, v117, v62
	ds_bpermute_b32 v152, v117, v151
	ds_bpermute_b32 v153, v117, v150
	s_waitcnt lgkmcnt(0)
	s_nop 1
	v_add_f32_dpp v159, v159, v159 quad_perm:[1,0,3,2] row_mask:0xf bank_mask:0xf
	ds_bpermute_b32 v156, v117, v154
	ds_bpermute_b32 v157, v117, v155
	ds_bpermute_b32 v160, v117, v159
	ds_bpermute_b32 v161, v117, v158
	v_add_u32_e32 v60, s5, v144
	v_add_u32_e32 v61, 0x1000, v60
	s_and_saveexec_b64 s[22:23], vcc
	s_cbranch_execz .LBB0_2739
	v_add_f32_e32 v151, v151, v152
	v_add_f32_e32 v63, v63, v148
	s_waitcnt lgkmcnt(0)
	v_add_f32_e32 v158, v158, v161
	v_add_f32_e32 v159, v159, v160
	v_add_f32_e32 v155, v155, v157
	v_add_f32_e32 v154, v154, v156
	v_add_f32_e32 v150, v150, v153
	v_add_f32_e32 v62, v62, v149
	ds_write2_b32 v60, v63, v151 offset1:2
	ds_write2_b32 v61, v62, v150 offset1:2
	ds_write2_b32 v60, v154, v159 offset0:4 offset1:6
	ds_write2_b32 v61, v155, v158 offset0:4 offset1:6
.LBB0_2739:
	s_or_b64 exec, exec, s[22:23]
	v_sub_f32_e32 v34, v34, v122
	v_exp_f32_e32 v62, v34
	v_sub_f32_e32 v34, v35, v122
	v_sub_f32_e32 v35, v146, v122
	v_exp_f32_e32 v63, v35
	v_sub_f32_e32 v35, v36, v122
	v_sub_f32_e32 v36, v39, v122
	v_exp_f32_e32 v148, v36
	v_sub_f32_e32 v36, v40, v122
	v_exp_f32_e32 v150, v35
	v_sub_f32_e32 v35, v37, v122
	v_exp_f32_e32 v153, v36
	v_sub_f32_e32 v36, v41, v122
	v_sub_f32_e32 v37, v43, v122
	v_exp_f32_e32 v149, v36
	v_sub_f32_e32 v36, v42, v122
	v_exp_f32_e32 v42, v37
	v_sub_f32_e32 v37, v44, v122
	s_waitcnt lgkmcnt(0)
	v_exp_f32_e32 v157, v37
	v_sub_f32_e32 v37, v45, v122
	v_exp_f32_e32 v34, v34
	v_exp_f32_e32 v146, v35
	v_sub_f32_e32 v35, v38, v122
	v_exp_f32_e32 v43, v37
	v_sub_f32_e32 v37, v46, v122
	v_exp_f32_e32 v35, v35
	v_exp_f32_e32 v45, v37
	v_sub_f32_e32 v37, v47, v122
	v_exp_f32_e32 v36, v36
	v_exp_f32_e32 v44, v37
	v_sub_f32_e32 v37, v64, v122
	v_exp_f32_e32 v161, v37
	v_mul_f32_e32 v41, v123, v34
	v_mul_f32_e32 v40, v123, v150
	v_mul_f32_e32 v39, v123, v35
	v_mul_f32_e32 v38, v123, v153
	v_mul_f32_e32 v35, v123, v45
	v_fma_f32 v45, v123, v62, v41
	v_fma_f32 v46, v123, v63, v40
	v_mul_f32_e32 v37, v123, v36
	v_mul_f32_e32 v36, v123, v157
	v_add_f32_e32 v45, v45, v46
	v_fma_f32 v46, v123, v146, v39
	v_fma_f32 v47, v123, v148, v38
	v_mul_f32_e32 v34, v123, v161
	v_add_f32_e32 v151, v46, v47
	v_fma_f32 v46, v123, v149, v37
	v_fma_f32 v47, v123, v42, v36
	v_add_f32_e32 v154, v46, v47
	v_fma_f32 v46, v123, v43, v35
	v_fma_f32 v47, v123, v44, v34
	v_add_f32_e32 v158, v46, v47
	ds_bpermute_b32 v47, v118, v40
	ds_bpermute_b32 v152, v118, v38
	ds_bpermute_b32 v156, v118, v36
	s_waitcnt lgkmcnt(0)
	v_fmac_f32_e32 v47, v123, v150
	ds_bpermute_b32 v160, v118, v34
	s_nop 1
	v_add_f32_dpp v45, v45, v45 quad_perm:[1,0,3,2] row_mask:0xf bank_mask:0xf
	v_fmac_f32_e32 v152, v123, v153
	s_waitcnt lgkmcnt(0)
	s_nop 1
	v_add_f32_dpp v150, v151, v151 quad_perm:[1,0,3,2] row_mask:0xf bank_mask:0xf
	s_nop 1
	v_add_f32_dpp v154, v154, v154 quad_perm:[1,0,3,2] row_mask:0xf bank_mask:0xf
	v_fmac_f32_e32 v156, v123, v157
	s_nop 1
	v_add_f32_dpp v158, v158, v158 quad_perm:[1,0,3,2] row_mask:0xf bank_mask:0xf
	v_fmac_f32_e32 v160, v123, v161
	ds_bpermute_b32 v46, v117, v45
	ds_bpermute_b32 v64, v117, v47
	ds_bpermute_b32 v151, v117, v150
	ds_bpermute_b32 v153, v117, v152
	ds_bpermute_b32 v155, v117, v154
	ds_bpermute_b32 v157, v117, v156
	ds_bpermute_b32 v159, v117, v158
	ds_bpermute_b32 v161, v117, v160
	s_and_saveexec_b64 s[22:23], vcc
	s_cbranch_execz .LBB0_2741
	s_waitcnt lgkmcnt(0)
	v_add_f32_e32 v150, v150, v151
	v_add_f32_e32 v45, v45, v46
	v_add_f32_e32 v160, v160, v161
	v_add_f32_e32 v158, v158, v159
	v_add_f32_e32 v156, v156, v157
	v_add_f32_e32 v154, v154, v155
	v_add_f32_e32 v152, v152, v153
	v_add_f32_e32 v47, v47, v64
	ds_write2_b32 v60, v45, v150 offset0:8 offset1:10
	ds_write2_b32 v61, v47, v152 offset0:8 offset1:10
	ds_write2_b32 v60, v154, v158 offset0:12 offset1:14
	ds_write2_b32 v61, v156, v160 offset0:12 offset1:14

.LBB0_2752:
	s_lshr_b32 s10, s52, 2
	s_cmp_lt_u32 s52, 4
	s_cselect_b64 vcc, -1, 0
	s_cmp_eq_u32 s10, 2
	s_cselect_b32 s12, s31, s29
	s_cselect_b32 s13, s48, s30
	s_cmp_eq_u32 s10, 1
	s_cselect_b64 s[10:11], -1, 0
	v_cndmask_b32_e64 v66, v106, v108, s[10:11]
	v_cndmask_b32_e64 v67, v107, v109, s[10:11]
	s_and_b64 s[10:11], s[10:11], exec
	s_cselect_b32 s14, s27, s28
	s_and_b64 s[10:11], vcc, exec
	s_cselect_b32 s14, s26, s14
	s_sub_i32 s10, s49, 32
	s_and_b32 s15, s10, 32
	s_or_b32 s10, s15, s14
	v_add_u32_e32 v80, s10, v100
	v_add_u32_e32 v144, 16, v80
	v_cndmask_b32_e32 v78, v66, v104, vcc
	v_subrev_u32_e32 v66, s14, v144
	v_cndmask_b32_e32 v79, v67, v105, vcc
	v_ashrrev_i32_e32 v67, 31, v66
	v_lshlrev_b64 v[66:67], 10, v[66:67]
	v_lshl_add_u64 v[66:67], v[78:79], 0, v[66:67]
	v_mov_b32_e32 v82, s13
	v_cmp_gt_i32_e64 s[10:11], s44, v144
	v_mov_b32_e32 v83, s12
	v_add_u32_e32 v147, 20, v80
	v_cndmask_b32_e64 v67, v82, v67, s[10:11]
	v_cndmask_b32_e64 v66, v83, v66, s[10:11]
	v_lshl_add_u64 v[66:67], v[66:67], 0, v[98:99]
	v_add_u32_e32 v146, 24, v80
	v_add_u32_e32 v145, 28, v80
	global_load_dwordx4 v[94:97], v[66:67], off
	global_load_dwordx4 v[74:77], v[66:67], off offset:512
	v_subrev_u32_e32 v66, s14, v147
	v_subrev_u32_e32 v70, s14, v146
	v_subrev_u32_e32 v80, s14, v145
	v_ashrrev_i32_e32 v67, 31, v66
	v_ashrrev_i32_e32 v71, 31, v70
	v_ashrrev_i32_e32 v81, 31, v80
	v_lshlrev_b64 v[66:67], 10, v[66:67]
	v_lshlrev_b64 v[70:71], 10, v[70:71]
	v_lshlrev_b64 v[80:81], 10, v[80:81]
	v_lshl_add_u64 v[66:67], v[78:79], 0, v[66:67]
	v_lshl_add_u64 v[70:71], v[78:79], 0, v[70:71]
	v_lshl_add_u64 v[78:79], v[78:79], 0, v[80:81]
	s_waitcnt vmcnt(0) lgkmcnt(0)
	v_mul_f32_e32 v80, v11, v3
	v_fmac_f32_e32 v80, v10, v2
	v_fmac_f32_e32 v80, v12, v4
	v_fmac_f32_e32 v80, v13, v5
	v_cmp_gt_i32_e64 s[10:11], s44, v147
	v_mul_f32_e32 v148, v11, v27
	v_fmac_f32_e32 v148, v10, v26
	v_cndmask_b32_e64 v67, v82, v67, s[10:11]
	s_waitcnt lgkmcnt(0)
	v_add_f32_dpp v80, v80, v80 quad_perm:[1,0,3,2] row_mask:0xf bank_mask:0xf
	v_cndmask_b32_e64 v66, v83, v66, s[10:11]
	v_cmp_gt_i32_e64 s[10:11], s44, v146
	v_mul_f32_e32 v125, v23, v3
	v_cndmask_b32_e64 v71, v82, v71, s[10:11]
	v_cndmask_b32_e64 v70, v83, v70, s[10:11]
	v_cmp_gt_i32_e64 s[10:11], s44, v145
	s_waitcnt lgkmcnt(0)
	v_add_f32_dpp v80, v80, v80 quad_perm:[2,3,0,1] row_mask:0xf bank_mask:0xf
	v_cndmask_b32_e64 v79, v82, v79, s[10:11]
	v_mul_f32_e32 v82, v15, v3
	v_fmac_f32_e32 v82, v14, v2
	v_fmac_f32_e32 v82, v16, v4
	v_fmac_f32_e32 v82, v17, v5
	v_cndmask_b32_e64 v78, v83, v78, s[10:11]
	s_and_b32 s10, s52, 12
	s_waitcnt lgkmcnt(0)
	v_add_f32_dpp v118, v80, v80 row_half_mirror row_mask:0xf bank_mask:0xf
	s_cmp_eq_u32 s10, 4
	s_waitcnt lgkmcnt(0)
	v_add_f32_dpp v120, v82, v82 quad_perm:[1,0,3,2] row_mask:0xf bank_mask:0xf
	s_cselect_b32 s12, s27, s28
	s_and_b64 s[10:11], vcc, exec
	s_cselect_b32 s10, s26, s12
	s_or_b32 s10, s10, s15
	v_add_u32_e32 v156, s10, v100
	v_sub_u32_e32 v84, 0x800, v156
	s_waitcnt lgkmcnt(0)
	v_add_f32_dpp v118, v118, v118 row_mirror row_mask:0xf bank_mask:0xf
	s_waitcnt lgkmcnt(0)
	v_add_f32_dpp v119, v120, v120 quad_perm:[2,3,0,1] row_mask:0xf bank_mask:0xf
	v_cvt_f32_u32_e32 v124, v84
	v_cmp_gt_i32_e32 vcc, s45, v156
	v_fmac_f32_e32 v125, v22, v2
	v_fma_f32 v118, -v127, v124, v118
	v_cndmask_b32_e32 v169, v135, v118, vcc
	s_waitcnt lgkmcnt(0)
	v_add_f32_dpp v120, v119, v119 row_half_mirror row_mask:0xf bank_mask:0xf
	v_pk_mul_f32 v[118:119], v[12:13], v[28:29]
	v_fmac_f32_e32 v125, v24, v4
	v_add_f32_e32 v118, v118, v148
	v_add_f32_e32 v118, v119, v118
	v_fmac_f32_e32 v125, v25, v5
	v_mul_f32_e32 v150, v15, v27
	v_fmac_f32_e32 v150, v14, v26
	s_waitcnt lgkmcnt(0)
	v_add_f32_dpp v118, v118, v118 quad_perm:[1,0,3,2] row_mask:0xf bank_mask:0xf
	v_fmac_f32_e32 v150, v16, v28
	s_waitcnt lgkmcnt(0)
	v_add_f32_dpp v125, v125, v125 quad_perm:[1,0,3,2] row_mask:0xf bank_mask:0xf
	v_fmac_f32_e32 v150, v17, v29
	s_waitcnt lgkmcnt(0)
	v_add_f32_dpp v118, v118, v118 quad_perm:[2,3,0,1] row_mask:0xf bank_mask:0xf
	s_movk_i32 s10, 0x7fd
	s_waitcnt lgkmcnt(0)
	s_nop 1
	v_add_f32_dpp v148, v125, v125 quad_perm:[2,3,0,1] row_mask:0xf bank_mask:0xf
	v_sub_u32_e32 v125, 0x7fc, v156
	s_waitcnt lgkmcnt(0)
	v_add_f32_dpp v118, v118, v118 row_half_mirror row_mask:0xf bank_mask:0xf
	v_cvt_f32_u32_e32 v125, v125
	v_cmp_gt_i32_e64 s[10:11], s10, v156
	v_mul_f32_e32 v154, v11, v35
	v_fmac_f32_e32 v154, v10, v34
	s_waitcnt lgkmcnt(0)
	v_add_f32_dpp v118, v118, v118 row_mirror row_mask:0xf bank_mask:0xf
	v_add_f32_dpp v119, v150, v150 quad_perm:[1,0,3,2] row_mask:0xf bank_mask:0xf
	v_mul_f32_e32 v151, v19, v27
	v_fma_f32 v118, -v127, v125, v118
	v_fmac_f32_e32 v151, v18, v26
	v_fmac_f32_e32 v151, v20, v28
	v_cndmask_b32_e64 v172, v135, v118, s[10:11]
	s_waitcnt lgkmcnt(0)
	v_add_f32_dpp v118, v119, v119 quad_perm:[2,3,0,1] row_mask:0xf bank_mask:0xf
	v_fmac_f32_e32 v151, v21, v29
	v_lshl_add_u64 v[66:67], v[66:67], 0, v[98:99]
	v_lshl_add_u64 v[70:71], v[70:71], 0, v[98:99]
	v_lshl_add_u64 v[78:79], v[78:79], 0, v[98:99]
	s_waitcnt lgkmcnt(0)
	v_add_f32_dpp v164, v118, v118 row_half_mirror row_mask:0xf bank_mask:0xf
	v_pk_mul_f32 v[118:119], v[12:13], v[36:37]
	s_waitcnt lgkmcnt(0)
	v_add_f32_dpp v150, v151, v151 quad_perm:[1,0,3,2] row_mask:0xf bank_mask:0xf
	v_mul_f32_e32 v152, v23, v27
	v_add_f32_e32 v118, v118, v154
	v_fmac_f32_e32 v152, v22, v26
	v_add_f32_e32 v118, v119, v118
	v_fmac_f32_e32 v152, v24, v28
	v_fmac_f32_e32 v152, v25, v29
	global_load_dwordx4 v[90:93], v[66:67], off
	s_nop 0
	global_load_dwordx4 v[66:69], v[66:67], off offset:512
	s_waitcnt lgkmcnt(0)
	v_add_f32_dpp v118, v118, v118 quad_perm:[1,0,3,2] row_mask:0xf bank_mask:0xf
	v_add_f32_dpp v152, v152, v152 quad_perm:[1,0,3,2] row_mask:0xf bank_mask:0xf
	global_load_dwordx4 v[86:89], v[70:71], off
	s_nop 0
	global_load_dwordx4 v[70:73], v[70:71], off offset:512
	s_nop 0
	global_load_dwordx4 v[82:85], v[78:79], off
	s_nop 0
	global_load_dwordx4 v[78:81], v[78:79], off offset:512
	v_mul_f32_e32 v154, v15, v35
	s_waitcnt lgkmcnt(0)
	v_add_f32_dpp v118, v118, v118 quad_perm:[2,3,0,1] row_mask:0xf bank_mask:0xf
	v_fmac_f32_e32 v154, v14, v34
	v_fmac_f32_e32 v154, v16, v36
	v_add_f32_dpp v150, v150, v150 quad_perm:[2,3,0,1] row_mask:0xf bank_mask:0xf
	v_add_f32_dpp v152, v152, v152 quad_perm:[2,3,0,1] row_mask:0xf bank_mask:0xf
	v_fmac_f32_e32 v154, v17, v37
	s_waitcnt lgkmcnt(0)
	v_add_f32_dpp v118, v118, v118 row_half_mirror row_mask:0xf bank_mask:0xf
	v_add_f32_dpp v158, v150, v150 row_half_mirror row_mask:0xf bank_mask:0xf
	v_add_f32_dpp v150, v152, v152 row_half_mirror row_mask:0xf bank_mask:0xf
	v_sub_u32_e32 v152, 0x7f8, v156
	v_add_f32_dpp v154, v154, v154 quad_perm:[1,0,3,2] row_mask:0xf bank_mask:0xf
	v_cvt_f32_u32_e32 v152, v152
	v_or_b32_e32 v153, 8, v156
	s_waitcnt lgkmcnt(0)
	v_add_f32_dpp v118, v118, v118 row_mirror row_mask:0xf bank_mask:0xf
	v_fma_f32 v118, -v127, v152, v118
	v_cmp_gt_i32_e64 s[12:13], s45, v153
	v_mul_f32_e32 v153, v19, v35
	v_fmac_f32_e32 v153, v18, v34
	v_cndmask_b32_e64 v173, v135, v118, s[12:13]
	v_add_f32_dpp v118, v154, v154 quad_perm:[2,3,0,1] row_mask:0xf bank_mask:0xf
	v_mul_f32_e32 v155, v23, v35
	v_fmac_f32_e32 v155, v22, v34
	v_fmac_f32_e32 v153, v20, v36
	v_fmac_f32_e32 v155, v24, v36
	v_fmac_f32_e32 v153, v21, v37
	v_fmac_f32_e32 v155, v25, v37
	s_movk_i32 s14, 0x7f5
	v_cmp_gt_i32_e64 s[14:15], s14, v156
	s_waitcnt lgkmcnt(0)
	v_add_f32_dpp v153, v153, v153 quad_perm:[1,0,3,2] row_mask:0xf bank_mask:0xf
	s_nop 1
	v_add_f32_dpp v160, v155, v155 quad_perm:[1,0,3,2] row_mask:0xf bank_mask:0xf
	v_pk_mul_f32 v[154:155], v[10:11], v[46:47]
	v_add_f32_dpp v167, v118, v118 row_half_mirror row_mask:0xf bank_mask:0xf
	v_pk_mul_f32 v[118:119], v[12:13], v[48:49]
	v_add_f32_e32 v154, v154, v155
	v_add_f32_e32 v118, v118, v154
	v_add_f32_e32 v118, v119, v118
	v_mul_f32_e32 v122, v19, v3
	s_waitcnt lgkmcnt(0)
	v_add_f32_dpp v153, v153, v153 quad_perm:[2,3,0,1] row_mask:0xf bank_mask:0xf
	v_add_f32_dpp v155, v160, v160 quad_perm:[2,3,0,1] row_mask:0xf bank_mask:0xf
	v_add_f32_dpp v118, v118, v118 quad_perm:[1,0,3,2] row_mask:0xf bank_mask:0xf
	v_fmac_f32_e32 v122, v18, v2
	s_waitcnt lgkmcnt(0)
	v_add_f32_dpp v160, v153, v153 row_half_mirror row_mask:0xf bank_mask:0xf
	v_add_f32_dpp v153, v155, v155 row_half_mirror row_mask:0xf bank_mask:0xf
	v_mul_f32_e32 v162, v15, v47
	v_add_f32_dpp v118, v118, v118 quad_perm:[2,3,0,1] row_mask:0xf bank_mask:0xf
	v_fmac_f32_e32 v162, v14, v46
	v_fmac_f32_e32 v162, v16, v48
	v_fmac_f32_e32 v162, v17, v49
	v_sub_u32_e32 v155, 0x7f4, v156
	s_waitcnt lgkmcnt(0)
	v_add_f32_dpp v118, v118, v118 row_half_mirror row_mask:0xf bank_mask:0xf
	v_cvt_f32_u32_e32 v155, v155
	v_add_f32_dpp v162, v162, v162 quad_perm:[1,0,3,2] row_mask:0xf bank_mask:0xf
	v_mul_f32_e32 v156, v19, v47
	s_waitcnt lgkmcnt(0)
	v_add_f32_dpp v118, v118, v118 row_mirror row_mask:0xf bank_mask:0xf
	v_fma_f32 v118, -v127, v155, v118
	v_cndmask_b32_e64 v174, v135, v118, s[14:15]
	v_add_f32_dpp v118, v162, v162 quad_perm:[2,3,0,1] row_mask:0xf bank_mask:0xf
	v_mul_f32_e32 v163, v23, v47
	v_fmac_f32_e32 v156, v18, v46
	v_fmac_f32_e32 v163, v22, v46
	v_fmac_f32_e32 v122, v20, v4
	v_fmac_f32_e32 v156, v20, v48
	v_fmac_f32_e32 v163, v24, v48
	v_fmac_f32_e32 v122, v21, v5
	v_fmac_f32_e32 v156, v21, v49
	v_fmac_f32_e32 v163, v25, v49
	v_max3_f32 v157, v169, s35, v172
	s_waitcnt lgkmcnt(0)
	v_add_f32_dpp v122, v122, v122 quad_perm:[1,0,3,2] row_mask:0xf bank_mask:0xf
	v_add_f32_dpp v170, v118, v118 row_half_mirror row_mask:0xf bank_mask:0xf
	v_add_f32_dpp v118, v156, v156 quad_perm:[1,0,3,2] row_mask:0xf bank_mask:0xf
	v_add_f32_dpp v156, v163, v163 quad_perm:[1,0,3,2] row_mask:0xf bank_mask:0xf
	v_max3_f32 v157, v157, v173, v174
	ds_bpermute_b32 v163, v142, v157
	s_waitcnt lgkmcnt(0)
	v_add_f32_dpp v122, v122, v122 quad_perm:[2,3,0,1] row_mask:0xf bank_mask:0xf
	v_add_f32_dpp v118, v118, v118 quad_perm:[2,3,0,1] row_mask:0xf bank_mask:0xf
	v_add_f32_dpp v156, v156, v156 quad_perm:[2,3,0,1] row_mask:0xf bank_mask:0xf
	v_max_f32_e32 v162, v163, v163
	v_max_f32_e32 v176, v157, v162
	ds_bpermute_b32 v177, v143, v176
	s_waitcnt lgkmcnt(0)
	v_add_f32_dpp v122, v122, v122 row_half_mirror row_mask:0xf bank_mask:0xf
	v_add_f32_dpp v148, v148, v148 row_half_mirror row_mask:0xf bank_mask:0xf
	v_add_f32_dpp v162, v118, v118 row_half_mirror row_mask:0xf bank_mask:0xf
	v_add_f32_dpp v156, v156, v156 row_half_mirror row_mask:0xf bank_mask:0xf
	ds_bpermute_b32 v121, v141, v120
	ds_bpermute_b32 v123, v141, v122
	ds_bpermute_b32 v149, v141, v148
	ds_bpermute_b32 v165, v141, v164
	ds_bpermute_b32 v159, v141, v158
	ds_bpermute_b32 v151, v141, v150
	ds_bpermute_b32 v168, v141, v167
	ds_bpermute_b32 v161, v141, v160
	ds_bpermute_b32 v154, v141, v153
	ds_bpermute_b32 v171, v141, v170
	ds_bpermute_b32 v163, v141, v162
	ds_bpermute_b32 v157, v141, v156
	v_max_f32_e32 v118, v177, v177
	v_max_f32_e32 v175, v176, v118
	v_cmp_neq_f32_e64 s[16:17], s35, v175
	v_mov_b64_e32 v[118:119], v[112:113]
	s_and_saveexec_b64 s[22:23], s[16:17]
	s_cbranch_execz .LBB0_2754
	v_max_f32_e32 v118, v175, v175
	v_max_f32_e32 v119, v113, v113
	v_max_f32_e32 v119, v119, v118
	v_sub_f32_e32 v118, v169, v119
	v_mul_f32_e32 v118, 0x3fb8aa3b, v118
	v_exp_f32_e32 v118, v118
	v_sub_f32_e32 v113, v113, v119
	v_mul_f32_e32 v113, 0x3fb8aa3b, v113
	v_add_f32_e32 v169, 0, v118
	v_pk_fma_f32 v[176:177], v[8:9], v[118:119], 0 op_sel_hi:[1,0,0]
	v_pk_fma_f32 v[178:179], v[6:7], v[118:119], 0 op_sel_hi:[1,0,0]
	v_sub_f32_e32 v118, v172, v119
	v_mul_f32_e32 v118, 0x3fb8aa3b, v118
	v_exp_f32_e32 v118, v118
	s_nop 0
	v_add_f32_e32 v169, v118, v169
	v_pk_fma_f32 v[176:177], v[32:33], v[118:119], v[176:177] op_sel_hi:[1,0,1]
	v_pk_fma_f32 v[178:179], v[30:31], v[118:119], v[178:179] op_sel_hi:[1,0,1]
	v_sub_f32_e32 v118, v173, v119
	v_mul_f32_e32 v118, 0x3fb8aa3b, v118
	v_exp_f32_e32 v118, v118
	s_nop 0
	v_add_f32_e32 v169, v118, v169
	v_pk_fma_f32 v[172:173], v[38:39], v[118:119], v[178:179] op_sel_hi:[1,0,1]
	v_pk_fma_f32 v[176:177], v[40:41], v[118:119], v[176:177] op_sel_hi:[1,0,1]
	v_sub_f32_e32 v118, v174, v119
	v_mul_f32_e32 v118, 0x3fb8aa3b, v118
	v_exp_f32_e32 v118, v118
	s_nop 0
	v_add_f32_e32 v169, v118, v169
	v_pk_fma_f32 v[174:175], v[56:57], v[118:119], v[176:177] op_sel_hi:[1,0,1]
	v_exp_f32_e32 v176, v113
	ds_bpermute_b32 v113, v142, v169
	v_pk_fma_f32 v[172:173], v[54:55], v[118:119], v[172:173] op_sel_hi:[1,0,1]
	ds_bpermute_b32 v178, v142, v174
	ds_bpermute_b32 v179, v142, v175
	s_waitcnt lgkmcnt(0)
	v_add_f32_e32 v113, v169, v113
	ds_bpermute_b32 v118, v143, v113
	v_pk_add_f32 v[174:175], v[174:175], v[178:179]
	ds_bpermute_b32 v178, v143, v174
	ds_bpermute_b32 v179, v143, v175
	s_waitcnt lgkmcnt(0)
	v_add_f32_e32 v118, v113, v118
	v_fmac_f32_e32 v118, v112, v176
	ds_bpermute_b32 v112, v142, v172
	ds_bpermute_b32 v113, v142, v173
	s_waitcnt lgkmcnt(0)
	v_pk_add_f32 v[112:113], v[172:173], v[112:113]
	ds_bpermute_b32 v172, v143, v112
	ds_bpermute_b32 v173, v143, v113
	s_waitcnt lgkmcnt(0)
	v_pk_add_f32 v[112:113], v[112:113], v[172:173]
	v_pk_add_f32 v[172:173], v[174:175], v[178:179]
	v_pk_fma_f32 v[62:63], v[62:63], v[176:177], v[112:113] op_sel_hi:[1,0,1]
	v_pk_fma_f32 v[64:65], v[64:65], v[176:177], v[172:173] op_sel_hi:[1,0,1]
	v_mov_b32_e32 v112, v118
	v_mov_b32_e32 v113, v119

.LBB0_2762:
	v_mul_f32_e32 v149, v11, v95
	v_fmac_f32_e32 v149, v10, v94
	v_fmac_f32_e32 v149, v12, v96
	v_fmac_f32_e32 v149, v13, v97
	v_sub_u32_e32 v148, 0x800, v144
	v_cvt_f32_u32_e32 v148, v148
	v_cmp_gt_i32_e32 vcc, s45, v144
	s_waitcnt vmcnt(0)
	v_pk_mul_f32 v[154:155], v[12:13], v[92:93]
	s_waitcnt lgkmcnt(0)
	v_add_f32_dpp v149, v149, v149 quad_perm:[1,0,3,2] row_mask:0xf bank_mask:0xf
	v_cmp_gt_i32_e64 s[10:11], s45, v147
	v_pk_mul_f32 v[158:159], v[12:13], v[88:89]
	v_cmp_gt_i32_e64 s[12:13], s45, v146
	v_pk_mul_f32 v[160:161], v[10:11], v[82:83]
	s_waitcnt lgkmcnt(0)
	v_add_f32_dpp v149, v149, v149 quad_perm:[2,3,0,1] row_mask:0xf bank_mask:0xf
	v_cmp_gt_i32_e64 s[14:15], s45, v145
	s_waitcnt lgkmcnt(0)
	v_add_f32_dpp v149, v149, v149 row_half_mirror row_mask:0xf bank_mask:0xf
	s_waitcnt lgkmcnt(0)
	s_nop 0
	v_add_f32_dpp v149, v149, v149 row_mirror row_mask:0xf bank_mask:0xf
	v_fma_f32 v149, -v127, v148, v149
	v_cndmask_b32_e32 v153, v135, v149, vcc
	v_mul_f32_e32 v149, v15, v95
	v_fmac_f32_e32 v149, v14, v94
	v_fmac_f32_e32 v149, v16, v96
	v_fmac_f32_e32 v149, v17, v97
	s_waitcnt lgkmcnt(0)
	s_nop 0
	v_add_f32_dpp v149, v149, v149 quad_perm:[1,0,3,2] row_mask:0xf bank_mask:0xf
	s_waitcnt lgkmcnt(0)
	s_nop 0
	v_add_f32_dpp v149, v149, v149 quad_perm:[2,3,0,1] row_mask:0xf bank_mask:0xf
	s_waitcnt lgkmcnt(0)
	s_nop 0
	v_add_f32_dpp v151, v149, v149 row_half_mirror row_mask:0xf bank_mask:0xf
	v_mul_f32_e32 v149, v19, v95
	v_mul_f32_e32 v95, v23, v95
	v_fmac_f32_e32 v149, v18, v94
	v_fmac_f32_e32 v95, v22, v94
	v_fmac_f32_e32 v149, v20, v96
	v_fmac_f32_e32 v95, v24, v96
	v_fmac_f32_e32 v149, v21, v97
	v_fmac_f32_e32 v95, v25, v97
	v_mul_f32_e32 v97, v11, v91
	v_fmac_f32_e32 v97, v10, v90
	v_add_f32_e32 v97, v154, v97
	v_add_f32_e32 v97, v155, v97
	ds_bpermute_b32 v152, v141, v151
	s_waitcnt lgkmcnt(0)
	v_add_f32_dpp v97, v97, v97 quad_perm:[1,0,3,2] row_mask:0xf bank_mask:0xf
	s_waitcnt lgkmcnt(0)
	s_nop 1
	v_add_f32_dpp v94, v95, v95 quad_perm:[1,0,3,2] row_mask:0xf bank_mask:0xf
	s_waitcnt lgkmcnt(0)
	v_add_f32_dpp v149, v149, v149 quad_perm:[1,0,3,2] row_mask:0xf bank_mask:0xf
	s_waitcnt lgkmcnt(0)
	v_add_f32_dpp v97, v97, v97 quad_perm:[2,3,0,1] row_mask:0xf bank_mask:0xf
	s_waitcnt lgkmcnt(0)
	v_add_f32_dpp v94, v94, v94 quad_perm:[2,3,0,1] row_mask:0xf bank_mask:0xf
	s_waitcnt lgkmcnt(0)
	v_add_f32_dpp v149, v149, v149 quad_perm:[2,3,0,1] row_mask:0xf bank_mask:0xf
	s_waitcnt lgkmcnt(0)
	v_add_f32_dpp v97, v97, v97 row_half_mirror row_mask:0xf bank_mask:0xf
	s_waitcnt lgkmcnt(0)
	v_add_f32_dpp v94, v94, v94 row_half_mirror row_mask:0xf bank_mask:0xf
	v_sub_u32_e32 v95, 0x7fc, v144
	v_cvt_f32_u32_e32 v95, v95
	s_waitcnt lgkmcnt(0)
	v_add_f32_dpp v149, v149, v149 row_half_mirror row_mask:0xf bank_mask:0xf
	s_waitcnt lgkmcnt(0)
	v_add_f32_dpp v97, v97, v97 row_mirror row_mask:0xf bank_mask:0xf
	ds_bpermute_b32 v150, v141, v149
	v_fma_f32 v97, -v127, v95, v97
	v_cndmask_b32_e64 v156, v135, v97, s[10:11]
	v_mul_f32_e32 v97, v15, v91
	v_fmac_f32_e32 v97, v14, v90
	v_fmac_f32_e32 v97, v16, v92
	v_fmac_f32_e32 v97, v17, v93
	v_max3_f32 v162, v153, s35, v156
	ds_bpermute_b32 v96, v141, v94
	s_waitcnt lgkmcnt(0)
	v_add_f32_dpp v97, v97, v97 quad_perm:[1,0,3,2] row_mask:0xf bank_mask:0xf
	s_waitcnt lgkmcnt(0)
	s_nop 0
	v_add_f32_dpp v97, v97, v97 quad_perm:[2,3,0,1] row_mask:0xf bank_mask:0xf
	s_waitcnt lgkmcnt(0)
	s_nop 0
	v_add_f32_dpp v154, v97, v97 row_half_mirror row_mask:0xf bank_mask:0xf
	v_mul_f32_e32 v97, v19, v91
	v_mul_f32_e32 v91, v23, v91
	v_fmac_f32_e32 v97, v18, v90
	v_fmac_f32_e32 v91, v22, v90
	v_fmac_f32_e32 v97, v20, v92
	v_fmac_f32_e32 v91, v24, v92
	v_fmac_f32_e32 v97, v21, v93
	v_fmac_f32_e32 v91, v25, v93
	v_mul_f32_e32 v93, v11, v87
	v_fmac_f32_e32 v93, v10, v86
	v_add_f32_e32 v93, v158, v93
	v_add_f32_e32 v93, v159, v93
	ds_bpermute_b32 v155, v141, v154
	s_waitcnt lgkmcnt(0)
	v_add_f32_dpp v93, v93, v93 quad_perm:[1,0,3,2] row_mask:0xf bank_mask:0xf
	s_waitcnt lgkmcnt(0)
	s_nop 1
	v_add_f32_dpp v90, v91, v91 quad_perm:[1,0,3,2] row_mask:0xf bank_mask:0xf
	s_waitcnt lgkmcnt(0)
	v_add_f32_dpp v97, v97, v97 quad_perm:[1,0,3,2] row_mask:0xf bank_mask:0xf
	s_waitcnt lgkmcnt(0)
	v_add_f32_dpp v93, v93, v93 quad_perm:[2,3,0,1] row_mask:0xf bank_mask:0xf
	s_waitcnt lgkmcnt(0)
	v_add_f32_dpp v90, v90, v90 quad_perm:[2,3,0,1] row_mask:0xf bank_mask:0xf
	ds_bpermute_b32 v91, v140, v90
	s_waitcnt lgkmcnt(0)
	v_add_f32_dpp v97, v97, v97 quad_perm:[2,3,0,1] row_mask:0xf bank_mask:0xf
	s_waitcnt lgkmcnt(0)
	v_add_f32_dpp v93, v93, v93 row_half_mirror row_mask:0xf bank_mask:0xf
	s_waitcnt lgkmcnt(0)
	v_add_f32_e32 v91, v90, v91
	v_sub_u32_e32 v90, 0x7f8, v144
	v_cvt_f32_u32_e32 v90, v90
	s_waitcnt lgkmcnt(0)
	v_add_f32_dpp v97, v97, v97 row_half_mirror row_mask:0xf bank_mask:0xf
	s_waitcnt lgkmcnt(0)
	v_add_f32_dpp v93, v93, v93 row_mirror row_mask:0xf bank_mask:0xf
	ds_bpermute_b32 v147, v141, v97
	v_fma_f32 v93, -v127, v90, v93
	v_cndmask_b32_e64 v159, v135, v93, s[12:13]
	v_mul_f32_e32 v93, v15, v87
	v_fmac_f32_e32 v93, v14, v86
	v_fmac_f32_e32 v93, v16, v88
	v_fmac_f32_e32 v93, v17, v89
	ds_bpermute_b32 v92, v141, v91
	s_waitcnt lgkmcnt(0)
	v_add_f32_dpp v93, v93, v93 quad_perm:[1,0,3,2] row_mask:0xf bank_mask:0xf
	s_waitcnt lgkmcnt(0)
	s_nop 0
	v_add_f32_dpp v93, v93, v93 quad_perm:[2,3,0,1] row_mask:0xf bank_mask:0xf
	s_waitcnt lgkmcnt(0)
	s_nop 0
	v_add_f32_dpp v157, v93, v93 row_half_mirror row_mask:0xf bank_mask:0xf
	v_mul_f32_e32 v93, v19, v87
	v_mul_f32_e32 v87, v23, v87
	v_fmac_f32_e32 v87, v22, v86
	v_fmac_f32_e32 v87, v24, v88
	v_fmac_f32_e32 v87, v25, v89
	v_fmac_f32_e32 v93, v18, v86
	v_fmac_f32_e32 v93, v20, v88
	v_fmac_f32_e32 v93, v21, v89
	v_add_f32_e32 v89, v160, v161
	s_waitcnt lgkmcnt(0)
	s_nop 1
	v_add_f32_dpp v86, v87, v87 quad_perm:[1,0,3,2] row_mask:0xf bank_mask:0xf
	ds_bpermute_b32 v158, v141, v157
	s_waitcnt lgkmcnt(0)
	v_add_f32_dpp v93, v93, v93 quad_perm:[1,0,3,2] row_mask:0xf bank_mask:0xf
	s_waitcnt lgkmcnt(0)
	v_add_f32_dpp v86, v86, v86 quad_perm:[2,3,0,1] row_mask:0xf bank_mask:0xf
	s_waitcnt lgkmcnt(0)
	v_add_f32_dpp v93, v93, v93 quad_perm:[2,3,0,1] row_mask:0xf bank_mask:0xf
	s_waitcnt lgkmcnt(0)
	v_add_f32_dpp v86, v86, v86 row_half_mirror row_mask:0xf bank_mask:0xf
	v_sub_u32_e32 v87, 0x7f4, v144
	v_pk_mul_f32 v[144:145], v[12:13], v[84:85]
	v_cvt_f32_u32_e32 v87, v87
	v_add_f32_e32 v89, v144, v89
	v_add_f32_e32 v89, v145, v89
	s_waitcnt lgkmcnt(0)
	v_add_f32_dpp v93, v93, v93 row_half_mirror row_mask:0xf bank_mask:0xf
	ds_bpermute_b32 v146, v141, v93
	ds_bpermute_b32 v88, v141, v86
	s_waitcnt lgkmcnt(0)
	v_add_f32_dpp v89, v89, v89 quad_perm:[1,0,3,2] row_mask:0xf bank_mask:0xf
	s_waitcnt lgkmcnt(0)
	s_nop 0
	v_add_f32_dpp v89, v89, v89 quad_perm:[2,3,0,1] row_mask:0xf bank_mask:0xf
	s_waitcnt lgkmcnt(0)
	s_nop 0
	v_add_f32_dpp v89, v89, v89 row_half_mirror row_mask:0xf bank_mask:0xf
	s_waitcnt lgkmcnt(0)
	s_nop 0
	v_add_f32_dpp v89, v89, v89 row_mirror row_mask:0xf bank_mask:0xf
	v_fma_f32 v89, -v127, v87, v89
	v_cndmask_b32_e64 v161, v135, v89, s[14:15]
	v_mul_f32_e32 v89, v15, v83
	v_fmac_f32_e32 v89, v14, v82
	v_fmac_f32_e32 v89, v16, v84
	v_fmac_f32_e32 v89, v17, v85
	v_max3_f32 v162, v162, v159, v161
	s_waitcnt lgkmcnt(0)
	v_add_f32_dpp v89, v89, v89 quad_perm:[1,0,3,2] row_mask:0xf bank_mask:0xf
	s_waitcnt lgkmcnt(0)
	s_nop 0
	v_add_f32_dpp v89, v89, v89 quad_perm:[2,3,0,1] row_mask:0xf bank_mask:0xf
	s_waitcnt lgkmcnt(0)
	s_nop 0
	v_add_f32_dpp v145, v89, v89 row_half_mirror row_mask:0xf bank_mask:0xf
	v_mul_f32_e32 v89, v19, v83
	v_mul_f32_e32 v83, v23, v83
	v_fmac_f32_e32 v89, v18, v82
	v_fmac_f32_e32 v83, v22, v82
	v_fmac_f32_e32 v89, v20, v84
	v_fmac_f32_e32 v83, v24, v84
	v_fmac_f32_e32 v89, v21, v85
	v_fmac_f32_e32 v83, v25, v85
	ds_bpermute_b32 v84, v142, v162
	ds_bpermute_b32 v160, v141, v145
	s_waitcnt lgkmcnt(0)
	v_add_f32_dpp v89, v89, v89 quad_perm:[1,0,3,2] row_mask:0xf bank_mask:0xf
	s_waitcnt lgkmcnt(0)
	s_nop 1
	v_add_f32_dpp v82, v83, v83 quad_perm:[1,0,3,2] row_mask:0xf bank_mask:0xf
	s_waitcnt lgkmcnt(0)
	v_max_f32_e32 v84, v84, v84
	v_max_f32_e32 v84, v162, v84
	ds_bpermute_b32 v85, v143, v84
	s_waitcnt lgkmcnt(0)
	v_add_f32_dpp v89, v89, v89 quad_perm:[2,3,0,1] row_mask:0xf bank_mask:0xf
	s_waitcnt lgkmcnt(0)
	v_add_f32_dpp v82, v82, v82 quad_perm:[2,3,0,1] row_mask:0xf bank_mask:0xf
	s_waitcnt lgkmcnt(0)
	v_max_f32_e32 v85, v85, v85
	v_max_f32_e32 v84, v84, v85
	v_cmp_neq_f32_e64 s[16:17], s35, v84
	s_waitcnt lgkmcnt(0)
	v_add_f32_dpp v89, v89, v89 row_half_mirror row_mask:0xf bank_mask:0xf
	s_waitcnt lgkmcnt(0)
	v_add_f32_dpp v82, v82, v82 row_half_mirror row_mask:0xf bank_mask:0xf
	ds_bpermute_b32 v144, v141, v89
	ds_bpermute_b32 v83, v141, v82
	s_and_saveexec_b64 s[24:25], s[16:17]
	s_cbranch_execz .LBB0_2764
	v_max_f32_e32 v84, v84, v84
	v_max_f32_e32 v85, v113, v113
	v_max_f32_e32 v119, v85, v84
	v_sub_f32_e32 v84, v113, v119
	v_mul_f32_e32 v113, 0x3fb8aa3b, v84
	v_sub_f32_e32 v84, v153, v119
	v_mul_f32_e32 v84, 0x3fb8aa3b, v84
	v_sub_f32_e32 v118, v156, v119
	v_exp_f32_e32 v84, v84
	v_mul_f32_e32 v118, 0x3fb8aa3b, v118
	v_exp_f32_e32 v118, v118
	v_exp_f32_e32 v156, v113
	v_add_f32_e32 v153, 0, v84
	v_pk_fma_f32 v[162:163], v[76:77], v[84:85], 0 op_sel_hi:[1,0,0]
	v_pk_fma_f32 v[84:85], v[74:75], v[84:85], 0 op_sel_hi:[1,0,0]
	v_add_f32_e32 v153, v118, v153
	v_pk_fma_f32 v[162:163], v[68:69], v[118:119], v[162:163] op_sel_hi:[1,0,1]
	v_pk_fma_f32 v[84:85], v[66:67], v[118:119], v[84:85] op_sel_hi:[1,0,1]
	v_sub_f32_e32 v118, v159, v119
	v_mul_f32_e32 v118, 0x3fb8aa3b, v118
	v_exp_f32_e32 v118, v118
	s_nop 0
	v_add_f32_e32 v153, v118, v153
	v_pk_fma_f32 v[84:85], v[70:71], v[118:119], v[84:85] op_sel_hi:[1,0,1]
	v_pk_fma_f32 v[162:163], v[72:73], v[118:119], v[162:163] op_sel_hi:[1,0,1]
	v_sub_f32_e32 v118, v161, v119
	v_mul_f32_e32 v118, 0x3fb8aa3b, v118
	v_exp_f32_e32 v118, v118
	s_nop 0
	v_add_f32_e32 v153, v118, v153
	ds_bpermute_b32 v113, v142, v153
	v_pk_fma_f32 v[162:163], v[80:81], v[118:119], v[162:163] op_sel_hi:[1,0,1]
	v_pk_fma_f32 v[84:85], v[78:79], v[118:119], v[84:85] op_sel_hi:[1,0,1]
	ds_bpermute_b32 v164, v142, v162
	ds_bpermute_b32 v165, v142, v163
	s_waitcnt lgkmcnt(0)
	v_add_f32_e32 v113, v153, v113
	ds_bpermute_b32 v118, v143, v113
	s_waitcnt lgkmcnt(0)
	v_pk_add_f32 v[162:163], v[162:163], v[164:165]
	ds_bpermute_b32 v164, v143, v162
	s_waitcnt lgkmcnt(0)
	v_add_f32_e32 v118, v113, v118
	v_fmac_f32_e32 v118, v112, v156
	ds_bpermute_b32 v112, v142, v84
	ds_bpermute_b32 v113, v142, v85
	ds_bpermute_b32 v165, v143, v163
	s_waitcnt lgkmcnt(0)
	v_pk_add_f32 v[84:85], v[84:85], v[112:113]
	ds_bpermute_b32 v112, v143, v84
	ds_bpermute_b32 v113, v143, v85
	s_waitcnt lgkmcnt(0)
	v_pk_add_f32 v[84:85], v[84:85], v[112:113]
	v_pk_add_f32 v[112:113], v[162:163], v[164:165]
	v_pk_fma_f32 v[62:63], v[62:63], v[156:157], v[84:85] op_sel_hi:[1,0,1]
	v_pk_fma_f32 v[64:65], v[64:65], v[156:157], v[112:113] op_sel_hi:[1,0,1]
	v_mov_b32_e32 v112, v118
	v_mov_b32_e32 v113, v119

.LBB0_2937:
	v_lshl_add_u64 v[18:19], s[68:69], 0, v[94:95]
	v_lshl_add_u64 v[22:23], s[68:69], 0, v[92:93]
	v_add_co_u32_e32 v20, vcc, 0x7800000, v18
	v_add_co_u32_e64 v102, s[6:7], s24, v22
	s_nop 0
	v_addc_co_u32_e32 v21, vcc, 0, v19, vcc
	v_addc_co_u32_e64 v103, s[6:7], 0, v23, s[6:7]
	v_add_co_u32_e64 v104, s[6:7], s25, v22
	v_add_co_u32_e32 v22, vcc, 0x7801000, v18
	s_nop 0
	v_addc_co_u32_e64 v105, s[6:7], 0, v23, s[6:7]
	global_load_dwordx4 v[78:81], v[20:21], off
	global_load_dwordx4 v[74:77], v[20:21], off offset:1024
	global_load_dwordx4 v[70:73], v[20:21], off offset:2048
	global_load_dwordx4 v[66:69], v[20:21], off offset:3072
	v_addc_co_u32_e32 v23, vcc, 0, v19, vcc
	v_add_co_u32_e32 v20, vcc, 0x7802000, v18
	global_load_dwordx4 v[62:65], v[22:23], off
	global_load_dwordx4 v[58:61], v[22:23], off offset:1024
	global_load_dwordx4 v[54:57], v[22:23], off offset:2048
	global_load_dwordx4 v[50:53], v[22:23], off offset:3072
	v_addc_co_u32_e32 v21, vcc, 0, v19, vcc
	v_add_co_u32_e32 v82, vcc, 0x7803000, v18
	global_load_dwordx4 v[46:49], v[20:21], off
	global_load_dwordx4 v[42:45], v[20:21], off offset:1024
	global_load_dwordx4 v[38:41], v[20:21], off offset:2048
	global_load_dwordx4 v[34:37], v[20:21], off offset:3072
	v_addc_co_u32_e32 v83, vcc, 0, v19, vcc
	global_load_dwordx4 v[30:33], v[82:83], off
	global_load_dwordx4 v[26:29], v[82:83], off offset:1024
	global_load_dwordx4 v[22:25], v[82:83], off offset:2048
	global_load_dwordx4 v[18:21], v[82:83], off offset:3072
	s_ashr_i32 s8, s12, 13
	s_add_i32 s9, s12, 0xffffc002
	s_cmpk_lt_i32 s12, 0x4000
	s_cselect_b32 s6, s8, s9
	s_mul_hi_i32 s7, s6, 0x9000
	s_mul_i32 s6, s6, 0x9000
	s_add_u32 s9, s3, s6
	s_addc_u32 s11, s4, s7
	s_add_u32 s6, s9, 0x6000
	s_addc_u32 s7, s11, 0
	s_add_u32 s10, s9, 0x7000
	s_addc_u32 s11, s11, 0
	v_lshl_add_u64 v[82:83], s[6:7], 0, v[90:91]
	v_lshl_add_u64 v[86:87], s[10:11], 0, v[90:91]
	global_load_dwordx4 v[82:85], v[82:83], off
	v_lshl_add_u64 v[148:149], s[6:7], 0, v[96:97]
	global_load_dwordx4 v[86:89], v[86:87], off
	v_lshl_add_u64 v[142:143], s[6:7], 0, v[98:99]
	v_lshl_add_u64 v[134:135], s[6:7], 0, v[100:101]
	s_add_i32 s6, s12, 0xffffc003
	s_cmpk_lt_i32 s12, 0x3fff
	s_cselect_b32 s6, s8, s6
	s_mul_hi_i32 s7, s6, 0x9000
	s_mul_i32 s6, s6, 0x9000
	s_add_u32 s9, s3, s6
	v_lshl_add_u64 v[152:153], s[10:11], 0, v[96:97]
	v_lshl_add_u64 v[146:147], s[10:11], 0, v[98:99]
	v_lshl_add_u64 v[140:141], s[10:11], 0, v[100:101]
	s_addc_u32 s11, s4, s7
	s_add_u32 s6, s9, 0x6000
	s_addc_u32 s7, s11, 0
	s_add_u32 s10, s9, 0x7000
	v_lshl_add_u64 v[132:133], s[6:7], 0, v[90:91]
	v_lshl_add_u64 v[126:127], s[6:7], 0, v[96:97]
	v_lshl_add_u64 v[118:119], s[6:7], 0, v[98:99]
	v_lshl_add_u64 v[114:115], s[6:7], 0, v[100:101]
	s_addc_u32 s11, s11, 0
	s_add_i32 s6, s12, 0xffffc004
	s_cmpk_lt_i32 s12, 0x3ffe
	s_cselect_b32 s6, s8, s6
	s_mul_hi_i32 s7, s6, 0x9000
	s_mul_i32 s6, s6, 0x9000
	s_add_u32 s6, s3, s6
	s_addc_u32 s7, s4, s7
	v_lshl_add_u64 v[138:139], s[10:11], 0, v[90:91]
	v_lshl_add_u64 v[130:131], s[10:11], 0, v[96:97]
	v_lshl_add_u64 v[122:123], s[10:11], 0, v[98:99]
	v_lshl_add_u64 v[116:117], s[10:11], 0, v[100:101]
	s_add_u32 s10, s6, 0x6000
	s_addc_u32 s11, s7, 0
	s_add_u32 s6, s6, 0x7000
	s_addc_u32 s7, s7, 0
	s_add_i32 s9, s12, 0xffffc005
	s_cmpk_lt_i32 s12, 0x3ffd
	v_lshl_add_u64 v[156:157], s[6:7], 0, v[90:91]
	v_lshl_add_u64 v[154:155], s[6:7], 0, v[96:97]
	v_lshl_add_u64 v[150:151], s[6:7], 0, v[98:99]
	v_lshl_add_u64 v[136:137], s[6:7], 0, v[100:101]
	s_cselect_b32 s6, s8, s9
	s_mul_hi_i32 s7, s6, 0x9000
	s_mul_i32 s6, s6, 0x9000
	s_add_u32 s6, s3, s6
	s_addc_u32 s7, s4, s7
	s_waitcnt vmcnt(0) lgkmcnt(0)
	v_pk_mul_f32 v[158:159], v[80:81], v[80:81]
	v_pk_mul_f32 v[160:161], v[78:79], v[78:79]
	v_pk_mul_f32 v[162:163], v[76:77], v[76:77]
	v_pk_mul_f32 v[164:165], v[74:75], v[74:75]
	v_mul_f32_e32 v174, v71, v71
	v_mul_f32_e32 v176, v73, v73
	v_mul_f32_e32 v187, v68, v68
	v_mul_f32_e32 v189, v69, v69
	v_pk_mov_b32 v[178:179], v[160:161], v[158:159] op_sel:[1,0]
	v_mov_b32_e32 v161, v159
	v_pk_mov_b32 v[158:159], v[164:165], v[162:163] op_sel:[1,0]
	v_mov_b32_e32 v165, v163
	v_pk_fma_f32 v[162:163], v[70:71], v[70:71], v[174:175] op_sel_hi:[1,1,0]
	v_pk_fma_f32 v[174:175], v[72:73], v[72:73], v[176:177] op_sel_hi:[1,1,0]
	v_pk_mul_f32 v[176:177], v[64:65], v[64:65]
	v_pk_mul_f32 v[180:181], v[62:63], v[62:63]
	v_pk_mul_f32 v[182:183], v[60:61], v[60:61]
	v_pk_mul_f32 v[184:185], v[58:59], v[58:59]
	v_mul_f32_e32 v186, v55, v55
	v_mul_f32_e32 v188, v57, v57
	v_pk_add_f32 v[160:161], v[178:179], v[160:161]
	v_pk_add_f32 v[158:159], v[158:159], v[164:165]
	v_mov_b32_e32 v163, v187
	v_mov_b32_e32 v175, v189
	v_pk_mov_b32 v[164:165], v[180:181], v[176:177] op_sel:[1,0]
	v_mov_b32_e32 v181, v177
	v_pk_mov_b32 v[176:177], v[184:185], v[182:183] op_sel:[1,0]
	v_mov_b32_e32 v185, v183
	v_pk_fma_f32 v[178:179], v[54:55], v[54:55], v[186:187] op_sel_hi:[1,1,0]
	v_pk_fma_f32 v[182:183], v[56:57], v[56:57], v[188:189] op_sel_hi:[1,1,0]
	v_pk_mul_f32 v[186:187], v[48:49], v[48:49]
	v_pk_mul_f32 v[188:189], v[46:47], v[46:47]
	v_pk_mul_f32 v[190:191], v[44:45], v[44:45]
	v_pk_mul_f32 v[192:193], v[42:43], v[42:43]
	v_mul_f32_e32 v197, v66, v66
	v_mul_f32_e32 v203, v67, v67
	v_mul_f32_e32 v195, v52, v52
	v_mul_f32_e32 v202, v53, v53
	v_mul_f32_e32 v194, v39, v39
	v_mul_f32_e32 v196, v41, v41
	v_pk_add_f32 v[198:199], v[160:161], v[160:161] op_sel:[0,1] op_sel_hi:[1,0]
	v_pk_add_f32 v[200:201], v[158:159], v[158:159] op_sel:[0,1] op_sel_hi:[1,0]
	v_pk_add_f32 v[174:175], v[162:163], v[174:175]
	v_pk_add_f32 v[158:159], v[164:165], v[180:181]
	v_pk_add_f32 v[160:161], v[176:177], v[184:185]
	v_pk_mov_b32 v[162:163], v[188:189], v[186:187] op_sel:[1,0]
	v_mov_b32_e32 v189, v187
	v_pk_mov_b32 v[164:165], v[192:193], v[190:191] op_sel:[1,0]
	v_mov_b32_e32 v193, v191
	v_mul_f32_e32 v208, v50, v50
	v_mul_f32_e32 v209, v51, v51
	v_mul_f32_e32 v212, v36, v36
	v_mul_f32_e32 v213, v37, v37
	v_mov_b32_e32 v179, v195
	v_mov_b32_e32 v183, v202
	v_pk_fma_f32 v[176:177], v[38:39], v[38:39], v[194:195] op_sel_hi:[1,1,0]
	v_pk_fma_f32 v[180:181], v[40:41], v[40:41], v[196:197] op_sel_hi:[1,1,0]
	v_pk_mul_f32 v[184:185], v[32:33], v[32:33]
	v_pk_mul_f32 v[186:187], v[30:31], v[30:31]
	v_pk_mul_f32 v[190:191], v[28:29], v[28:29]
	v_pk_mul_f32 v[194:195], v[26:27], v[26:27]
	v_mov_b32_e32 v199, v197
	v_mov_b32_e32 v201, v203
	v_pk_add_f32 v[204:205], v[158:159], v[158:159] op_sel:[0,1] op_sel_hi:[1,0]
	v_pk_add_f32 v[206:207], v[160:161], v[160:161] op_sel:[0,1] op_sel_hi:[1,0]
	v_pk_add_f32 v[162:163], v[162:163], v[188:189]
	v_pk_add_f32 v[164:165], v[164:165], v[192:193]
	v_mul_f32_e32 v210, v34, v34
	v_mul_f32_e32 v211, v35, v35
	v_pk_add_f32 v[178:179], v[178:179], v[182:183]
	v_mov_b32_e32 v177, v212
	v_mov_b32_e32 v181, v213
	v_pk_mov_b32 v[182:183], v[186:187], v[184:185] op_sel:[1,0]
	v_mov_b32_e32 v187, v185
	v_pk_mov_b32 v[184:185], v[194:195], v[190:191] op_sel:[1,0]
	v_mov_b32_e32 v195, v191
	v_pk_add_f32 v[188:189], v[198:199], v[200:201]
	v_mov_b32_e32 v205, v208
	v_mov_b32_e32 v207, v209
	v_pk_add_f32 v[190:191], v[162:163], v[162:163] op_sel:[0,1] op_sel_hi:[1,0]
	v_pk_add_f32 v[192:193], v[164:165], v[164:165] op_sel:[0,1] op_sel_hi:[1,0]
	v_pk_add_f32 v[176:177], v[176:177], v[180:181]
	v_pk_add_f32 v[174:175], v[188:189], v[174:175]
	v_pk_add_f32 v[180:181], v[204:205], v[206:207]
	v_mov_b32_e32 v191, v210
	v_mov_b32_e32 v193, v211
	v_pk_add_f32 v[162:163], v[182:183], v[186:187]
	v_add_f32_e32 v182, v174, v175
	v_pk_add_f32 v[174:175], v[180:181], v[178:179]
	v_pk_add_f32 v[178:179], v[190:191], v[192:193]
	v_add_f32_e32 v180, v174, v175
	v_pk_add_f32 v[174:175], v[178:179], v[176:177]
	v_add_f32_e32 v174, v174, v175
	s_add_u32 s18, s6, 0x6000
	s_waitcnt lgkmcnt(0)
	s_nop 1
	v_add_f32_dpp v176, v182, v182 quad_perm:[1,0,3,2] row_mask:0xf bank_mask:0xf
	s_waitcnt lgkmcnt(0)
	s_nop 1
	v_add_f32_dpp v177, v180, v180 quad_perm:[1,0,3,2] row_mask:0xf bank_mask:0xf
	s_waitcnt lgkmcnt(0)
	s_nop 1
	v_add_f32_dpp v174, v174, v174 quad_perm:[1,0,3,2] row_mask:0xf bank_mask:0xf
	s_waitcnt lgkmcnt(0)
	s_nop 1
	v_add_f32_dpp v176, v176, v176 quad_perm:[2,3,0,1] row_mask:0xf bank_mask:0xf
	s_waitcnt lgkmcnt(0)
	s_nop 1
	v_add_f32_dpp v177, v177, v177 quad_perm:[2,3,0,1] row_mask:0xf bank_mask:0xf
	s_waitcnt lgkmcnt(0)
	s_nop 1
	v_add_f32_dpp v174, v174, v174 quad_perm:[2,3,0,1] row_mask:0xf bank_mask:0xf
	s_waitcnt lgkmcnt(0)
	s_nop 1
	v_add_f32_dpp v176, v176, v176 row_half_mirror row_mask:0xf bank_mask:0xf
	s_waitcnt lgkmcnt(0)
	s_nop 1
	v_add_f32_dpp v177, v177, v177 row_half_mirror row_mask:0xf bank_mask:0xf
	s_waitcnt lgkmcnt(0)
	s_nop 1
	v_add_f32_dpp v174, v174, v174 row_half_mirror row_mask:0xf bank_mask:0xf
	s_waitcnt lgkmcnt(0)
	s_nop 1
	v_add_f32_dpp v176, v176, v176 row_mirror row_mask:0xf bank_mask:0xf
	ds_bpermute_b32 v178, v170, v176
	s_waitcnt lgkmcnt(2)
	s_nop 1
	v_add_f32_dpp v177, v177, v177 row_mirror row_mask:0xf bank_mask:0xf
	ds_bpermute_b32 v179, v170, v177
	s_waitcnt lgkmcnt(2)
	s_nop 1
	v_add_f32_dpp v174, v174, v174 row_mirror row_mask:0xf bank_mask:0xf
	ds_bpermute_b32 v175, v170, v174
	s_waitcnt lgkmcnt(2)
	v_add_f32_e32 v176, v176, v178
	ds_bpermute_b32 v178, v171, v176
	s_waitcnt lgkmcnt(2)
	v_add_f32_e32 v177, v177, v179
	ds_bpermute_b32 v179, v171, v177
	s_waitcnt lgkmcnt(2)
	v_add_f32_e32 v174, v174, v175
	ds_bpermute_b32 v175, v171, v174
	s_waitcnt lgkmcnt(2)
	v_add_f32_e32 v176, v176, v178
	v_fmamk_f32 v176, v176, 0x3a800000, v172
	s_addc_u32 s19, s7, 0
	s_waitcnt lgkmcnt(1)
	v_add_f32_e32 v177, v177, v179
	v_mul_f32_e32 v178, 0x4f800000, v176
	v_cmp_gt_f32_e32 vcc, s13, v176
	s_add_u32 s20, s6, 0x7000
	v_fmamk_f32 v177, v177, 0x3a800000, v172
	s_waitcnt lgkmcnt(0)
	v_add_f32_e32 v174, v174, v175
	v_cndmask_b32_e32 v175, v176, v178, vcc
	s_addc_u32 s21, s7, 0
	v_mul_f32_e32 v176, 0x4f800000, v177
	v_cmp_gt_f32_e64 s[6:7], s13, v177
	v_sqrt_f32_e32 v178, v175
	v_fmamk_f32 v174, v174, 0x3a800000, v172
	v_cndmask_b32_e64 v176, v177, v176, s[6:7]
	v_mul_f32_e32 v177, 0x4f800000, v174
	v_cmp_gt_f32_e64 s[8:9], s13, v174
	v_sqrt_f32_e32 v179, v176
	v_add_u32_e32 v180, -1, v178
	v_cndmask_b32_e64 v174, v174, v177, s[8:9]
	v_sqrt_f32_e32 v177, v174
	v_add_u32_e32 v181, 1, v178
	v_fma_f32 v182, -v180, v178, v175
	v_lshl_add_u64 v[112:113], s[10:11], 0, v[90:91]
	v_lshl_add_u64 v[106:107], s[10:11], 0, v[96:97]
	v_lshl_add_u64 v[110:111], s[10:11], 0, v[98:99]
	v_lshl_add_u64 v[108:109], s[10:11], 0, v[100:101]
	v_pk_add_f32 v[164:165], v[184:185], v[194:195]
	v_fma_f32 v183, -v181, v178, v175
	v_add_u32_e32 v184, -1, v179
	v_cmp_ge_f32_e64 s[10:11], 0, v182
	v_add_u32_e32 v185, 1, v179
	v_fma_f32 v182, -v185, v179, v176
	v_cndmask_b32_e64 v178, v178, v180, s[10:11]
	v_fma_f32 v180, -v184, v179, v176
	v_cmp_lt_f32_e64 s[10:11], 0, v183
	v_add_u32_e32 v186, -1, v177
	v_add_u32_e32 v187, 1, v177
	v_cndmask_b32_e64 v178, v178, v181, s[10:11]
	v_cmp_ge_f32_e64 s[10:11], 0, v180
	v_fma_f32 v180, -v186, v177, v174
	v_fma_f32 v181, -v187, v177, v174
	v_cndmask_b32_e64 v179, v179, v184, s[10:11]
	v_cmp_lt_f32_e64 s[10:11], 0, v182
	v_mul_f32_e32 v182, 0x37800000, v178
	v_cndmask_b32_e32 v178, v178, v182, vcc
	v_cndmask_b32_e64 v179, v179, v185, s[10:11]
	v_cmp_ge_f32_e64 s[10:11], 0, v180
	v_mul_f32_e32 v180, 0x37800000, v179
	v_cmp_class_f32_e32 vcc, v175, v173
	v_cndmask_b32_e64 v177, v177, v186, s[10:11]
	v_cmp_lt_f32_e64 s[10:11], 0, v181
	v_cndmask_b32_e32 v175, v178, v175, vcc
	v_cndmask_b32_e64 v178, v179, v180, s[6:7]
	v_cndmask_b32_e64 v177, v177, v187, s[10:11]
	v_cmp_class_f32_e32 vcc, v176, v173
	v_mul_f32_e32 v179, 0x37800000, v177
	v_div_scale_f32 v180, s[6:7], v175, v175, 1.0
	v_cndmask_b32_e32 v176, v178, v176, vcc
	v_cndmask_b32_e64 v177, v177, v179, s[8:9]
	v_cmp_class_f32_e32 vcc, v174, v173
	v_rcp_f32_e32 v178, v180
	v_div_scale_f32 v179, s[8:9], v176, v176, 1.0
	v_cndmask_b32_e32 v177, v177, v174, vcc
	v_rcp_f32_e32 v183, v179
	v_div_scale_f32 v184, s[10:11], v177, v177, 1.0
	v_rcp_f32_e32 v186, v184
	v_fma_f32 v174, -v180, v178, 1.0
	v_div_scale_f32 v181, s[6:7], 1.0, v175, 1.0
	v_fmac_f32_e32 v178, v174, v178
	v_fma_f32 v174, -v179, v183, 1.0
	v_div_scale_f32 v182, s[8:9], 1.0, v176, 1.0
	v_mul_f32_e32 v187, v181, v178
	v_fmac_f32_e32 v183, v174, v183
	v_fma_f32 v174, -v184, v186, 1.0
	v_fma_f32 v188, -v180, v187, v181
	v_mul_f32_e32 v189, v182, v183
	v_div_scale_f32 v185, s[10:11], 1.0, v177, 1.0
	v_fmac_f32_e32 v186, v174, v186
	v_fmac_f32_e32 v187, v188, v178
	v_fma_f32 v174, -v179, v189, v182
	v_mul_f32_e32 v188, v185, v186
	v_fma_f32 v180, -v180, v187, v181
	v_fmac_f32_e32 v189, v174, v183
	s_mov_b64 vcc, s[6:7]
	v_fma_f32 v174, -v184, v188, v185
	v_div_fmas_f32 v178, v180, v178, v187
	v_fma_f32 v179, -v179, v189, v182
	s_mov_b64 vcc, s[8:9]
	v_fmac_f32_e32 v188, v174, v186
	v_div_fixup_f32 v174, v178, v175, 1.0
	v_div_fmas_f32 v175, v179, v183, v189
	v_fma_f32 v178, -v184, v188, v185
	v_pk_mul_f32 v[80:81], v[80:81], v[174:175] op_sel_hi:[1,0]
	v_pk_mul_f32 v[78:79], v[78:79], v[174:175] op_sel_hi:[1,0]
	s_mov_b64 vcc, s[10:11]
	v_pk_add_f32 v[88:89], v[88:89], 1.0 op_sel_hi:[1,0]
	v_pk_add_f32 v[86:87], v[86:87], 1.0 op_sel_hi:[1,0]
	v_pk_mul_f32 v[76:77], v[76:77], v[174:175] op_sel_hi:[1,0]
	v_pk_mul_f32 v[74:75], v[74:75], v[174:175] op_sel_hi:[1,0]
	v_pk_mul_f32 v[72:73], v[72:73], v[174:175] op_sel_hi:[1,0]
	v_pk_mul_f32 v[70:71], v[70:71], v[174:175] op_sel_hi:[1,0]
	v_pk_mul_f32 v[68:69], v[68:69], v[174:175] op_sel_hi:[1,0]
	v_pk_mul_f32 v[66:67], v[66:67], v[174:175] op_sel_hi:[1,0]
	v_div_fixup_f32 v174, v175, v176, 1.0
	v_div_fmas_f32 v176, v178, v186, v188
	v_pk_mul_f32 v[78:79], v[2:3], v[78:79]
	v_pk_mul_f32 v[80:81], v[4:5], v[80:81]
	v_pk_mul_f32 v[64:65], v[64:65], v[174:175] op_sel_hi:[1,0]
	v_pk_mul_f32 v[62:63], v[62:63], v[174:175] op_sel_hi:[1,0]
	v_pk_mul_f32 v[60:61], v[60:61], v[174:175] op_sel_hi:[1,0]
	v_pk_mul_f32 v[58:59], v[58:59], v[174:175] op_sel_hi:[1,0]
	v_pk_mul_f32 v[56:57], v[56:57], v[174:175] op_sel_hi:[1,0]
	v_pk_mul_f32 v[54:55], v[54:55], v[174:175] op_sel_hi:[1,0]
	v_pk_mul_f32 v[52:53], v[52:53], v[174:175] op_sel_hi:[1,0]
	v_pk_mul_f32 v[174:175], v[50:51], v[174:175] op_sel_hi:[1,0]
	v_div_fixup_f32 v50, v176, v177, 1.0
	v_pk_fma_f32 v[80:81], v[88:89], v[80:81], v[84:85]
	v_pk_fma_f32 v[78:79], v[86:87], v[78:79], v[82:83]
	v_pk_mul_f32 v[86:87], v[16:17], v[52:53]
	v_pk_mul_f32 v[48:49], v[48:49], v[50:51] op_sel_hi:[1,0]
	v_pk_mul_f32 v[46:47], v[46:47], v[50:51] op_sel_hi:[1,0]
	v_pk_mul_f32 v[82:83], v[10:11], v[54:55]
	v_pk_mul_f32 v[84:85], v[14:15], v[174:175]
	v_pk_mul_f32 v[88:89], v[2:3], v[46:47]
	v_pk_mul_f32 v[174:175], v[4:5], v[48:49]
	v_cvt_pk_bf16_f32 v46, v78, v79
	v_cvt_pk_bf16_f32 v47, v80, v81
	global_store_dwordx2 v[102:103], v[46:47], off
	global_load_dwordx4 v[46:49], v[152:153], off
	s_nop 0
	global_load_dwordx4 v[52:55], v[148:149], off
	v_pk_mul_f32 v[74:75], v[6:7], v[74:75]
	v_pk_mul_f32 v[76:77], v[8:9], v[76:77]
	v_pk_mul_f32 v[70:71], v[10:11], v[70:71]
	v_pk_mul_f32 v[72:73], v[12:13], v[72:73]
	v_pk_mul_f32 v[66:67], v[66:67], v[14:15]
	v_pk_mul_f32 v[68:69], v[68:69], v[16:17]
	v_pk_mul_f32 v[62:63], v[2:3], v[62:63]
	v_pk_mul_f32 v[64:65], v[4:5], v[64:65]
	v_pk_mul_f32 v[58:59], v[6:7], v[58:59]
	v_pk_mul_f32 v[60:61], v[8:9], v[60:61]
	v_pk_mul_f32 v[56:57], v[12:13], v[56:57]
	v_mul_f32_e32 v196, v23, v23
	v_mul_f32_e32 v202, v25, v25
	v_mul_f32_e32 v214, v18, v18
	v_mul_f32_e32 v215, v19, v19
	v_mul_f32_e32 v216, v20, v20
	v_mul_f32_e32 v217, v21, v21
	v_pk_fma_f32 v[158:159], v[22:23], v[22:23], v[196:197] op_sel_hi:[1,1,0]
	v_pk_fma_f32 v[160:161], v[24:25], v[24:25], v[202:203] op_sel_hi:[1,1,0]
	v_mov_b32_e32 v159, v216
	v_mov_b32_e32 v161, v217
	v_lshl_add_u64 v[144:145], s[20:21], 0, v[90:91]
	v_lshl_add_u64 v[128:129], s[18:19], 0, v[90:91]
	v_lshl_add_u64 v[124:125], s[20:21], 0, v[96:97]
	v_lshl_add_u64 v[120:121], s[18:19], 0, v[96:97]
	s_add_i32 s12, s12, 32
	v_lshl_add_u64 v[92:93], v[92:93], 0, s[14:15]
	v_lshl_add_u64 v[94:95], v[94:95], 0, s[16:17]
	s_cmp_lt_i32 s12, s2
	s_waitcnt vmcnt(0) lgkmcnt(0)
	v_pk_add_f32 v[48:49], v[48:49], 1.0 op_sel_hi:[1,0]
	v_pk_add_f32 v[46:47], v[46:47], 1.0 op_sel_hi:[1,0]
	v_pk_fma_f32 v[48:49], v[48:49], v[76:77], v[54:55]
	v_pk_fma_f32 v[46:47], v[46:47], v[74:75], v[52:53]
	v_cvt_pk_bf16_f32 v46, v46, v47
	v_cvt_pk_bf16_f32 v47, v48, v49
	global_store_dwordx2 v[102:103], v[46:47], off offset:512
	global_load_dwordx4 v[46:49], v[146:147], off
	s_nop 0
	global_load_dwordx4 v[52:55], v[142:143], off
	s_waitcnt vmcnt(0) lgkmcnt(0)
	v_pk_add_f32 v[48:49], v[48:49], 1.0 op_sel_hi:[1,0]
	v_pk_add_f32 v[46:47], v[46:47], 1.0 op_sel_hi:[1,0]
	v_pk_fma_f32 v[48:49], v[72:73], v[48:49], v[54:55]
	v_pk_fma_f32 v[46:47], v[70:71], v[46:47], v[52:53]
	v_cvt_pk_bf16_f32 v46, v46, v47
	v_cvt_pk_bf16_f32 v47, v48, v49
	global_store_dwordx2 v[102:103], v[46:47], off offset:1024
	global_load_dwordx4 v[46:49], v[140:141], off
	s_nop 0
	global_load_dwordx4 v[52:55], v[134:135], off
	s_waitcnt vmcnt(0) lgkmcnt(0)
	v_pk_add_f32 v[48:49], v[48:49], 1.0 op_sel_hi:[1,0]
	v_pk_add_f32 v[46:47], v[46:47], 1.0 op_sel_hi:[1,0]
	v_pk_fma_f32 v[48:49], v[68:69], v[48:49], v[54:55]
	v_pk_fma_f32 v[46:47], v[66:67], v[46:47], v[52:53]
	v_cvt_pk_bf16_f32 v46, v46, v47
	v_cvt_pk_bf16_f32 v47, v48, v49
	global_store_dwordx2 v[102:103], v[46:47], off offset:1536
	global_load_dwordx4 v[46:49], v[138:139], off
	s_nop 0
	global_load_dwordx4 v[52:55], v[132:133], off
	s_waitcnt vmcnt(0) lgkmcnt(0)
	v_pk_add_f32 v[48:49], v[48:49], 1.0 op_sel_hi:[1,0]
	v_pk_add_f32 v[46:47], v[46:47], 1.0 op_sel_hi:[1,0]
	v_pk_fma_f32 v[48:49], v[48:49], v[64:65], v[54:55]
	v_pk_fma_f32 v[46:47], v[46:47], v[62:63], v[52:53]
	v_cvt_pk_bf16_f32 v46, v46, v47
	v_cvt_pk_bf16_f32 v47, v48, v49
	global_store_dwordx2 v[102:103], v[46:47], off offset:2048
	global_load_dwordx4 v[46:49], v[130:131], off
	s_nop 0
	global_load_dwordx4 v[52:55], v[126:127], off
	s_waitcnt vmcnt(0) lgkmcnt(0)
	v_pk_add_f32 v[48:49], v[48:49], 1.0 op_sel_hi:[1,0]
	v_pk_add_f32 v[46:47], v[46:47], 1.0 op_sel_hi:[1,0]
	v_pk_fma_f32 v[48:49], v[48:49], v[60:61], v[54:55]
	v_pk_fma_f32 v[46:47], v[46:47], v[58:59], v[52:53]
	v_cvt_pk_bf16_f32 v46, v46, v47
	v_cvt_pk_bf16_f32 v47, v48, v49
	global_store_dwordx2 v[102:103], v[46:47], off offset:2560
	global_load_dwordx4 v[46:49], v[122:123], off
	s_nop 0
	global_load_dwordx4 v[52:55], v[118:119], off
	v_pk_add_f32 v[58:59], v[164:165], v[164:165] op_sel:[0,1] op_sel_hi:[1,0]
	v_pk_add_f32 v[60:61], v[158:159], v[160:161]
	v_mov_b32_e32 v59, v215
	s_waitcnt vmcnt(0) lgkmcnt(0)
	v_pk_add_f32 v[48:49], v[48:49], 1.0 op_sel_hi:[1,0]
	v_pk_add_f32 v[46:47], v[46:47], 1.0 op_sel_hi:[1,0]
	v_pk_fma_f32 v[48:49], v[48:49], v[56:57], v[54:55]
	v_pk_fma_f32 v[46:47], v[46:47], v[82:83], v[52:53]
	v_cvt_pk_bf16_f32 v46, v46, v47
	v_cvt_pk_bf16_f32 v47, v48, v49
	global_store_dwordx2 v[102:103], v[46:47], off offset:3072
	global_load_dwordx4 v[46:49], v[116:117], off
	s_nop 0
	global_load_dwordx4 v[52:55], v[114:115], off
	v_pk_add_f32 v[56:57], v[162:163], v[162:163] op_sel:[0,1] op_sel_hi:[1,0]
	s_waitcnt vmcnt(0) lgkmcnt(0)
	v_pk_add_f32 v[48:49], v[48:49], 1.0 op_sel_hi:[1,0]
	v_pk_add_f32 v[46:47], v[46:47], 1.0 op_sel_hi:[1,0]
	v_pk_fma_f32 v[48:49], v[86:87], v[48:49], v[54:55]
	v_pk_fma_f32 v[46:47], v[84:85], v[46:47], v[52:53]
	v_cvt_pk_bf16_f32 v46, v46, v47
	v_cvt_pk_bf16_f32 v47, v48, v49
	global_store_dwordx2 v[102:103], v[46:47], off offset:3584
	global_load_dwordx4 v[46:49], v[156:157], off
	s_nop 0
	global_load_dwordx4 v[52:55], v[112:113], off
	v_mov_b32_e32 v57, v214
	s_waitcnt vmcnt(0) lgkmcnt(0)
	v_pk_add_f32 v[48:49], v[48:49], 1.0 op_sel_hi:[1,0]
	v_pk_add_f32 v[46:47], v[46:47], 1.0 op_sel_hi:[1,0]
	v_pk_fma_f32 v[48:49], v[48:49], v[174:175], v[54:55]
	v_pk_fma_f32 v[46:47], v[46:47], v[88:89], v[52:53]
	v_bfe_u32 v51, v46, 16, 1
	v_bfe_u32 v52, v47, 16, 1
	v_add3_u32 v46, v46, v51, s22
	v_add3_u32 v47, v47, v52, s22
	v_lshrrev_b32_e32 v46, 16, v46
	v_and_or_b32 v46, v47, s23, v46
	v_cvt_pk_bf16_f32 v47, v48, v49
	global_store_dwordx2 v[104:105], v[46:47], off
	global_load_dwordx4 v[46:49], v[154:155], off
	s_nop 0
	global_load_dwordx4 v[52:55], v[106:107], off
	v_pk_mul_f32 v[44:45], v[44:45], v[50:51] op_sel_hi:[1,0]
	v_pk_mul_f32 v[42:43], v[42:43], v[50:51] op_sel_hi:[1,0]
	v_pk_mul_f32 v[44:45], v[8:9], v[44:45]
	v_pk_mul_f32 v[42:43], v[6:7], v[42:43]
	s_waitcnt vmcnt(0) lgkmcnt(0)
	v_pk_add_f32 v[48:49], v[48:49], 1.0 op_sel_hi:[1,0]
	v_pk_add_f32 v[46:47], v[46:47], 1.0 op_sel_hi:[1,0]
	v_pk_fma_f32 v[44:45], v[48:49], v[44:45], v[54:55]
	v_pk_fma_f32 v[42:43], v[46:47], v[42:43], v[52:53]
	v_cvt_pk_bf16_f32 v42, v42, v43
	v_cvt_pk_bf16_f32 v43, v44, v45
	global_store_dwordx2 v[104:105], v[42:43], off offset:512
	global_load_dwordx4 v[42:45], v[150:151], off
	s_nop 0
	global_load_dwordx4 v[46:49], v[110:111], off
	v_pk_add_f32 v[52:53], v[56:57], v[58:59]
	s_waitcnt vmcnt(0) lgkmcnt(0)
	v_pk_add_f32 v[44:45], v[44:45], 1.0 op_sel_hi:[1,0]
	v_pk_add_f32 v[52:53], v[52:53], v[60:61]
	v_pk_add_f32 v[42:43], v[42:43], 1.0 op_sel_hi:[1,0]
	v_add_f32_e32 v51, v52, v53
	s_waitcnt lgkmcnt(0)
	s_nop 1
	v_add_f32_dpp v51, v51, v51 quad_perm:[1,0,3,2] row_mask:0xf bank_mask:0xf
	ds_bpermute_b32 v52, v167, v51
	s_waitcnt lgkmcnt(0)
	v_add_f32_e32 v51, v51, v52
	v_pk_mul_f32 v[40:41], v[40:41], v[50:51] op_sel_hi:[1,0]
	v_pk_mul_f32 v[38:39], v[38:39], v[50:51] op_sel_hi:[1,0]
	v_pk_mul_f32 v[40:41], v[12:13], v[40:41]
	v_pk_mul_f32 v[38:39], v[10:11], v[38:39]
	v_pk_fma_f32 v[40:41], v[44:45], v[40:41], v[48:49]
	v_pk_fma_f32 v[38:39], v[42:43], v[38:39], v[46:47]
	v_cvt_pk_bf16_f32 v38, v38, v39
	v_cvt_pk_bf16_f32 v39, v40, v41
	global_store_dwordx2 v[104:105], v[38:39], off offset:1024
	global_load_dwordx4 v[38:41], v[136:137], off
	s_nop 0
	global_load_dwordx4 v[42:45], v[108:109], off
	v_pk_mul_f32 v[36:37], v[36:37], v[50:51] op_sel_hi:[1,0]
	v_pk_mul_f32 v[34:35], v[34:35], v[50:51] op_sel_hi:[1,0]
	v_pk_mul_f32 v[36:37], v[16:17], v[36:37]
	v_pk_mul_f32 v[34:35], v[14:15], v[34:35]
	ds_bpermute_b32 v46, v168, v51
	s_waitcnt lgkmcnt(0)
	v_add_f32_e32 v46, v51, v46
	ds_bpermute_b32 v47, v169, v46
	s_waitcnt lgkmcnt(0)
	v_add_f32_e32 v46, v46, v47
	ds_bpermute_b32 v47, v170, v46
	s_waitcnt lgkmcnt(0)
	v_add_f32_e32 v46, v46, v47
	ds_bpermute_b32 v47, v171, v46
	s_waitcnt lgkmcnt(0)
	v_add_f32_e32 v46, v46, v47
	v_fmamk_f32 v46, v46, 0x3a800000, v172
	v_mul_f32_e32 v47, 0x4f800000, v46
	v_cmp_gt_f32_e32 vcc, s13, v46
	s_waitcnt vmcnt(0)
	v_pk_add_f32 v[40:41], v[40:41], 1.0 op_sel_hi:[1,0]
	v_pk_add_f32 v[38:39], v[38:39], 1.0 op_sel_hi:[1,0]
	v_pk_fma_f32 v[36:37], v[36:37], v[40:41], v[44:45]
	v_pk_fma_f32 v[34:35], v[34:35], v[38:39], v[42:43]
	v_cvt_pk_bf16_f32 v34, v34, v35
	v_cvt_pk_bf16_f32 v35, v36, v37
	global_store_dwordx2 v[104:105], v[34:35], off offset:1536
	global_load_dwordx4 v[34:37], v[144:145], off
	s_nop 0
	global_load_dwordx4 v[38:41], v[128:129], off
	v_cndmask_b32_e32 v42, v46, v47, vcc
	v_sqrt_f32_e32 v43, v42
	s_waitcnt vmcnt(0) lgkmcnt(0)
	v_pk_add_f32 v[36:37], v[36:37], 1.0 op_sel_hi:[1,0]
	v_add_u32_e32 v44, -1, v43
	v_add_u32_e32 v45, 1, v43
	v_fma_f32 v46, -v44, v43, v42
	v_fma_f32 v47, -v45, v43, v42
	v_cmp_ge_f32_e64 s[6:7], 0, v46
	v_pk_add_f32 v[34:35], v[34:35], 1.0 op_sel_hi:[1,0]
	s_nop 0
	v_cndmask_b32_e64 v43, v43, v44, s[6:7]
	v_cmp_lt_f32_e64 s[6:7], 0, v47
	s_nop 1
	v_cndmask_b32_e64 v43, v43, v45, s[6:7]
	v_mul_f32_e32 v44, 0x37800000, v43
	v_cndmask_b32_e32 v43, v43, v44, vcc
	v_cmp_class_f32_e32 vcc, v42, v173
	s_nop 1
	v_cndmask_b32_e32 v42, v43, v42, vcc
	v_div_scale_f32 v43, s[6:7], v42, v42, 1.0
	v_rcp_f32_e32 v45, v43
	v_div_scale_f32 v44, vcc, 1.0, v42, 1.0
	v_fma_f32 v46, -v43, v45, 1.0
	v_fmac_f32_e32 v45, v46, v45
	v_mul_f32_e32 v46, v44, v45
	v_fma_f32 v47, -v43, v46, v44
	v_fmac_f32_e32 v46, v47, v45
	v_fma_f32 v43, -v43, v46, v44
	v_div_fmas_f32 v43, v43, v45, v46
	v_div_fixup_f32 v42, v43, v42, 1.0
	v_pk_mul_f32 v[32:33], v[32:33], v[42:43] op_sel_hi:[1,0]
	v_pk_mul_f32 v[30:31], v[30:31], v[42:43] op_sel_hi:[1,0]
	v_pk_mul_f32 v[32:33], v[4:5], v[32:33]
	v_pk_mul_f32 v[30:31], v[2:3], v[30:31]
	v_pk_fma_f32 v[32:33], v[36:37], v[32:33], v[40:41]
	v_pk_fma_f32 v[30:31], v[34:35], v[30:31], v[38:39]
	v_cvt_pk_bf16_f32 v30, v30, v31
	v_cvt_pk_bf16_f32 v31, v32, v33
	global_store_dwordx2 v[104:105], v[30:31], off offset:2048
	global_load_dwordx4 v[30:33], v[124:125], off
	s_nop 0
	global_load_dwordx4 v[34:37], v[120:121], off
	v_pk_mul_f32 v[28:29], v[28:29], v[42:43] op_sel_hi:[1,0]
	v_pk_mul_f32 v[26:27], v[26:27], v[42:43] op_sel_hi:[1,0]
	v_pk_mul_f32 v[28:29], v[8:9], v[28:29]
	v_pk_mul_f32 v[26:27], v[6:7], v[26:27]
	v_lshl_add_u64 v[40:41], s[20:21], 0, v[98:99]
	v_lshl_add_u64 v[38:39], s[18:19], 0, v[98:99]
	v_pk_mul_f32 v[24:25], v[24:25], v[42:43] op_sel_hi:[1,0]
	v_pk_mul_f32 v[22:23], v[22:23], v[42:43] op_sel_hi:[1,0]
	v_pk_mul_f32 v[24:25], v[12:13], v[24:25]
	v_pk_mul_f32 v[22:23], v[10:11], v[22:23]
	v_pk_mul_f32 v[20:21], v[20:21], v[42:43] op_sel_hi:[1,0]
	v_pk_mul_f32 v[18:19], v[18:19], v[42:43] op_sel_hi:[1,0]
	v_pk_mul_f32 v[20:21], v[16:17], v[20:21]
	v_pk_mul_f32 v[18:19], v[14:15], v[18:19]
	s_waitcnt vmcnt(0) lgkmcnt(0)
	v_pk_add_f32 v[32:33], v[32:33], 1.0 op_sel_hi:[1,0]
	v_pk_add_f32 v[30:31], v[30:31], 1.0 op_sel_hi:[1,0]
	v_pk_fma_f32 v[28:29], v[32:33], v[28:29], v[36:37]
	v_pk_fma_f32 v[26:27], v[30:31], v[26:27], v[34:35]
	v_cvt_pk_bf16_f32 v26, v26, v27
	v_cvt_pk_bf16_f32 v27, v28, v29
	global_store_dwordx2 v[104:105], v[26:27], off offset:2560
	global_load_dwordx4 v[26:29], v[40:41], off
	s_nop 0
	global_load_dwordx4 v[30:33], v[38:39], off
	v_lshl_add_u64 v[36:37], s[20:21], 0, v[100:101]
	v_lshl_add_u64 v[34:35], s[18:19], 0, v[100:101]
	s_waitcnt vmcnt(0) lgkmcnt(0)
	v_pk_add_f32 v[28:29], v[28:29], 1.0 op_sel_hi:[1,0]
	v_pk_add_f32 v[26:27], v[26:27], 1.0 op_sel_hi:[1,0]
	v_pk_fma_f32 v[24:25], v[28:29], v[24:25], v[32:33]
	v_pk_fma_f32 v[22:23], v[26:27], v[22:23], v[30:31]
	v_cvt_pk_bf16_f32 v22, v22, v23
	v_cvt_pk_bf16_f32 v23, v24, v25
	global_store_dwordx2 v[104:105], v[22:23], off offset:3072
	global_load_dwordx4 v[22:25], v[36:37], off
	s_nop 0
	global_load_dwordx4 v[26:29], v[34:35], off
	s_waitcnt vmcnt(0) lgkmcnt(0)
	v_pk_add_f32 v[24:25], v[24:25], 1.0 op_sel_hi:[1,0]
	v_pk_add_f32 v[22:23], v[22:23], 1.0 op_sel_hi:[1,0]
	v_pk_fma_f32 v[20:21], v[20:21], v[24:25], v[28:29]
	v_pk_fma_f32 v[18:19], v[18:19], v[22:23], v[26:27]
	v_cvt_pk_bf16_f32 v18, v18, v19
	v_cvt_pk_bf16_f32 v19, v20, v21
	global_store_dwordx2 v[104:105], v[18:19], off offset:3584
	s_cbranch_scc1 .LBB0_2937

.LBB0_2965:
	ds_read2_b32 v[20:21], v18 offset1:2
	ds_read2st64_b32 v[22:23], v19 offset1:4
	s_add_i32 s8, s8, -8
	s_cmp_eq_u32 s8, 0
	s_waitcnt lgkmcnt(0)
	v_mfma_f32_32x32x2_f32 v[2:17], v20, v22, v[2:17]
	v_mfma_f32_32x32x2_f32 v[2:17], v21, v23, v[2:17]
	ds_read2_b32 v[20:21], v18 offset0:4 offset1:6
	ds_read2st64_b32 v[22:23], v19 offset0:8 offset1:12
	s_waitcnt lgkmcnt(0)
	v_mfma_f32_32x32x2_f32 v[2:17], v20, v22, v[2:17]
	v_mfma_f32_32x32x2_f32 v[2:17], v21, v23, v[2:17]
	ds_read2_b32 v[20:21], v18 offset0:8 offset1:10
	ds_read2st64_b32 v[22:23], v19 offset0:16 offset1:20
	s_waitcnt lgkmcnt(0)
	v_mfma_f32_32x32x2_f32 v[2:17], v20, v22, v[2:17]
	v_mfma_f32_32x32x2_f32 v[2:17], v21, v23, v[2:17]
	ds_read2_b32 v[20:21], v18 offset0:12 offset1:14
	ds_read2st64_b32 v[22:23], v19 offset0:24 offset1:28
	v_add_u32_e32 v19, 0x2000, v19
	v_add_u32_e32 v18, 64, v18
	s_waitcnt lgkmcnt(0)
	v_mfma_f32_32x32x2_f32 v[2:17], v20, v22, v[2:17]
	v_mfma_f32_32x32x2_f32 v[2:17], v21, v23, v[2:17]
	s_cbranch_scc0 .LBB0_2965
	v_add_u32_e32 v18, 0xc200, v103
	s_barrier
	s_nop 14
	ds_write2_b32 v18, v2, v3 offset0:64 offset1:196
	v_add_u32_e32 v2, 0xc600, v103
	ds_write2_b32 v2, v4, v5 offset0:72 offset1:204
	v_add_u32_e32 v2, 0xd200, v103
	ds_write2_b32 v2, v6, v7 offset0:96 offset1:228
	v_add_u32_e32 v2, 0xd600, v103
	ds_write2_b32 v2, v8, v9 offset0:104 offset1:236
	v_add_u32_e32 v2, 0xe400, v103
	ds_write2_b32 v2, v10, v11 offset1:132
	v_add_u32_e32 v2, 0xe800, v103
	ds_write2_b32 v2, v12, v13 offset0:8 offset1:140
	v_add_u32_e32 v2, 0xf400, v103
	ds_write2_b32 v2, v14, v15 offset0:32 offset1:164
	v_add_u32_e32 v2, 0xf800, v103
	v_mov_b64_e32 v[18:19], s[0:1]
	ds_write2_b32 v2, v16, v17 offset0:40 offset1:172
	s_waitcnt lgkmcnt(0)
	s_barrier
	ds_read_b128 v[14:17], v95 offset:49920
	ds_read_b128 v[10:13], v95 offset:49936
	ds_read_b128 v[6:9], v95 offset:49952
	ds_read_b128 v[2:5], v95 offset:49968
	s_load_dwordx2 s[98:99], s[0:1], 0xa8
	s_waitcnt vmcnt(0) lgkmcnt(0)
	v_mov_b32_e32 v22, s98
	v_mov_b32_e32 v23, s99
	v_mov_b32_e32 v1, v229
	v_add_u32_e32 v60, s36, v94
	v_mov_b64_e32 v[18:19], s[12:13]
	v_and_b32_e32 v21, 64, v166
	s_lshl_b32 s70, s35, 2
	v_mad_i64_i32 v[18:19], s[8:9], v60, s29, v[18:19]
	v_xor_b32_e32 v20, 1, v166
	v_lshlrev_b32_e32 v42, 2, v54
	v_add_u32_e32 v59, 64, v21
	v_lshl_add_u64 v[18:19], v[18:19], 0, s[70:71]
	v_cmp_lt_i32_e32 vcc, v20, v59
	v_lshl_add_u64 v[30:31], v[18:19], 0, v[42:43]
	s_waitcnt lgkmcnt(0)
	v_mov_b32_e32 v26, v15
	v_cndmask_b32_e32 v20, v166, v20, vcc
	v_add_co_u32_e32 v18, vcc, s4, v30
	v_lshlrev_b32_e32 v61, 2, v20
	s_nop 0
	v_addc_co_u32_e32 v19, vcc, 0, v31, vcc
	global_load_dwordx4 v[18:21], v[18:19], off offset:1184
	v_mov_b32_e32 v27, v11
	v_mov_b32_e32 v24, v14
	v_mov_b32_e32 v25, v10
	v_mov_b32_e32 v36, v7
	v_mov_b32_e32 v37, v3
	v_pk_mul_f32 v[26:27], v[26:27], v[26:27]
	v_mov_b32_e32 v28, v16
	v_mov_b32_e32 v29, v12
	v_mov_b32_e32 v34, v6
	v_mov_b32_e32 v35, v2
	v_pk_mul_f32 v[36:37], v[36:37], v[36:37]
	v_pk_fma_f32 v[24:25], v[24:25], v[24:25], v[26:27]
	v_mov_b32_e32 v32, v17
	v_mov_b32_e32 v33, v13
	v_mov_b32_e32 v38, v8
	v_mov_b32_e32 v39, v4
	v_pk_fma_f32 v[26:27], v[34:35], v[34:35], v[36:37]
	v_pk_fma_f32 v[24:25], v[28:29], v[28:29], v[24:25]
	v_mov_b32_e32 v40, v9
	v_mov_b32_e32 v41, v5
	v_pk_fma_f32 v[26:27], v[38:39], v[38:39], v[26:27]
	v_pk_fma_f32 v[24:25], v[32:33], v[32:33], v[24:25]
	v_pk_fma_f32 v[26:27], v[40:41], v[40:41], v[26:27]
	v_add_f32_e32 v24, v24, v25
	v_add_f32_e32 v24, v24, v26
	v_add_f32_e32 v24, v24, v27
	v_xor_b32_e32 v26, 2, v166
	v_cmp_lt_i32_e32 vcc, v26, v59
	v_lshl_add_u64 v[62:63], v[30:31], 0, s[72:73]
	v_mov_b32_e32 v38, v14
	v_cndmask_b32_e32 v26, v166, v26, vcc
	v_lshlrev_b32_e32 v26, 2, v26
	s_waitcnt lgkmcnt(0)
	s_nop 1
	v_add_f32_dpp v24, v24, v24 quad_perm:[1,0,3,2] row_mask:0xf bank_mask:0xf
	v_ashrrev_i32_e32 v61, 31, v60
	s_lshl_b32 s70, s35, 1
	s_mov_b64 s[76:77], 0
	s_waitcnt lgkmcnt(0)
	s_nop 1
	v_add_f32_dpp v32, v24, v24 quad_perm:[2,3,0,1] row_mask:0xf bank_mask:0xf
	v_lshl_add_u64 v[64:65], v[22:23], 0, v[42:43]
	global_load_dwordx4 v[26:29], v[64:65], off
	v_xor_b32_e32 v22, 4, v166
	v_cmp_lt_i32_e32 vcc, v22, v59
	s_nop 1
	v_cndmask_b32_e32 v22, v166, v22, vcc
	v_lshlrev_b32_e32 v22, 2, v22
	global_load_dwordx4 v[22:25], v[64:65], off offset:16
	s_waitcnt lgkmcnt(0)
	s_nop 1
	v_add_f32_dpp v30, v32, v32 row_half_mirror row_mask:0xf bank_mask:0xf
	v_fmamk_f32 v30, v30, 0x3c000000, v104
	v_mul_f32_e32 v31, 0x4f800000, v30
	v_cmp_gt_f32_e32 vcc, s31, v30
	s_nop 1
	v_cndmask_b32_e32 v39, v30, v31, vcc
	v_sqrt_f32_e32 v40, v39
	global_load_dwordx4 v[30:33], v[62:63], off offset:16
	global_load_dwordx4 v[34:37], v[62:63], off offset:48
	v_add_u32_e32 v14, -1, v40
	v_add_u32_e32 v41, 1, v40
	v_fma_f32 v42, -v14, v40, v39
	v_fma_f32 v59, -v41, v40, v39
	v_cmp_ge_f32_e64 s[8:9], 0, v42
	s_nop 1
	v_cndmask_b32_e64 v14, v40, v14, s[8:9]
	v_cmp_lt_f32_e64 s[8:9], 0, v59
	s_nop 1
	v_cndmask_b32_e64 v14, v14, v41, s[8:9]
	v_mul_f32_e32 v40, 0x37800000, v14
	v_cndmask_b32_e32 v14, v14, v40, vcc
	v_cmp_class_f32_e32 vcc, v39, v105
	s_nop 1
	v_cndmask_b32_e32 v14, v14, v39, vcc
	v_div_scale_f32 v40, s[8:9], v14, v14, 1.0
	v_rcp_f32_e32 v41, v40
	v_mov_b32_e32 v39, v16
	v_div_scale_f32 v16, vcc, 1.0, v14, 1.0
	v_fma_f32 v42, -v40, v41, 1.0
	v_fmac_f32_e32 v41, v42, v41
	v_mul_f32_e32 v42, v16, v41
	v_fma_f32 v59, -v40, v42, v16
	v_fmac_f32_e32 v42, v59, v41
	v_fma_f32 v16, -v40, v42, v16
	v_div_fmas_f32 v16, v16, v41, v42
	v_div_fixup_f32 v14, v16, v14, 1.0
	v_pk_mul_f32 v[110:111], v[38:39], v[14:15] op_sel_hi:[1,0]
	s_waitcnt vmcnt(0)
	v_mul_f32_e32 v16, 0xbfb8aa3b, v18
	v_mul_f32_e32 v38, 0xbfb8aa3b, v20
	v_exp_f32_e32 v112, v16
	v_exp_f32_e32 v113, v38
	v_mul_f32_e32 v16, 0xbfb8aa3b, v19
	global_load_dwordx4 v[38:41], v[64:65], off offset:48
	global_load_dwordx4 v[106:109], v[64:65], off offset:32
	v_exp_f32_e32 v64, v16
	v_pk_add_f32 v[112:113], v[112:113], 1.0 op_sel_hi:[1,0]
	s_nop 0
	v_div_scale_f32 v16, s[8:9], v113, v113, v20
	v_rcp_f32_e32 v65, v16
	v_div_scale_f32 v59, s[8:9], v112, v112, v18
	v_rcp_f32_e32 v116, v59
	v_fma_f32 v114, -v16, v65, 1.0
	v_div_scale_f32 v42, vcc, v20, v113, v20
	v_fmac_f32_e32 v65, v114, v65
	v_fma_f32 v115, -v59, v116, 1.0
	v_mul_f32_e32 v114, v42, v65
	v_fmac_f32_e32 v116, v115, v116
	v_fma_f32 v115, -v16, v114, v42
	v_fmac_f32_e32 v114, v115, v65
	v_fma_f32 v16, -v16, v114, v42
	v_div_fmas_f32 v16, v16, v65, v114
	v_div_scale_f32 v117, s[8:9], v18, v112, v18
	v_div_fixup_f32 v113, v16, v113, v20
	v_mul_f32_e32 v20, 0xbfb8aa3b, v21
	v_mul_f32_e32 v118, v117, v116
	v_exp_f32_e32 v65, v20
	v_fma_f32 v119, -v59, v118, v117
	v_fmac_f32_e32 v118, v119, v116
	v_fma_f32 v16, -v59, v118, v117
	s_mov_b64 vcc, s[8:9]
	v_div_fmas_f32 v16, v16, v116, v118
	v_pk_add_f32 v[64:65], v[64:65], 1.0 op_sel_hi:[1,0]
	v_div_fixup_f32 v112, v16, v112, v18
	v_mov_b32_e32 v16, v15
	v_div_scale_f32 v15, s[8:9], v65, v65, v21
	v_rcp_f32_e32 v18, v15
	v_mov_b32_e32 v114, v26
	v_mov_b32_e32 v115, v28
	v_mov_b32_e32 v28, v27
	v_fma_f32 v20, -v15, v18, 1.0
	v_fmac_f32_e32 v18, v20, v18
	v_div_scale_f32 v20, vcc, v21, v65, v21
	v_mul_f32_e32 v26, v20, v18
	v_fma_f32 v27, -v15, v26, v20
	v_fmac_f32_e32 v26, v27, v18
	v_pk_mul_f32 v[16:17], v[16:17], v[14:15] op_sel_hi:[1,0]
	v_fma_f32 v15, -v15, v26, v20
	v_div_scale_f32 v20, s[8:9], v64, v64, v19
	v_rcp_f32_e32 v27, v20
	v_div_fmas_f32 v15, v15, v18, v26
	v_div_fixup_f32 v21, v15, v65, v21
	v_pk_mul_f32 v[16:17], v[28:29], v[16:17]
	v_fma_f32 v15, -v20, v27, 1.0
	v_fmac_f32_e32 v27, v15, v27
	v_div_scale_f32 v15, vcc, v19, v64, v19
	v_mul_f32_e32 v18, v15, v27
	v_fma_f32 v26, -v20, v18, v15
	v_fmac_f32_e32 v18, v26, v27
	v_fma_f32 v15, -v20, v18, v15
	v_div_fmas_f32 v15, v15, v27, v18
	v_div_fixup_f32 v20, v15, v64, v19
	v_pk_mul_f32 v[20:21], v[20:21], v[16:17]
	global_load_dwordx4 v[16:19], v[62:63], off offset:32
	s_waitcnt lgkmcnt(0)
	v_mul_f32_e32 v15, 0xbfb8aa3b, v30
	v_exp_f32_e32 v26, v15
	v_mul_f32_e32 v15, 0xbfb8aa3b, v31
	v_exp_f32_e32 v28, v15
	v_mul_f32_e32 v15, 0xbfb8aa3b, v32
	v_exp_f32_e32 v27, v15
	v_mov_b32_e32 v62, v10
	v_mov_b32_e32 v63, v12
	v_pk_mul_f32 v[62:63], v[62:63], v[14:15] op_sel_hi:[1,0]
	v_pk_add_f32 v[26:27], v[26:27], 1.0 op_sel_hi:[1,0]
	v_mov_b32_e32 v64, v22
	v_div_scale_f32 v10, s[8:9], v27, v27, v32
	v_rcp_f32_e32 v12, v10
	v_mov_b32_e32 v65, v24
	v_pk_mul_f32 v[110:111], v[114:115], v[110:111]
	v_pk_mul_f32 v[62:63], v[62:63], v[64:65]
	v_fma_f32 v15, -v10, v12, 1.0
	v_fmac_f32_e32 v12, v15, v12
	v_div_scale_f32 v15, vcc, v32, v27, v32
	v_mul_f32_e32 v22, v15, v12
	v_fma_f32 v24, -v10, v22, v15
	v_fmac_f32_e32 v22, v24, v12
	v_fma_f32 v10, -v10, v22, v15
	v_div_scale_f32 v15, s[8:9], v26, v26, v30
	v_rcp_f32_e32 v24, v15
	v_div_fmas_f32 v10, v10, v12, v22
	v_div_fixup_f32 v27, v10, v27, v32
	v_pk_mul_f32 v[110:111], v[112:113], v[110:111]
	v_fma_f32 v10, -v15, v24, 1.0
	v_fmac_f32_e32 v24, v10, v24
	v_div_scale_f32 v10, vcc, v30, v26, v30
	v_mul_f32_e32 v12, v10, v24
	v_fma_f32 v22, -v15, v12, v10
	v_fmac_f32_e32 v12, v22, v24
	v_fma_f32 v10, -v15, v12, v10
	v_div_fmas_f32 v10, v10, v24, v12
	v_mul_f32_e32 v12, 0xbfb8aa3b, v33
	v_exp_f32_e32 v29, v12
	v_div_fixup_f32 v26, v10, v26, v30
	v_mov_b32_e32 v12, v11
	v_mov_b32_e32 v24, v23
	v_pk_add_f32 v[10:11], v[28:29], 1.0 op_sel_hi:[1,0]
	v_pk_mul_f32 v[26:27], v[62:63], v[26:27]
	v_div_scale_f32 v15, s[8:9], v11, v11, v33
	v_rcp_f32_e32 v22, v15
	v_pk_mul_f32 v[12:13], v[12:13], v[14:15] op_sel_hi:[1,0]
	v_lshlrev_b32_e32 v42, 1, v54
	v_pk_mul_f32 v[12:13], v[12:13], v[24:25]
	v_fma_f32 v23, -v15, v22, 1.0
	v_fmac_f32_e32 v22, v23, v22
	v_div_scale_f32 v23, vcc, v33, v11, v33
	v_mul_f32_e32 v24, v23, v22
	v_fma_f32 v25, -v15, v24, v23
	v_fmac_f32_e32 v24, v25, v22
	v_fma_f32 v15, -v15, v24, v23
	v_div_scale_f32 v23, s[8:9], v10, v10, v31
	v_rcp_f32_e32 v25, v23
	v_div_fmas_f32 v15, v15, v22, v24
	v_div_fixup_f32 v11, v15, v11, v33
	v_fma_f32 v15, -v23, v25, 1.0
	v_fmac_f32_e32 v25, v15, v25
	v_div_scale_f32 v15, vcc, v31, v10, v31
	v_mul_f32_e32 v22, v15, v25
	v_fma_f32 v24, -v23, v22, v15
	v_fmac_f32_e32 v22, v24, v25
	v_fma_f32 v15, -v23, v22, v15
	v_div_fmas_f32 v15, v15, v25, v22
	v_div_fixup_f32 v10, v15, v10, v31
	v_pk_mul_f32 v[10:11], v[12:13], v[10:11]
	v_cvt_pk_bf16_f32 v13, v27, v11
	v_cvt_pk_bf16_f32 v11, v111, v21
	s_waitcnt vmcnt(0)
	v_mul_f32_e32 v15, 0xbfb8aa3b, v16
	v_cvt_pk_bf16_f32 v12, v26, v10
	v_cvt_pk_bf16_f32 v10, v110, v20
	v_exp_f32_e32 v20, v15
	v_mul_f32_e32 v15, 0xbfb8aa3b, v17
	v_exp_f32_e32 v22, v15
	v_mul_f32_e32 v15, 0xbfb8aa3b, v18
	v_exp_f32_e32 v21, v15
	v_mov_b32_e32 v24, v6
	v_mov_b32_e32 v25, v8
	v_pk_mul_f32 v[24:25], v[24:25], v[14:15] op_sel_hi:[1,0]
	v_pk_add_f32 v[20:21], v[20:21], 1.0 op_sel_hi:[1,0]
	v_mov_b32_e32 v26, v106
	v_div_scale_f32 v6, s[8:9], v21, v21, v18
	v_rcp_f32_e32 v8, v6
	v_mov_b32_e32 v27, v108
	v_pk_mul_f32 v[24:25], v[24:25], v[26:27]
	v_mov_b32_e32 v108, v107
	v_fma_f32 v15, -v6, v8, 1.0
	v_fmac_f32_e32 v8, v15, v8
	v_div_scale_f32 v15, vcc, v18, v21, v18
	v_mul_f32_e32 v23, v15, v8
	v_fma_f32 v26, -v6, v23, v15
	v_fmac_f32_e32 v23, v26, v8
	v_fma_f32 v6, -v6, v23, v15
	v_div_scale_f32 v15, s[8:9], v20, v20, v16
	v_rcp_f32_e32 v26, v15
	v_div_fmas_f32 v6, v6, v8, v23
	v_div_fixup_f32 v21, v6, v21, v18
	v_fma_f32 v6, -v15, v26, 1.0
	v_fmac_f32_e32 v26, v6, v26
	v_div_scale_f32 v6, vcc, v16, v20, v16
	v_mul_f32_e32 v8, v6, v26
	v_fma_f32 v18, -v15, v8, v6
	v_fmac_f32_e32 v8, v18, v26
	v_fma_f32 v6, -v15, v8, v6
	v_div_fmas_f32 v6, v6, v26, v8
	v_mul_f32_e32 v8, 0xbfb8aa3b, v19
	v_exp_f32_e32 v23, v8
	v_div_fixup_f32 v20, v6, v20, v16
	v_mov_b32_e32 v8, v7
	v_pk_mul_f32 v[20:21], v[24:25], v[20:21]
	v_pk_add_f32 v[6:7], v[22:23], 1.0 op_sel_hi:[1,0]
	s_nop 0
	v_div_scale_f32 v15, s[8:9], v7, v7, v19
	v_rcp_f32_e32 v16, v15
	v_pk_mul_f32 v[8:9], v[8:9], v[14:15] op_sel_hi:[1,0]
	v_fma_f32 v18, -v15, v16, 1.0
	v_fmac_f32_e32 v16, v18, v16
	v_div_scale_f32 v18, vcc, v19, v7, v19
	v_mul_f32_e32 v22, v18, v16
	v_fma_f32 v23, -v15, v22, v18
	v_fmac_f32_e32 v22, v23, v16
	v_fma_f32 v15, -v15, v22, v18
	v_div_scale_f32 v18, s[8:9], v6, v6, v17
	v_rcp_f32_e32 v23, v18
	v_div_fmas_f32 v15, v15, v16, v22
	v_div_fixup_f32 v7, v15, v7, v19
	v_pk_mul_f32 v[8:9], v[8:9], v[108:109]
	v_fma_f32 v15, -v18, v23, 1.0
	v_fmac_f32_e32 v23, v15, v23
	v_div_scale_f32 v15, vcc, v17, v6, v17
	v_mul_f32_e32 v16, v15, v23
	v_fma_f32 v19, -v18, v16, v15
	v_fmac_f32_e32 v16, v19, v23
	v_fma_f32 v15, -v18, v16, v15
	v_div_fmas_f32 v15, v15, v23, v16
	v_div_fixup_f32 v6, v15, v6, v17
	v_pk_mul_f32 v[6:7], v[8:9], v[6:7]
	v_mul_f32_e32 v9, 0xbfb8aa3b, v35
	v_mul_f32_e32 v8, 0xbfb8aa3b, v34
	v_exp_f32_e32 v16, v9
	v_mul_f32_e32 v9, 0xbfb8aa3b, v36
	v_exp_f32_e32 v8, v8
	v_exp_f32_e32 v9, v9
	v_mov_b32_e32 v18, v2
	v_mov_b32_e32 v19, v4
	v_pk_mul_f32 v[18:19], v[18:19], v[14:15] op_sel_hi:[1,0]
	v_pk_add_f32 v[8:9], v[8:9], 1.0 op_sel_hi:[1,0]
	v_mov_b32_e32 v22, v38
	v_div_scale_f32 v2, s[8:9], v9, v9, v36
	v_rcp_f32_e32 v4, v2
	v_mov_b32_e32 v23, v40
	v_pk_mul_f32 v[18:19], v[18:19], v[22:23]
	v_mov_b32_e32 v40, v39
	v_fma_f32 v15, -v2, v4, 1.0
	v_fmac_f32_e32 v4, v15, v4
	v_div_scale_f32 v15, vcc, v36, v9, v36
	v_mul_f32_e32 v17, v15, v4
	v_fma_f32 v22, -v2, v17, v15
	v_fmac_f32_e32 v17, v22, v4
	v_fma_f32 v2, -v2, v17, v15
	v_div_scale_f32 v15, s[8:9], v8, v8, v34
	v_rcp_f32_e32 v22, v15
	v_div_fmas_f32 v2, v2, v4, v17
	v_div_fixup_f32 v9, v2, v9, v36
	v_fma_f32 v2, -v15, v22, 1.0
	v_fmac_f32_e32 v22, v2, v22
	v_div_scale_f32 v2, vcc, v34, v8, v34
	v_mul_f32_e32 v4, v2, v22
	v_fma_f32 v17, -v15, v4, v2
	v_fmac_f32_e32 v4, v17, v22
	v_fma_f32 v2, -v15, v4, v2
	v_div_fmas_f32 v2, v2, v22, v4
	v_mul_f32_e32 v4, 0xbfb8aa3b, v37
	v_exp_f32_e32 v17, v4
	v_div_fixup_f32 v8, v2, v8, v34
	v_mov_b32_e32 v4, v3
	v_pk_mul_f32 v[8:9], v[18:19], v[8:9]
	v_pk_add_f32 v[2:3], v[16:17], 1.0 op_sel_hi:[1,0]
	s_nop 0
	v_div_scale_f32 v15, s[8:9], v3, v3, v37
	v_rcp_f32_e32 v16, v15
	v_pk_mul_f32 v[4:5], v[4:5], v[14:15] op_sel_hi:[1,0]
	v_fma_f32 v14, -v15, v16, 1.0
	v_fmac_f32_e32 v16, v14, v16
	v_div_scale_f32 v14, vcc, v37, v3, v37
	v_mul_f32_e32 v17, v14, v16
	v_fma_f32 v18, -v15, v17, v14
	v_fmac_f32_e32 v17, v18, v16
	v_fma_f32 v14, -v15, v17, v14
	v_div_scale_f32 v15, s[8:9], v2, v2, v35
	v_rcp_f32_e32 v18, v15
	v_div_fmas_f32 v14, v14, v16, v17
	v_div_fixup_f32 v3, v14, v3, v37
	v_pk_mul_f32 v[4:5], v[4:5], v[40:41]
	v_fma_f32 v14, -v15, v18, 1.0
	v_fmac_f32_e32 v18, v14, v18
	v_div_scale_f32 v14, vcc, v35, v2, v35
	v_mul_f32_e32 v16, v14, v18
	v_fma_f32 v17, -v15, v16, v14
	v_fmac_f32_e32 v16, v17, v18
	v_fma_f32 v14, -v15, v16, v14
	v_div_fmas_f32 v14, v14, v18, v16
	v_div_fixup_f32 v2, v14, v2, v35
	v_pk_mul_f32 v[2:3], v[4:5], v[2:3]
	v_bfe_u32 v5, v2, 16, 1
	v_add3_u32 v2, v2, v5, s33
	v_bfe_u32 v14, v8, 16, 1
	v_add3_u32 v8, v8, v14, s33
	v_lshrrev_b32_e32 v4, 16, v8
	v_cvt_pk_bf16_f32 v5, v9, v3
	v_and_or_b32 v4, v2, s34, v4
	v_cvt_pk_bf16_f32 v3, v21, v7
	v_cvt_pk_bf16_f32 v2, v20, v6
	v_lshlrev_b64 v[6:7], 11, v[60:61]
	v_lshl_add_u64 v[6:7], s[68:69], 0, v[6:7]
	v_lshl_add_u64 v[6:7], v[6:7], 0, s[70:71]
	v_lshl_add_u64 v[6:7], v[6:7], 0, v[42:43]
	v_lshl_add_u64 v[8:9], v[6:7], 0, s[74:75]
	v_add_co_u32_e32 v6, vcc, 0xdc00000, v6
	s_nop 1
	v_addc_co_u32_e32 v7, vcc, 0, v7, vcc
	global_store_dwordx4 v[6:7], v[10:13], off offset:1024
	global_store_dwordx4 v[8:9], v[2:5], off offset:16
	s_branch .LBB0_2949

.LBB0_3086:
	v_lshl_add_u64 v[18:19], s[68:69], 0, v[94:95]
	v_lshl_add_u64 v[22:23], s[68:69], 0, v[92:93]
	v_add_co_u32_e32 v20, vcc, 0x7800000, v18
	v_add_co_u32_e64 v102, s[6:7], s22, v22
	s_nop 0
	v_addc_co_u32_e32 v21, vcc, 0, v19, vcc
	v_addc_co_u32_e64 v103, s[6:7], 0, v23, s[6:7]
	v_add_co_u32_e64 v104, s[6:7], s23, v22
	v_add_co_u32_e32 v22, vcc, 0x7801000, v18
	s_nop 0
	v_addc_co_u32_e64 v105, s[6:7], 0, v23, s[6:7]
	global_load_dwordx4 v[78:81], v[20:21], off
	global_load_dwordx4 v[74:77], v[20:21], off offset:1024
	global_load_dwordx4 v[70:73], v[20:21], off offset:2048
	global_load_dwordx4 v[66:69], v[20:21], off offset:3072
	v_addc_co_u32_e32 v23, vcc, 0, v19, vcc
	v_add_co_u32_e32 v20, vcc, 0x7802000, v18
	global_load_dwordx4 v[62:65], v[22:23], off
	global_load_dwordx4 v[58:61], v[22:23], off offset:1024
	global_load_dwordx4 v[54:57], v[22:23], off offset:2048
	global_load_dwordx4 v[50:53], v[22:23], off offset:3072
	v_addc_co_u32_e32 v21, vcc, 0, v19, vcc
	v_add_co_u32_e32 v82, vcc, 0x7803000, v18
	global_load_dwordx4 v[46:49], v[20:21], off
	global_load_dwordx4 v[42:45], v[20:21], off offset:1024
	global_load_dwordx4 v[38:41], v[20:21], off offset:2048
	global_load_dwordx4 v[34:37], v[20:21], off offset:3072
	v_addc_co_u32_e32 v83, vcc, 0, v19, vcc
	global_load_dwordx4 v[30:33], v[82:83], off
	global_load_dwordx4 v[26:29], v[82:83], off offset:1024
	global_load_dwordx4 v[22:25], v[82:83], off offset:2048
	global_load_dwordx4 v[18:21], v[82:83], off offset:3072
	s_add_i32 s24, s8, 32
	s_add_i32 s10, s8, 0xffffc022
	s_ashr_i32 s9, s24, 13
	s_cmpk_lt_i32 s24, 0x4000
	s_cselect_b32 s6, s9, s10
	s_mul_hi_i32 s7, s6, 0x9000
	s_mul_i32 s6, s6, 0x9000
	s_add_u32 s10, s4, s6
	s_addc_u32 s11, s5, s7
	s_add_u32 s6, s10, 0x6000
	s_addc_u32 s7, s11, 0
	s_add_u32 s10, s10, 0x7000
	s_addc_u32 s11, s11, 0
	v_lshl_add_u64 v[82:83], s[6:7], 0, v[90:91]
	v_lshl_add_u64 v[86:87], s[10:11], 0, v[90:91]
	global_load_dwordx4 v[82:85], v[82:83], off
	v_lshl_add_u64 v[148:149], s[6:7], 0, v[96:97]
	global_load_dwordx4 v[86:89], v[86:87], off
	v_lshl_add_u64 v[142:143], s[6:7], 0, v[98:99]
	v_lshl_add_u64 v[134:135], s[6:7], 0, v[100:101]
	s_add_i32 s6, s8, 0xffffc023
	s_cmpk_lt_i32 s24, 0x3fff
	s_cselect_b32 s6, s9, s6
	s_mul_hi_i32 s7, s6, 0x9000
	s_mul_i32 s6, s6, 0x9000
	v_lshl_add_u64 v[152:153], s[10:11], 0, v[96:97]
	v_lshl_add_u64 v[146:147], s[10:11], 0, v[98:99]
	v_lshl_add_u64 v[140:141], s[10:11], 0, v[100:101]
	s_add_u32 s10, s4, s6
	s_addc_u32 s11, s5, s7
	s_add_u32 s6, s10, 0x6000
	s_addc_u32 s7, s11, 0
	s_add_u32 s10, s10, 0x7000
	v_lshl_add_u64 v[132:133], s[6:7], 0, v[90:91]
	v_lshl_add_u64 v[126:127], s[6:7], 0, v[96:97]
	v_lshl_add_u64 v[118:119], s[6:7], 0, v[98:99]
	v_lshl_add_u64 v[114:115], s[6:7], 0, v[100:101]
	s_addc_u32 s11, s11, 0
	s_add_i32 s6, s8, 0xffffc024
	s_cmpk_lt_i32 s24, 0x3ffe
	s_cselect_b32 s6, s9, s6
	s_mul_hi_i32 s7, s6, 0x9000
	s_mul_i32 s6, s6, 0x9000
	s_add_u32 s6, s4, s6
	s_addc_u32 s7, s5, s7
	v_lshl_add_u64 v[138:139], s[10:11], 0, v[90:91]
	v_lshl_add_u64 v[130:131], s[10:11], 0, v[96:97]
	v_lshl_add_u64 v[124:125], s[10:11], 0, v[98:99]
	v_lshl_add_u64 v[116:117], s[10:11], 0, v[100:101]
	s_add_u32 s10, s6, 0x6000
	s_addc_u32 s11, s7, 0
	s_add_u32 s6, s6, 0x7000
	s_addc_u32 s7, s7, 0
	s_addk_i32 s8, 0xc025
	s_cmpk_lt_i32 s24, 0x3ffd
	v_lshl_add_u64 v[156:157], s[6:7], 0, v[90:91]
	v_lshl_add_u64 v[154:155], s[6:7], 0, v[96:97]
	v_lshl_add_u64 v[150:151], s[6:7], 0, v[98:99]
	v_lshl_add_u64 v[136:137], s[6:7], 0, v[100:101]
	s_cselect_b32 s6, s9, s8
	s_mul_hi_i32 s7, s6, 0x9000
	s_mul_i32 s6, s6, 0x9000
	s_add_u32 s6, s4, s6
	s_waitcnt vmcnt(0) lgkmcnt(0)
	v_pk_mul_f32 v[158:159], v[80:81], v[80:81]
	v_pk_mul_f32 v[160:161], v[78:79], v[78:79]
	v_pk_mul_f32 v[162:163], v[76:77], v[76:77]
	v_pk_mul_f32 v[164:165], v[74:75], v[74:75]
	v_mul_f32_e32 v174, v71, v71
	v_mul_f32_e32 v176, v73, v73
	v_mul_f32_e32 v187, v68, v68
	v_mul_f32_e32 v189, v69, v69
	v_pk_mov_b32 v[178:179], v[160:161], v[158:159] op_sel:[1,0]
	v_mov_b32_e32 v161, v159
	v_pk_mov_b32 v[158:159], v[164:165], v[162:163] op_sel:[1,0]
	v_mov_b32_e32 v165, v163
	v_pk_fma_f32 v[162:163], v[70:71], v[70:71], v[174:175] op_sel_hi:[1,1,0]
	v_pk_fma_f32 v[174:175], v[72:73], v[72:73], v[176:177] op_sel_hi:[1,1,0]
	v_pk_mul_f32 v[176:177], v[64:65], v[64:65]
	v_pk_mul_f32 v[180:181], v[62:63], v[62:63]
	v_pk_mul_f32 v[182:183], v[60:61], v[60:61]
	v_pk_mul_f32 v[184:185], v[58:59], v[58:59]
	v_mul_f32_e32 v186, v55, v55
	v_mul_f32_e32 v188, v57, v57
	v_pk_add_f32 v[160:161], v[178:179], v[160:161]
	v_pk_add_f32 v[158:159], v[158:159], v[164:165]
	v_mov_b32_e32 v163, v187
	v_mov_b32_e32 v175, v189
	v_pk_mov_b32 v[164:165], v[180:181], v[176:177] op_sel:[1,0]
	v_mov_b32_e32 v181, v177
	v_pk_mov_b32 v[176:177], v[184:185], v[182:183] op_sel:[1,0]
	v_mov_b32_e32 v185, v183
	v_pk_fma_f32 v[178:179], v[54:55], v[54:55], v[186:187] op_sel_hi:[1,1,0]
	v_pk_fma_f32 v[182:183], v[56:57], v[56:57], v[188:189] op_sel_hi:[1,1,0]
	v_pk_mul_f32 v[186:187], v[48:49], v[48:49]
	v_pk_mul_f32 v[188:189], v[46:47], v[46:47]
	v_pk_mul_f32 v[190:191], v[44:45], v[44:45]
	v_pk_mul_f32 v[192:193], v[42:43], v[42:43]
	v_mul_f32_e32 v173, v66, v66
	v_mul_f32_e32 v197, v67, v67
	v_mul_f32_e32 v195, v52, v52
	v_mul_f32_e32 v202, v53, v53
	v_mul_f32_e32 v194, v39, v39
	v_mul_f32_e32 v196, v41, v41
	v_pk_add_f32 v[198:199], v[160:161], v[160:161] op_sel:[0,1] op_sel_hi:[1,0]
	v_pk_add_f32 v[200:201], v[158:159], v[158:159] op_sel:[0,1] op_sel_hi:[1,0]
	v_pk_add_f32 v[174:175], v[162:163], v[174:175]
	v_pk_add_f32 v[158:159], v[164:165], v[180:181]
	v_pk_add_f32 v[160:161], v[176:177], v[184:185]
	v_pk_mov_b32 v[162:163], v[188:189], v[186:187] op_sel:[1,0]
	v_mov_b32_e32 v189, v187
	v_pk_mov_b32 v[164:165], v[192:193], v[190:191] op_sel:[1,0]
	v_mov_b32_e32 v193, v191
	v_mul_f32_e32 v203, v50, v50
	v_mul_f32_e32 v208, v51, v51
	v_mul_f32_e32 v211, v36, v36
	v_mul_f32_e32 v212, v37, v37
	v_mov_b32_e32 v179, v195
	v_mov_b32_e32 v183, v202
	v_pk_fma_f32 v[176:177], v[38:39], v[38:39], v[194:195] op_sel_hi:[1,1,0]
	v_pk_fma_f32 v[180:181], v[40:41], v[40:41], v[196:197] op_sel_hi:[1,1,0]
	v_pk_mul_f32 v[184:185], v[32:33], v[32:33]
	v_pk_mul_f32 v[186:187], v[30:31], v[30:31]
	v_pk_mul_f32 v[190:191], v[28:29], v[28:29]
	v_pk_mul_f32 v[194:195], v[26:27], v[26:27]
	v_mov_b32_e32 v199, v173
	v_mov_b32_e32 v201, v197
	v_pk_add_f32 v[204:205], v[158:159], v[158:159] op_sel:[0,1] op_sel_hi:[1,0]
	v_pk_add_f32 v[206:207], v[160:161], v[160:161] op_sel:[0,1] op_sel_hi:[1,0]
	v_pk_add_f32 v[162:163], v[162:163], v[188:189]
	v_pk_add_f32 v[164:165], v[164:165], v[192:193]
	v_mul_f32_e32 v209, v34, v34
	v_mul_f32_e32 v210, v35, v35
	v_pk_add_f32 v[178:179], v[178:179], v[182:183]
	v_mov_b32_e32 v177, v211
	v_mov_b32_e32 v181, v212
	v_pk_mov_b32 v[182:183], v[186:187], v[184:185] op_sel:[1,0]
	v_mov_b32_e32 v187, v185
	v_pk_mov_b32 v[184:185], v[194:195], v[190:191] op_sel:[1,0]
	v_mov_b32_e32 v195, v191
	v_pk_add_f32 v[188:189], v[198:199], v[200:201]
	v_mov_b32_e32 v205, v203
	v_mov_b32_e32 v207, v208
	v_pk_add_f32 v[190:191], v[162:163], v[162:163] op_sel:[0,1] op_sel_hi:[1,0]
	v_pk_add_f32 v[192:193], v[164:165], v[164:165] op_sel:[0,1] op_sel_hi:[1,0]
	v_pk_add_f32 v[176:177], v[176:177], v[180:181]
	v_pk_add_f32 v[174:175], v[188:189], v[174:175]
	v_pk_add_f32 v[180:181], v[204:205], v[206:207]
	v_mov_b32_e32 v191, v209
	v_mov_b32_e32 v193, v210
	v_add_f32_e32 v173, v174, v175
	v_pk_add_f32 v[174:175], v[180:181], v[178:179]
	v_pk_add_f32 v[178:179], v[190:191], v[192:193]
	v_add_f32_e32 v180, v174, v175
	v_pk_add_f32 v[174:175], v[178:179], v[176:177]
	v_add_f32_e32 v174, v174, v175
	s_addc_u32 s7, s5, s7
	s_waitcnt lgkmcnt(0)
	s_nop 1
	v_add_f32_dpp v173, v173, v173 quad_perm:[1,0,3,2] row_mask:0xf bank_mask:0xf
	s_waitcnt lgkmcnt(0)
	s_nop 1
	v_add_f32_dpp v175, v180, v180 quad_perm:[1,0,3,2] row_mask:0xf bank_mask:0xf
	s_waitcnt lgkmcnt(0)
	s_nop 1
	v_add_f32_dpp v174, v174, v174 quad_perm:[1,0,3,2] row_mask:0xf bank_mask:0xf
	s_waitcnt lgkmcnt(0)
	s_nop 1
	v_add_f32_dpp v173, v173, v173 quad_perm:[2,3,0,1] row_mask:0xf bank_mask:0xf
	s_waitcnt lgkmcnt(0)
	s_nop 1
	v_add_f32_dpp v175, v175, v175 quad_perm:[2,3,0,1] row_mask:0xf bank_mask:0xf
	s_waitcnt lgkmcnt(0)
	s_nop 1
	v_add_f32_dpp v174, v174, v174 quad_perm:[2,3,0,1] row_mask:0xf bank_mask:0xf
	s_waitcnt lgkmcnt(0)
	s_nop 1
	v_add_f32_dpp v173, v173, v173 row_half_mirror row_mask:0xf bank_mask:0xf
	s_waitcnt lgkmcnt(0)
	s_nop 1
	v_add_f32_dpp v175, v175, v175 row_half_mirror row_mask:0xf bank_mask:0xf
	s_waitcnt lgkmcnt(0)
	s_nop 1
	v_add_f32_dpp v174, v174, v174 row_half_mirror row_mask:0xf bank_mask:0xf
	s_waitcnt lgkmcnt(0)
	s_nop 1
	v_add_f32_dpp v173, v173, v173 row_mirror row_mask:0xf bank_mask:0xf
	ds_bpermute_b32 v176, v169, v173
	s_waitcnt lgkmcnt(2)
	s_nop 1
	v_add_f32_dpp v175, v175, v175 row_mirror row_mask:0xf bank_mask:0xf
	ds_bpermute_b32 v178, v169, v175
	s_waitcnt lgkmcnt(2)
	s_nop 1
	v_add_f32_dpp v174, v174, v174 row_mirror row_mask:0xf bank_mask:0xf
	ds_bpermute_b32 v177, v169, v174
	s_waitcnt lgkmcnt(2)
	v_add_f32_e32 v173, v173, v176
	ds_bpermute_b32 v176, v170, v173
	s_waitcnt lgkmcnt(2)
	v_add_f32_e32 v175, v175, v178
	ds_bpermute_b32 v178, v170, v175
	s_waitcnt lgkmcnt(2)
	v_add_f32_e32 v174, v174, v177
	ds_bpermute_b32 v177, v170, v174
	s_waitcnt lgkmcnt(2)
	v_add_f32_e32 v173, v173, v176
	s_add_u32 s16, s6, 0x6000
	v_fmamk_f32 v173, v173, 0x3a800000, v171
	s_addc_u32 s17, s7, 0
	s_waitcnt lgkmcnt(1)
	v_add_f32_e32 v175, v175, v178
	v_mul_f32_e32 v176, 0x4f800000, v173
	v_cmp_gt_f32_e32 vcc, s2, v173
	s_add_u32 s18, s6, 0x7000
	v_fmamk_f32 v175, v175, 0x3a800000, v171
	v_cndmask_b32_e32 v173, v173, v176, vcc
	s_addc_u32 s19, s7, 0
	s_waitcnt lgkmcnt(0)
	v_add_f32_e32 v174, v174, v177
	v_mul_f32_e32 v176, 0x4f800000, v175
	v_cmp_gt_f32_e64 s[6:7], s2, v175
	v_sqrt_f32_e32 v177, v173
	v_fmamk_f32 v174, v174, 0x3a800000, v171
	v_cndmask_b32_e64 v175, v175, v176, s[6:7]
	v_mul_f32_e32 v176, 0x4f800000, v174
	v_cmp_gt_f32_e64 s[8:9], s2, v174
	v_sqrt_f32_e32 v178, v175
	v_add_u32_e32 v179, -1, v177
	v_cndmask_b32_e64 v174, v174, v176, s[8:9]
	v_sqrt_f32_e32 v176, v174
	v_add_u32_e32 v180, 1, v177
	v_fma_f32 v181, -v179, v177, v173
	v_lshl_add_u64 v[112:113], s[10:11], 0, v[90:91]
	v_lshl_add_u64 v[106:107], s[10:11], 0, v[96:97]
	v_lshl_add_u64 v[108:109], s[10:11], 0, v[98:99]
	v_lshl_add_u64 v[110:111], s[10:11], 0, v[100:101]
	v_pk_add_f32 v[162:163], v[182:183], v[186:187]
	v_fma_f32 v182, -v180, v177, v173
	v_add_u32_e32 v183, -1, v178
	v_cmp_ge_f32_e64 s[10:11], 0, v181
	v_pk_add_f32 v[164:165], v[184:185], v[194:195]
	v_add_u32_e32 v184, 1, v178
	v_cndmask_b32_e64 v177, v177, v179, s[10:11]
	v_fma_f32 v179, -v183, v178, v175
	v_cmp_lt_f32_e64 s[10:11], 0, v182
	v_fma_f32 v181, -v184, v178, v175
	v_add_u32_e32 v185, -1, v176
	v_cndmask_b32_e64 v177, v177, v180, s[10:11]
	v_cmp_ge_f32_e64 s[10:11], 0, v179
	v_add_u32_e32 v186, 1, v176
	v_fma_f32 v179, -v185, v176, v174
	v_cndmask_b32_e64 v178, v178, v183, s[10:11]
	v_cmp_lt_f32_e64 s[10:11], 0, v181
	v_fma_f32 v180, -v186, v176, v174
	v_mul_f32_e32 v181, 0x37800000, v177
	v_cndmask_b32_e64 v178, v178, v184, s[10:11]
	v_cmp_ge_f32_e64 s[10:11], 0, v179
	v_cndmask_b32_e32 v177, v177, v181, vcc
	v_cmp_class_f32_e32 vcc, v173, v172
	v_cndmask_b32_e64 v176, v176, v185, s[10:11]
	v_cmp_lt_f32_e64 s[10:11], 0, v180
	v_mul_f32_e32 v179, 0x37800000, v178
	v_cndmask_b32_e32 v173, v177, v173, vcc
	v_cndmask_b32_e64 v176, v176, v186, s[10:11]
	v_cndmask_b32_e64 v177, v178, v179, s[6:7]
	v_cmp_class_f32_e32 vcc, v175, v172
	v_mul_f32_e32 v178, 0x37800000, v176
	v_div_scale_f32 v179, s[6:7], v173, v173, 1.0
	v_cndmask_b32_e32 v175, v177, v175, vcc
	v_cndmask_b32_e64 v176, v176, v178, s[8:9]
	v_cmp_class_f32_e32 vcc, v174, v172
	v_rcp_f32_e32 v177, v179
	v_div_scale_f32 v178, s[8:9], v175, v175, 1.0
	v_cndmask_b32_e32 v176, v176, v174, vcc
	v_rcp_f32_e32 v182, v178
	v_div_scale_f32 v183, s[10:11], v176, v176, 1.0
	v_rcp_f32_e32 v185, v183
	v_fma_f32 v174, -v179, v177, 1.0
	v_div_scale_f32 v180, s[6:7], 1.0, v173, 1.0
	v_fmac_f32_e32 v177, v174, v177
	v_fma_f32 v174, -v178, v182, 1.0
	v_mul_f32_e32 v186, v180, v177
	v_div_scale_f32 v181, s[8:9], 1.0, v175, 1.0
	v_fmac_f32_e32 v182, v174, v182
	v_fma_f32 v174, -v183, v185, 1.0
	v_fma_f32 v187, -v179, v186, v180
	v_div_scale_f32 v184, s[10:11], 1.0, v176, 1.0
	v_mul_f32_e32 v188, v181, v182
	v_fmac_f32_e32 v185, v174, v185
	v_fmac_f32_e32 v186, v187, v177
	v_fma_f32 v174, -v178, v188, v181
	v_mul_f32_e32 v187, v184, v185
	v_fma_f32 v179, -v179, v186, v180
	s_mov_b64 vcc, s[6:7]
	v_fmac_f32_e32 v188, v174, v182
	v_fma_f32 v174, -v183, v187, v184
	v_div_fmas_f32 v177, v179, v177, v186
	v_fma_f32 v178, -v178, v188, v181
	v_fmac_f32_e32 v187, v174, v185
	v_div_fixup_f32 v174, v177, v173, 1.0
	s_mov_b64 vcc, s[8:9]
	v_div_fmas_f32 v173, v178, v182, v188
	v_fma_f32 v177, -v183, v187, v184
	v_pk_mul_f32 v[80:81], v[80:81], v[174:175] op_sel_hi:[1,0]
	v_pk_mul_f32 v[78:79], v[78:79], v[174:175] op_sel_hi:[1,0]
	s_mov_b64 vcc, s[10:11]
	v_pk_add_f32 v[88:89], v[88:89], 1.0 op_sel_hi:[1,0]
	v_pk_add_f32 v[86:87], v[86:87], 1.0 op_sel_hi:[1,0]
	v_pk_mul_f32 v[76:77], v[76:77], v[174:175] op_sel_hi:[1,0]
	v_pk_mul_f32 v[74:75], v[74:75], v[174:175] op_sel_hi:[1,0]
	v_pk_mul_f32 v[72:73], v[72:73], v[174:175] op_sel_hi:[1,0]
	v_pk_mul_f32 v[70:71], v[70:71], v[174:175] op_sel_hi:[1,0]
	v_pk_mul_f32 v[68:69], v[68:69], v[174:175] op_sel_hi:[1,0]
	v_pk_mul_f32 v[66:67], v[66:67], v[174:175] op_sel_hi:[1,0]
	v_div_fixup_f32 v174, v173, v175, 1.0
	v_div_fmas_f32 v173, v177, v185, v187
	v_pk_mul_f32 v[78:79], v[2:3], v[78:79]
	v_pk_mul_f32 v[80:81], v[4:5], v[80:81]
	v_pk_mul_f32 v[64:65], v[64:65], v[174:175] op_sel_hi:[1,0]
	v_pk_mul_f32 v[62:63], v[62:63], v[174:175] op_sel_hi:[1,0]
	v_pk_mul_f32 v[60:61], v[60:61], v[174:175] op_sel_hi:[1,0]
	v_pk_mul_f32 v[58:59], v[58:59], v[174:175] op_sel_hi:[1,0]
	v_pk_mul_f32 v[56:57], v[56:57], v[174:175] op_sel_hi:[1,0]
	v_pk_mul_f32 v[54:55], v[54:55], v[174:175] op_sel_hi:[1,0]
	v_pk_mul_f32 v[52:53], v[52:53], v[174:175] op_sel_hi:[1,0]
	v_pk_mul_f32 v[174:175], v[50:51], v[174:175] op_sel_hi:[1,0]
	v_div_fixup_f32 v50, v173, v176, 1.0
	v_pk_fma_f32 v[80:81], v[88:89], v[80:81], v[84:85]
	v_pk_fma_f32 v[78:79], v[86:87], v[78:79], v[82:83]
	v_pk_mul_f32 v[86:87], v[16:17], v[52:53]
	v_pk_mul_f32 v[48:49], v[48:49], v[50:51] op_sel_hi:[1,0]
	v_pk_mul_f32 v[46:47], v[46:47], v[50:51] op_sel_hi:[1,0]
	v_pk_mul_f32 v[82:83], v[10:11], v[54:55]
	v_pk_mul_f32 v[84:85], v[14:15], v[174:175]
	v_pk_mul_f32 v[88:89], v[2:3], v[46:47]
	v_pk_mul_f32 v[174:175], v[4:5], v[48:49]
	v_cvt_pk_bf16_f32 v46, v78, v79
	v_cvt_pk_bf16_f32 v47, v80, v81
	global_store_dwordx2 v[102:103], v[46:47], off
	global_load_dwordx4 v[46:49], v[152:153], off
	s_nop 0
	global_load_dwordx4 v[52:55], v[148:149], off
	v_pk_mul_f32 v[74:75], v[6:7], v[74:75]
	v_pk_mul_f32 v[76:77], v[8:9], v[76:77]
	v_pk_mul_f32 v[70:71], v[10:11], v[70:71]
	v_pk_mul_f32 v[72:73], v[12:13], v[72:73]
	v_pk_mul_f32 v[66:67], v[66:67], v[14:15]
	v_pk_mul_f32 v[68:69], v[68:69], v[16:17]
	v_pk_mul_f32 v[62:63], v[2:3], v[62:63]
	v_pk_mul_f32 v[64:65], v[4:5], v[64:65]
	v_pk_mul_f32 v[58:59], v[6:7], v[58:59]
	v_pk_mul_f32 v[60:61], v[8:9], v[60:61]
	v_pk_mul_f32 v[56:57], v[12:13], v[56:57]
	v_mul_f32_e32 v196, v23, v23
	v_mul_f32_e32 v202, v25, v25
	v_mul_f32_e32 v213, v18, v18
	v_mul_f32_e32 v214, v19, v19
	v_mul_f32_e32 v215, v20, v20
	v_mul_f32_e32 v216, v21, v21
	v_pk_fma_f32 v[158:159], v[22:23], v[22:23], v[196:197] op_sel_hi:[1,1,0]
	v_pk_fma_f32 v[160:161], v[24:25], v[24:25], v[202:203] op_sel_hi:[1,1,0]
	v_mov_b32_e32 v159, v215
	v_mov_b32_e32 v161, v216
	v_lshl_add_u64 v[144:145], s[18:19], 0, v[90:91]
	v_lshl_add_u64 v[128:129], s[16:17], 0, v[90:91]
	v_lshl_add_u64 v[122:123], s[18:19], 0, v[96:97]
	v_lshl_add_u64 v[120:121], s[16:17], 0, v[96:97]
	v_lshl_add_u64 v[92:93], v[92:93], 0, s[12:13]
	v_lshl_add_u64 v[94:95], v[94:95], 0, s[14:15]
	s_mov_b32 s8, s24
	s_cmp_lt_i32 s24, s20
	s_waitcnt vmcnt(0) lgkmcnt(0)
	v_pk_add_f32 v[48:49], v[48:49], 1.0 op_sel_hi:[1,0]
	v_pk_add_f32 v[46:47], v[46:47], 1.0 op_sel_hi:[1,0]
	v_pk_fma_f32 v[48:49], v[48:49], v[76:77], v[54:55]
	v_pk_fma_f32 v[46:47], v[46:47], v[74:75], v[52:53]
	v_cvt_pk_bf16_f32 v46, v46, v47
	v_cvt_pk_bf16_f32 v47, v48, v49
	global_store_dwordx2 v[102:103], v[46:47], off offset:512
	global_load_dwordx4 v[46:49], v[146:147], off
	s_nop 0
	global_load_dwordx4 v[52:55], v[142:143], off
	s_waitcnt vmcnt(0) lgkmcnt(0)
	v_pk_add_f32 v[48:49], v[48:49], 1.0 op_sel_hi:[1,0]
	v_pk_add_f32 v[46:47], v[46:47], 1.0 op_sel_hi:[1,0]
	v_pk_fma_f32 v[48:49], v[72:73], v[48:49], v[54:55]
	v_pk_fma_f32 v[46:47], v[70:71], v[46:47], v[52:53]
	v_cvt_pk_bf16_f32 v46, v46, v47
	v_cvt_pk_bf16_f32 v47, v48, v49
	global_store_dwordx2 v[102:103], v[46:47], off offset:1024
	global_load_dwordx4 v[46:49], v[140:141], off
	s_nop 0
	global_load_dwordx4 v[52:55], v[134:135], off
	s_waitcnt vmcnt(0) lgkmcnt(0)
	v_pk_add_f32 v[48:49], v[48:49], 1.0 op_sel_hi:[1,0]
	v_pk_add_f32 v[46:47], v[46:47], 1.0 op_sel_hi:[1,0]
	v_pk_fma_f32 v[48:49], v[68:69], v[48:49], v[54:55]
	v_pk_fma_f32 v[46:47], v[66:67], v[46:47], v[52:53]
	v_cvt_pk_bf16_f32 v46, v46, v47
	v_cvt_pk_bf16_f32 v47, v48, v49
	global_store_dwordx2 v[102:103], v[46:47], off offset:1536
	global_load_dwordx4 v[46:49], v[138:139], off
	s_nop 0
	global_load_dwordx4 v[52:55], v[132:133], off
	s_waitcnt vmcnt(0) lgkmcnt(0)
	v_pk_add_f32 v[48:49], v[48:49], 1.0 op_sel_hi:[1,0]
	v_pk_add_f32 v[46:47], v[46:47], 1.0 op_sel_hi:[1,0]
	v_pk_fma_f32 v[48:49], v[48:49], v[64:65], v[54:55]
	v_pk_fma_f32 v[46:47], v[46:47], v[62:63], v[52:53]
	v_cvt_pk_bf16_f32 v46, v46, v47
	v_cvt_pk_bf16_f32 v47, v48, v49
	global_store_dwordx2 v[102:103], v[46:47], off offset:2048
	global_load_dwordx4 v[46:49], v[130:131], off
	s_nop 0
	global_load_dwordx4 v[52:55], v[126:127], off
	s_waitcnt vmcnt(0) lgkmcnt(0)
	v_pk_add_f32 v[48:49], v[48:49], 1.0 op_sel_hi:[1,0]
	v_pk_add_f32 v[46:47], v[46:47], 1.0 op_sel_hi:[1,0]
	v_pk_fma_f32 v[48:49], v[48:49], v[60:61], v[54:55]
	v_pk_fma_f32 v[46:47], v[46:47], v[58:59], v[52:53]
	v_cvt_pk_bf16_f32 v46, v46, v47
	v_cvt_pk_bf16_f32 v47, v48, v49
	global_store_dwordx2 v[102:103], v[46:47], off offset:2560
	global_load_dwordx4 v[46:49], v[124:125], off
	s_nop 0
	global_load_dwordx4 v[52:55], v[118:119], off
	v_pk_add_f32 v[58:59], v[164:165], v[164:165] op_sel:[0,1] op_sel_hi:[1,0]
	v_pk_add_f32 v[60:61], v[158:159], v[160:161]
	v_mov_b32_e32 v59, v214
	s_waitcnt vmcnt(0) lgkmcnt(0)
	v_pk_add_f32 v[48:49], v[48:49], 1.0 op_sel_hi:[1,0]
	v_pk_add_f32 v[46:47], v[46:47], 1.0 op_sel_hi:[1,0]
	v_pk_fma_f32 v[48:49], v[48:49], v[56:57], v[54:55]
	v_pk_fma_f32 v[46:47], v[46:47], v[82:83], v[52:53]
	v_cvt_pk_bf16_f32 v46, v46, v47
	v_cvt_pk_bf16_f32 v47, v48, v49
	global_store_dwordx2 v[102:103], v[46:47], off offset:3072
	global_load_dwordx4 v[46:49], v[116:117], off
	s_nop 0
	global_load_dwordx4 v[52:55], v[114:115], off
	v_pk_add_f32 v[56:57], v[162:163], v[162:163] op_sel:[0,1] op_sel_hi:[1,0]
	s_waitcnt vmcnt(0) lgkmcnt(0)
	v_pk_add_f32 v[48:49], v[48:49], 1.0 op_sel_hi:[1,0]
	v_pk_add_f32 v[46:47], v[46:47], 1.0 op_sel_hi:[1,0]
	v_pk_fma_f32 v[48:49], v[86:87], v[48:49], v[54:55]
	v_pk_fma_f32 v[46:47], v[84:85], v[46:47], v[52:53]
	v_cvt_pk_bf16_f32 v46, v46, v47
	v_cvt_pk_bf16_f32 v47, v48, v49
	global_store_dwordx2 v[102:103], v[46:47], off offset:3584
	global_load_dwordx4 v[46:49], v[156:157], off
	s_nop 0
	global_load_dwordx4 v[52:55], v[112:113], off
	v_mov_b32_e32 v57, v213
	s_waitcnt vmcnt(0) lgkmcnt(0)
	v_pk_add_f32 v[48:49], v[48:49], 1.0 op_sel_hi:[1,0]
	v_pk_add_f32 v[46:47], v[46:47], 1.0 op_sel_hi:[1,0]
	v_pk_fma_f32 v[48:49], v[48:49], v[174:175], v[54:55]
	v_pk_fma_f32 v[46:47], v[46:47], v[88:89], v[52:53]
	v_bfe_u32 v51, v46, 16, 1
	v_bfe_u32 v52, v47, 16, 1
	v_add3_u32 v46, v46, v51, s3
	v_add3_u32 v47, v47, v52, s3
	v_lshrrev_b32_e32 v46, 16, v46
	v_and_or_b32 v46, v47, s21, v46
	v_cvt_pk_bf16_f32 v47, v48, v49
	global_store_dwordx2 v[104:105], v[46:47], off
	global_load_dwordx4 v[46:49], v[154:155], off
	s_nop 0
	global_load_dwordx4 v[52:55], v[106:107], off
	v_pk_mul_f32 v[44:45], v[44:45], v[50:51] op_sel_hi:[1,0]
	v_pk_mul_f32 v[42:43], v[42:43], v[50:51] op_sel_hi:[1,0]
	v_pk_mul_f32 v[44:45], v[8:9], v[44:45]
	v_pk_mul_f32 v[42:43], v[6:7], v[42:43]
	s_waitcnt vmcnt(0) lgkmcnt(0)
	v_pk_add_f32 v[48:49], v[48:49], 1.0 op_sel_hi:[1,0]
	v_pk_add_f32 v[46:47], v[46:47], 1.0 op_sel_hi:[1,0]
	v_pk_fma_f32 v[44:45], v[48:49], v[44:45], v[54:55]
	v_pk_fma_f32 v[42:43], v[46:47], v[42:43], v[52:53]
	v_cvt_pk_bf16_f32 v42, v42, v43
	v_cvt_pk_bf16_f32 v43, v44, v45
	global_store_dwordx2 v[104:105], v[42:43], off offset:512
	global_load_dwordx4 v[42:45], v[150:151], off
	s_nop 0
	global_load_dwordx4 v[46:49], v[108:109], off
	v_pk_add_f32 v[52:53], v[56:57], v[58:59]
	s_waitcnt vmcnt(0) lgkmcnt(0)
	v_pk_add_f32 v[44:45], v[44:45], 1.0 op_sel_hi:[1,0]
	v_pk_add_f32 v[52:53], v[52:53], v[60:61]
	v_pk_add_f32 v[42:43], v[42:43], 1.0 op_sel_hi:[1,0]
	v_add_f32_e32 v51, v52, v53
	s_waitcnt lgkmcnt(0)
	s_nop 1
	v_add_f32_dpp v51, v51, v51 quad_perm:[1,0,3,2] row_mask:0xf bank_mask:0xf
	ds_bpermute_b32 v52, v166, v51
	s_waitcnt lgkmcnt(0)
	v_add_f32_e32 v51, v51, v52
	v_pk_mul_f32 v[40:41], v[40:41], v[50:51] op_sel_hi:[1,0]
	v_pk_mul_f32 v[38:39], v[38:39], v[50:51] op_sel_hi:[1,0]
	v_pk_mul_f32 v[40:41], v[12:13], v[40:41]
	v_pk_mul_f32 v[38:39], v[10:11], v[38:39]
	v_pk_fma_f32 v[40:41], v[44:45], v[40:41], v[48:49]
	v_pk_fma_f32 v[38:39], v[42:43], v[38:39], v[46:47]
	v_cvt_pk_bf16_f32 v38, v38, v39
	v_cvt_pk_bf16_f32 v39, v40, v41
	global_store_dwordx2 v[104:105], v[38:39], off offset:1024
	global_load_dwordx4 v[38:41], v[136:137], off
	s_nop 0
	global_load_dwordx4 v[42:45], v[110:111], off
	v_pk_mul_f32 v[36:37], v[36:37], v[50:51] op_sel_hi:[1,0]
	v_pk_mul_f32 v[34:35], v[34:35], v[50:51] op_sel_hi:[1,0]
	v_pk_mul_f32 v[36:37], v[16:17], v[36:37]
	v_pk_mul_f32 v[34:35], v[14:15], v[34:35]
	ds_bpermute_b32 v46, v167, v51
	s_waitcnt lgkmcnt(0)
	v_add_f32_e32 v46, v51, v46
	ds_bpermute_b32 v47, v168, v46
	s_waitcnt lgkmcnt(0)
	v_add_f32_e32 v46, v46, v47
	ds_bpermute_b32 v47, v169, v46
	s_waitcnt lgkmcnt(0)
	v_add_f32_e32 v46, v46, v47
	ds_bpermute_b32 v47, v170, v46
	s_waitcnt lgkmcnt(0)
	v_add_f32_e32 v46, v46, v47
	v_fmamk_f32 v46, v46, 0x3a800000, v171
	v_mul_f32_e32 v47, 0x4f800000, v46
	v_cmp_gt_f32_e32 vcc, s2, v46
	s_waitcnt vmcnt(0)
	v_pk_add_f32 v[40:41], v[40:41], 1.0 op_sel_hi:[1,0]
	v_pk_add_f32 v[38:39], v[38:39], 1.0 op_sel_hi:[1,0]
	v_pk_fma_f32 v[36:37], v[36:37], v[40:41], v[44:45]
	v_pk_fma_f32 v[34:35], v[34:35], v[38:39], v[42:43]
	v_cvt_pk_bf16_f32 v34, v34, v35
	v_cvt_pk_bf16_f32 v35, v36, v37
	global_store_dwordx2 v[104:105], v[34:35], off offset:1536
	global_load_dwordx4 v[34:37], v[144:145], off
	s_nop 0
	global_load_dwordx4 v[38:41], v[128:129], off
	v_cndmask_b32_e32 v42, v46, v47, vcc
	v_sqrt_f32_e32 v43, v42
	s_waitcnt vmcnt(0) lgkmcnt(0)
	v_pk_add_f32 v[36:37], v[36:37], 1.0 op_sel_hi:[1,0]
	v_add_u32_e32 v44, -1, v43
	v_add_u32_e32 v45, 1, v43
	v_fma_f32 v46, -v44, v43, v42
	v_fma_f32 v47, -v45, v43, v42
	v_cmp_ge_f32_e64 s[6:7], 0, v46
	v_pk_add_f32 v[34:35], v[34:35], 1.0 op_sel_hi:[1,0]
	s_nop 0
	v_cndmask_b32_e64 v43, v43, v44, s[6:7]
	v_cmp_lt_f32_e64 s[6:7], 0, v47
	s_nop 1
	v_cndmask_b32_e64 v43, v43, v45, s[6:7]
	v_mul_f32_e32 v44, 0x37800000, v43
	v_cndmask_b32_e32 v43, v43, v44, vcc
	v_cmp_class_f32_e32 vcc, v42, v172
	s_nop 1
	v_cndmask_b32_e32 v42, v43, v42, vcc
	v_div_scale_f32 v43, s[6:7], v42, v42, 1.0
	v_rcp_f32_e32 v45, v43
	v_div_scale_f32 v44, vcc, 1.0, v42, 1.0
	v_fma_f32 v46, -v43, v45, 1.0
	v_fmac_f32_e32 v45, v46, v45
	v_mul_f32_e32 v46, v44, v45
	v_fma_f32 v47, -v43, v46, v44
	v_fmac_f32_e32 v46, v47, v45
	v_fma_f32 v43, -v43, v46, v44
	v_div_fmas_f32 v43, v43, v45, v46
	v_div_fixup_f32 v42, v43, v42, 1.0
	v_pk_mul_f32 v[32:33], v[32:33], v[42:43] op_sel_hi:[1,0]
	v_pk_mul_f32 v[30:31], v[30:31], v[42:43] op_sel_hi:[1,0]
	v_pk_mul_f32 v[32:33], v[4:5], v[32:33]
	v_pk_mul_f32 v[30:31], v[2:3], v[30:31]
	v_pk_fma_f32 v[32:33], v[36:37], v[32:33], v[40:41]
	v_pk_fma_f32 v[30:31], v[34:35], v[30:31], v[38:39]
	v_cvt_pk_bf16_f32 v30, v30, v31
	v_cvt_pk_bf16_f32 v31, v32, v33
	global_store_dwordx2 v[104:105], v[30:31], off offset:2048
	global_load_dwordx4 v[30:33], v[122:123], off
	s_nop 0
	global_load_dwordx4 v[34:37], v[120:121], off
	v_pk_mul_f32 v[28:29], v[28:29], v[42:43] op_sel_hi:[1,0]
	v_pk_mul_f32 v[26:27], v[26:27], v[42:43] op_sel_hi:[1,0]
	v_pk_mul_f32 v[28:29], v[8:9], v[28:29]
	v_pk_mul_f32 v[26:27], v[6:7], v[26:27]
	v_lshl_add_u64 v[40:41], s[18:19], 0, v[98:99]
	v_lshl_add_u64 v[38:39], s[16:17], 0, v[98:99]
	v_pk_mul_f32 v[24:25], v[24:25], v[42:43] op_sel_hi:[1,0]
	v_pk_mul_f32 v[22:23], v[22:23], v[42:43] op_sel_hi:[1,0]
	v_pk_mul_f32 v[24:25], v[12:13], v[24:25]
	v_pk_mul_f32 v[22:23], v[10:11], v[22:23]
	v_pk_mul_f32 v[20:21], v[20:21], v[42:43] op_sel_hi:[1,0]
	v_pk_mul_f32 v[18:19], v[18:19], v[42:43] op_sel_hi:[1,0]
	v_pk_mul_f32 v[20:21], v[16:17], v[20:21]
	v_pk_mul_f32 v[18:19], v[14:15], v[18:19]
	s_waitcnt vmcnt(0) lgkmcnt(0)
	v_pk_add_f32 v[32:33], v[32:33], 1.0 op_sel_hi:[1,0]
	v_pk_add_f32 v[30:31], v[30:31], 1.0 op_sel_hi:[1,0]
	v_pk_fma_f32 v[28:29], v[32:33], v[28:29], v[36:37]
	v_pk_fma_f32 v[26:27], v[30:31], v[26:27], v[34:35]
	v_cvt_pk_bf16_f32 v26, v26, v27
	v_cvt_pk_bf16_f32 v27, v28, v29
	global_store_dwordx2 v[104:105], v[26:27], off offset:2560
	global_load_dwordx4 v[26:29], v[40:41], off
	s_nop 0
	global_load_dwordx4 v[30:33], v[38:39], off
	v_lshl_add_u64 v[36:37], s[18:19], 0, v[100:101]
	v_lshl_add_u64 v[34:35], s[16:17], 0, v[100:101]
	s_waitcnt vmcnt(0) lgkmcnt(0)
	v_pk_add_f32 v[28:29], v[28:29], 1.0 op_sel_hi:[1,0]
	v_pk_add_f32 v[26:27], v[26:27], 1.0 op_sel_hi:[1,0]
	v_pk_fma_f32 v[24:25], v[28:29], v[24:25], v[32:33]
	v_pk_fma_f32 v[22:23], v[26:27], v[22:23], v[30:31]
	v_cvt_pk_bf16_f32 v22, v22, v23
	v_cvt_pk_bf16_f32 v23, v24, v25
	global_store_dwordx2 v[104:105], v[22:23], off offset:3072
	global_load_dwordx4 v[22:25], v[36:37], off
	s_nop 0
	global_load_dwordx4 v[26:29], v[34:35], off
	s_waitcnt vmcnt(0) lgkmcnt(0)
	v_pk_add_f32 v[24:25], v[24:25], 1.0 op_sel_hi:[1,0]
	v_pk_add_f32 v[22:23], v[22:23], 1.0 op_sel_hi:[1,0]
	v_pk_fma_f32 v[20:21], v[20:21], v[24:25], v[28:29]
	v_pk_fma_f32 v[18:19], v[18:19], v[22:23], v[26:27]
	v_cvt_pk_bf16_f32 v18, v18, v19
	v_cvt_pk_bf16_f32 v19, v20, v21
	global_store_dwordx2 v[104:105], v[18:19], off offset:3584
	s_cbranch_scc1 .LBB0_3086

.LBB0_3194:
	v_lshl_add_u64 v[18:19], s[12:13], 0, v[94:95]
	v_lshl_add_u64 v[22:23], s[12:13], 0, v[92:93]
	v_add_co_u32_e32 v20, vcc, 0x7800000, v18
	v_add_co_u32_e64 v102, s[6:7], s29, v22
	s_nop 0
	v_addc_co_u32_e32 v21, vcc, 0, v19, vcc
	v_addc_co_u32_e64 v103, s[6:7], 0, v23, s[6:7]
	v_add_co_u32_e64 v104, s[6:7], s30, v22
	v_add_co_u32_e32 v22, vcc, 0x7801000, v18
	s_nop 0
	v_addc_co_u32_e64 v105, s[6:7], 0, v23, s[6:7]
	global_load_dwordx4 v[78:81], v[20:21], off
	global_load_dwordx4 v[74:77], v[20:21], off offset:1024
	global_load_dwordx4 v[70:73], v[20:21], off offset:2048
	global_load_dwordx4 v[66:69], v[20:21], off offset:3072
	v_addc_co_u32_e32 v23, vcc, 0, v19, vcc
	v_add_co_u32_e32 v20, vcc, 0x7802000, v18
	global_load_dwordx4 v[62:65], v[22:23], off
	global_load_dwordx4 v[58:61], v[22:23], off offset:1024
	global_load_dwordx4 v[54:57], v[22:23], off offset:2048
	global_load_dwordx4 v[50:53], v[22:23], off offset:3072
	v_addc_co_u32_e32 v21, vcc, 0, v19, vcc
	global_load_dwordx4 v[46:49], v[20:21], off
	global_load_dwordx4 v[42:45], v[20:21], off offset:1024
	global_load_dwordx4 v[38:41], v[20:21], off offset:2048
	global_load_dwordx4 v[34:37], v[20:21], off offset:3072
	v_add_co_u32_e32 v82, vcc, 0x7803000, v18
	s_ashr_i32 s8, s24, 13
	s_nop 0
	v_addc_co_u32_e32 v83, vcc, 0, v19, vcc
	global_load_dwordx4 v[30:33], v[82:83], off
	global_load_dwordx4 v[26:29], v[82:83], off offset:1024
	global_load_dwordx4 v[22:25], v[82:83], off offset:2048
	global_load_dwordx4 v[18:21], v[82:83], off offset:3072
	s_add_i32 s9, s24, 0xffffc002
	s_cmpk_lt_i32 s24, 0x4000
	s_cselect_b32 s6, s8, s9
	s_addk_i32 s6, 0x82
	s_mul_hi_i32 s7, s6, 0x9000
	s_mul_i32 s6, s6, 0x9000
	s_add_u32 s6, s14, s6
	s_addc_u32 s7, s15, s7
	s_add_u32 s10, s6, 0x1000
	s_addc_u32 s11, s7, 0
	v_lshl_add_u64 v[124:125], s[6:7], 0, v[90:91]
	v_lshl_add_u64 v[86:87], s[10:11], 0, v[90:91]
	global_load_dwordx4 v[82:85], v[124:125], off
	s_add_i32 s6, s24, 0xffffc003
	global_load_dwordx4 v[86:89], v[86:87], off
	s_cmpk_lt_i32 s24, 0x3fff
	s_cselect_b32 s6, s8, s6
	s_addk_i32 s6, 0x82
	s_mul_hi_i32 s7, s6, 0x9000
	s_mul_i32 s6, s6, 0x9000
	s_add_u32 s6, s14, s6
	s_addc_u32 s7, s15, s7
	v_lshl_add_u64 v[134:135], s[10:11], 0, v[96:97]
	v_lshl_add_u64 v[130:131], s[10:11], 0, v[98:99]
	v_lshl_add_u64 v[128:129], s[10:11], 0, v[100:101]
	s_add_u32 s10, s6, 0x1000
	v_lshl_add_u64 v[110:111], s[6:7], 0, v[90:91]
	s_addc_u32 s11, s7, 0
	s_add_i32 s6, s24, 0xffffc004
	s_cmpk_lt_i32 s24, 0x3ffe
	s_cselect_b32 s6, s8, s6
	s_addk_i32 s6, 0x82
	s_mul_hi_i32 s7, s6, 0x9000
	s_mul_i32 s6, s6, 0x9000
	v_lshl_add_u64 v[126:127], s[10:11], 0, v[90:91]
	v_lshl_add_u64 v[120:121], s[10:11], 0, v[96:97]
	v_lshl_add_u64 v[116:117], s[10:11], 0, v[98:99]
	v_lshl_add_u64 v[112:113], s[10:11], 0, v[100:101]
	s_add_u32 s10, s14, s6
	s_addc_u32 s11, s15, s7
	s_add_u32 s6, s10, 0x1000
	s_addc_u32 s7, s11, 0
	s_add_i32 s9, s24, 0xffffc005
	s_cmpk_lt_i32 s24, 0x3ffd
	v_lshl_add_u64 v[138:139], s[6:7], 0, v[90:91]
	v_lshl_add_u64 v[136:137], s[6:7], 0, v[96:97]
	v_lshl_add_u64 v[132:133], s[6:7], 0, v[98:99]
	v_lshl_add_u64 v[122:123], s[6:7], 0, v[100:101]
	s_cselect_b32 s6, s8, s9
	s_addk_i32 s6, 0x82
	s_mul_hi_i32 s7, s6, 0x9000
	s_mul_i32 s6, s6, 0x9000
	s_add_u32 s6, s14, s6
	s_addc_u32 s7, s15, s7
	s_add_u32 s40, s6, 0x1000
	v_lshl_add_u64 v[106:107], s[6:7], 0, v[90:91]
	s_addc_u32 s41, s7, 0
	v_lshl_add_u64 v[108:109], s[10:11], 0, v[90:91]
	v_lshl_add_u64 v[118:119], s[40:41], 0, v[90:91]
	v_lshl_add_u64 v[114:115], s[40:41], 0, v[96:97]
	s_add_i32 s24, s24, 32
	v_lshl_add_u64 v[92:93], v[92:93], 0, s[26:27]
	s_waitcnt vmcnt(0) lgkmcnt(0)
	v_pk_mul_f32 v[140:141], v[80:81], v[80:81]
	v_pk_mul_f32 v[142:143], v[78:79], v[78:79]
	v_pk_mul_f32 v[144:145], v[76:77], v[76:77]
	v_pk_mul_f32 v[146:147], v[74:75], v[74:75]
	v_mul_f32_e32 v156, v71, v71
	v_mul_f32_e32 v158, v73, v73
	v_pk_mov_b32 v[160:161], v[142:143], v[140:141] op_sel:[1,0]
	v_mov_b32_e32 v143, v141
	v_pk_mov_b32 v[140:141], v[146:147], v[144:145] op_sel:[1,0]
	v_mov_b32_e32 v147, v145
	v_mul_f32_e32 v169, v68, v68
	v_mul_f32_e32 v171, v69, v69
	v_pk_fma_f32 v[144:145], v[70:71], v[70:71], v[156:157] op_sel_hi:[1,1,0]
	v_pk_fma_f32 v[156:157], v[72:73], v[72:73], v[158:159] op_sel_hi:[1,1,0]
	v_pk_mul_f32 v[158:159], v[64:65], v[64:65]
	v_pk_mul_f32 v[162:163], v[62:63], v[62:63]
	v_pk_mul_f32 v[164:165], v[60:61], v[60:61]
	v_pk_mul_f32 v[166:167], v[58:59], v[58:59]
	v_mul_f32_e32 v168, v55, v55
	v_mul_f32_e32 v170, v57, v57
	v_pk_add_f32 v[142:143], v[160:161], v[142:143]
	v_pk_add_f32 v[140:141], v[140:141], v[146:147]
	v_mul_f32_e32 v155, v66, v66
	v_mul_f32_e32 v179, v67, v67
	v_mov_b32_e32 v145, v169
	v_mov_b32_e32 v157, v171
	v_pk_mov_b32 v[146:147], v[162:163], v[158:159] op_sel:[1,0]
	v_mov_b32_e32 v163, v159
	v_pk_mov_b32 v[158:159], v[166:167], v[164:165] op_sel:[1,0]
	v_mov_b32_e32 v167, v165
	v_pk_fma_f32 v[160:161], v[54:55], v[54:55], v[168:169] op_sel_hi:[1,1,0]
	v_pk_fma_f32 v[164:165], v[56:57], v[56:57], v[170:171] op_sel_hi:[1,1,0]
	v_pk_mul_f32 v[168:169], v[48:49], v[48:49]
	v_pk_mul_f32 v[170:171], v[46:47], v[46:47]
	v_pk_add_f32 v[180:181], v[142:143], v[142:143] op_sel:[0,1] op_sel_hi:[1,0]
	v_pk_add_f32 v[182:183], v[140:141], v[140:141] op_sel:[0,1] op_sel_hi:[1,0]
	v_mul_f32_e32 v177, v52, v52
	v_pk_mul_f32 v[172:173], v[44:45], v[44:45]
	v_pk_mul_f32 v[174:175], v[42:43], v[42:43]
	v_mul_f32_e32 v176, v39, v39
	v_mul_f32_e32 v178, v41, v41
	v_pk_add_f32 v[156:157], v[144:145], v[156:157]
	v_pk_add_f32 v[140:141], v[146:147], v[162:163]
	v_pk_add_f32 v[142:143], v[158:159], v[166:167]
	v_pk_mov_b32 v[144:145], v[170:171], v[168:169] op_sel:[1,0]
	v_mov_b32_e32 v171, v169
	v_mov_b32_e32 v181, v155
	v_mov_b32_e32 v183, v179
	v_mul_f32_e32 v185, v50, v50
	v_mul_f32_e32 v190, v51, v51
	v_mul_f32_e32 v184, v53, v53
	v_mul_f32_e32 v193, v36, v36
	v_mul_f32_e32 v194, v37, v37
	v_pk_mov_b32 v[146:147], v[174:175], v[172:173] op_sel:[1,0]
	v_mov_b32_e32 v175, v173
	v_pk_fma_f32 v[158:159], v[38:39], v[38:39], v[176:177] op_sel_hi:[1,1,0]
	v_pk_fma_f32 v[162:163], v[40:41], v[40:41], v[178:179] op_sel_hi:[1,1,0]
	v_pk_add_f32 v[186:187], v[140:141], v[140:141] op_sel:[0,1] op_sel_hi:[1,0]
	v_pk_add_f32 v[188:189], v[142:143], v[142:143] op_sel:[0,1] op_sel_hi:[1,0]
	v_pk_add_f32 v[144:145], v[144:145], v[170:171]
	v_pk_add_f32 v[170:171], v[180:181], v[182:183]
	v_mov_b32_e32 v161, v177
	v_mov_b32_e32 v165, v184
	v_pk_mul_f32 v[166:167], v[32:33], v[32:33]
	v_pk_mul_f32 v[168:169], v[30:31], v[30:31]
	v_pk_mul_f32 v[172:173], v[28:29], v[28:29]
	v_pk_mul_f32 v[176:177], v[26:27], v[26:27]
	v_pk_add_f32 v[146:147], v[146:147], v[174:175]
	v_mov_b32_e32 v159, v193
	v_mov_b32_e32 v163, v194
	v_mov_b32_e32 v187, v185
	v_mov_b32_e32 v189, v190
	v_pk_add_f32 v[156:157], v[170:171], v[156:157]
	v_mul_f32_e32 v191, v34, v34
	v_mul_f32_e32 v192, v35, v35
	v_pk_add_f32 v[160:161], v[160:161], v[164:165]
	v_pk_mov_b32 v[164:165], v[168:169], v[166:167] op_sel:[1,0]
	v_mov_b32_e32 v169, v167
	v_pk_mov_b32 v[166:167], v[176:177], v[172:173] op_sel:[1,0]
	v_mov_b32_e32 v177, v173
	v_pk_add_f32 v[172:173], v[144:145], v[144:145] op_sel:[0,1] op_sel_hi:[1,0]
	v_pk_add_f32 v[174:175], v[146:147], v[146:147] op_sel:[0,1] op_sel_hi:[1,0]
	v_pk_add_f32 v[158:159], v[158:159], v[162:163]
	v_pk_add_f32 v[162:163], v[186:187], v[188:189]
	v_add_f32_e32 v155, v156, v157
	v_mov_b32_e32 v173, v191
	v_mov_b32_e32 v175, v192
	v_pk_add_f32 v[156:157], v[162:163], v[160:161]
	ds_bpermute_b32 v163, v1, v155
	v_pk_add_f32 v[160:161], v[172:173], v[174:175]
	v_add_f32_e32 v162, v156, v157
	v_pk_add_f32 v[156:157], v[160:161], v[158:159]
	v_add_f32_e32 v156, v156, v157
	s_waitcnt lgkmcnt(0)
	v_add_f32_e32 v155, v155, v163
	s_waitcnt lgkmcnt(0)
	s_nop 1
	v_add_f32_dpp v158, v162, v162 quad_perm:[1,0,3,2] row_mask:0xf bank_mask:0xf
	s_waitcnt lgkmcnt(0)
	s_nop 1
	v_add_f32_dpp v156, v156, v156 quad_perm:[1,0,3,2] row_mask:0xf bank_mask:0xf
	s_waitcnt lgkmcnt(0)
	s_nop 1
	v_add_f32_dpp v155, v155, v155 quad_perm:[2,3,0,1] row_mask:0xf bank_mask:0xf
	ds_bpermute_b32 v159, v149, v155
	s_waitcnt lgkmcnt(2)
	s_nop 1
	v_add_f32_dpp v158, v158, v158 quad_perm:[2,3,0,1] row_mask:0xf bank_mask:0xf
	s_waitcnt lgkmcnt(0)
	s_nop 1
	v_add_f32_dpp v156, v156, v156 quad_perm:[2,3,0,1] row_mask:0xf bank_mask:0xf
	s_waitcnt lgkmcnt(0)
	v_add_f32_e32 v155, v155, v159
	ds_bpermute_b32 v159, v150, v155
	s_waitcnt lgkmcnt(2)
	s_nop 1
	v_add_f32_dpp v158, v158, v158 row_half_mirror row_mask:0xf bank_mask:0xf
	s_waitcnt lgkmcnt(0)
	s_nop 1
	v_add_f32_dpp v156, v156, v156 row_half_mirror row_mask:0xf bank_mask:0xf
	s_waitcnt lgkmcnt(0)
	v_add_f32_e32 v155, v155, v159
	ds_bpermute_b32 v159, v151, v155
	s_waitcnt lgkmcnt(2)
	s_nop 1
	v_add_f32_dpp v158, v158, v158 row_mirror row_mask:0xf bank_mask:0xf
	ds_bpermute_b32 v160, v151, v158
	s_waitcnt lgkmcnt(2)
	s_nop 1
	v_add_f32_dpp v156, v156, v156 row_mirror row_mask:0xf bank_mask:0xf
	ds_bpermute_b32 v157, v151, v156
	s_waitcnt lgkmcnt(2)
	v_add_f32_e32 v155, v155, v159
	ds_bpermute_b32 v159, v152, v155
	s_waitcnt lgkmcnt(2)
	v_add_f32_e32 v158, v158, v160
	ds_bpermute_b32 v160, v152, v158
	s_waitcnt lgkmcnt(2)
	v_add_f32_e32 v156, v156, v157
	ds_bpermute_b32 v157, v152, v156
	s_waitcnt lgkmcnt(2)
	v_add_f32_e32 v155, v155, v159
	v_fmamk_f32 v155, v155, 0x3a800000, v153
	s_waitcnt lgkmcnt(1)
	v_add_f32_e32 v158, v158, v160
	v_mul_f32_e32 v159, 0x4f800000, v155
	v_cmp_gt_f32_e32 vcc, s17, v155
	v_fmamk_f32 v158, v158, 0x3a800000, v153
	s_waitcnt lgkmcnt(0)
	v_add_f32_e32 v156, v156, v157
	v_cndmask_b32_e32 v155, v155, v159, vcc
	v_mul_f32_e32 v157, 0x4f800000, v158
	v_cmp_gt_f32_e64 s[6:7], s17, v158
	v_sqrt_f32_e32 v159, v155
	v_fmamk_f32 v156, v156, 0x3a800000, v153
	v_cndmask_b32_e64 v157, v158, v157, s[6:7]
	v_mul_f32_e32 v158, 0x4f800000, v156
	v_cmp_gt_f32_e64 s[8:9], s17, v156
	v_sqrt_f32_e32 v160, v157
	v_add_u32_e32 v161, -1, v159
	v_cndmask_b32_e64 v156, v156, v158, s[8:9]
	v_sqrt_f32_e32 v158, v156
	v_add_u32_e32 v162, 1, v159
	v_fma_f32 v163, -v161, v159, v155
	v_pk_add_f32 v[144:145], v[164:165], v[168:169]
	v_fma_f32 v164, -v162, v159, v155
	v_add_u32_e32 v165, -1, v160
	v_cmp_ge_f32_e64 s[10:11], 0, v163
	v_pk_add_f32 v[146:147], v[166:167], v[176:177]
	v_add_u32_e32 v166, 1, v160
	v_cndmask_b32_e64 v159, v159, v161, s[10:11]
	v_fma_f32 v161, -v165, v160, v157
	v_cmp_lt_f32_e64 s[10:11], 0, v164
	v_fma_f32 v163, -v166, v160, v157
	v_add_u32_e32 v167, -1, v158
	v_cndmask_b32_e64 v159, v159, v162, s[10:11]
	v_cmp_ge_f32_e64 s[10:11], 0, v161
	v_add_u32_e32 v168, 1, v158
	v_fma_f32 v161, -v167, v158, v156
	v_cndmask_b32_e64 v160, v160, v165, s[10:11]
	v_cmp_lt_f32_e64 s[10:11], 0, v163
	v_fma_f32 v162, -v168, v158, v156
	v_mul_f32_e32 v163, 0x37800000, v159
	v_cndmask_b32_e64 v160, v160, v166, s[10:11]
	v_cmp_ge_f32_e64 s[10:11], 0, v161
	v_cndmask_b32_e32 v159, v159, v163, vcc
	v_cmp_class_f32_e32 vcc, v155, v154
	v_cndmask_b32_e64 v158, v158, v167, s[10:11]
	v_cmp_lt_f32_e64 s[10:11], 0, v162
	v_mul_f32_e32 v161, 0x37800000, v160
	v_cndmask_b32_e32 v155, v159, v155, vcc
	v_cndmask_b32_e64 v158, v158, v168, s[10:11]
	v_cndmask_b32_e64 v159, v160, v161, s[6:7]
	v_cmp_class_f32_e32 vcc, v157, v154
	v_mul_f32_e32 v160, 0x37800000, v158
	v_div_scale_f32 v161, s[6:7], v155, v155, 1.0
	v_cndmask_b32_e32 v157, v159, v157, vcc
	v_cndmask_b32_e64 v158, v158, v160, s[8:9]
	v_cmp_class_f32_e32 vcc, v156, v154
	v_rcp_f32_e32 v159, v161
	v_div_scale_f32 v160, s[8:9], v157, v157, 1.0
	v_cndmask_b32_e32 v158, v158, v156, vcc
	v_rcp_f32_e32 v164, v160
	v_div_scale_f32 v165, s[10:11], v158, v158, 1.0
	v_rcp_f32_e32 v167, v165
	v_fma_f32 v156, -v161, v159, 1.0
	v_div_scale_f32 v162, s[6:7], 1.0, v155, 1.0
	v_fmac_f32_e32 v159, v156, v159
	v_fma_f32 v156, -v160, v164, 1.0
	v_mul_f32_e32 v168, v162, v159
	v_div_scale_f32 v163, s[8:9], 1.0, v157, 1.0
	v_fmac_f32_e32 v164, v156, v164
	v_fma_f32 v156, -v165, v167, 1.0
	v_fma_f32 v169, -v161, v168, v162
	v_div_scale_f32 v166, s[10:11], 1.0, v158, 1.0
	v_mul_f32_e32 v170, v163, v164
	v_fmac_f32_e32 v167, v156, v167
	v_fmac_f32_e32 v168, v169, v159
	v_fma_f32 v156, -v160, v170, v163
	v_mul_f32_e32 v169, v166, v167
	v_fma_f32 v161, -v161, v168, v162
	s_mov_b64 vcc, s[6:7]
	v_fmac_f32_e32 v170, v156, v164
	v_fma_f32 v156, -v165, v169, v166
	v_div_fmas_f32 v159, v161, v159, v168
	v_fma_f32 v160, -v160, v170, v163
	v_fmac_f32_e32 v169, v156, v167
	v_div_fixup_f32 v156, v159, v155, 1.0
	s_mov_b64 vcc, s[8:9]
	v_div_fmas_f32 v155, v160, v164, v170
	v_fma_f32 v159, -v165, v169, v166
	v_pk_mul_f32 v[80:81], v[80:81], v[156:157] op_sel_hi:[1,0]
	v_pk_mul_f32 v[78:79], v[78:79], v[156:157] op_sel_hi:[1,0]
	s_mov_b64 vcc, s[10:11]
	v_pk_add_f32 v[88:89], v[88:89], 1.0 op_sel_hi:[1,0]
	v_pk_add_f32 v[86:87], v[86:87], 1.0 op_sel_hi:[1,0]
	v_pk_mul_f32 v[76:77], v[76:77], v[156:157] op_sel_hi:[1,0]
	v_pk_mul_f32 v[74:75], v[74:75], v[156:157] op_sel_hi:[1,0]
	v_pk_mul_f32 v[72:73], v[72:73], v[156:157] op_sel_hi:[1,0]
	v_pk_mul_f32 v[70:71], v[70:71], v[156:157] op_sel_hi:[1,0]
	v_pk_mul_f32 v[68:69], v[68:69], v[156:157] op_sel_hi:[1,0]
	v_pk_mul_f32 v[66:67], v[66:67], v[156:157] op_sel_hi:[1,0]
	v_div_fixup_f32 v156, v155, v157, 1.0
	v_div_fmas_f32 v155, v159, v167, v169
	v_pk_mul_f32 v[78:79], v[78:79], v[2:3]
	v_pk_mul_f32 v[80:81], v[80:81], v[4:5]
	v_pk_mul_f32 v[64:65], v[64:65], v[156:157] op_sel_hi:[1,0]
	v_pk_mul_f32 v[62:63], v[62:63], v[156:157] op_sel_hi:[1,0]
	v_pk_mul_f32 v[60:61], v[60:61], v[156:157] op_sel_hi:[1,0]
	v_pk_mul_f32 v[58:59], v[58:59], v[156:157] op_sel_hi:[1,0]
	v_pk_mul_f32 v[56:57], v[56:57], v[156:157] op_sel_hi:[1,0]
	v_pk_mul_f32 v[54:55], v[54:55], v[156:157] op_sel_hi:[1,0]
	v_pk_mul_f32 v[52:53], v[52:53], v[156:157] op_sel_hi:[1,0]
	v_pk_mul_f32 v[156:157], v[50:51], v[156:157] op_sel_hi:[1,0]
	v_div_fixup_f32 v50, v155, v158, 1.0
	v_pk_fma_f32 v[80:81], v[80:81], v[88:89], v[84:85]
	v_pk_fma_f32 v[78:79], v[78:79], v[86:87], v[82:83]
	v_pk_mul_f32 v[86:87], v[52:53], v[16:17]
	v_pk_mul_f32 v[48:49], v[48:49], v[50:51] op_sel_hi:[1,0]
	v_pk_mul_f32 v[46:47], v[46:47], v[50:51] op_sel_hi:[1,0]
	v_pk_mul_f32 v[82:83], v[54:55], v[10:11]
	v_pk_mul_f32 v[84:85], v[156:157], v[14:15]
	v_pk_mul_f32 v[88:89], v[46:47], v[2:3]
	v_pk_mul_f32 v[156:157], v[48:49], v[4:5]
	v_cvt_pk_bf16_f32 v46, v78, v79
	v_cvt_pk_bf16_f32 v47, v80, v81
	global_store_dwordx2 v[102:103], v[46:47], off
	global_load_dwordx4 v[46:49], v[134:135], off
	s_nop 0
	global_load_dwordx4 v[52:55], v[124:125], off offset:1024
	v_pk_mul_f32 v[74:75], v[74:75], v[6:7]
	v_pk_mul_f32 v[76:77], v[76:77], v[8:9]
	v_pk_mul_f32 v[70:71], v[70:71], v[10:11]
	v_pk_mul_f32 v[72:73], v[72:73], v[12:13]
	v_pk_mul_f32 v[66:67], v[66:67], v[14:15]
	v_pk_mul_f32 v[68:69], v[68:69], v[16:17]
	v_pk_mul_f32 v[62:63], v[62:63], v[2:3]
	v_pk_mul_f32 v[64:65], v[64:65], v[4:5]
	v_pk_mul_f32 v[58:59], v[58:59], v[6:7]
	v_pk_mul_f32 v[60:61], v[60:61], v[8:9]
	v_pk_mul_f32 v[56:57], v[56:57], v[12:13]
	v_mul_f32_e32 v178, v23, v23
	v_mul_f32_e32 v184, v25, v25
	v_mul_f32_e32 v195, v18, v18
	v_mul_f32_e32 v196, v19, v19
	v_mul_f32_e32 v197, v20, v20
	v_mul_f32_e32 v198, v21, v21
	v_pk_fma_f32 v[140:141], v[22:23], v[22:23], v[178:179] op_sel_hi:[1,1,0]
	v_pk_fma_f32 v[142:143], v[24:25], v[24:25], v[184:185] op_sel_hi:[1,1,0]
	v_mov_b32_e32 v141, v197
	v_mov_b32_e32 v143, v198
	v_lshl_add_u64 v[94:95], v[94:95], 0, s[38:39]
	s_cmp_lt_i32 s24, s5
	s_waitcnt vmcnt(0) lgkmcnt(0)
	v_pk_add_f32 v[48:49], v[48:49], 1.0 op_sel_hi:[1,0]
	v_pk_add_f32 v[46:47], v[46:47], 1.0 op_sel_hi:[1,0]
	v_pk_fma_f32 v[48:49], v[76:77], v[48:49], v[54:55]
	v_pk_fma_f32 v[46:47], v[74:75], v[46:47], v[52:53]
	v_cvt_pk_bf16_f32 v46, v46, v47
	v_cvt_pk_bf16_f32 v47, v48, v49
	global_store_dwordx2 v[102:103], v[46:47], off offset:512
	global_load_dwordx4 v[46:49], v[130:131], off
	s_nop 0
	global_load_dwordx4 v[52:55], v[124:125], off offset:2048
	s_waitcnt vmcnt(0) lgkmcnt(0)
	v_pk_add_f32 v[48:49], v[48:49], 1.0 op_sel_hi:[1,0]
	v_pk_add_f32 v[46:47], v[46:47], 1.0 op_sel_hi:[1,0]
	v_pk_fma_f32 v[48:49], v[72:73], v[48:49], v[54:55]
	v_pk_fma_f32 v[46:47], v[70:71], v[46:47], v[52:53]
	v_cvt_pk_bf16_f32 v46, v46, v47
	v_cvt_pk_bf16_f32 v47, v48, v49
	global_store_dwordx2 v[102:103], v[46:47], off offset:1024
	global_load_dwordx4 v[46:49], v[128:129], off
	s_nop 0
	global_load_dwordx4 v[52:55], v[124:125], off offset:3072
	s_waitcnt vmcnt(0) lgkmcnt(0)
	v_pk_add_f32 v[48:49], v[48:49], 1.0 op_sel_hi:[1,0]
	v_pk_add_f32 v[46:47], v[46:47], 1.0 op_sel_hi:[1,0]
	v_pk_fma_f32 v[48:49], v[68:69], v[48:49], v[54:55]
	v_pk_fma_f32 v[46:47], v[66:67], v[46:47], v[52:53]
	v_cvt_pk_bf16_f32 v46, v46, v47
	v_cvt_pk_bf16_f32 v47, v48, v49
	global_store_dwordx2 v[102:103], v[46:47], off offset:1536
	global_load_dwordx4 v[46:49], v[126:127], off
	s_nop 0
	global_load_dwordx4 v[52:55], v[110:111], off
	s_waitcnt vmcnt(0) lgkmcnt(0)
	v_pk_add_f32 v[48:49], v[48:49], 1.0 op_sel_hi:[1,0]
	v_pk_add_f32 v[46:47], v[46:47], 1.0 op_sel_hi:[1,0]
	v_pk_fma_f32 v[48:49], v[64:65], v[48:49], v[54:55]
	v_pk_fma_f32 v[46:47], v[62:63], v[46:47], v[52:53]
	v_cvt_pk_bf16_f32 v46, v46, v47
	v_cvt_pk_bf16_f32 v47, v48, v49
	global_store_dwordx2 v[102:103], v[46:47], off offset:2048
	global_load_dwordx4 v[46:49], v[120:121], off
	s_nop 0
	global_load_dwordx4 v[52:55], v[110:111], off offset:1024
	s_waitcnt vmcnt(0) lgkmcnt(0)
	v_pk_add_f32 v[48:49], v[48:49], 1.0 op_sel_hi:[1,0]
	v_pk_add_f32 v[46:47], v[46:47], 1.0 op_sel_hi:[1,0]
	v_pk_fma_f32 v[48:49], v[60:61], v[48:49], v[54:55]
	v_pk_fma_f32 v[46:47], v[58:59], v[46:47], v[52:53]
	v_cvt_pk_bf16_f32 v46, v46, v47
	v_cvt_pk_bf16_f32 v47, v48, v49
	global_store_dwordx2 v[102:103], v[46:47], off offset:2560
	global_load_dwordx4 v[46:49], v[116:117], off
	s_nop 0
	global_load_dwordx4 v[52:55], v[110:111], off offset:2048
	v_pk_add_f32 v[58:59], v[146:147], v[146:147] op_sel:[0,1] op_sel_hi:[1,0]
	v_pk_add_f32 v[60:61], v[140:141], v[142:143]
	v_mov_b32_e32 v59, v196
	s_waitcnt vmcnt(0) lgkmcnt(0)
	v_pk_add_f32 v[48:49], v[48:49], 1.0 op_sel_hi:[1,0]
	v_pk_add_f32 v[46:47], v[46:47], 1.0 op_sel_hi:[1,0]
	v_pk_fma_f32 v[48:49], v[56:57], v[48:49], v[54:55]
	v_pk_fma_f32 v[46:47], v[82:83], v[46:47], v[52:53]
	v_cvt_pk_bf16_f32 v46, v46, v47
	v_cvt_pk_bf16_f32 v47, v48, v49
	global_store_dwordx2 v[102:103], v[46:47], off offset:3072
	global_load_dwordx4 v[46:49], v[112:113], off
	s_nop 0
	global_load_dwordx4 v[52:55], v[110:111], off offset:3072
	v_pk_add_f32 v[56:57], v[144:145], v[144:145] op_sel:[0,1] op_sel_hi:[1,0]
	s_waitcnt vmcnt(0) lgkmcnt(0)
	v_pk_add_f32 v[48:49], v[48:49], 1.0 op_sel_hi:[1,0]
	v_pk_add_f32 v[46:47], v[46:47], 1.0 op_sel_hi:[1,0]
	v_pk_fma_f32 v[48:49], v[86:87], v[48:49], v[54:55]
	v_pk_fma_f32 v[46:47], v[84:85], v[46:47], v[52:53]
	v_cvt_pk_bf16_f32 v46, v46, v47
	v_cvt_pk_bf16_f32 v47, v48, v49
	global_store_dwordx2 v[102:103], v[46:47], off offset:3584
	global_load_dwordx4 v[46:49], v[138:139], off
	s_nop 0
	global_load_dwordx4 v[52:55], v[108:109], off
	v_mov_b32_e32 v57, v195
	s_waitcnt vmcnt(0) lgkmcnt(0)
	v_pk_add_f32 v[48:49], v[48:49], 1.0 op_sel_hi:[1,0]
	v_pk_add_f32 v[46:47], v[46:47], 1.0 op_sel_hi:[1,0]
	v_pk_fma_f32 v[48:49], v[156:157], v[48:49], v[54:55]
	v_pk_fma_f32 v[46:47], v[88:89], v[46:47], v[52:53]
	v_bfe_u32 v51, v46, 16, 1
	v_bfe_u32 v52, v47, 16, 1
	v_add3_u32 v46, v46, v51, s25
	v_add3_u32 v47, v47, v52, s25
	v_lshrrev_b32_e32 v46, 16, v46
	v_and_or_b32 v46, v47, s28, v46
	v_cvt_pk_bf16_f32 v47, v48, v49
	global_store_dwordx2 v[104:105], v[46:47], off
	global_load_dwordx4 v[46:49], v[136:137], off
	s_nop 0
	global_load_dwordx4 v[52:55], v[108:109], off offset:1024
	v_pk_mul_f32 v[44:45], v[44:45], v[50:51] op_sel_hi:[1,0]
	v_pk_mul_f32 v[42:43], v[42:43], v[50:51] op_sel_hi:[1,0]
	v_pk_mul_f32 v[44:45], v[44:45], v[8:9]
	v_pk_mul_f32 v[42:43], v[42:43], v[6:7]
	s_waitcnt vmcnt(0) lgkmcnt(0)
	v_pk_add_f32 v[48:49], v[48:49], 1.0 op_sel_hi:[1,0]
	v_pk_add_f32 v[46:47], v[46:47], 1.0 op_sel_hi:[1,0]
	v_pk_fma_f32 v[44:45], v[44:45], v[48:49], v[54:55]
	v_pk_fma_f32 v[42:43], v[42:43], v[46:47], v[52:53]
	v_cvt_pk_bf16_f32 v42, v42, v43
	v_cvt_pk_bf16_f32 v43, v44, v45
	global_store_dwordx2 v[104:105], v[42:43], off offset:512
	global_load_dwordx4 v[42:45], v[132:133], off
	s_nop 0
	global_load_dwordx4 v[46:49], v[108:109], off offset:2048
	v_pk_add_f32 v[52:53], v[56:57], v[58:59]
	s_waitcnt vmcnt(0) lgkmcnt(0)
	v_pk_add_f32 v[44:45], v[44:45], 1.0 op_sel_hi:[1,0]
	v_pk_add_f32 v[52:53], v[52:53], v[60:61]
	v_pk_add_f32 v[42:43], v[42:43], 1.0 op_sel_hi:[1,0]
	v_add_f32_e32 v51, v52, v53
	s_waitcnt lgkmcnt(0)
	s_nop 1
	v_add_f32_dpp v51, v51, v51 quad_perm:[1,0,3,2] row_mask:0xf bank_mask:0xf
	ds_bpermute_b32 v52, v148, v51
	s_waitcnt lgkmcnt(0)
	v_add_f32_e32 v51, v51, v52
	v_pk_mul_f32 v[40:41], v[40:41], v[50:51] op_sel_hi:[1,0]
	v_pk_mul_f32 v[38:39], v[38:39], v[50:51] op_sel_hi:[1,0]
	v_pk_mul_f32 v[40:41], v[40:41], v[12:13]
	v_pk_mul_f32 v[38:39], v[38:39], v[10:11]
	v_pk_fma_f32 v[40:41], v[40:41], v[44:45], v[48:49]
	v_pk_fma_f32 v[38:39], v[38:39], v[42:43], v[46:47]
	v_cvt_pk_bf16_f32 v38, v38, v39
	v_cvt_pk_bf16_f32 v39, v40, v41
	global_store_dwordx2 v[104:105], v[38:39], off offset:1024
	global_load_dwordx4 v[38:41], v[122:123], off
	s_nop 0
	global_load_dwordx4 v[42:45], v[108:109], off offset:3072
	v_pk_mul_f32 v[36:37], v[36:37], v[50:51] op_sel_hi:[1,0]
	v_pk_mul_f32 v[34:35], v[34:35], v[50:51] op_sel_hi:[1,0]
	v_pk_mul_f32 v[36:37], v[36:37], v[16:17]
	v_pk_mul_f32 v[34:35], v[34:35], v[14:15]
	ds_bpermute_b32 v46, v149, v51
	s_waitcnt lgkmcnt(0)
	v_add_f32_e32 v46, v51, v46
	ds_bpermute_b32 v47, v150, v46
	s_waitcnt lgkmcnt(0)
	v_add_f32_e32 v46, v46, v47
	ds_bpermute_b32 v47, v151, v46
	s_waitcnt lgkmcnt(0)
	v_add_f32_e32 v46, v46, v47
	ds_bpermute_b32 v47, v152, v46
	s_waitcnt lgkmcnt(0)
	v_add_f32_e32 v46, v46, v47
	v_fmamk_f32 v46, v46, 0x3a800000, v153
	v_mul_f32_e32 v47, 0x4f800000, v46
	v_cmp_gt_f32_e32 vcc, s17, v46
	s_waitcnt vmcnt(0)
	v_pk_add_f32 v[40:41], v[40:41], 1.0 op_sel_hi:[1,0]
	v_pk_add_f32 v[38:39], v[38:39], 1.0 op_sel_hi:[1,0]
	v_pk_fma_f32 v[36:37], v[36:37], v[40:41], v[44:45]
	v_pk_fma_f32 v[34:35], v[34:35], v[38:39], v[42:43]
	v_cvt_pk_bf16_f32 v34, v34, v35
	v_cvt_pk_bf16_f32 v35, v36, v37
	global_store_dwordx2 v[104:105], v[34:35], off offset:1536
	global_load_dwordx4 v[34:37], v[118:119], off
	s_nop 0
	global_load_dwordx4 v[38:41], v[106:107], off
	v_cndmask_b32_e32 v42, v46, v47, vcc
	v_sqrt_f32_e32 v43, v42
	s_waitcnt vmcnt(0) lgkmcnt(0)
	v_pk_add_f32 v[36:37], v[36:37], 1.0 op_sel_hi:[1,0]
	v_add_u32_e32 v44, -1, v43
	v_add_u32_e32 v45, 1, v43
	v_fma_f32 v46, -v44, v43, v42
	v_fma_f32 v47, -v45, v43, v42
	v_cmp_ge_f32_e64 s[6:7], 0, v46
	v_pk_add_f32 v[34:35], v[34:35], 1.0 op_sel_hi:[1,0]
	s_nop 0
	v_cndmask_b32_e64 v43, v43, v44, s[6:7]
	v_cmp_lt_f32_e64 s[6:7], 0, v47
	s_nop 1
	v_cndmask_b32_e64 v43, v43, v45, s[6:7]
	v_mul_f32_e32 v44, 0x37800000, v43
	v_cndmask_b32_e32 v43, v43, v44, vcc
	v_cmp_class_f32_e32 vcc, v42, v154
	s_nop 1
	v_cndmask_b32_e32 v42, v43, v42, vcc
	v_div_scale_f32 v43, s[6:7], v42, v42, 1.0
	v_rcp_f32_e32 v45, v43
	v_div_scale_f32 v44, vcc, 1.0, v42, 1.0
	v_fma_f32 v46, -v43, v45, 1.0
	v_fmac_f32_e32 v45, v46, v45
	v_mul_f32_e32 v46, v44, v45
	v_fma_f32 v47, -v43, v46, v44
	v_fmac_f32_e32 v46, v47, v45
	v_fma_f32 v43, -v43, v46, v44
	v_div_fmas_f32 v43, v43, v45, v46
	v_div_fixup_f32 v42, v43, v42, 1.0
	v_pk_mul_f32 v[32:33], v[32:33], v[42:43] op_sel_hi:[1,0]
	v_pk_mul_f32 v[30:31], v[30:31], v[42:43] op_sel_hi:[1,0]
	v_pk_mul_f32 v[32:33], v[32:33], v[4:5]
	v_pk_mul_f32 v[30:31], v[30:31], v[2:3]
	v_pk_fma_f32 v[32:33], v[32:33], v[36:37], v[40:41]
	v_pk_fma_f32 v[30:31], v[30:31], v[34:35], v[38:39]
	v_cvt_pk_bf16_f32 v30, v30, v31
	v_cvt_pk_bf16_f32 v31, v32, v33
	global_store_dwordx2 v[104:105], v[30:31], off offset:2048
	global_load_dwordx4 v[30:33], v[114:115], off
	s_nop 0
	global_load_dwordx4 v[34:37], v[106:107], off offset:1024
	v_pk_mul_f32 v[28:29], v[28:29], v[42:43] op_sel_hi:[1,0]
	v_pk_mul_f32 v[26:27], v[26:27], v[42:43] op_sel_hi:[1,0]
	v_pk_mul_f32 v[28:29], v[28:29], v[8:9]
	v_pk_mul_f32 v[26:27], v[26:27], v[6:7]
	v_lshl_add_u64 v[38:39], s[40:41], 0, v[98:99]
	v_pk_mul_f32 v[24:25], v[24:25], v[42:43] op_sel_hi:[1,0]
	v_pk_mul_f32 v[22:23], v[22:23], v[42:43] op_sel_hi:[1,0]
	v_pk_mul_f32 v[24:25], v[24:25], v[12:13]
	v_pk_mul_f32 v[22:23], v[22:23], v[10:11]
	v_pk_mul_f32 v[20:21], v[20:21], v[42:43] op_sel_hi:[1,0]
	v_pk_mul_f32 v[18:19], v[18:19], v[42:43] op_sel_hi:[1,0]
	v_pk_mul_f32 v[20:21], v[20:21], v[16:17]
	v_pk_mul_f32 v[18:19], v[18:19], v[14:15]
	s_waitcnt vmcnt(0) lgkmcnt(0)
	v_pk_add_f32 v[32:33], v[32:33], 1.0 op_sel_hi:[1,0]
	v_pk_add_f32 v[30:31], v[30:31], 1.0 op_sel_hi:[1,0]
	v_pk_fma_f32 v[28:29], v[28:29], v[32:33], v[36:37]
	v_pk_fma_f32 v[26:27], v[26:27], v[30:31], v[34:35]
	v_cvt_pk_bf16_f32 v26, v26, v27
	v_cvt_pk_bf16_f32 v27, v28, v29
	global_store_dwordx2 v[104:105], v[26:27], off offset:2560
	global_load_dwordx4 v[26:29], v[38:39], off
	s_nop 0
	global_load_dwordx4 v[30:33], v[106:107], off offset:2048
	v_lshl_add_u64 v[34:35], s[40:41], 0, v[100:101]
	s_waitcnt vmcnt(0) lgkmcnt(0)
	v_pk_add_f32 v[28:29], v[28:29], 1.0 op_sel_hi:[1,0]
	v_pk_add_f32 v[26:27], v[26:27], 1.0 op_sel_hi:[1,0]
	v_pk_fma_f32 v[24:25], v[24:25], v[28:29], v[32:33]
	v_pk_fma_f32 v[22:23], v[22:23], v[26:27], v[30:31]
	v_cvt_pk_bf16_f32 v22, v22, v23
	v_cvt_pk_bf16_f32 v23, v24, v25
	global_store_dwordx2 v[104:105], v[22:23], off offset:3072
	global_load_dwordx4 v[22:25], v[34:35], off
	s_nop 0
	global_load_dwordx4 v[26:29], v[106:107], off offset:3072
	s_waitcnt vmcnt(0) lgkmcnt(0)
	v_pk_add_f32 v[24:25], v[24:25], 1.0 op_sel_hi:[1,0]
	v_pk_add_f32 v[22:23], v[22:23], 1.0 op_sel_hi:[1,0]
	v_pk_fma_f32 v[20:21], v[20:21], v[24:25], v[28:29]
	v_pk_fma_f32 v[18:19], v[18:19], v[22:23], v[26:27]
	v_cvt_pk_bf16_f32 v18, v18, v19
	v_cvt_pk_bf16_f32 v19, v20, v21
	global_store_dwordx2 v[104:105], v[18:19], off offset:3584
	s_cbranch_scc1 .LBB0_3194

.LBB0_3341:
	v_lshl_add_u64 v[18:19], s[12:13], 0, v[94:95]
	v_lshl_add_u64 v[22:23], s[12:13], 0, v[92:93]
	v_add_co_u32_e32 v20, vcc, 0x7800000, v18
	v_add_co_u32_e64 v102, s[6:7], s28, v22
	s_nop 0
	v_addc_co_u32_e32 v21, vcc, 0, v19, vcc
	v_addc_co_u32_e64 v103, s[6:7], 0, v23, s[6:7]
	v_add_co_u32_e64 v104, s[6:7], s29, v22
	v_add_co_u32_e32 v22, vcc, 0x7801000, v18
	s_nop 0
	v_addc_co_u32_e64 v105, s[6:7], 0, v23, s[6:7]
	global_load_dwordx4 v[78:81], v[20:21], off
	global_load_dwordx4 v[74:77], v[20:21], off offset:1024
	global_load_dwordx4 v[70:73], v[20:21], off offset:2048
	global_load_dwordx4 v[66:69], v[20:21], off offset:3072
	v_addc_co_u32_e32 v23, vcc, 0, v19, vcc
	v_add_co_u32_e32 v20, vcc, 0x7802000, v18
	global_load_dwordx4 v[62:65], v[22:23], off
	global_load_dwordx4 v[58:61], v[22:23], off offset:1024
	global_load_dwordx4 v[54:57], v[22:23], off offset:2048
	global_load_dwordx4 v[50:53], v[22:23], off offset:3072
	v_addc_co_u32_e32 v21, vcc, 0, v19, vcc
	v_add_co_u32_e32 v82, vcc, 0x7803000, v18
	global_load_dwordx4 v[46:49], v[20:21], off
	global_load_dwordx4 v[42:45], v[20:21], off offset:1024
	global_load_dwordx4 v[38:41], v[20:21], off offset:2048
	global_load_dwordx4 v[34:37], v[20:21], off offset:3072
	v_addc_co_u32_e32 v83, vcc, 0, v19, vcc
	global_load_dwordx4 v[30:33], v[82:83], off
	global_load_dwordx4 v[26:29], v[82:83], off offset:1024
	global_load_dwordx4 v[22:25], v[82:83], off offset:2048
	global_load_dwordx4 v[18:21], v[82:83], off offset:3072
	s_add_i32 s30, s8, 32
	s_add_i32 s10, s8, 0xffffc022
	s_ashr_i32 s9, s30, 13
	s_cmpk_lt_i32 s30, 0x4000
	s_cselect_b32 s6, s9, s10
	s_addk_i32 s6, 0x82
	s_mul_hi_i32 s7, s6, 0x9000
	s_mul_i32 s6, s6, 0x9000
	s_add_u32 s6, s14, s6
	s_addc_u32 s7, s15, s7
	s_add_u32 s10, s6, 0x1000
	s_addc_u32 s11, s7, 0
	v_lshl_add_u64 v[124:125], s[6:7], 0, v[90:91]
	v_lshl_add_u64 v[86:87], s[10:11], 0, v[90:91]
	global_load_dwordx4 v[82:85], v[124:125], off
	s_add_i32 s6, s8, 0xffffc023
	global_load_dwordx4 v[86:89], v[86:87], off
	s_cmpk_lt_i32 s30, 0x3fff
	s_cselect_b32 s6, s9, s6
	s_addk_i32 s6, 0x82
	s_mul_hi_i32 s7, s6, 0x9000
	s_mul_i32 s6, s6, 0x9000
	s_add_u32 s6, s14, s6
	s_addc_u32 s7, s15, s7
	v_lshl_add_u64 v[134:135], s[10:11], 0, v[96:97]
	v_lshl_add_u64 v[130:131], s[10:11], 0, v[98:99]
	v_lshl_add_u64 v[128:129], s[10:11], 0, v[100:101]
	s_add_u32 s10, s6, 0x1000
	v_lshl_add_u64 v[110:111], s[6:7], 0, v[90:91]
	s_addc_u32 s11, s7, 0
	s_add_i32 s6, s8, 0xffffc024
	s_cmpk_lt_i32 s30, 0x3ffe
	s_cselect_b32 s6, s9, s6
	s_addk_i32 s6, 0x82
	s_mul_hi_i32 s7, s6, 0x9000
	s_mul_i32 s6, s6, 0x9000
	v_lshl_add_u64 v[126:127], s[10:11], 0, v[90:91]
	v_lshl_add_u64 v[120:121], s[10:11], 0, v[96:97]
	v_lshl_add_u64 v[116:117], s[10:11], 0, v[98:99]
	v_lshl_add_u64 v[112:113], s[10:11], 0, v[100:101]
	s_add_u32 s10, s14, s6
	s_addc_u32 s11, s15, s7
	s_add_u32 s6, s10, 0x1000
	s_addc_u32 s7, s11, 0
	s_addk_i32 s8, 0xc025
	s_cmpk_lt_i32 s30, 0x3ffd
	v_lshl_add_u64 v[138:139], s[6:7], 0, v[90:91]
	v_lshl_add_u64 v[136:137], s[6:7], 0, v[96:97]
	v_lshl_add_u64 v[132:133], s[6:7], 0, v[98:99]
	v_lshl_add_u64 v[122:123], s[6:7], 0, v[100:101]
	s_cselect_b32 s6, s9, s8
	s_addk_i32 s6, 0x82
	s_mul_hi_i32 s7, s6, 0x9000
	s_mul_i32 s6, s6, 0x9000
	s_add_u32 s6, s14, s6
	s_addc_u32 s7, s15, s7
	s_add_u32 s22, s6, 0x1000
	v_lshl_add_u64 v[106:107], s[6:7], 0, v[90:91]
	s_addc_u32 s23, s7, 0
	v_lshl_add_u64 v[108:109], s[10:11], 0, v[90:91]
	v_lshl_add_u64 v[118:119], s[22:23], 0, v[90:91]
	v_lshl_add_u64 v[114:115], s[22:23], 0, v[96:97]
	v_lshl_add_u64 v[92:93], v[92:93], 0, s[16:17]
	s_waitcnt vmcnt(0) lgkmcnt(0)
	v_pk_mul_f32 v[140:141], v[80:81], v[80:81]
	v_pk_mul_f32 v[142:143], v[78:79], v[78:79]
	v_pk_mul_f32 v[144:145], v[76:77], v[76:77]
	v_pk_mul_f32 v[146:147], v[74:75], v[74:75]
	v_mul_f32_e32 v156, v71, v71
	v_mul_f32_e32 v158, v73, v73
	v_mul_f32_e32 v169, v68, v68
	v_mul_f32_e32 v171, v69, v69
	v_pk_mov_b32 v[160:161], v[142:143], v[140:141] op_sel:[1,0]
	v_mov_b32_e32 v143, v141
	v_pk_mov_b32 v[140:141], v[146:147], v[144:145] op_sel:[1,0]
	v_mov_b32_e32 v147, v145
	v_pk_fma_f32 v[144:145], v[70:71], v[70:71], v[156:157] op_sel_hi:[1,1,0]
	v_pk_fma_f32 v[156:157], v[72:73], v[72:73], v[158:159] op_sel_hi:[1,1,0]
	v_pk_mul_f32 v[158:159], v[64:65], v[64:65]
	v_pk_mul_f32 v[162:163], v[62:63], v[62:63]
	v_pk_mul_f32 v[164:165], v[60:61], v[60:61]
	v_pk_mul_f32 v[166:167], v[58:59], v[58:59]
	v_mul_f32_e32 v168, v55, v55
	v_mul_f32_e32 v170, v57, v57
	v_pk_add_f32 v[142:143], v[160:161], v[142:143]
	v_pk_add_f32 v[140:141], v[140:141], v[146:147]
	v_mov_b32_e32 v145, v169
	v_mov_b32_e32 v157, v171
	v_pk_mov_b32 v[146:147], v[162:163], v[158:159] op_sel:[1,0]
	v_mov_b32_e32 v163, v159
	v_pk_mov_b32 v[158:159], v[166:167], v[164:165] op_sel:[1,0]
	v_mov_b32_e32 v167, v165
	v_pk_fma_f32 v[160:161], v[54:55], v[54:55], v[168:169] op_sel_hi:[1,1,0]
	v_pk_fma_f32 v[164:165], v[56:57], v[56:57], v[170:171] op_sel_hi:[1,1,0]
	v_pk_mul_f32 v[168:169], v[48:49], v[48:49]
	v_pk_mul_f32 v[170:171], v[46:47], v[46:47]
	v_pk_mul_f32 v[172:173], v[44:45], v[44:45]
	v_pk_mul_f32 v[174:175], v[42:43], v[42:43]
	v_mul_f32_e32 v155, v66, v66
	v_mul_f32_e32 v179, v67, v67
	v_mul_f32_e32 v177, v52, v52
	v_mul_f32_e32 v184, v53, v53
	v_mul_f32_e32 v176, v39, v39
	v_mul_f32_e32 v178, v41, v41
	v_pk_add_f32 v[180:181], v[142:143], v[142:143] op_sel:[0,1] op_sel_hi:[1,0]
	v_pk_add_f32 v[182:183], v[140:141], v[140:141] op_sel:[0,1] op_sel_hi:[1,0]
	v_pk_add_f32 v[156:157], v[144:145], v[156:157]
	v_pk_add_f32 v[140:141], v[146:147], v[162:163]
	v_pk_add_f32 v[142:143], v[158:159], v[166:167]
	v_pk_mov_b32 v[144:145], v[170:171], v[168:169] op_sel:[1,0]
	v_mov_b32_e32 v171, v169
	v_pk_mov_b32 v[146:147], v[174:175], v[172:173] op_sel:[1,0]
	v_mov_b32_e32 v175, v173
	v_mul_f32_e32 v185, v50, v50
	v_mul_f32_e32 v190, v51, v51
	v_mul_f32_e32 v193, v36, v36
	v_mul_f32_e32 v194, v37, v37
	v_mov_b32_e32 v161, v177
	v_mov_b32_e32 v165, v184
	v_pk_fma_f32 v[158:159], v[38:39], v[38:39], v[176:177] op_sel_hi:[1,1,0]
	v_pk_fma_f32 v[162:163], v[40:41], v[40:41], v[178:179] op_sel_hi:[1,1,0]
	v_pk_mul_f32 v[166:167], v[32:33], v[32:33]
	v_pk_mul_f32 v[168:169], v[30:31], v[30:31]
	v_pk_mul_f32 v[172:173], v[28:29], v[28:29]
	v_pk_mul_f32 v[176:177], v[26:27], v[26:27]
	v_mov_b32_e32 v181, v155
	v_mov_b32_e32 v183, v179
	v_pk_add_f32 v[186:187], v[140:141], v[140:141] op_sel:[0,1] op_sel_hi:[1,0]
	v_pk_add_f32 v[188:189], v[142:143], v[142:143] op_sel:[0,1] op_sel_hi:[1,0]
	v_pk_add_f32 v[144:145], v[144:145], v[170:171]
	v_pk_add_f32 v[146:147], v[146:147], v[174:175]
	v_mul_f32_e32 v191, v34, v34
	v_mul_f32_e32 v192, v35, v35
	v_pk_add_f32 v[160:161], v[160:161], v[164:165]
	v_mov_b32_e32 v159, v193
	v_mov_b32_e32 v163, v194
	v_pk_mov_b32 v[164:165], v[168:169], v[166:167] op_sel:[1,0]
	v_mov_b32_e32 v169, v167
	v_pk_mov_b32 v[166:167], v[176:177], v[172:173] op_sel:[1,0]
	v_mov_b32_e32 v177, v173
	v_pk_add_f32 v[170:171], v[180:181], v[182:183]
	v_mov_b32_e32 v187, v185
	v_mov_b32_e32 v189, v190
	v_pk_add_f32 v[172:173], v[144:145], v[144:145] op_sel:[0,1] op_sel_hi:[1,0]
	v_pk_add_f32 v[174:175], v[146:147], v[146:147] op_sel:[0,1] op_sel_hi:[1,0]
	v_pk_add_f32 v[158:159], v[158:159], v[162:163]
	v_pk_add_f32 v[156:157], v[170:171], v[156:157]
	v_pk_add_f32 v[162:163], v[186:187], v[188:189]
	v_mov_b32_e32 v173, v191
	v_mov_b32_e32 v175, v192
	v_add_f32_e32 v155, v156, v157
	v_pk_add_f32 v[156:157], v[162:163], v[160:161]
	v_pk_add_f32 v[160:161], v[172:173], v[174:175]
	v_add_f32_e32 v162, v156, v157
	v_pk_add_f32 v[156:157], v[160:161], v[158:159]
	v_add_f32_e32 v156, v156, v157
	v_pk_add_f32 v[144:145], v[164:165], v[168:169]
	s_waitcnt lgkmcnt(0)
	s_nop 1
	v_add_f32_dpp v155, v155, v155 quad_perm:[1,0,3,2] row_mask:0xf bank_mask:0xf
	s_waitcnt lgkmcnt(0)
	s_nop 1
	v_add_f32_dpp v159, v162, v162 quad_perm:[1,0,3,2] row_mask:0xf bank_mask:0xf
	s_waitcnt lgkmcnt(0)
	s_nop 1
	v_add_f32_dpp v156, v156, v156 quad_perm:[1,0,3,2] row_mask:0xf bank_mask:0xf
	s_waitcnt lgkmcnt(0)
	s_nop 1
	v_add_f32_dpp v155, v155, v155 quad_perm:[2,3,0,1] row_mask:0xf bank_mask:0xf
	s_waitcnt lgkmcnt(0)
	s_nop 1
	v_add_f32_dpp v159, v159, v159 quad_perm:[2,3,0,1] row_mask:0xf bank_mask:0xf
	s_waitcnt lgkmcnt(0)
	s_nop 1
	v_add_f32_dpp v156, v156, v156 quad_perm:[2,3,0,1] row_mask:0xf bank_mask:0xf
	s_waitcnt lgkmcnt(0)
	s_nop 1
	v_add_f32_dpp v155, v155, v155 row_half_mirror row_mask:0xf bank_mask:0xf
	s_waitcnt lgkmcnt(0)
	s_nop 1
	v_add_f32_dpp v159, v159, v159 row_half_mirror row_mask:0xf bank_mask:0xf
	s_waitcnt lgkmcnt(0)
	s_nop 1
	v_add_f32_dpp v156, v156, v156 row_half_mirror row_mask:0xf bank_mask:0xf
	s_waitcnt lgkmcnt(0)
	s_nop 1
	v_add_f32_dpp v155, v155, v155 row_mirror row_mask:0xf bank_mask:0xf
	ds_bpermute_b32 v158, v151, v155
	s_waitcnt lgkmcnt(2)
	s_nop 1
	v_add_f32_dpp v159, v159, v159 row_mirror row_mask:0xf bank_mask:0xf
	ds_bpermute_b32 v160, v151, v159
	s_waitcnt lgkmcnt(2)
	s_nop 1
	v_add_f32_dpp v156, v156, v156 row_mirror row_mask:0xf bank_mask:0xf
	ds_bpermute_b32 v157, v151, v156
	s_waitcnt lgkmcnt(2)
	v_add_f32_e32 v155, v155, v158
	ds_bpermute_b32 v158, v152, v155
	s_waitcnt lgkmcnt(2)
	v_add_f32_e32 v159, v159, v160
	ds_bpermute_b32 v160, v152, v159
	s_waitcnt lgkmcnt(2)
	v_add_f32_e32 v156, v156, v157
	ds_bpermute_b32 v157, v152, v156
	s_waitcnt lgkmcnt(2)
	v_add_f32_e32 v155, v155, v158
	v_fmamk_f32 v155, v155, 0x3a800000, v153
	s_waitcnt lgkmcnt(1)
	v_add_f32_e32 v158, v159, v160
	v_mul_f32_e32 v159, 0x4f800000, v155
	v_cmp_gt_f32_e32 vcc, s25, v155
	v_fmamk_f32 v158, v158, 0x3a800000, v153
	s_waitcnt lgkmcnt(0)
	v_add_f32_e32 v156, v156, v157
	v_cndmask_b32_e32 v155, v155, v159, vcc
	v_mul_f32_e32 v157, 0x4f800000, v158
	v_cmp_gt_f32_e64 s[6:7], s25, v158
	v_sqrt_f32_e32 v159, v155
	v_fmamk_f32 v156, v156, 0x3a800000, v153
	v_cndmask_b32_e64 v157, v158, v157, s[6:7]
	v_mul_f32_e32 v158, 0x4f800000, v156
	v_cmp_gt_f32_e64 s[8:9], s25, v156
	v_sqrt_f32_e32 v160, v157
	v_add_u32_e32 v161, -1, v159
	v_cndmask_b32_e64 v156, v156, v158, s[8:9]
	v_sqrt_f32_e32 v158, v156
	v_add_u32_e32 v162, 1, v159
	v_fma_f32 v163, -v161, v159, v155
	v_fma_f32 v164, -v162, v159, v155
	v_add_u32_e32 v165, -1, v160
	v_cmp_ge_f32_e64 s[10:11], 0, v163
	v_pk_add_f32 v[146:147], v[166:167], v[176:177]
	v_add_u32_e32 v166, 1, v160
	v_cndmask_b32_e64 v159, v159, v161, s[10:11]
	v_fma_f32 v161, -v165, v160, v157
	v_cmp_lt_f32_e64 s[10:11], 0, v164
	v_fma_f32 v163, -v166, v160, v157
	v_add_u32_e32 v167, -1, v158
	v_cndmask_b32_e64 v159, v159, v162, s[10:11]
	v_cmp_ge_f32_e64 s[10:11], 0, v161
	v_add_u32_e32 v168, 1, v158
	v_fma_f32 v161, -v167, v158, v156
	v_cndmask_b32_e64 v160, v160, v165, s[10:11]
	v_cmp_lt_f32_e64 s[10:11], 0, v163
	v_fma_f32 v162, -v168, v158, v156
	v_mul_f32_e32 v163, 0x37800000, v159
	v_cndmask_b32_e64 v160, v160, v166, s[10:11]
	v_cmp_ge_f32_e64 s[10:11], 0, v161
	v_cndmask_b32_e32 v159, v159, v163, vcc
	v_cmp_class_f32_e32 vcc, v155, v154
	v_cndmask_b32_e64 v158, v158, v167, s[10:11]
	v_cmp_lt_f32_e64 s[10:11], 0, v162
	v_mul_f32_e32 v161, 0x37800000, v160
	v_cndmask_b32_e32 v155, v159, v155, vcc
	v_cndmask_b32_e64 v158, v158, v168, s[10:11]
	v_cndmask_b32_e64 v159, v160, v161, s[6:7]
	v_cmp_class_f32_e32 vcc, v157, v154
	v_mul_f32_e32 v160, 0x37800000, v158
	v_div_scale_f32 v161, s[6:7], v155, v155, 1.0
	v_cndmask_b32_e32 v157, v159, v157, vcc
	v_cndmask_b32_e64 v158, v158, v160, s[8:9]
	v_cmp_class_f32_e32 vcc, v156, v154
	v_rcp_f32_e32 v159, v161
	v_div_scale_f32 v160, s[8:9], v157, v157, 1.0
	v_cndmask_b32_e32 v158, v158, v156, vcc
	v_rcp_f32_e32 v164, v160
	v_div_scale_f32 v165, s[10:11], v158, v158, 1.0
	v_rcp_f32_e32 v167, v165
	v_fma_f32 v156, -v161, v159, 1.0
	v_div_scale_f32 v162, s[6:7], 1.0, v155, 1.0
	v_fmac_f32_e32 v159, v156, v159
	v_fma_f32 v156, -v160, v164, 1.0
	v_mul_f32_e32 v168, v162, v159
	v_div_scale_f32 v163, s[8:9], 1.0, v157, 1.0
	v_fmac_f32_e32 v164, v156, v164
	v_fma_f32 v156, -v165, v167, 1.0
	v_fma_f32 v169, -v161, v168, v162
	v_div_scale_f32 v166, s[10:11], 1.0, v158, 1.0
	v_mul_f32_e32 v170, v163, v164
	v_fmac_f32_e32 v167, v156, v167
	v_fmac_f32_e32 v168, v169, v159
	v_fma_f32 v156, -v160, v170, v163
	v_mul_f32_e32 v169, v166, v167
	v_fma_f32 v161, -v161, v168, v162
	s_mov_b64 vcc, s[6:7]
	v_fmac_f32_e32 v170, v156, v164
	v_fma_f32 v156, -v165, v169, v166
	v_div_fmas_f32 v159, v161, v159, v168
	v_fma_f32 v160, -v160, v170, v163
	v_fmac_f32_e32 v169, v156, v167
	v_div_fixup_f32 v156, v159, v155, 1.0
	s_mov_b64 vcc, s[8:9]
	v_div_fmas_f32 v155, v160, v164, v170
	v_fma_f32 v159, -v165, v169, v166
	v_pk_mul_f32 v[80:81], v[80:81], v[156:157] op_sel_hi:[1,0]
	v_pk_mul_f32 v[78:79], v[78:79], v[156:157] op_sel_hi:[1,0]
	s_mov_b64 vcc, s[10:11]
	v_pk_add_f32 v[88:89], v[88:89], 1.0 op_sel_hi:[1,0]
	v_pk_add_f32 v[86:87], v[86:87], 1.0 op_sel_hi:[1,0]
	v_pk_mul_f32 v[76:77], v[76:77], v[156:157] op_sel_hi:[1,0]
	v_pk_mul_f32 v[74:75], v[74:75], v[156:157] op_sel_hi:[1,0]
	v_pk_mul_f32 v[72:73], v[72:73], v[156:157] op_sel_hi:[1,0]
	v_pk_mul_f32 v[70:71], v[70:71], v[156:157] op_sel_hi:[1,0]
	v_pk_mul_f32 v[68:69], v[68:69], v[156:157] op_sel_hi:[1,0]
	v_pk_mul_f32 v[66:67], v[66:67], v[156:157] op_sel_hi:[1,0]
	v_div_fixup_f32 v156, v155, v157, 1.0
	v_div_fmas_f32 v155, v159, v167, v169
	v_pk_mul_f32 v[78:79], v[78:79], v[2:3]
	v_pk_mul_f32 v[80:81], v[80:81], v[4:5]
	v_pk_mul_f32 v[64:65], v[64:65], v[156:157] op_sel_hi:[1,0]
	v_pk_mul_f32 v[62:63], v[62:63], v[156:157] op_sel_hi:[1,0]
	v_pk_mul_f32 v[60:61], v[60:61], v[156:157] op_sel_hi:[1,0]
	v_pk_mul_f32 v[58:59], v[58:59], v[156:157] op_sel_hi:[1,0]
	v_pk_mul_f32 v[56:57], v[56:57], v[156:157] op_sel_hi:[1,0]
	v_pk_mul_f32 v[54:55], v[54:55], v[156:157] op_sel_hi:[1,0]
	v_pk_mul_f32 v[52:53], v[52:53], v[156:157] op_sel_hi:[1,0]
	v_pk_mul_f32 v[156:157], v[50:51], v[156:157] op_sel_hi:[1,0]
	v_div_fixup_f32 v50, v155, v158, 1.0
	v_pk_fma_f32 v[80:81], v[80:81], v[88:89], v[84:85]
	v_pk_fma_f32 v[78:79], v[78:79], v[86:87], v[82:83]
	v_pk_mul_f32 v[86:87], v[52:53], v[16:17]
	v_pk_mul_f32 v[48:49], v[48:49], v[50:51] op_sel_hi:[1,0]
	v_pk_mul_f32 v[46:47], v[46:47], v[50:51] op_sel_hi:[1,0]
	v_pk_mul_f32 v[82:83], v[54:55], v[10:11]
	v_pk_mul_f32 v[84:85], v[156:157], v[14:15]
	v_pk_mul_f32 v[88:89], v[46:47], v[2:3]
	v_pk_mul_f32 v[156:157], v[48:49], v[4:5]
	v_cvt_pk_bf16_f32 v46, v78, v79
	v_cvt_pk_bf16_f32 v47, v80, v81
	global_store_dwordx2 v[102:103], v[46:47], off
	global_load_dwordx4 v[46:49], v[134:135], off
	s_nop 0
	global_load_dwordx4 v[52:55], v[124:125], off offset:1024
	v_pk_mul_f32 v[74:75], v[74:75], v[6:7]
	v_pk_mul_f32 v[76:77], v[76:77], v[8:9]
	v_pk_mul_f32 v[70:71], v[70:71], v[10:11]
	v_pk_mul_f32 v[72:73], v[72:73], v[12:13]
	v_pk_mul_f32 v[66:67], v[66:67], v[14:15]
	v_pk_mul_f32 v[68:69], v[68:69], v[16:17]
	v_pk_mul_f32 v[62:63], v[62:63], v[2:3]
	v_pk_mul_f32 v[64:65], v[64:65], v[4:5]
	v_pk_mul_f32 v[58:59], v[58:59], v[6:7]
	v_pk_mul_f32 v[60:61], v[60:61], v[8:9]
	v_pk_mul_f32 v[56:57], v[56:57], v[12:13]
	v_mul_f32_e32 v178, v23, v23
	v_mul_f32_e32 v184, v25, v25
	v_mul_f32_e32 v195, v18, v18
	v_mul_f32_e32 v196, v19, v19
	v_mul_f32_e32 v197, v20, v20
	v_mul_f32_e32 v198, v21, v21
	v_pk_fma_f32 v[140:141], v[22:23], v[22:23], v[178:179] op_sel_hi:[1,1,0]
	v_pk_fma_f32 v[142:143], v[24:25], v[24:25], v[184:185] op_sel_hi:[1,1,0]
	v_mov_b32_e32 v141, v197
	v_mov_b32_e32 v143, v198
	v_lshl_add_u64 v[94:95], v[94:95], 0, s[18:19]
	s_mov_b32 s8, s30
	s_cmp_lt_i32 s30, s24
	s_waitcnt vmcnt(0) lgkmcnt(0)
	v_pk_add_f32 v[48:49], v[48:49], 1.0 op_sel_hi:[1,0]
	v_pk_add_f32 v[46:47], v[46:47], 1.0 op_sel_hi:[1,0]
	v_pk_fma_f32 v[48:49], v[76:77], v[48:49], v[54:55]
	v_pk_fma_f32 v[46:47], v[74:75], v[46:47], v[52:53]
	v_cvt_pk_bf16_f32 v46, v46, v47
	v_cvt_pk_bf16_f32 v47, v48, v49
	global_store_dwordx2 v[102:103], v[46:47], off offset:512
	global_load_dwordx4 v[46:49], v[130:131], off
	s_nop 0
	global_load_dwordx4 v[52:55], v[124:125], off offset:2048
	s_waitcnt vmcnt(0) lgkmcnt(0)
	v_pk_add_f32 v[48:49], v[48:49], 1.0 op_sel_hi:[1,0]
	v_pk_add_f32 v[46:47], v[46:47], 1.0 op_sel_hi:[1,0]
	v_pk_fma_f32 v[48:49], v[72:73], v[48:49], v[54:55]
	v_pk_fma_f32 v[46:47], v[70:71], v[46:47], v[52:53]
	v_cvt_pk_bf16_f32 v46, v46, v47
	v_cvt_pk_bf16_f32 v47, v48, v49
	global_store_dwordx2 v[102:103], v[46:47], off offset:1024
	global_load_dwordx4 v[46:49], v[128:129], off
	s_nop 0
	global_load_dwordx4 v[52:55], v[124:125], off offset:3072
	s_waitcnt vmcnt(0) lgkmcnt(0)
	v_pk_add_f32 v[48:49], v[48:49], 1.0 op_sel_hi:[1,0]
	v_pk_add_f32 v[46:47], v[46:47], 1.0 op_sel_hi:[1,0]
	v_pk_fma_f32 v[48:49], v[68:69], v[48:49], v[54:55]
	v_pk_fma_f32 v[46:47], v[66:67], v[46:47], v[52:53]
	v_cvt_pk_bf16_f32 v46, v46, v47
	v_cvt_pk_bf16_f32 v47, v48, v49
	global_store_dwordx2 v[102:103], v[46:47], off offset:1536
	global_load_dwordx4 v[46:49], v[126:127], off
	s_nop 0
	global_load_dwordx4 v[52:55], v[110:111], off
	s_waitcnt vmcnt(0) lgkmcnt(0)
	v_pk_add_f32 v[48:49], v[48:49], 1.0 op_sel_hi:[1,0]
	v_pk_add_f32 v[46:47], v[46:47], 1.0 op_sel_hi:[1,0]
	v_pk_fma_f32 v[48:49], v[64:65], v[48:49], v[54:55]
	v_pk_fma_f32 v[46:47], v[62:63], v[46:47], v[52:53]
	v_cvt_pk_bf16_f32 v46, v46, v47
	v_cvt_pk_bf16_f32 v47, v48, v49
	global_store_dwordx2 v[102:103], v[46:47], off offset:2048
	global_load_dwordx4 v[46:49], v[120:121], off
	s_nop 0
	global_load_dwordx4 v[52:55], v[110:111], off offset:1024
	s_waitcnt vmcnt(0) lgkmcnt(0)
	v_pk_add_f32 v[48:49], v[48:49], 1.0 op_sel_hi:[1,0]
	v_pk_add_f32 v[46:47], v[46:47], 1.0 op_sel_hi:[1,0]
	v_pk_fma_f32 v[48:49], v[60:61], v[48:49], v[54:55]
	v_pk_fma_f32 v[46:47], v[58:59], v[46:47], v[52:53]
	v_cvt_pk_bf16_f32 v46, v46, v47
	v_cvt_pk_bf16_f32 v47, v48, v49
	global_store_dwordx2 v[102:103], v[46:47], off offset:2560
	global_load_dwordx4 v[46:49], v[116:117], off
	s_nop 0
	global_load_dwordx4 v[52:55], v[110:111], off offset:2048
	v_pk_add_f32 v[58:59], v[146:147], v[146:147] op_sel:[0,1] op_sel_hi:[1,0]
	v_pk_add_f32 v[60:61], v[140:141], v[142:143]
	v_mov_b32_e32 v59, v196
	s_waitcnt vmcnt(0) lgkmcnt(0)
	v_pk_add_f32 v[48:49], v[48:49], 1.0 op_sel_hi:[1,0]
	v_pk_add_f32 v[46:47], v[46:47], 1.0 op_sel_hi:[1,0]
	v_pk_fma_f32 v[48:49], v[56:57], v[48:49], v[54:55]
	v_pk_fma_f32 v[46:47], v[82:83], v[46:47], v[52:53]
	v_cvt_pk_bf16_f32 v46, v46, v47
	v_cvt_pk_bf16_f32 v47, v48, v49
	global_store_dwordx2 v[102:103], v[46:47], off offset:3072
	global_load_dwordx4 v[46:49], v[112:113], off
	s_nop 0
	global_load_dwordx4 v[52:55], v[110:111], off offset:3072
	v_pk_add_f32 v[56:57], v[144:145], v[144:145] op_sel:[0,1] op_sel_hi:[1,0]
	s_waitcnt vmcnt(0) lgkmcnt(0)
	v_pk_add_f32 v[48:49], v[48:49], 1.0 op_sel_hi:[1,0]
	v_pk_add_f32 v[46:47], v[46:47], 1.0 op_sel_hi:[1,0]
	v_pk_fma_f32 v[48:49], v[86:87], v[48:49], v[54:55]
	v_pk_fma_f32 v[46:47], v[84:85], v[46:47], v[52:53]
	v_cvt_pk_bf16_f32 v46, v46, v47
	v_cvt_pk_bf16_f32 v47, v48, v49
	global_store_dwordx2 v[102:103], v[46:47], off offset:3584
	global_load_dwordx4 v[46:49], v[138:139], off
	s_nop 0
	global_load_dwordx4 v[52:55], v[108:109], off
	v_mov_b32_e32 v57, v195
	s_waitcnt vmcnt(0) lgkmcnt(0)
	v_pk_add_f32 v[48:49], v[48:49], 1.0 op_sel_hi:[1,0]
	v_pk_add_f32 v[46:47], v[46:47], 1.0 op_sel_hi:[1,0]
	v_pk_fma_f32 v[48:49], v[156:157], v[48:49], v[54:55]
	v_pk_fma_f32 v[46:47], v[88:89], v[46:47], v[52:53]
	v_bfe_u32 v51, v46, 16, 1
	v_bfe_u32 v52, v47, 16, 1
	v_add3_u32 v46, v46, v51, s26
	v_add3_u32 v47, v47, v52, s26
	v_lshrrev_b32_e32 v46, 16, v46
	v_and_or_b32 v46, v47, s27, v46
	v_cvt_pk_bf16_f32 v47, v48, v49
	global_store_dwordx2 v[104:105], v[46:47], off
	global_load_dwordx4 v[46:49], v[136:137], off
	s_nop 0
	global_load_dwordx4 v[52:55], v[108:109], off offset:1024
	v_pk_mul_f32 v[44:45], v[44:45], v[50:51] op_sel_hi:[1,0]
	v_pk_mul_f32 v[42:43], v[42:43], v[50:51] op_sel_hi:[1,0]
	v_pk_mul_f32 v[44:45], v[44:45], v[8:9]
	v_pk_mul_f32 v[42:43], v[42:43], v[6:7]
	s_waitcnt vmcnt(0) lgkmcnt(0)
	v_pk_add_f32 v[48:49], v[48:49], 1.0 op_sel_hi:[1,0]
	v_pk_add_f32 v[46:47], v[46:47], 1.0 op_sel_hi:[1,0]
	v_pk_fma_f32 v[44:45], v[44:45], v[48:49], v[54:55]
	v_pk_fma_f32 v[42:43], v[42:43], v[46:47], v[52:53]
	v_cvt_pk_bf16_f32 v42, v42, v43
	v_cvt_pk_bf16_f32 v43, v44, v45
	global_store_dwordx2 v[104:105], v[42:43], off offset:512
	global_load_dwordx4 v[42:45], v[132:133], off
	s_nop 0
	global_load_dwordx4 v[46:49], v[108:109], off offset:2048
	v_pk_add_f32 v[52:53], v[56:57], v[58:59]
	s_waitcnt vmcnt(0) lgkmcnt(0)
	v_pk_add_f32 v[44:45], v[44:45], 1.0 op_sel_hi:[1,0]
	v_pk_add_f32 v[52:53], v[52:53], v[60:61]
	v_pk_add_f32 v[42:43], v[42:43], 1.0 op_sel_hi:[1,0]
	v_add_f32_e32 v51, v52, v53
	s_waitcnt lgkmcnt(0)
	s_nop 1
	v_add_f32_dpp v51, v51, v51 quad_perm:[1,0,3,2] row_mask:0xf bank_mask:0xf
	ds_bpermute_b32 v52, v148, v51
	s_waitcnt lgkmcnt(0)
	v_add_f32_e32 v51, v51, v52
	v_pk_mul_f32 v[40:41], v[40:41], v[50:51] op_sel_hi:[1,0]
	v_pk_mul_f32 v[38:39], v[38:39], v[50:51] op_sel_hi:[1,0]
	v_pk_mul_f32 v[40:41], v[40:41], v[12:13]
	v_pk_mul_f32 v[38:39], v[38:39], v[10:11]
	v_pk_fma_f32 v[40:41], v[40:41], v[44:45], v[48:49]
	v_pk_fma_f32 v[38:39], v[38:39], v[42:43], v[46:47]
	v_cvt_pk_bf16_f32 v38, v38, v39
	v_cvt_pk_bf16_f32 v39, v40, v41
	global_store_dwordx2 v[104:105], v[38:39], off offset:1024
	global_load_dwordx4 v[38:41], v[122:123], off
	s_nop 0
	global_load_dwordx4 v[42:45], v[108:109], off offset:3072
	v_pk_mul_f32 v[36:37], v[36:37], v[50:51] op_sel_hi:[1,0]
	v_pk_mul_f32 v[34:35], v[34:35], v[50:51] op_sel_hi:[1,0]
	v_pk_mul_f32 v[36:37], v[36:37], v[16:17]
	v_pk_mul_f32 v[34:35], v[34:35], v[14:15]
	ds_bpermute_b32 v46, v149, v51
	s_waitcnt lgkmcnt(0)
	v_add_f32_e32 v46, v51, v46
	ds_bpermute_b32 v47, v150, v46
	s_waitcnt lgkmcnt(0)
	v_add_f32_e32 v46, v46, v47
	ds_bpermute_b32 v47, v151, v46
	s_waitcnt lgkmcnt(0)
	v_add_f32_e32 v46, v46, v47
	ds_bpermute_b32 v47, v152, v46
	s_waitcnt lgkmcnt(0)
	v_add_f32_e32 v46, v46, v47
	v_fmamk_f32 v46, v46, 0x3a800000, v153
	v_mul_f32_e32 v47, 0x4f800000, v46
	v_cmp_gt_f32_e32 vcc, s25, v46
	s_waitcnt vmcnt(0)
	v_pk_add_f32 v[40:41], v[40:41], 1.0 op_sel_hi:[1,0]
	v_pk_add_f32 v[38:39], v[38:39], 1.0 op_sel_hi:[1,0]
	v_pk_fma_f32 v[36:37], v[36:37], v[40:41], v[44:45]
	v_pk_fma_f32 v[34:35], v[34:35], v[38:39], v[42:43]
	v_cvt_pk_bf16_f32 v34, v34, v35
	v_cvt_pk_bf16_f32 v35, v36, v37
	global_store_dwordx2 v[104:105], v[34:35], off offset:1536
	global_load_dwordx4 v[34:37], v[118:119], off
	s_nop 0
	global_load_dwordx4 v[38:41], v[106:107], off
	v_cndmask_b32_e32 v42, v46, v47, vcc
	v_sqrt_f32_e32 v43, v42
	s_waitcnt vmcnt(0) lgkmcnt(0)
	v_pk_add_f32 v[36:37], v[36:37], 1.0 op_sel_hi:[1,0]
	v_add_u32_e32 v44, -1, v43
	v_add_u32_e32 v45, 1, v43
	v_fma_f32 v46, -v44, v43, v42
	v_fma_f32 v47, -v45, v43, v42
	v_cmp_ge_f32_e64 s[6:7], 0, v46
	v_pk_add_f32 v[34:35], v[34:35], 1.0 op_sel_hi:[1,0]
	s_nop 0
	v_cndmask_b32_e64 v43, v43, v44, s[6:7]
	v_cmp_lt_f32_e64 s[6:7], 0, v47
	s_nop 1
	v_cndmask_b32_e64 v43, v43, v45, s[6:7]
	v_mul_f32_e32 v44, 0x37800000, v43
	v_cndmask_b32_e32 v43, v43, v44, vcc
	v_cmp_class_f32_e32 vcc, v42, v154
	s_nop 1
	v_cndmask_b32_e32 v42, v43, v42, vcc
	v_div_scale_f32 v43, s[6:7], v42, v42, 1.0
	v_rcp_f32_e32 v45, v43
	v_div_scale_f32 v44, vcc, 1.0, v42, 1.0
	v_fma_f32 v46, -v43, v45, 1.0
	v_fmac_f32_e32 v45, v46, v45
	v_mul_f32_e32 v46, v44, v45
	v_fma_f32 v47, -v43, v46, v44
	v_fmac_f32_e32 v46, v47, v45
	v_fma_f32 v43, -v43, v46, v44
	v_div_fmas_f32 v43, v43, v45, v46
	v_div_fixup_f32 v42, v43, v42, 1.0
	v_pk_mul_f32 v[32:33], v[32:33], v[42:43] op_sel_hi:[1,0]
	v_pk_mul_f32 v[30:31], v[30:31], v[42:43] op_sel_hi:[1,0]
	v_pk_mul_f32 v[32:33], v[32:33], v[4:5]
	v_pk_mul_f32 v[30:31], v[30:31], v[2:3]
	v_pk_fma_f32 v[32:33], v[32:33], v[36:37], v[40:41]
	v_pk_fma_f32 v[30:31], v[30:31], v[34:35], v[38:39]
	v_cvt_pk_bf16_f32 v30, v30, v31
	v_cvt_pk_bf16_f32 v31, v32, v33
	global_store_dwordx2 v[104:105], v[30:31], off offset:2048
	global_load_dwordx4 v[30:33], v[114:115], off
	s_nop 0
	global_load_dwordx4 v[34:37], v[106:107], off offset:1024
	v_pk_mul_f32 v[28:29], v[28:29], v[42:43] op_sel_hi:[1,0]
	v_pk_mul_f32 v[26:27], v[26:27], v[42:43] op_sel_hi:[1,0]
	v_pk_mul_f32 v[28:29], v[28:29], v[8:9]
	v_pk_mul_f32 v[26:27], v[26:27], v[6:7]
	v_lshl_add_u64 v[38:39], s[22:23], 0, v[98:99]
	v_pk_mul_f32 v[24:25], v[24:25], v[42:43] op_sel_hi:[1,0]
	v_pk_mul_f32 v[22:23], v[22:23], v[42:43] op_sel_hi:[1,0]
	v_pk_mul_f32 v[24:25], v[24:25], v[12:13]
	v_pk_mul_f32 v[22:23], v[22:23], v[10:11]
	v_pk_mul_f32 v[20:21], v[20:21], v[42:43] op_sel_hi:[1,0]
	v_pk_mul_f32 v[18:19], v[18:19], v[42:43] op_sel_hi:[1,0]
	v_pk_mul_f32 v[20:21], v[20:21], v[16:17]
	v_pk_mul_f32 v[18:19], v[18:19], v[14:15]
	s_waitcnt vmcnt(0) lgkmcnt(0)
	v_pk_add_f32 v[32:33], v[32:33], 1.0 op_sel_hi:[1,0]
	v_pk_add_f32 v[30:31], v[30:31], 1.0 op_sel_hi:[1,0]
	v_pk_fma_f32 v[28:29], v[28:29], v[32:33], v[36:37]
	v_pk_fma_f32 v[26:27], v[26:27], v[30:31], v[34:35]
	v_cvt_pk_bf16_f32 v26, v26, v27
	v_cvt_pk_bf16_f32 v27, v28, v29
	global_store_dwordx2 v[104:105], v[26:27], off offset:2560
	global_load_dwordx4 v[26:29], v[38:39], off
	s_nop 0
	global_load_dwordx4 v[30:33], v[106:107], off offset:2048
	v_lshl_add_u64 v[34:35], s[22:23], 0, v[100:101]
	s_waitcnt vmcnt(0) lgkmcnt(0)
	v_pk_add_f32 v[28:29], v[28:29], 1.0 op_sel_hi:[1,0]
	v_pk_add_f32 v[26:27], v[26:27], 1.0 op_sel_hi:[1,0]
	v_pk_fma_f32 v[24:25], v[24:25], v[28:29], v[32:33]
	v_pk_fma_f32 v[22:23], v[22:23], v[26:27], v[30:31]
	v_cvt_pk_bf16_f32 v22, v22, v23
	v_cvt_pk_bf16_f32 v23, v24, v25
	global_store_dwordx2 v[104:105], v[22:23], off offset:3072
	global_load_dwordx4 v[22:25], v[34:35], off
	s_nop 0
	global_load_dwordx4 v[26:29], v[106:107], off offset:3072
	s_waitcnt vmcnt(0) lgkmcnt(0)
	v_pk_add_f32 v[24:25], v[24:25], 1.0 op_sel_hi:[1,0]
	v_pk_add_f32 v[22:23], v[22:23], 1.0 op_sel_hi:[1,0]
	v_pk_fma_f32 v[20:21], v[20:21], v[24:25], v[28:29]
	v_pk_fma_f32 v[18:19], v[18:19], v[22:23], v[26:27]
	v_cvt_pk_bf16_f32 v18, v18, v19
	v_cvt_pk_bf16_f32 v19, v20, v21
	global_store_dwordx2 v[104:105], v[18:19], off offset:3584
	s_cbranch_scc1 .LBB0_3341

.LBB0_3449:
	v_lshl_add_u64 v[18:19], s[38:39], 0, v[94:95]
	v_lshl_add_u64 v[22:23], s[38:39], 0, v[92:93]
	v_add_co_u32_e32 v20, vcc, 0x7800000, v18
	v_add_co_u32_e64 v102, s[6:7], s30, v22
	s_nop 0
	v_addc_co_u32_e32 v21, vcc, 0, v19, vcc
	v_addc_co_u32_e64 v103, s[6:7], 0, v23, s[6:7]
	v_add_co_u32_e64 v104, s[6:7], s31, v22
	v_add_co_u32_e32 v22, vcc, 0x7801000, v18
	s_nop 0
	v_addc_co_u32_e64 v105, s[6:7], 0, v23, s[6:7]
	global_load_dwordx4 v[78:81], v[20:21], off
	global_load_dwordx4 v[74:77], v[20:21], off offset:1024
	global_load_dwordx4 v[70:73], v[20:21], off offset:2048
	global_load_dwordx4 v[66:69], v[20:21], off offset:3072
	v_addc_co_u32_e32 v23, vcc, 0, v19, vcc
	v_add_co_u32_e32 v20, vcc, 0x7802000, v18
	global_load_dwordx4 v[62:65], v[22:23], off
	global_load_dwordx4 v[58:61], v[22:23], off offset:1024
	global_load_dwordx4 v[54:57], v[22:23], off offset:2048
	global_load_dwordx4 v[50:53], v[22:23], off offset:3072
	v_addc_co_u32_e32 v21, vcc, 0, v19, vcc
	global_load_dwordx4 v[46:49], v[20:21], off
	global_load_dwordx4 v[42:45], v[20:21], off offset:1024
	global_load_dwordx4 v[38:41], v[20:21], off offset:2048
	global_load_dwordx4 v[34:37], v[20:21], off offset:3072
	v_add_co_u32_e32 v18, vcc, 0x7803000, v18
	s_ashr_i32 s8, s20, 13
	s_nop 0
	v_addc_co_u32_e32 v19, vcc, 0, v19, vcc
	global_load_dwordx4 v[30:33], v[18:19], off
	global_load_dwordx4 v[26:29], v[18:19], off offset:1024
	global_load_dwordx4 v[22:25], v[18:19], off offset:2048
	s_nop 0
	global_load_dwordx4 v[18:21], v[18:19], off offset:3072
	s_add_i32 s9, s20, 0xffffc002
	s_cmpk_lt_i32 s20, 0x4000
	s_cselect_b32 s6, s8, s9
	s_addk_i32 s6, 0x82
	s_mul_hi_i32 s7, s6, 0x9000
	s_mul_i32 s6, s6, 0x9000
	s_add_u32 s6, s26, s6
	s_addc_u32 s7, s27, s7
	s_add_u32 s10, s6, 0x1000
	s_addc_u32 s11, s7, 0
	v_lshl_add_u64 v[122:123], s[6:7], 0, v[90:91]
	v_lshl_add_u64 v[86:87], s[10:11], 0, v[90:91]
	global_load_dwordx4 v[82:85], v[122:123], off
	s_add_i32 s6, s20, 0xffffc003
	global_load_dwordx4 v[86:89], v[86:87], off
	s_cmpk_lt_i32 s20, 0x3fff
	s_cselect_b32 s6, s8, s6
	s_addk_i32 s6, 0x82
	s_mul_hi_i32 s7, s6, 0x9000
	s_mul_i32 s6, s6, 0x9000
	s_add_u32 s6, s26, s6
	s_addc_u32 s7, s27, s7
	v_lshl_add_u64 v[138:139], s[10:11], 0, v[96:97]
	v_lshl_add_u64 v[134:135], s[10:11], 0, v[98:99]
	v_lshl_add_u64 v[128:129], s[10:11], 0, v[100:101]
	s_add_u32 s10, s6, 0x1000
	v_lshl_add_u64 v[110:111], s[6:7], 0, v[90:91]
	s_addc_u32 s11, s7, 0
	s_add_i32 s6, s20, 0xffffc004
	s_cmpk_lt_i32 s20, 0x3ffe
	s_cselect_b32 s6, s8, s6
	s_addk_i32 s6, 0x82
	s_mul_hi_i32 s7, s6, 0x9000
	s_mul_i32 s6, s6, 0x9000
	v_lshl_add_u64 v[124:125], s[10:11], 0, v[90:91]
	v_lshl_add_u64 v[118:119], s[10:11], 0, v[96:97]
	v_lshl_add_u64 v[114:115], s[10:11], 0, v[98:99]
	v_lshl_add_u64 v[112:113], s[10:11], 0, v[100:101]
	s_add_u32 s10, s26, s6
	s_addc_u32 s11, s27, s7
	s_add_u32 s6, s10, 0x1000
	s_addc_u32 s7, s11, 0
	s_add_i32 s9, s20, 0xffffc005
	s_cmpk_lt_i32 s20, 0x3ffd
	v_lshl_add_u64 v[142:143], s[6:7], 0, v[90:91]
	v_lshl_add_u64 v[140:141], s[6:7], 0, v[96:97]
	v_lshl_add_u64 v[136:137], s[6:7], 0, v[98:99]
	v_lshl_add_u64 v[126:127], s[6:7], 0, v[100:101]
	s_cselect_b32 s6, s8, s9
	s_addk_i32 s6, 0x82
	s_mul_hi_i32 s7, s6, 0x9000
	s_mul_i32 s6, s6, 0x9000
	s_add_u32 s6, s26, s6
	s_addc_u32 s7, s27, s7
	s_add_u32 s44, s6, 0x1000
	v_lshl_add_u64 v[106:107], s[6:7], 0, v[90:91]
	s_addc_u32 s45, s7, 0
	v_lshl_add_u64 v[108:109], s[10:11], 0, v[90:91]
	v_lshl_add_u64 v[120:121], s[44:45], 0, v[90:91]
	v_lshl_add_u64 v[116:117], s[44:45], 0, v[96:97]
	s_add_i32 s20, s20, 32
	v_lshl_add_u64 v[92:93], v[92:93], 0, s[22:23]
	s_waitcnt vmcnt(0) lgkmcnt(0)
	v_pk_mul_f32 v[144:145], v[80:81], v[80:81]
	v_pk_mul_f32 v[146:147], v[78:79], v[78:79]
	v_pk_mul_f32 v[148:149], v[76:77], v[76:77]
	v_pk_mul_f32 v[150:151], v[74:75], v[74:75]
	v_mul_f32_e32 v160, v71, v71
	v_mul_f32_e32 v162, v73, v73
	v_pk_mov_b32 v[164:165], v[146:147], v[144:145] op_sel:[1,0]
	v_mov_b32_e32 v147, v145
	v_pk_mov_b32 v[144:145], v[150:151], v[148:149] op_sel:[1,0]
	v_mov_b32_e32 v151, v149
	v_mul_f32_e32 v173, v68, v68
	v_mul_f32_e32 v175, v69, v69
	v_pk_fma_f32 v[148:149], v[70:71], v[70:71], v[160:161] op_sel_hi:[1,1,0]
	v_pk_fma_f32 v[160:161], v[72:73], v[72:73], v[162:163] op_sel_hi:[1,1,0]
	v_pk_mul_f32 v[162:163], v[64:65], v[64:65]
	v_pk_mul_f32 v[166:167], v[62:63], v[62:63]
	v_pk_mul_f32 v[168:169], v[60:61], v[60:61]
	v_pk_mul_f32 v[170:171], v[58:59], v[58:59]
	v_mul_f32_e32 v172, v55, v55
	v_mul_f32_e32 v174, v57, v57
	v_pk_add_f32 v[146:147], v[164:165], v[146:147]
	v_pk_add_f32 v[144:145], v[144:145], v[150:151]
	v_mul_f32_e32 v159, v66, v66
	v_mul_f32_e32 v183, v67, v67
	v_mov_b32_e32 v149, v173
	v_mov_b32_e32 v161, v175
	v_pk_mov_b32 v[150:151], v[166:167], v[162:163] op_sel:[1,0]
	v_mov_b32_e32 v167, v163
	v_pk_mov_b32 v[162:163], v[170:171], v[168:169] op_sel:[1,0]
	v_mov_b32_e32 v171, v169
	v_pk_fma_f32 v[164:165], v[54:55], v[54:55], v[172:173] op_sel_hi:[1,1,0]
	v_pk_fma_f32 v[168:169], v[56:57], v[56:57], v[174:175] op_sel_hi:[1,1,0]
	v_pk_mul_f32 v[172:173], v[48:49], v[48:49]
	v_pk_mul_f32 v[174:175], v[46:47], v[46:47]
	v_pk_add_f32 v[184:185], v[146:147], v[146:147] op_sel:[0,1] op_sel_hi:[1,0]
	v_pk_add_f32 v[186:187], v[144:145], v[144:145] op_sel:[0,1] op_sel_hi:[1,0]
	v_mul_f32_e32 v181, v52, v52
	v_pk_mul_f32 v[176:177], v[44:45], v[44:45]
	v_pk_mul_f32 v[178:179], v[42:43], v[42:43]
	v_mul_f32_e32 v180, v39, v39
	v_mul_f32_e32 v182, v41, v41
	v_pk_add_f32 v[160:161], v[148:149], v[160:161]
	v_pk_add_f32 v[144:145], v[150:151], v[166:167]
	v_pk_add_f32 v[146:147], v[162:163], v[170:171]
	v_pk_mov_b32 v[148:149], v[174:175], v[172:173] op_sel:[1,0]
	v_mov_b32_e32 v175, v173
	v_mov_b32_e32 v185, v159
	v_mov_b32_e32 v187, v183
	v_mul_f32_e32 v189, v50, v50
	v_mul_f32_e32 v194, v51, v51
	v_mul_f32_e32 v188, v53, v53
	v_mul_f32_e32 v197, v36, v36
	v_mul_f32_e32 v198, v37, v37
	v_pk_mov_b32 v[150:151], v[178:179], v[176:177] op_sel:[1,0]
	v_mov_b32_e32 v179, v177
	v_pk_fma_f32 v[162:163], v[38:39], v[38:39], v[180:181] op_sel_hi:[1,1,0]
	v_pk_fma_f32 v[166:167], v[40:41], v[40:41], v[182:183] op_sel_hi:[1,1,0]
	v_pk_add_f32 v[190:191], v[144:145], v[144:145] op_sel:[0,1] op_sel_hi:[1,0]
	v_pk_add_f32 v[192:193], v[146:147], v[146:147] op_sel:[0,1] op_sel_hi:[1,0]
	v_pk_add_f32 v[148:149], v[148:149], v[174:175]
	v_pk_add_f32 v[174:175], v[184:185], v[186:187]
	v_mov_b32_e32 v165, v181
	v_mov_b32_e32 v169, v188
	v_pk_mul_f32 v[170:171], v[32:33], v[32:33]
	v_pk_mul_f32 v[172:173], v[30:31], v[30:31]
	v_pk_mul_f32 v[176:177], v[28:29], v[28:29]
	v_pk_mul_f32 v[180:181], v[26:27], v[26:27]
	v_pk_add_f32 v[150:151], v[150:151], v[178:179]
	v_mov_b32_e32 v163, v197
	v_mov_b32_e32 v167, v198
	v_mov_b32_e32 v191, v189
	v_mov_b32_e32 v193, v194
	v_pk_add_f32 v[160:161], v[174:175], v[160:161]
	v_mul_f32_e32 v195, v34, v34
	v_mul_f32_e32 v196, v35, v35
	v_pk_add_f32 v[164:165], v[164:165], v[168:169]
	v_pk_mov_b32 v[168:169], v[172:173], v[170:171] op_sel:[1,0]
	v_mov_b32_e32 v173, v171
	v_pk_mov_b32 v[170:171], v[180:181], v[176:177] op_sel:[1,0]
	v_mov_b32_e32 v181, v177
	v_pk_add_f32 v[176:177], v[148:149], v[148:149] op_sel:[0,1] op_sel_hi:[1,0]
	v_pk_add_f32 v[178:179], v[150:151], v[150:151] op_sel:[0,1] op_sel_hi:[1,0]
	v_pk_add_f32 v[162:163], v[162:163], v[166:167]
	v_pk_add_f32 v[166:167], v[190:191], v[192:193]
	v_add_f32_e32 v159, v160, v161
	v_mov_b32_e32 v177, v195
	v_mov_b32_e32 v179, v196
	v_pk_add_f32 v[160:161], v[166:167], v[164:165]
	ds_bpermute_b32 v167, v133, v159
	v_pk_add_f32 v[164:165], v[176:177], v[178:179]
	v_add_f32_e32 v166, v160, v161
	v_pk_add_f32 v[160:161], v[164:165], v[162:163]
	v_add_f32_e32 v160, v160, v161
	s_waitcnt lgkmcnt(0)
	v_add_f32_e32 v159, v159, v167
	s_waitcnt lgkmcnt(0)
	s_nop 1
	v_add_f32_dpp v162, v166, v166 quad_perm:[1,0,3,2] row_mask:0xf bank_mask:0xf
	s_waitcnt lgkmcnt(0)
	s_nop 1
	v_add_f32_dpp v160, v160, v160 quad_perm:[1,0,3,2] row_mask:0xf bank_mask:0xf
	s_waitcnt lgkmcnt(0)
	s_nop 1
	v_add_f32_dpp v159, v159, v159 quad_perm:[2,3,0,1] row_mask:0xf bank_mask:0xf
	ds_bpermute_b32 v163, v153, v159
	s_waitcnt lgkmcnt(2)
	s_nop 1
	v_add_f32_dpp v162, v162, v162 quad_perm:[2,3,0,1] row_mask:0xf bank_mask:0xf
	s_waitcnt lgkmcnt(0)
	s_nop 1
	v_add_f32_dpp v160, v160, v160 quad_perm:[2,3,0,1] row_mask:0xf bank_mask:0xf
	s_waitcnt lgkmcnt(0)
	v_add_f32_e32 v159, v159, v163
	ds_bpermute_b32 v163, v154, v159
	s_waitcnt lgkmcnt(2)
	s_nop 1
	v_add_f32_dpp v162, v162, v162 row_half_mirror row_mask:0xf bank_mask:0xf
	s_waitcnt lgkmcnt(0)
	s_nop 1
	v_add_f32_dpp v160, v160, v160 row_half_mirror row_mask:0xf bank_mask:0xf
	s_waitcnt lgkmcnt(0)
	v_add_f32_e32 v159, v159, v163
	ds_bpermute_b32 v163, v155, v159
	s_waitcnt lgkmcnt(2)
	s_nop 1
	v_add_f32_dpp v162, v162, v162 row_mirror row_mask:0xf bank_mask:0xf
	ds_bpermute_b32 v164, v155, v162
	s_waitcnt lgkmcnt(2)
	s_nop 1
	v_add_f32_dpp v160, v160, v160 row_mirror row_mask:0xf bank_mask:0xf
	ds_bpermute_b32 v161, v155, v160
	s_waitcnt lgkmcnt(2)
	v_add_f32_e32 v159, v159, v163
	ds_bpermute_b32 v163, v156, v159
	s_waitcnt lgkmcnt(2)
	v_add_f32_e32 v162, v162, v164
	ds_bpermute_b32 v164, v156, v162
	s_waitcnt lgkmcnt(2)
	v_add_f32_e32 v160, v160, v161
	ds_bpermute_b32 v161, v156, v160
	s_waitcnt lgkmcnt(2)
	v_add_f32_e32 v159, v159, v163
	v_fmamk_f32 v159, v159, 0x3a800000, v157
	s_waitcnt lgkmcnt(1)
	v_add_f32_e32 v162, v162, v164
	v_mul_f32_e32 v163, 0x4f800000, v159
	v_cmp_gt_f32_e32 vcc, s21, v159
	v_fmamk_f32 v162, v162, 0x3a800000, v157
	s_waitcnt lgkmcnt(0)
	v_add_f32_e32 v160, v160, v161
	v_cndmask_b32_e32 v159, v159, v163, vcc
	v_mul_f32_e32 v161, 0x4f800000, v162
	v_cmp_gt_f32_e64 s[6:7], s21, v162
	v_sqrt_f32_e32 v163, v159
	v_fmamk_f32 v160, v160, 0x3a800000, v157
	v_cndmask_b32_e64 v161, v162, v161, s[6:7]
	v_mul_f32_e32 v162, 0x4f800000, v160
	v_cmp_gt_f32_e64 s[8:9], s21, v160
	v_sqrt_f32_e32 v164, v161
	v_add_u32_e32 v165, -1, v163
	v_cndmask_b32_e64 v160, v160, v162, s[8:9]
	v_sqrt_f32_e32 v162, v160
	v_add_u32_e32 v166, 1, v163
	v_fma_f32 v167, -v165, v163, v159
	v_pk_add_f32 v[148:149], v[168:169], v[172:173]
	v_fma_f32 v168, -v166, v163, v159
	v_add_u32_e32 v169, -1, v164
	v_cmp_ge_f32_e64 s[10:11], 0, v167
	v_pk_add_f32 v[150:151], v[170:171], v[180:181]
	v_add_u32_e32 v170, 1, v164
	v_cndmask_b32_e64 v163, v163, v165, s[10:11]
	v_fma_f32 v165, -v169, v164, v161
	v_cmp_lt_f32_e64 s[10:11], 0, v168
	v_fma_f32 v167, -v170, v164, v161
	v_add_u32_e32 v171, -1, v162
	v_cndmask_b32_e64 v163, v163, v166, s[10:11]
	v_cmp_ge_f32_e64 s[10:11], 0, v165
	v_add_u32_e32 v172, 1, v162
	v_fma_f32 v165, -v171, v162, v160
	v_cndmask_b32_e64 v164, v164, v169, s[10:11]
	v_cmp_lt_f32_e64 s[10:11], 0, v167
	v_fma_f32 v166, -v172, v162, v160
	v_mul_f32_e32 v167, 0x37800000, v163
	v_cndmask_b32_e64 v164, v164, v170, s[10:11]
	v_cmp_ge_f32_e64 s[10:11], 0, v165
	v_cndmask_b32_e32 v163, v163, v167, vcc
	v_cmp_class_f32_e32 vcc, v159, v158
	v_cndmask_b32_e64 v162, v162, v171, s[10:11]
	v_cmp_lt_f32_e64 s[10:11], 0, v166
	v_mul_f32_e32 v165, 0x37800000, v164
	v_cndmask_b32_e32 v159, v163, v159, vcc
	v_cndmask_b32_e64 v162, v162, v172, s[10:11]
	v_cndmask_b32_e64 v163, v164, v165, s[6:7]
	v_cmp_class_f32_e32 vcc, v161, v158
	v_mul_f32_e32 v164, 0x37800000, v162
	v_div_scale_f32 v165, s[6:7], v159, v159, 1.0
	v_cndmask_b32_e32 v161, v163, v161, vcc
	v_cndmask_b32_e64 v162, v162, v164, s[8:9]
	v_cmp_class_f32_e32 vcc, v160, v158
	v_rcp_f32_e32 v163, v165
	v_div_scale_f32 v164, s[8:9], v161, v161, 1.0
	v_cndmask_b32_e32 v162, v162, v160, vcc
	v_rcp_f32_e32 v168, v164
	v_div_scale_f32 v169, s[10:11], v162, v162, 1.0
	v_rcp_f32_e32 v171, v169
	v_fma_f32 v160, -v165, v163, 1.0
	v_div_scale_f32 v166, s[6:7], 1.0, v159, 1.0
	v_fmac_f32_e32 v163, v160, v163
	v_fma_f32 v160, -v164, v168, 1.0
	v_mul_f32_e32 v172, v166, v163
	v_div_scale_f32 v167, s[8:9], 1.0, v161, 1.0
	v_fmac_f32_e32 v168, v160, v168
	v_fma_f32 v160, -v169, v171, 1.0
	v_fma_f32 v173, -v165, v172, v166
	v_div_scale_f32 v170, s[10:11], 1.0, v162, 1.0
	v_mul_f32_e32 v174, v167, v168
	v_fmac_f32_e32 v171, v160, v171
	v_fmac_f32_e32 v172, v173, v163
	v_fma_f32 v160, -v164, v174, v167
	v_mul_f32_e32 v173, v170, v171
	v_fma_f32 v165, -v165, v172, v166
	s_mov_b64 vcc, s[6:7]
	v_fmac_f32_e32 v174, v160, v168
	v_fma_f32 v160, -v169, v173, v170
	v_div_fmas_f32 v163, v165, v163, v172
	v_fma_f32 v164, -v164, v174, v167
	v_fmac_f32_e32 v173, v160, v171
	v_div_fixup_f32 v160, v163, v159, 1.0
	s_mov_b64 vcc, s[8:9]
	v_div_fmas_f32 v159, v164, v168, v174
	v_fma_f32 v163, -v169, v173, v170
	v_pk_mul_f32 v[80:81], v[80:81], v[160:161] op_sel_hi:[1,0]
	v_pk_mul_f32 v[78:79], v[78:79], v[160:161] op_sel_hi:[1,0]
	s_mov_b64 vcc, s[10:11]
	v_pk_add_f32 v[88:89], v[88:89], 1.0 op_sel_hi:[1,0]
	v_pk_add_f32 v[86:87], v[86:87], 1.0 op_sel_hi:[1,0]
	v_pk_mul_f32 v[76:77], v[76:77], v[160:161] op_sel_hi:[1,0]
	v_pk_mul_f32 v[74:75], v[74:75], v[160:161] op_sel_hi:[1,0]
	v_pk_mul_f32 v[72:73], v[72:73], v[160:161] op_sel_hi:[1,0]
	v_pk_mul_f32 v[70:71], v[70:71], v[160:161] op_sel_hi:[1,0]
	v_pk_mul_f32 v[68:69], v[68:69], v[160:161] op_sel_hi:[1,0]
	v_pk_mul_f32 v[66:67], v[66:67], v[160:161] op_sel_hi:[1,0]
	v_div_fixup_f32 v160, v159, v161, 1.0
	v_div_fmas_f32 v159, v163, v171, v173
	v_pk_mul_f32 v[78:79], v[78:79], v[2:3]
	v_pk_mul_f32 v[80:81], v[80:81], v[4:5]
	v_pk_mul_f32 v[64:65], v[64:65], v[160:161] op_sel_hi:[1,0]
	v_pk_mul_f32 v[62:63], v[62:63], v[160:161] op_sel_hi:[1,0]
	v_pk_mul_f32 v[60:61], v[60:61], v[160:161] op_sel_hi:[1,0]
	v_pk_mul_f32 v[58:59], v[58:59], v[160:161] op_sel_hi:[1,0]
	v_pk_mul_f32 v[56:57], v[56:57], v[160:161] op_sel_hi:[1,0]
	v_pk_mul_f32 v[54:55], v[54:55], v[160:161] op_sel_hi:[1,0]
	v_pk_mul_f32 v[52:53], v[52:53], v[160:161] op_sel_hi:[1,0]
	v_pk_mul_f32 v[50:51], v[50:51], v[160:161] op_sel_hi:[1,0]
	v_div_fixup_f32 v160, v159, v162, 1.0
	v_pk_fma_f32 v[80:81], v[80:81], v[88:89], v[84:85]
	v_pk_fma_f32 v[78:79], v[78:79], v[86:87], v[82:83]
	v_pk_mul_f32 v[82:83], v[50:51], v[14:15]
	v_pk_mul_f32 v[84:85], v[52:53], v[16:17]
	v_pk_mul_f32 v[48:49], v[48:49], v[160:161] op_sel_hi:[1,0]
	v_pk_mul_f32 v[46:47], v[46:47], v[160:161] op_sel_hi:[1,0]
	v_pk_mul_f32 v[86:87], v[46:47], v[2:3]
	v_pk_mul_f32 v[88:89], v[48:49], v[4:5]
	v_cvt_pk_bf16_f32 v46, v78, v79
	v_cvt_pk_bf16_f32 v47, v80, v81
	global_store_dwordx2 v[102:103], v[46:47], off
	global_load_dwordx4 v[46:49], v[138:139], off
	s_nop 0
	global_load_dwordx4 v[50:53], v[122:123], off offset:1024
	v_pk_mul_f32 v[74:75], v[74:75], v[6:7]
	v_pk_mul_f32 v[76:77], v[76:77], v[8:9]
	v_pk_mul_f32 v[70:71], v[70:71], v[10:11]
	v_pk_mul_f32 v[72:73], v[72:73], v[12:13]
	v_pk_mul_f32 v[66:67], v[66:67], v[14:15]
	v_pk_mul_f32 v[68:69], v[68:69], v[16:17]
	v_pk_mul_f32 v[62:63], v[62:63], v[2:3]
	v_pk_mul_f32 v[64:65], v[64:65], v[4:5]
	v_pk_mul_f32 v[58:59], v[58:59], v[6:7]
	v_pk_mul_f32 v[60:61], v[60:61], v[8:9]
	v_pk_mul_f32 v[54:55], v[54:55], v[10:11]
	v_pk_mul_f32 v[56:57], v[56:57], v[12:13]
	v_pk_mul_f32 v[44:45], v[44:45], v[160:161] op_sel_hi:[1,0]
	v_pk_mul_f32 v[42:43], v[42:43], v[160:161] op_sel_hi:[1,0]
	v_pk_mul_f32 v[44:45], v[44:45], v[8:9]
	v_pk_mul_f32 v[42:43], v[42:43], v[6:7]
	v_pk_mul_f32 v[40:41], v[40:41], v[160:161] op_sel_hi:[1,0]
	v_pk_mul_f32 v[38:39], v[38:39], v[160:161] op_sel_hi:[1,0]
	v_pk_mul_f32 v[40:41], v[40:41], v[12:13]
	v_pk_mul_f32 v[38:39], v[38:39], v[10:11]
	v_pk_mul_f32 v[36:37], v[36:37], v[160:161] op_sel_hi:[1,0]
	v_pk_mul_f32 v[34:35], v[34:35], v[160:161] op_sel_hi:[1,0]
	v_pk_mul_f32 v[36:37], v[36:37], v[16:17]
	v_pk_mul_f32 v[34:35], v[34:35], v[14:15]
	v_mul_f32_e32 v182, v23, v23
	v_mul_f32_e32 v188, v25, v25
	v_mul_f32_e32 v199, v18, v18
	v_mul_f32_e32 v200, v19, v19
	v_mul_f32_e32 v201, v20, v20
	v_mul_f32_e32 v202, v21, v21
	v_pk_fma_f32 v[144:145], v[22:23], v[22:23], v[182:183] op_sel_hi:[1,1,0]
	v_pk_fma_f32 v[146:147], v[24:25], v[24:25], v[188:189] op_sel_hi:[1,1,0]
	v_mov_b32_e32 v145, v201
	v_mov_b32_e32 v147, v202
	v_lshl_add_u64 v[94:95], v[94:95], 0, s[24:25]
	s_cmp_lt_i32 s20, s13
	s_waitcnt vmcnt(0) lgkmcnt(0)
	v_pk_add_f32 v[48:49], v[48:49], 1.0 op_sel_hi:[1,0]
	v_pk_add_f32 v[46:47], v[46:47], 1.0 op_sel_hi:[1,0]
	v_pk_fma_f32 v[48:49], v[76:77], v[48:49], v[52:53]
	v_pk_fma_f32 v[46:47], v[74:75], v[46:47], v[50:51]
	v_cvt_pk_bf16_f32 v46, v46, v47
	v_cvt_pk_bf16_f32 v47, v48, v49
	global_store_dwordx2 v[102:103], v[46:47], off offset:512
	global_load_dwordx4 v[46:49], v[134:135], off
	s_nop 0
	global_load_dwordx4 v[50:53], v[122:123], off offset:2048
	s_waitcnt vmcnt(0) lgkmcnt(0)
	v_pk_add_f32 v[48:49], v[48:49], 1.0 op_sel_hi:[1,0]
	v_pk_add_f32 v[46:47], v[46:47], 1.0 op_sel_hi:[1,0]
	v_pk_fma_f32 v[48:49], v[72:73], v[48:49], v[52:53]
	v_pk_fma_f32 v[46:47], v[70:71], v[46:47], v[50:51]
	v_cvt_pk_bf16_f32 v46, v46, v47
	v_cvt_pk_bf16_f32 v47, v48, v49
	global_store_dwordx2 v[102:103], v[46:47], off offset:1024
	global_load_dwordx4 v[46:49], v[128:129], off
	s_nop 0
	global_load_dwordx4 v[50:53], v[122:123], off offset:3072
	s_waitcnt vmcnt(0) lgkmcnt(0)
	v_pk_add_f32 v[48:49], v[48:49], 1.0 op_sel_hi:[1,0]
	v_pk_add_f32 v[46:47], v[46:47], 1.0 op_sel_hi:[1,0]
	v_pk_fma_f32 v[48:49], v[68:69], v[48:49], v[52:53]
	v_pk_fma_f32 v[46:47], v[66:67], v[46:47], v[50:51]
	v_cvt_pk_bf16_f32 v46, v46, v47
	v_cvt_pk_bf16_f32 v47, v48, v49
	global_store_dwordx2 v[102:103], v[46:47], off offset:1536
	global_load_dwordx4 v[46:49], v[124:125], off
	s_nop 0
	global_load_dwordx4 v[50:53], v[110:111], off
	s_waitcnt vmcnt(0) lgkmcnt(0)
	v_pk_add_f32 v[48:49], v[48:49], 1.0 op_sel_hi:[1,0]
	v_pk_add_f32 v[46:47], v[46:47], 1.0 op_sel_hi:[1,0]
	v_pk_fma_f32 v[48:49], v[64:65], v[48:49], v[52:53]
	v_pk_fma_f32 v[46:47], v[62:63], v[46:47], v[50:51]
	v_cvt_pk_bf16_f32 v46, v46, v47
	v_cvt_pk_bf16_f32 v47, v48, v49
	global_store_dwordx2 v[102:103], v[46:47], off offset:2048
	global_load_dwordx4 v[46:49], v[118:119], off
	s_nop 0
	global_load_dwordx4 v[50:53], v[110:111], off offset:1024
	s_waitcnt vmcnt(0) lgkmcnt(0)
	v_pk_add_f32 v[48:49], v[48:49], 1.0 op_sel_hi:[1,0]
	v_pk_add_f32 v[46:47], v[46:47], 1.0 op_sel_hi:[1,0]
	v_pk_fma_f32 v[48:49], v[60:61], v[48:49], v[52:53]
	v_pk_fma_f32 v[46:47], v[58:59], v[46:47], v[50:51]
	v_cvt_pk_bf16_f32 v46, v46, v47
	v_cvt_pk_bf16_f32 v47, v48, v49
	global_store_dwordx2 v[102:103], v[46:47], off offset:2560
	global_load_dwordx4 v[46:49], v[114:115], off
	s_nop 0
	global_load_dwordx4 v[50:53], v[110:111], off offset:2048
	v_pk_add_f32 v[58:59], v[144:145], v[146:147]
	s_waitcnt vmcnt(0) lgkmcnt(0)
	v_pk_add_f32 v[48:49], v[48:49], 1.0 op_sel_hi:[1,0]
	v_pk_add_f32 v[46:47], v[46:47], 1.0 op_sel_hi:[1,0]
	v_pk_fma_f32 v[48:49], v[56:57], v[48:49], v[52:53]
	v_pk_fma_f32 v[46:47], v[54:55], v[46:47], v[50:51]
	v_cvt_pk_bf16_f32 v46, v46, v47
	v_cvt_pk_bf16_f32 v47, v48, v49
	global_store_dwordx2 v[102:103], v[46:47], off offset:3072
	global_load_dwordx4 v[46:49], v[112:113], off
	s_nop 0
	global_load_dwordx4 v[50:53], v[110:111], off offset:3072
	v_pk_add_f32 v[54:55], v[148:149], v[148:149] op_sel:[0,1] op_sel_hi:[1,0]
	v_pk_add_f32 v[56:57], v[150:151], v[150:151] op_sel:[0,1] op_sel_hi:[1,0]
	v_mov_b32_e32 v55, v199
	v_mov_b32_e32 v57, v200
	s_waitcnt vmcnt(0) lgkmcnt(0)
	v_pk_add_f32 v[48:49], v[48:49], 1.0 op_sel_hi:[1,0]
	v_pk_add_f32 v[46:47], v[46:47], 1.0 op_sel_hi:[1,0]
	v_pk_fma_f32 v[48:49], v[84:85], v[48:49], v[52:53]
	v_pk_fma_f32 v[46:47], v[82:83], v[46:47], v[50:51]
	v_cvt_pk_bf16_f32 v46, v46, v47
	v_cvt_pk_bf16_f32 v47, v48, v49
	global_store_dwordx2 v[102:103], v[46:47], off offset:3584
	global_load_dwordx4 v[46:49], v[142:143], off
	s_nop 0
	global_load_dwordx4 v[50:53], v[108:109], off
	s_waitcnt vmcnt(0) lgkmcnt(0)
	v_pk_add_f32 v[48:49], v[48:49], 1.0 op_sel_hi:[1,0]
	v_pk_add_f32 v[46:47], v[46:47], 1.0 op_sel_hi:[1,0]
	v_pk_fma_f32 v[48:49], v[88:89], v[48:49], v[52:53]
	v_pk_fma_f32 v[46:47], v[86:87], v[46:47], v[50:51]
	v_cvt_pk_bf16_f32 v46, v46, v47
	v_cvt_pk_bf16_f32 v47, v48, v49
	global_store_dwordx2 v[104:105], v[46:47], off
	global_load_dwordx4 v[46:49], v[140:141], off
	s_nop 0
	global_load_dwordx4 v[50:53], v[108:109], off offset:1024
	s_waitcnt vmcnt(0) lgkmcnt(0)
	v_pk_add_f32 v[48:49], v[48:49], 1.0 op_sel_hi:[1,0]
	v_pk_add_f32 v[46:47], v[46:47], 1.0 op_sel_hi:[1,0]
	v_pk_fma_f32 v[44:45], v[44:45], v[48:49], v[52:53]
	v_pk_fma_f32 v[42:43], v[42:43], v[46:47], v[50:51]
	v_cvt_pk_bf16_f32 v42, v42, v43
	v_cvt_pk_bf16_f32 v43, v44, v45
	global_store_dwordx2 v[104:105], v[42:43], off offset:512
	global_load_dwordx4 v[42:45], v[136:137], off
	s_nop 0
	global_load_dwordx4 v[46:49], v[108:109], off offset:2048
	v_pk_add_f32 v[50:51], v[54:55], v[56:57]
	s_waitcnt vmcnt(0) lgkmcnt(0)
	v_pk_add_f32 v[44:45], v[44:45], 1.0 op_sel_hi:[1,0]
	v_pk_add_f32 v[42:43], v[42:43], 1.0 op_sel_hi:[1,0]
	v_pk_fma_f32 v[40:41], v[40:41], v[44:45], v[48:49]
	v_pk_fma_f32 v[38:39], v[38:39], v[42:43], v[46:47]
	v_cvt_pk_bf16_f32 v38, v38, v39
	v_cvt_pk_bf16_f32 v39, v40, v41
	global_store_dwordx2 v[104:105], v[38:39], off offset:1024
	global_load_dwordx4 v[38:41], v[126:127], off
	s_nop 0
	global_load_dwordx4 v[42:45], v[108:109], off offset:3072
	v_pk_add_f32 v[50:51], v[50:51], v[58:59]
	s_waitcnt vmcnt(0) lgkmcnt(0)
	v_pk_add_f32 v[40:41], v[40:41], 1.0 op_sel_hi:[1,0]
	v_pk_add_f32 v[38:39], v[38:39], 1.0 op_sel_hi:[1,0]
	v_pk_fma_f32 v[36:37], v[36:37], v[40:41], v[44:45]
	v_pk_fma_f32 v[34:35], v[34:35], v[38:39], v[42:43]
	v_cvt_pk_bf16_f32 v34, v34, v35
	v_cvt_pk_bf16_f32 v35, v36, v37
	global_store_dwordx2 v[104:105], v[34:35], off offset:1536
	global_load_dwordx4 v[34:37], v[120:121], off
	s_nop 0
	global_load_dwordx4 v[38:41], v[106:107], off
	v_add_f32_e32 v50, v50, v51
	s_waitcnt lgkmcnt(0)
	s_nop 1
	v_add_f32_dpp v50, v50, v50 quad_perm:[1,0,3,2] row_mask:0xf bank_mask:0xf
	ds_bpermute_b32 v51, v152, v50
	s_waitcnt lgkmcnt(0)
	v_add_f32_e32 v50, v50, v51
	ds_bpermute_b32 v46, v153, v50
	s_waitcnt lgkmcnt(0)
	v_add_f32_e32 v46, v50, v46
	ds_bpermute_b32 v47, v154, v46
	s_waitcnt lgkmcnt(0)
	v_add_f32_e32 v46, v46, v47
	ds_bpermute_b32 v47, v155, v46
	s_waitcnt lgkmcnt(0)
	v_add_f32_e32 v46, v46, v47
	ds_bpermute_b32 v47, v156, v46
	s_waitcnt lgkmcnt(0)
	v_add_f32_e32 v46, v46, v47
	v_fmamk_f32 v46, v46, 0x3a800000, v157
	v_mul_f32_e32 v47, 0x4f800000, v46
	v_cmp_gt_f32_e32 vcc, s21, v46
	s_waitcnt vmcnt(0)
	v_pk_add_f32 v[36:37], v[36:37], 1.0 op_sel_hi:[1,0]
	v_cndmask_b32_e32 v42, v46, v47, vcc
	v_sqrt_f32_e32 v43, v42
	v_pk_add_f32 v[34:35], v[34:35], 1.0 op_sel_hi:[1,0]
	v_add_u32_e32 v44, -1, v43
	v_add_u32_e32 v45, 1, v43
	v_fma_f32 v46, -v44, v43, v42
	v_fma_f32 v47, -v45, v43, v42
	v_cmp_ge_f32_e64 s[6:7], 0, v46
	s_nop 1
	v_cndmask_b32_e64 v43, v43, v44, s[6:7]
	v_cmp_lt_f32_e64 s[6:7], 0, v47
	s_nop 1
	v_cndmask_b32_e64 v43, v43, v45, s[6:7]
	v_mul_f32_e32 v44, 0x37800000, v43
	v_cndmask_b32_e32 v43, v43, v44, vcc
	v_cmp_class_f32_e32 vcc, v42, v158
	s_nop 1
	v_cndmask_b32_e32 v42, v43, v42, vcc
	v_div_scale_f32 v43, s[6:7], v42, v42, 1.0
	v_rcp_f32_e32 v45, v43
	v_div_scale_f32 v44, vcc, 1.0, v42, 1.0
	v_fma_f32 v46, -v43, v45, 1.0
	v_fmac_f32_e32 v45, v46, v45
	v_mul_f32_e32 v46, v44, v45
	v_fma_f32 v47, -v43, v46, v44
	v_fmac_f32_e32 v46, v47, v45
	v_fma_f32 v43, -v43, v46, v44
	v_div_fmas_f32 v43, v43, v45, v46
	v_div_fixup_f32 v42, v43, v42, 1.0
	v_pk_mul_f32 v[32:33], v[32:33], v[42:43] op_sel_hi:[1,0]
	v_pk_mul_f32 v[30:31], v[30:31], v[42:43] op_sel_hi:[1,0]
	v_pk_mul_f32 v[32:33], v[32:33], v[4:5]
	v_pk_mul_f32 v[30:31], v[30:31], v[2:3]
	v_pk_fma_f32 v[32:33], v[32:33], v[36:37], v[40:41]
	v_pk_fma_f32 v[30:31], v[30:31], v[34:35], v[38:39]
	v_cvt_pk_bf16_f32 v30, v30, v31
	v_cvt_pk_bf16_f32 v31, v32, v33
	global_store_dwordx2 v[104:105], v[30:31], off offset:2048
	global_load_dwordx4 v[30:33], v[116:117], off
	s_nop 0
	global_load_dwordx4 v[34:37], v[106:107], off offset:1024
	v_pk_mul_f32 v[28:29], v[28:29], v[42:43] op_sel_hi:[1,0]
	v_pk_mul_f32 v[26:27], v[26:27], v[42:43] op_sel_hi:[1,0]
	v_pk_mul_f32 v[28:29], v[28:29], v[8:9]
	v_pk_mul_f32 v[26:27], v[26:27], v[6:7]
	v_lshl_add_u64 v[38:39], s[44:45], 0, v[98:99]
	v_pk_mul_f32 v[24:25], v[24:25], v[42:43] op_sel_hi:[1,0]
	v_pk_mul_f32 v[22:23], v[22:23], v[42:43] op_sel_hi:[1,0]
	v_pk_mul_f32 v[24:25], v[24:25], v[12:13]
	v_pk_mul_f32 v[22:23], v[22:23], v[10:11]
	v_pk_mul_f32 v[20:21], v[20:21], v[42:43] op_sel_hi:[1,0]
	v_pk_mul_f32 v[18:19], v[18:19], v[42:43] op_sel_hi:[1,0]
	v_pk_mul_f32 v[20:21], v[20:21], v[16:17]
	v_pk_mul_f32 v[18:19], v[18:19], v[14:15]
	s_waitcnt vmcnt(0) lgkmcnt(0)
	v_pk_add_f32 v[32:33], v[32:33], 1.0 op_sel_hi:[1,0]
	v_pk_add_f32 v[30:31], v[30:31], 1.0 op_sel_hi:[1,0]
	v_pk_fma_f32 v[28:29], v[28:29], v[32:33], v[36:37]
	v_pk_fma_f32 v[26:27], v[26:27], v[30:31], v[34:35]
	v_cvt_pk_bf16_f32 v26, v26, v27
	v_cvt_pk_bf16_f32 v27, v28, v29
	global_store_dwordx2 v[104:105], v[26:27], off offset:2560
	global_load_dwordx4 v[26:29], v[38:39], off
	s_nop 0
	global_load_dwordx4 v[30:33], v[106:107], off offset:2048
	v_lshl_add_u64 v[34:35], s[44:45], 0, v[100:101]
	s_waitcnt vmcnt(0) lgkmcnt(0)
	v_pk_add_f32 v[28:29], v[28:29], 1.0 op_sel_hi:[1,0]
	v_pk_add_f32 v[26:27], v[26:27], 1.0 op_sel_hi:[1,0]
	v_pk_fma_f32 v[24:25], v[24:25], v[28:29], v[32:33]
	v_pk_fma_f32 v[22:23], v[22:23], v[26:27], v[30:31]
	v_cvt_pk_bf16_f32 v22, v22, v23
	v_cvt_pk_bf16_f32 v23, v24, v25
	global_store_dwordx2 v[104:105], v[22:23], off offset:3072
	global_load_dwordx4 v[22:25], v[34:35], off
	s_nop 0
	global_load_dwordx4 v[26:29], v[106:107], off offset:3072
	s_waitcnt vmcnt(0) lgkmcnt(0)
	v_pk_add_f32 v[24:25], v[24:25], 1.0 op_sel_hi:[1,0]
	v_pk_add_f32 v[22:23], v[22:23], 1.0 op_sel_hi:[1,0]
	v_pk_fma_f32 v[20:21], v[20:21], v[24:25], v[28:29]
	v_pk_fma_f32 v[18:19], v[18:19], v[22:23], v[26:27]
	v_cvt_pk_bf16_f32 v18, v18, v19
	v_cvt_pk_bf16_f32 v19, v20, v21
	global_store_dwordx2 v[104:105], v[18:19], off offset:3584
	s_cbranch_scc1 .LBB0_3449

.LBB0_3611:
	v_lshl_add_u64 v[18:19], s[38:39], 0, v[94:95]
	v_lshl_add_u64 v[22:23], s[38:39], 0, v[92:93]
	v_add_co_u32_e32 v20, vcc, 0x7800000, v18
	v_add_co_u32_e64 v102, s[6:7], s23, v22
	s_nop 0
	v_addc_co_u32_e32 v21, vcc, 0, v19, vcc
	v_addc_co_u32_e64 v103, s[6:7], 0, v23, s[6:7]
	v_add_co_u32_e64 v104, s[6:7], s24, v22
	v_add_co_u32_e32 v22, vcc, 0x7801000, v18
	s_nop 0
	v_addc_co_u32_e64 v105, s[6:7], 0, v23, s[6:7]
	global_load_dwordx4 v[78:81], v[20:21], off
	global_load_dwordx4 v[74:77], v[20:21], off offset:1024
	global_load_dwordx4 v[70:73], v[20:21], off offset:2048
	global_load_dwordx4 v[66:69], v[20:21], off offset:3072
	v_addc_co_u32_e32 v23, vcc, 0, v19, vcc
	v_add_co_u32_e32 v20, vcc, 0x7802000, v18
	global_load_dwordx4 v[62:65], v[22:23], off
	global_load_dwordx4 v[58:61], v[22:23], off offset:1024
	global_load_dwordx4 v[54:57], v[22:23], off offset:2048
	global_load_dwordx4 v[50:53], v[22:23], off offset:3072
	v_addc_co_u32_e32 v21, vcc, 0, v19, vcc
	v_add_co_u32_e32 v82, vcc, 0x7803000, v18
	global_load_dwordx4 v[46:49], v[20:21], off
	global_load_dwordx4 v[42:45], v[20:21], off offset:1024
	global_load_dwordx4 v[38:41], v[20:21], off offset:2048
	global_load_dwordx4 v[34:37], v[20:21], off offset:3072
	v_addc_co_u32_e32 v83, vcc, 0, v19, vcc
	global_load_dwordx4 v[30:33], v[82:83], off
	global_load_dwordx4 v[26:29], v[82:83], off offset:1024
	global_load_dwordx4 v[22:25], v[82:83], off offset:2048
	global_load_dwordx4 v[18:21], v[82:83], off offset:3072
	s_add_i32 s25, s8, 32
	s_add_i32 s10, s8, 0xffffc022
	s_ashr_i32 s9, s25, 13
	s_cmpk_lt_i32 s25, 0x4000
	s_cselect_b32 s6, s9, s10
	s_addk_i32 s6, 0x82
	s_mul_hi_i32 s7, s6, 0x9000
	s_mul_i32 s6, s6, 0x9000
	s_add_u32 s6, s2, s6
	s_addc_u32 s7, s5, s7
	s_add_u32 s10, s6, 0x1000
	s_addc_u32 s11, s7, 0
	v_lshl_add_u64 v[124:125], s[6:7], 0, v[90:91]
	v_lshl_add_u64 v[86:87], s[10:11], 0, v[90:91]
	global_load_dwordx4 v[82:85], v[124:125], off
	s_add_i32 s6, s8, 0xffffc023
	global_load_dwordx4 v[86:89], v[86:87], off
	s_cmpk_lt_i32 s25, 0x3fff
	s_cselect_b32 s6, s9, s6
	s_addk_i32 s6, 0x82
	s_mul_hi_i32 s7, s6, 0x9000
	s_mul_i32 s6, s6, 0x9000
	s_add_u32 s6, s2, s6
	s_addc_u32 s7, s5, s7
	v_lshl_add_u64 v[138:139], s[10:11], 0, v[96:97]
	v_lshl_add_u64 v[134:135], s[10:11], 0, v[98:99]
	v_lshl_add_u64 v[128:129], s[10:11], 0, v[100:101]
	s_add_u32 s10, s6, 0x1000
	v_lshl_add_u64 v[110:111], s[6:7], 0, v[90:91]
	s_addc_u32 s11, s7, 0
	s_add_i32 s6, s8, 0xffffc024
	s_cmpk_lt_i32 s25, 0x3ffe
	s_cselect_b32 s6, s9, s6
	s_addk_i32 s6, 0x82
	s_mul_hi_i32 s7, s6, 0x9000
	s_mul_i32 s6, s6, 0x9000
	v_lshl_add_u64 v[126:127], s[10:11], 0, v[90:91]
	v_lshl_add_u64 v[120:121], s[10:11], 0, v[96:97]
	v_lshl_add_u64 v[116:117], s[10:11], 0, v[98:99]
	v_lshl_add_u64 v[112:113], s[10:11], 0, v[100:101]
	s_add_u32 s10, s2, s6
	s_addc_u32 s11, s5, s7
	s_add_u32 s6, s10, 0x1000
	s_addc_u32 s7, s11, 0
	s_addk_i32 s8, 0xc025
	s_cmpk_lt_i32 s25, 0x3ffd
	v_lshl_add_u64 v[142:143], s[6:7], 0, v[90:91]
	v_lshl_add_u64 v[140:141], s[6:7], 0, v[96:97]
	v_lshl_add_u64 v[136:137], s[6:7], 0, v[98:99]
	v_lshl_add_u64 v[122:123], s[6:7], 0, v[100:101]
	s_cselect_b32 s6, s9, s8
	s_addk_i32 s6, 0x82
	s_mul_hi_i32 s7, s6, 0x9000
	s_mul_i32 s6, s6, 0x9000
	s_add_u32 s6, s2, s6
	s_addc_u32 s7, s5, s7
	s_add_u32 s20, s6, 0x1000
	v_lshl_add_u64 v[106:107], s[6:7], 0, v[90:91]
	s_addc_u32 s21, s7, 0
	v_lshl_add_u64 v[108:109], s[10:11], 0, v[90:91]
	v_lshl_add_u64 v[118:119], s[20:21], 0, v[90:91]
	v_lshl_add_u64 v[114:115], s[20:21], 0, v[96:97]
	v_lshl_add_u64 v[92:93], v[92:93], 0, s[14:15]
	s_waitcnt vmcnt(0) lgkmcnt(0)
	v_pk_mul_f32 v[144:145], v[80:81], v[80:81]
	v_pk_mul_f32 v[146:147], v[78:79], v[78:79]
	v_pk_mul_f32 v[148:149], v[76:77], v[76:77]
	v_pk_mul_f32 v[150:151], v[74:75], v[74:75]
	v_mul_f32_e32 v158, v71, v71
	v_mul_f32_e32 v160, v73, v73
	v_mul_f32_e32 v171, v68, v68
	v_mul_f32_e32 v173, v69, v69
	v_pk_mov_b32 v[162:163], v[146:147], v[144:145] op_sel:[1,0]
	v_mov_b32_e32 v147, v145
	v_pk_mov_b32 v[144:145], v[150:151], v[148:149] op_sel:[1,0]
	v_mov_b32_e32 v151, v149
	v_pk_fma_f32 v[148:149], v[70:71], v[70:71], v[158:159] op_sel_hi:[1,1,0]
	v_pk_fma_f32 v[158:159], v[72:73], v[72:73], v[160:161] op_sel_hi:[1,1,0]
	v_pk_mul_f32 v[160:161], v[64:65], v[64:65]
	v_pk_mul_f32 v[164:165], v[62:63], v[62:63]
	v_pk_mul_f32 v[166:167], v[60:61], v[60:61]
	v_pk_mul_f32 v[168:169], v[58:59], v[58:59]
	v_mul_f32_e32 v170, v55, v55
	v_mul_f32_e32 v172, v57, v57
	v_pk_add_f32 v[146:147], v[162:163], v[146:147]
	v_pk_add_f32 v[144:145], v[144:145], v[150:151]
	v_mov_b32_e32 v149, v171
	v_mov_b32_e32 v159, v173
	v_pk_mov_b32 v[150:151], v[164:165], v[160:161] op_sel:[1,0]
	v_mov_b32_e32 v165, v161
	v_pk_mov_b32 v[160:161], v[168:169], v[166:167] op_sel:[1,0]
	v_mov_b32_e32 v169, v167
	v_pk_fma_f32 v[162:163], v[54:55], v[54:55], v[170:171] op_sel_hi:[1,1,0]
	v_pk_fma_f32 v[166:167], v[56:57], v[56:57], v[172:173] op_sel_hi:[1,1,0]
	v_pk_mul_f32 v[170:171], v[48:49], v[48:49]
	v_pk_mul_f32 v[172:173], v[46:47], v[46:47]
	v_pk_mul_f32 v[174:175], v[44:45], v[44:45]
	v_pk_mul_f32 v[176:177], v[42:43], v[42:43]
	v_mul_f32_e32 v157, v66, v66
	v_mul_f32_e32 v181, v67, v67
	v_mul_f32_e32 v179, v52, v52
	v_mul_f32_e32 v186, v53, v53
	v_mul_f32_e32 v178, v39, v39
	v_mul_f32_e32 v180, v41, v41
	v_pk_add_f32 v[182:183], v[146:147], v[146:147] op_sel:[0,1] op_sel_hi:[1,0]
	v_pk_add_f32 v[184:185], v[144:145], v[144:145] op_sel:[0,1] op_sel_hi:[1,0]
	v_pk_add_f32 v[158:159], v[148:149], v[158:159]
	v_pk_add_f32 v[144:145], v[150:151], v[164:165]
	v_pk_add_f32 v[146:147], v[160:161], v[168:169]
	v_pk_mov_b32 v[148:149], v[172:173], v[170:171] op_sel:[1,0]
	v_mov_b32_e32 v173, v171
	v_pk_mov_b32 v[150:151], v[176:177], v[174:175] op_sel:[1,0]
	v_mov_b32_e32 v177, v175
	v_mul_f32_e32 v187, v50, v50
	v_mul_f32_e32 v192, v51, v51
	v_mul_f32_e32 v195, v36, v36
	v_mul_f32_e32 v196, v37, v37
	v_mov_b32_e32 v163, v179
	v_mov_b32_e32 v167, v186
	v_pk_fma_f32 v[160:161], v[38:39], v[38:39], v[178:179] op_sel_hi:[1,1,0]
	v_pk_fma_f32 v[164:165], v[40:41], v[40:41], v[180:181] op_sel_hi:[1,1,0]
	v_pk_mul_f32 v[168:169], v[32:33], v[32:33]
	v_pk_mul_f32 v[170:171], v[30:31], v[30:31]
	v_pk_mul_f32 v[174:175], v[28:29], v[28:29]
	v_pk_mul_f32 v[178:179], v[26:27], v[26:27]
	v_mov_b32_e32 v183, v157
	v_mov_b32_e32 v185, v181
	v_pk_add_f32 v[188:189], v[144:145], v[144:145] op_sel:[0,1] op_sel_hi:[1,0]
	v_pk_add_f32 v[190:191], v[146:147], v[146:147] op_sel:[0,1] op_sel_hi:[1,0]
	v_pk_add_f32 v[148:149], v[148:149], v[172:173]
	v_pk_add_f32 v[150:151], v[150:151], v[176:177]
	v_mul_f32_e32 v193, v34, v34
	v_mul_f32_e32 v194, v35, v35
	v_pk_add_f32 v[162:163], v[162:163], v[166:167]
	v_mov_b32_e32 v161, v195
	v_mov_b32_e32 v165, v196
	v_pk_mov_b32 v[166:167], v[170:171], v[168:169] op_sel:[1,0]
	v_mov_b32_e32 v171, v169
	v_pk_mov_b32 v[168:169], v[178:179], v[174:175] op_sel:[1,0]
	v_mov_b32_e32 v179, v175
	v_pk_add_f32 v[172:173], v[182:183], v[184:185]
	v_mov_b32_e32 v189, v187
	v_mov_b32_e32 v191, v192
	v_pk_add_f32 v[174:175], v[148:149], v[148:149] op_sel:[0,1] op_sel_hi:[1,0]
	v_pk_add_f32 v[176:177], v[150:151], v[150:151] op_sel:[0,1] op_sel_hi:[1,0]
	v_pk_add_f32 v[160:161], v[160:161], v[164:165]
	v_pk_add_f32 v[158:159], v[172:173], v[158:159]
	v_pk_add_f32 v[164:165], v[188:189], v[190:191]
	v_mov_b32_e32 v175, v193
	v_mov_b32_e32 v177, v194
	v_add_f32_e32 v157, v158, v159
	v_pk_add_f32 v[158:159], v[164:165], v[162:163]
	v_pk_add_f32 v[162:163], v[174:175], v[176:177]
	v_add_f32_e32 v164, v158, v159
	v_pk_add_f32 v[158:159], v[162:163], v[160:161]
	v_add_f32_e32 v158, v158, v159
	v_pk_add_f32 v[148:149], v[166:167], v[170:171]
	s_waitcnt lgkmcnt(0)
	s_nop 1
	v_add_f32_dpp v157, v157, v157 quad_perm:[1,0,3,2] row_mask:0xf bank_mask:0xf
	s_waitcnt lgkmcnt(0)
	s_nop 1
	v_add_f32_dpp v161, v164, v164 quad_perm:[1,0,3,2] row_mask:0xf bank_mask:0xf
	s_waitcnt lgkmcnt(0)
	s_nop 1
	v_add_f32_dpp v158, v158, v158 quad_perm:[1,0,3,2] row_mask:0xf bank_mask:0xf
	s_waitcnt lgkmcnt(0)
	s_nop 1
	v_add_f32_dpp v157, v157, v157 quad_perm:[2,3,0,1] row_mask:0xf bank_mask:0xf
	s_waitcnt lgkmcnt(0)
	s_nop 1
	v_add_f32_dpp v161, v161, v161 quad_perm:[2,3,0,1] row_mask:0xf bank_mask:0xf
	s_waitcnt lgkmcnt(0)
	s_nop 1
	v_add_f32_dpp v158, v158, v158 quad_perm:[2,3,0,1] row_mask:0xf bank_mask:0xf
	s_waitcnt lgkmcnt(0)
	s_nop 1
	v_add_f32_dpp v157, v157, v157 row_half_mirror row_mask:0xf bank_mask:0xf
	s_waitcnt lgkmcnt(0)
	s_nop 1
	v_add_f32_dpp v161, v161, v161 row_half_mirror row_mask:0xf bank_mask:0xf
	s_waitcnt lgkmcnt(0)
	s_nop 1
	v_add_f32_dpp v158, v158, v158 row_half_mirror row_mask:0xf bank_mask:0xf
	s_waitcnt lgkmcnt(0)
	s_nop 1
	v_add_f32_dpp v157, v157, v157 row_mirror row_mask:0xf bank_mask:0xf
	ds_bpermute_b32 v160, v153, v157
	s_waitcnt lgkmcnt(2)
	s_nop 1
	v_add_f32_dpp v161, v161, v161 row_mirror row_mask:0xf bank_mask:0xf
	ds_bpermute_b32 v162, v153, v161
	s_waitcnt lgkmcnt(2)
	s_nop 1
	v_add_f32_dpp v158, v158, v158 row_mirror row_mask:0xf bank_mask:0xf
	ds_bpermute_b32 v159, v153, v158
	s_waitcnt lgkmcnt(2)
	v_add_f32_e32 v157, v157, v160
	ds_bpermute_b32 v160, v154, v157
	s_waitcnt lgkmcnt(2)
	v_add_f32_e32 v161, v161, v162
	ds_bpermute_b32 v162, v154, v161
	s_waitcnt lgkmcnt(2)
	v_add_f32_e32 v158, v158, v159
	ds_bpermute_b32 v159, v154, v158
	s_waitcnt lgkmcnt(2)
	v_add_f32_e32 v157, v157, v160
	v_fmamk_f32 v157, v157, 0x3a800000, v155
	s_waitcnt lgkmcnt(1)
	v_add_f32_e32 v160, v161, v162
	v_mul_f32_e32 v161, 0x4f800000, v157
	v_cmp_gt_f32_e32 vcc, s3, v157
	v_fmamk_f32 v160, v160, 0x3a800000, v155
	s_waitcnt lgkmcnt(0)
	v_add_f32_e32 v158, v158, v159
	v_cndmask_b32_e32 v157, v157, v161, vcc
	v_mul_f32_e32 v159, 0x4f800000, v160
	v_cmp_gt_f32_e64 s[6:7], s3, v160
	v_sqrt_f32_e32 v161, v157
	v_fmamk_f32 v158, v158, 0x3a800000, v155
	v_cndmask_b32_e64 v159, v160, v159, s[6:7]
	v_mul_f32_e32 v160, 0x4f800000, v158
	v_cmp_gt_f32_e64 s[8:9], s3, v158
	v_sqrt_f32_e32 v162, v159
	v_add_u32_e32 v163, -1, v161
	v_cndmask_b32_e64 v158, v158, v160, s[8:9]
	v_sqrt_f32_e32 v160, v158
	v_add_u32_e32 v164, 1, v161
	v_fma_f32 v165, -v163, v161, v157
	v_fma_f32 v166, -v164, v161, v157
	v_add_u32_e32 v167, -1, v162
	v_cmp_ge_f32_e64 s[10:11], 0, v165
	v_pk_add_f32 v[150:151], v[168:169], v[178:179]
	v_add_u32_e32 v168, 1, v162
	v_cndmask_b32_e64 v161, v161, v163, s[10:11]
	v_fma_f32 v163, -v167, v162, v159
	v_cmp_lt_f32_e64 s[10:11], 0, v166
	v_fma_f32 v165, -v168, v162, v159
	v_add_u32_e32 v169, -1, v160
	v_cndmask_b32_e64 v161, v161, v164, s[10:11]
	v_cmp_ge_f32_e64 s[10:11], 0, v163
	v_add_u32_e32 v170, 1, v160
	v_fma_f32 v163, -v169, v160, v158
	v_cndmask_b32_e64 v162, v162, v167, s[10:11]
	v_cmp_lt_f32_e64 s[10:11], 0, v165
	v_fma_f32 v164, -v170, v160, v158
	v_mul_f32_e32 v165, 0x37800000, v161
	v_cndmask_b32_e64 v162, v162, v168, s[10:11]
	v_cmp_ge_f32_e64 s[10:11], 0, v163
	v_cndmask_b32_e32 v161, v161, v165, vcc
	v_cmp_class_f32_e32 vcc, v157, v156
	v_cndmask_b32_e64 v160, v160, v169, s[10:11]
	v_cmp_lt_f32_e64 s[10:11], 0, v164
	v_mul_f32_e32 v163, 0x37800000, v162
	v_cndmask_b32_e32 v157, v161, v157, vcc
	v_cndmask_b32_e64 v160, v160, v170, s[10:11]
	v_cndmask_b32_e64 v161, v162, v163, s[6:7]
	v_cmp_class_f32_e32 vcc, v159, v156
	v_mul_f32_e32 v162, 0x37800000, v160
	v_div_scale_f32 v163, s[6:7], v157, v157, 1.0
	v_cndmask_b32_e32 v159, v161, v159, vcc
	v_cndmask_b32_e64 v160, v160, v162, s[8:9]
	v_cmp_class_f32_e32 vcc, v158, v156
	v_rcp_f32_e32 v161, v163
	v_div_scale_f32 v162, s[8:9], v159, v159, 1.0
	v_cndmask_b32_e32 v160, v160, v158, vcc
	v_rcp_f32_e32 v166, v162
	v_div_scale_f32 v167, s[10:11], v160, v160, 1.0
	v_rcp_f32_e32 v169, v167
	v_fma_f32 v158, -v163, v161, 1.0
	v_div_scale_f32 v164, s[6:7], 1.0, v157, 1.0
	v_fmac_f32_e32 v161, v158, v161
	v_fma_f32 v158, -v162, v166, 1.0
	v_mul_f32_e32 v170, v164, v161
	v_div_scale_f32 v165, s[8:9], 1.0, v159, 1.0
	v_fmac_f32_e32 v166, v158, v166
	v_fma_f32 v158, -v167, v169, 1.0
	v_fma_f32 v171, -v163, v170, v164
	v_div_scale_f32 v168, s[10:11], 1.0, v160, 1.0
	v_mul_f32_e32 v172, v165, v166
	v_fmac_f32_e32 v169, v158, v169
	v_fmac_f32_e32 v170, v171, v161
	v_fma_f32 v158, -v162, v172, v165
	v_mul_f32_e32 v171, v168, v169
	v_fma_f32 v163, -v163, v170, v164
	s_mov_b64 vcc, s[6:7]
	v_fmac_f32_e32 v172, v158, v166
	v_fma_f32 v158, -v167, v171, v168
	v_div_fmas_f32 v161, v163, v161, v170
	v_fma_f32 v162, -v162, v172, v165
	v_fmac_f32_e32 v171, v158, v169
	v_div_fixup_f32 v158, v161, v157, 1.0
	s_mov_b64 vcc, s[8:9]
	v_div_fmas_f32 v157, v162, v166, v172
	v_fma_f32 v161, -v167, v171, v168
	v_pk_mul_f32 v[80:81], v[80:81], v[158:159] op_sel_hi:[1,0]
	v_pk_mul_f32 v[78:79], v[78:79], v[158:159] op_sel_hi:[1,0]
	s_mov_b64 vcc, s[10:11]
	v_pk_add_f32 v[88:89], v[88:89], 1.0 op_sel_hi:[1,0]
	v_pk_add_f32 v[86:87], v[86:87], 1.0 op_sel_hi:[1,0]
	v_pk_mul_f32 v[76:77], v[76:77], v[158:159] op_sel_hi:[1,0]
	v_pk_mul_f32 v[74:75], v[74:75], v[158:159] op_sel_hi:[1,0]
	v_pk_mul_f32 v[72:73], v[72:73], v[158:159] op_sel_hi:[1,0]
	v_pk_mul_f32 v[70:71], v[70:71], v[158:159] op_sel_hi:[1,0]
	v_pk_mul_f32 v[68:69], v[68:69], v[158:159] op_sel_hi:[1,0]
	v_pk_mul_f32 v[66:67], v[66:67], v[158:159] op_sel_hi:[1,0]
	v_div_fixup_f32 v158, v157, v159, 1.0
	v_div_fmas_f32 v157, v161, v169, v171
	v_pk_mul_f32 v[78:79], v[78:79], v[2:3]
	v_pk_mul_f32 v[80:81], v[80:81], v[4:5]
	v_pk_mul_f32 v[64:65], v[64:65], v[158:159] op_sel_hi:[1,0]
	v_pk_mul_f32 v[62:63], v[62:63], v[158:159] op_sel_hi:[1,0]
	v_pk_mul_f32 v[60:61], v[60:61], v[158:159] op_sel_hi:[1,0]
	v_pk_mul_f32 v[58:59], v[58:59], v[158:159] op_sel_hi:[1,0]
	v_pk_mul_f32 v[56:57], v[56:57], v[158:159] op_sel_hi:[1,0]
	v_pk_mul_f32 v[54:55], v[54:55], v[158:159] op_sel_hi:[1,0]
	v_pk_mul_f32 v[52:53], v[52:53], v[158:159] op_sel_hi:[1,0]
	v_pk_mul_f32 v[158:159], v[50:51], v[158:159] op_sel_hi:[1,0]
	v_div_fixup_f32 v50, v157, v160, 1.0
	v_pk_fma_f32 v[80:81], v[80:81], v[88:89], v[84:85]
	v_pk_fma_f32 v[78:79], v[78:79], v[86:87], v[82:83]
	v_pk_mul_f32 v[86:87], v[52:53], v[16:17]
	v_pk_mul_f32 v[48:49], v[48:49], v[50:51] op_sel_hi:[1,0]
	v_pk_mul_f32 v[46:47], v[46:47], v[50:51] op_sel_hi:[1,0]
	v_pk_mul_f32 v[82:83], v[54:55], v[10:11]
	v_pk_mul_f32 v[84:85], v[158:159], v[14:15]
	v_pk_mul_f32 v[88:89], v[46:47], v[2:3]
	v_pk_mul_f32 v[158:159], v[48:49], v[4:5]
	v_cvt_pk_bf16_f32 v46, v78, v79
	v_cvt_pk_bf16_f32 v47, v80, v81
	global_store_dwordx2 v[102:103], v[46:47], off
	global_load_dwordx4 v[46:49], v[138:139], off
	s_nop 0
	global_load_dwordx4 v[52:55], v[124:125], off offset:1024
	v_pk_mul_f32 v[74:75], v[74:75], v[6:7]
	v_pk_mul_f32 v[76:77], v[76:77], v[8:9]
	v_pk_mul_f32 v[70:71], v[70:71], v[10:11]
	v_pk_mul_f32 v[72:73], v[72:73], v[12:13]
	v_pk_mul_f32 v[66:67], v[66:67], v[14:15]
	v_pk_mul_f32 v[68:69], v[68:69], v[16:17]
	v_pk_mul_f32 v[62:63], v[62:63], v[2:3]
	v_pk_mul_f32 v[64:65], v[64:65], v[4:5]
	v_pk_mul_f32 v[58:59], v[58:59], v[6:7]
	v_pk_mul_f32 v[60:61], v[60:61], v[8:9]
	v_pk_mul_f32 v[56:57], v[56:57], v[12:13]
	v_mul_f32_e32 v180, v23, v23
	v_mul_f32_e32 v186, v25, v25
	v_mul_f32_e32 v197, v18, v18
	v_mul_f32_e32 v198, v19, v19
	v_mul_f32_e32 v199, v20, v20
	v_mul_f32_e32 v200, v21, v21
	v_pk_fma_f32 v[144:145], v[22:23], v[22:23], v[180:181] op_sel_hi:[1,1,0]
	v_pk_fma_f32 v[146:147], v[24:25], v[24:25], v[186:187] op_sel_hi:[1,1,0]
	v_mov_b32_e32 v145, v199
	v_mov_b32_e32 v147, v200
	v_lshl_add_u64 v[94:95], v[94:95], 0, s[18:19]
	s_mov_b32 s8, s25
	s_cmp_lt_i32 s25, s13
	s_waitcnt vmcnt(0) lgkmcnt(0)
	v_pk_add_f32 v[48:49], v[48:49], 1.0 op_sel_hi:[1,0]
	v_pk_add_f32 v[46:47], v[46:47], 1.0 op_sel_hi:[1,0]
	v_pk_fma_f32 v[48:49], v[76:77], v[48:49], v[54:55]
	v_pk_fma_f32 v[46:47], v[74:75], v[46:47], v[52:53]
	v_cvt_pk_bf16_f32 v46, v46, v47
	v_cvt_pk_bf16_f32 v47, v48, v49
	global_store_dwordx2 v[102:103], v[46:47], off offset:512
	global_load_dwordx4 v[46:49], v[134:135], off
	s_nop 0
	global_load_dwordx4 v[52:55], v[124:125], off offset:2048
	s_waitcnt vmcnt(0) lgkmcnt(0)
	v_pk_add_f32 v[48:49], v[48:49], 1.0 op_sel_hi:[1,0]
	v_pk_add_f32 v[46:47], v[46:47], 1.0 op_sel_hi:[1,0]
	v_pk_fma_f32 v[48:49], v[72:73], v[48:49], v[54:55]
	v_pk_fma_f32 v[46:47], v[70:71], v[46:47], v[52:53]
	v_cvt_pk_bf16_f32 v46, v46, v47
	v_cvt_pk_bf16_f32 v47, v48, v49
	global_store_dwordx2 v[102:103], v[46:47], off offset:1024
	global_load_dwordx4 v[46:49], v[128:129], off
	s_nop 0
	global_load_dwordx4 v[52:55], v[124:125], off offset:3072
	s_waitcnt vmcnt(0) lgkmcnt(0)
	v_pk_add_f32 v[48:49], v[48:49], 1.0 op_sel_hi:[1,0]
	v_pk_add_f32 v[46:47], v[46:47], 1.0 op_sel_hi:[1,0]
	v_pk_fma_f32 v[48:49], v[68:69], v[48:49], v[54:55]
	v_pk_fma_f32 v[46:47], v[66:67], v[46:47], v[52:53]
	v_cvt_pk_bf16_f32 v46, v46, v47
	v_cvt_pk_bf16_f32 v47, v48, v49
	global_store_dwordx2 v[102:103], v[46:47], off offset:1536
	global_load_dwordx4 v[46:49], v[126:127], off
	s_nop 0
	global_load_dwordx4 v[52:55], v[110:111], off
	s_waitcnt vmcnt(0) lgkmcnt(0)
	v_pk_add_f32 v[48:49], v[48:49], 1.0 op_sel_hi:[1,0]
	v_pk_add_f32 v[46:47], v[46:47], 1.0 op_sel_hi:[1,0]
	v_pk_fma_f32 v[48:49], v[64:65], v[48:49], v[54:55]
	v_pk_fma_f32 v[46:47], v[62:63], v[46:47], v[52:53]
	v_cvt_pk_bf16_f32 v46, v46, v47
	v_cvt_pk_bf16_f32 v47, v48, v49
	global_store_dwordx2 v[102:103], v[46:47], off offset:2048
	global_load_dwordx4 v[46:49], v[120:121], off
	s_nop 0
	global_load_dwordx4 v[52:55], v[110:111], off offset:1024
	s_waitcnt vmcnt(0) lgkmcnt(0)
	v_pk_add_f32 v[48:49], v[48:49], 1.0 op_sel_hi:[1,0]
	v_pk_add_f32 v[46:47], v[46:47], 1.0 op_sel_hi:[1,0]
	v_pk_fma_f32 v[48:49], v[60:61], v[48:49], v[54:55]
	v_pk_fma_f32 v[46:47], v[58:59], v[46:47], v[52:53]
	v_cvt_pk_bf16_f32 v46, v46, v47
	v_cvt_pk_bf16_f32 v47, v48, v49
	global_store_dwordx2 v[102:103], v[46:47], off offset:2560
	global_load_dwordx4 v[46:49], v[116:117], off
	s_nop 0
	global_load_dwordx4 v[52:55], v[110:111], off offset:2048
	v_pk_add_f32 v[58:59], v[150:151], v[150:151] op_sel:[0,1] op_sel_hi:[1,0]
	v_pk_add_f32 v[60:61], v[144:145], v[146:147]
	v_mov_b32_e32 v59, v198
	s_waitcnt vmcnt(0) lgkmcnt(0)
	v_pk_add_f32 v[48:49], v[48:49], 1.0 op_sel_hi:[1,0]
	v_pk_add_f32 v[46:47], v[46:47], 1.0 op_sel_hi:[1,0]
	v_pk_fma_f32 v[48:49], v[56:57], v[48:49], v[54:55]
	v_pk_fma_f32 v[46:47], v[82:83], v[46:47], v[52:53]
	v_cvt_pk_bf16_f32 v46, v46, v47
	v_cvt_pk_bf16_f32 v47, v48, v49
	global_store_dwordx2 v[102:103], v[46:47], off offset:3072
	global_load_dwordx4 v[46:49], v[112:113], off
	s_nop 0
	global_load_dwordx4 v[52:55], v[110:111], off offset:3072
	v_pk_add_f32 v[56:57], v[148:149], v[148:149] op_sel:[0,1] op_sel_hi:[1,0]
	s_waitcnt vmcnt(0) lgkmcnt(0)
	v_pk_add_f32 v[48:49], v[48:49], 1.0 op_sel_hi:[1,0]
	v_pk_add_f32 v[46:47], v[46:47], 1.0 op_sel_hi:[1,0]
	v_pk_fma_f32 v[48:49], v[86:87], v[48:49], v[54:55]
	v_pk_fma_f32 v[46:47], v[84:85], v[46:47], v[52:53]
	v_cvt_pk_bf16_f32 v46, v46, v47
	v_cvt_pk_bf16_f32 v47, v48, v49
	global_store_dwordx2 v[102:103], v[46:47], off offset:3584
	global_load_dwordx4 v[46:49], v[142:143], off
	s_nop 0
	global_load_dwordx4 v[52:55], v[108:109], off
	v_mov_b32_e32 v57, v197
	s_waitcnt vmcnt(0) lgkmcnt(0)
	v_pk_add_f32 v[48:49], v[48:49], 1.0 op_sel_hi:[1,0]
	v_pk_add_f32 v[46:47], v[46:47], 1.0 op_sel_hi:[1,0]
	v_pk_fma_f32 v[48:49], v[158:159], v[48:49], v[54:55]
	v_pk_fma_f32 v[46:47], v[88:89], v[46:47], v[52:53]
	v_bfe_u32 v51, v46, 16, 1
	v_bfe_u32 v52, v47, 16, 1
	v_add3_u32 v46, v46, v51, s4
	v_add3_u32 v47, v47, v52, s4
	v_lshrrev_b32_e32 v46, 16, v46
	v_and_or_b32 v46, v47, s22, v46
	v_cvt_pk_bf16_f32 v47, v48, v49
	global_store_dwordx2 v[104:105], v[46:47], off
	global_load_dwordx4 v[46:49], v[140:141], off
	s_nop 0
	global_load_dwordx4 v[52:55], v[108:109], off offset:1024
	v_pk_mul_f32 v[44:45], v[44:45], v[50:51] op_sel_hi:[1,0]
	v_pk_mul_f32 v[42:43], v[42:43], v[50:51] op_sel_hi:[1,0]
	v_pk_mul_f32 v[44:45], v[44:45], v[8:9]
	v_pk_mul_f32 v[42:43], v[42:43], v[6:7]
	s_waitcnt vmcnt(0) lgkmcnt(0)
	v_pk_add_f32 v[48:49], v[48:49], 1.0 op_sel_hi:[1,0]
	v_pk_add_f32 v[46:47], v[46:47], 1.0 op_sel_hi:[1,0]
	v_pk_fma_f32 v[44:45], v[44:45], v[48:49], v[54:55]
	v_pk_fma_f32 v[42:43], v[42:43], v[46:47], v[52:53]
	v_cvt_pk_bf16_f32 v42, v42, v43
	v_cvt_pk_bf16_f32 v43, v44, v45
	global_store_dwordx2 v[104:105], v[42:43], off offset:512
	global_load_dwordx4 v[42:45], v[136:137], off
	s_nop 0
	global_load_dwordx4 v[46:49], v[108:109], off offset:2048
	v_pk_add_f32 v[52:53], v[56:57], v[58:59]
	s_waitcnt vmcnt(0) lgkmcnt(0)
	v_pk_add_f32 v[44:45], v[44:45], 1.0 op_sel_hi:[1,0]
	v_pk_add_f32 v[52:53], v[52:53], v[60:61]
	v_pk_add_f32 v[42:43], v[42:43], 1.0 op_sel_hi:[1,0]
	v_add_f32_e32 v51, v52, v53
	s_waitcnt lgkmcnt(0)
	s_nop 1
	v_add_f32_dpp v51, v51, v51 quad_perm:[1,0,3,2] row_mask:0xf bank_mask:0xf
	ds_bpermute_b32 v52, v131, v51
	s_waitcnt lgkmcnt(0)
	v_add_f32_e32 v51, v51, v52
	v_pk_mul_f32 v[40:41], v[40:41], v[50:51] op_sel_hi:[1,0]
	v_pk_mul_f32 v[38:39], v[38:39], v[50:51] op_sel_hi:[1,0]
	v_pk_mul_f32 v[40:41], v[40:41], v[12:13]
	v_pk_mul_f32 v[38:39], v[38:39], v[10:11]
	v_pk_fma_f32 v[40:41], v[40:41], v[44:45], v[48:49]
	v_pk_fma_f32 v[38:39], v[38:39], v[42:43], v[46:47]
	v_cvt_pk_bf16_f32 v38, v38, v39
	v_cvt_pk_bf16_f32 v39, v40, v41
	global_store_dwordx2 v[104:105], v[38:39], off offset:1024
	global_load_dwordx4 v[38:41], v[122:123], off
	s_nop 0
	global_load_dwordx4 v[42:45], v[108:109], off offset:3072
	v_pk_mul_f32 v[36:37], v[36:37], v[50:51] op_sel_hi:[1,0]
	v_pk_mul_f32 v[34:35], v[34:35], v[50:51] op_sel_hi:[1,0]
	v_pk_mul_f32 v[36:37], v[36:37], v[16:17]
	v_pk_mul_f32 v[34:35], v[34:35], v[14:15]
	ds_bpermute_b32 v46, v133, v51
	s_waitcnt lgkmcnt(0)
	v_add_f32_e32 v46, v51, v46
	ds_bpermute_b32 v47, v152, v46
	s_waitcnt lgkmcnt(0)
	v_add_f32_e32 v46, v46, v47
	ds_bpermute_b32 v47, v153, v46
	s_waitcnt lgkmcnt(0)
	v_add_f32_e32 v46, v46, v47
	ds_bpermute_b32 v47, v154, v46
	s_waitcnt lgkmcnt(0)
	v_add_f32_e32 v46, v46, v47
	v_fmamk_f32 v46, v46, 0x3a800000, v155
	v_mul_f32_e32 v47, 0x4f800000, v46
	v_cmp_gt_f32_e32 vcc, s3, v46
	s_waitcnt vmcnt(0)
	v_pk_add_f32 v[40:41], v[40:41], 1.0 op_sel_hi:[1,0]
	v_pk_add_f32 v[38:39], v[38:39], 1.0 op_sel_hi:[1,0]
	v_pk_fma_f32 v[36:37], v[36:37], v[40:41], v[44:45]
	v_pk_fma_f32 v[34:35], v[34:35], v[38:39], v[42:43]
	v_cvt_pk_bf16_f32 v34, v34, v35
	v_cvt_pk_bf16_f32 v35, v36, v37
	global_store_dwordx2 v[104:105], v[34:35], off offset:1536
	global_load_dwordx4 v[34:37], v[118:119], off
	s_nop 0
	global_load_dwordx4 v[38:41], v[106:107], off
	v_cndmask_b32_e32 v42, v46, v47, vcc
	v_sqrt_f32_e32 v43, v42
	s_waitcnt vmcnt(0) lgkmcnt(0)
	v_pk_add_f32 v[36:37], v[36:37], 1.0 op_sel_hi:[1,0]
	v_add_u32_e32 v44, -1, v43
	v_add_u32_e32 v45, 1, v43
	v_fma_f32 v46, -v44, v43, v42
	v_fma_f32 v47, -v45, v43, v42
	v_cmp_ge_f32_e64 s[6:7], 0, v46
	v_pk_add_f32 v[34:35], v[34:35], 1.0 op_sel_hi:[1,0]
	s_nop 0
	v_cndmask_b32_e64 v43, v43, v44, s[6:7]
	v_cmp_lt_f32_e64 s[6:7], 0, v47
	s_nop 1
	v_cndmask_b32_e64 v43, v43, v45, s[6:7]
	v_mul_f32_e32 v44, 0x37800000, v43
	v_cndmask_b32_e32 v43, v43, v44, vcc
	v_cmp_class_f32_e32 vcc, v42, v156
	s_nop 1
	v_cndmask_b32_e32 v42, v43, v42, vcc
	v_div_scale_f32 v43, s[6:7], v42, v42, 1.0
	v_rcp_f32_e32 v45, v43
	v_div_scale_f32 v44, vcc, 1.0, v42, 1.0
	v_fma_f32 v46, -v43, v45, 1.0
	v_fmac_f32_e32 v45, v46, v45
	v_mul_f32_e32 v46, v44, v45
	v_fma_f32 v47, -v43, v46, v44
	v_fmac_f32_e32 v46, v47, v45
	v_fma_f32 v43, -v43, v46, v44
	v_div_fmas_f32 v43, v43, v45, v46
	v_div_fixup_f32 v42, v43, v42, 1.0
	v_pk_mul_f32 v[32:33], v[32:33], v[42:43] op_sel_hi:[1,0]
	v_pk_mul_f32 v[30:31], v[30:31], v[42:43] op_sel_hi:[1,0]
	v_pk_mul_f32 v[32:33], v[32:33], v[4:5]
	v_pk_mul_f32 v[30:31], v[30:31], v[2:3]
	v_pk_fma_f32 v[32:33], v[32:33], v[36:37], v[40:41]
	v_pk_fma_f32 v[30:31], v[30:31], v[34:35], v[38:39]
	v_cvt_pk_bf16_f32 v30, v30, v31
	v_cvt_pk_bf16_f32 v31, v32, v33
	global_store_dwordx2 v[104:105], v[30:31], off offset:2048
	global_load_dwordx4 v[30:33], v[114:115], off
	s_nop 0
	global_load_dwordx4 v[34:37], v[106:107], off offset:1024
	v_pk_mul_f32 v[28:29], v[28:29], v[42:43] op_sel_hi:[1,0]
	v_pk_mul_f32 v[26:27], v[26:27], v[42:43] op_sel_hi:[1,0]
	v_pk_mul_f32 v[28:29], v[28:29], v[8:9]
	v_pk_mul_f32 v[26:27], v[26:27], v[6:7]
	v_lshl_add_u64 v[38:39], s[20:21], 0, v[98:99]
	v_pk_mul_f32 v[24:25], v[24:25], v[42:43] op_sel_hi:[1,0]
	v_pk_mul_f32 v[22:23], v[22:23], v[42:43] op_sel_hi:[1,0]
	v_pk_mul_f32 v[24:25], v[24:25], v[12:13]
	v_pk_mul_f32 v[22:23], v[22:23], v[10:11]
	v_pk_mul_f32 v[20:21], v[20:21], v[42:43] op_sel_hi:[1,0]
	v_pk_mul_f32 v[18:19], v[18:19], v[42:43] op_sel_hi:[1,0]
	v_pk_mul_f32 v[20:21], v[20:21], v[16:17]
	v_pk_mul_f32 v[18:19], v[18:19], v[14:15]
	s_waitcnt vmcnt(0) lgkmcnt(0)
	v_pk_add_f32 v[32:33], v[32:33], 1.0 op_sel_hi:[1,0]
	v_pk_add_f32 v[30:31], v[30:31], 1.0 op_sel_hi:[1,0]
	v_pk_fma_f32 v[28:29], v[28:29], v[32:33], v[36:37]
	v_pk_fma_f32 v[26:27], v[26:27], v[30:31], v[34:35]
	v_cvt_pk_bf16_f32 v26, v26, v27
	v_cvt_pk_bf16_f32 v27, v28, v29
	global_store_dwordx2 v[104:105], v[26:27], off offset:2560
	global_load_dwordx4 v[26:29], v[38:39], off
	s_nop 0
	global_load_dwordx4 v[30:33], v[106:107], off offset:2048
	v_lshl_add_u64 v[34:35], s[20:21], 0, v[100:101]
	s_waitcnt vmcnt(0) lgkmcnt(0)
	v_pk_add_f32 v[28:29], v[28:29], 1.0 op_sel_hi:[1,0]
	v_pk_add_f32 v[26:27], v[26:27], 1.0 op_sel_hi:[1,0]
	v_pk_fma_f32 v[24:25], v[24:25], v[28:29], v[32:33]
	v_pk_fma_f32 v[22:23], v[22:23], v[26:27], v[30:31]
	v_cvt_pk_bf16_f32 v22, v22, v23
	v_cvt_pk_bf16_f32 v23, v24, v25
	global_store_dwordx2 v[104:105], v[22:23], off offset:3072
	global_load_dwordx4 v[22:25], v[34:35], off
	s_nop 0
	global_load_dwordx4 v[26:29], v[106:107], off offset:3072
	s_waitcnt vmcnt(0) lgkmcnt(0)
	v_pk_add_f32 v[24:25], v[24:25], 1.0 op_sel_hi:[1,0]
	v_pk_add_f32 v[22:23], v[22:23], 1.0 op_sel_hi:[1,0]
	v_pk_fma_f32 v[20:21], v[20:21], v[24:25], v[28:29]
	v_pk_fma_f32 v[18:19], v[18:19], v[22:23], v[26:27]
	v_cvt_pk_bf16_f32 v18, v18, v19
	v_cvt_pk_bf16_f32 v19, v20, v21
	global_store_dwordx2 v[104:105], v[18:19], off offset:3584
	s_cbranch_scc1 .LBB0_3611

.LBB0_4898:
	s_cmp_lt_i32 s5, 4
	s_cselect_b64 s[20:21], -1, 0
	s_cmp_gt_i32 s5, 3
	s_waitcnt lgkmcnt(0)
	s_barrier
	s_cbranch_scc1 .LBB0_4900
	s_lshl_b32 s6, s5, 9
	s_add_i32 s6, s3, s6
	v_lshl_add_u32 v4, v1, 2, s6
	ds_read2st64_b32 v[2:3], v4 offset0:4 offset1:5
	v_and_b32_e32 v5, 64, v166
	v_xor_b32_e32 v6, 1, v166
	v_add_u32_e32 v5, 64, v5
	v_cmp_lt_i32_e32 vcc, v6, v5
	s_waitcnt lgkmcnt(0)
	v_max_f32_e32 v7, v3, v3
	v_max_f32_e32 v8, v2, v2
	v_cndmask_b32_e32 v6, v166, v6, vcc
	v_max_f32_e32 v7, v8, v7
	v_lshlrev_b32_e32 v6, 2, v6
	ds_bpermute_b32 v8, v6, v7
	v_xor_b32_e32 v9, 2, v166
	v_cmp_lt_i32_e32 vcc, v9, v5
	v_xor_b32_e32 v10, 4, v166
	v_xor_b32_e32 v11, 8, v166
	s_waitcnt lgkmcnt(0)
	v_max_f32_e32 v8, v8, v8
	v_max_f32_e32 v7, v7, v8
	v_cndmask_b32_e32 v8, v166, v9, vcc
	v_lshlrev_b32_e32 v8, 2, v8
	ds_bpermute_b32 v9, v8, v7
	v_cmp_lt_i32_e32 vcc, v10, v5
	v_xor_b32_e32 v12, 16, v166
	v_xor_b32_e32 v13, 32, v166
	s_waitcnt lgkmcnt(0)
	v_max_f32_e32 v9, v9, v9
	v_max_f32_e32 v7, v7, v9
	v_cndmask_b32_e32 v9, v166, v10, vcc
	v_lshlrev_b32_e32 v9, 2, v9
	ds_bpermute_b32 v10, v9, v7
	v_cmp_lt_i32_e32 vcc, v11, v5
	s_waitcnt lgkmcnt(0)
	v_max_f32_e32 v10, v10, v10
	v_max_f32_e32 v7, v7, v10
	v_cndmask_b32_e32 v10, v166, v11, vcc
	v_lshlrev_b32_e32 v10, 2, v10
	ds_bpermute_b32 v11, v10, v7
	v_cmp_lt_i32_e32 vcc, v12, v5
	s_waitcnt lgkmcnt(0)
	v_max_f32_e32 v11, v11, v11
	v_max_f32_e32 v7, v7, v11
	v_cndmask_b32_e32 v11, v166, v12, vcc
	v_lshlrev_b32_e32 v11, 2, v11
	ds_bpermute_b32 v12, v11, v7
	v_cmp_lt_i32_e32 vcc, v13, v5
	s_waitcnt lgkmcnt(0)
	v_max_f32_e32 v12, v12, v12
	v_cndmask_b32_e32 v5, v166, v13, vcc
	v_max_f32_e32 v7, v7, v12
	v_lshlrev_b32_e32 v5, 2, v5
	ds_bpermute_b32 v12, v5, v7
	s_waitcnt lgkmcnt(0)
	v_max_f32_e32 v12, v12, v12
	v_max_f32_e32 v7, v7, v12
	v_sub_f32_e32 v2, v2, v7
	v_sub_f32_e32 v3, v3, v7
	v_mul_f32_e32 v2, 0x3fb8aa3b, v2
	v_mul_f32_e32 v3, 0x3fb8aa3b, v3
	v_exp_f32_e32 v2, v2
	v_exp_f32_e32 v3, v3
	s_nop 0
	v_add_f32_e32 v7, v2, v3
	ds_bpermute_b32 v6, v6, v7
	s_waitcnt lgkmcnt(0)
	v_add_f32_e32 v6, v7, v6
	s_waitcnt lgkmcnt(0)
	s_nop 1
	v_add_f32_dpp v6, v6, v6 quad_perm:[2,3,0,1] row_mask:0xf bank_mask:0xf
	ds_bpermute_b32 v7, v9, v6
	s_waitcnt lgkmcnt(0)
	v_add_f32_e32 v6, v6, v7
	ds_bpermute_b32 v7, v10, v6
	s_waitcnt lgkmcnt(0)
	v_add_f32_e32 v6, v6, v7
	ds_bpermute_b32 v7, v11, v6
	s_waitcnt lgkmcnt(0)
	v_add_f32_e32 v6, v6, v7
	ds_bpermute_b32 v5, v5, v6
	s_waitcnt lgkmcnt(0)
	v_add_f32_e32 v5, v6, v5
	v_max_f32_e32 v5, 0xda24260, v5
	v_div_scale_f32 v6, s[6:7], v5, v5, 1.0
	v_rcp_f32_e32 v7, v6
	v_div_scale_f32 v8, vcc, 1.0, v5, 1.0
	v_fma_f32 v9, -v6, v7, 1.0
	v_fmac_f32_e32 v7, v9, v7
	v_mul_f32_e32 v9, v8, v7
	v_fma_f32 v10, -v6, v9, v8
	v_fmac_f32_e32 v9, v10, v7
	v_fma_f32 v6, -v6, v9, v8
	v_div_fmas_f32 v6, v6, v7, v9
	v_div_fixup_f32 v5, v6, v5, 1.0
	v_mul_f32_e32 v2, v2, v5
	v_mul_f32_e32 v3, v3, v5
	ds_write2st64_b32 v4, v2, v3 offset0:4 offset1:5

.LBB0_5341:
	s_lshr_b32 s10, s48, 2
	s_cmp_lt_u32 s48, 4
	s_cselect_b64 vcc, -1, 0
	s_cmp_eq_u32 s10, 2
	s_cselect_b32 s12, s31, s29
	s_cselect_b32 s13, s42, s30
	s_cmp_eq_u32 s10, 1
	s_cselect_b64 s[10:11], -1, 0
	v_cndmask_b32_e64 v66, v106, v108, s[10:11]
	v_cndmask_b32_e64 v67, v107, v109, s[10:11]
	s_and_b64 s[10:11], s[10:11], exec
	s_cselect_b32 s14, s27, s28
	s_and_b64 s[10:11], vcc, exec
	s_cselect_b32 s14, s26, s14
	s_sub_i32 s10, s43, 32
	s_and_b32 s15, s10, 32
	s_or_b32 s10, s15, s14
	v_add_u32_e32 v80, s10, v100
	v_add_u32_e32 v144, 16, v80
	v_cndmask_b32_e32 v78, v66, v104, vcc
	v_subrev_u32_e32 v66, s14, v144
	v_cndmask_b32_e32 v79, v67, v105, vcc
	v_ashrrev_i32_e32 v67, 31, v66
	v_lshlrev_b64 v[66:67], 10, v[66:67]
	v_lshl_add_u64 v[66:67], v[78:79], 0, v[66:67]
	v_mov_b32_e32 v82, s13
	v_cmp_gt_i32_e64 s[10:11], s44, v144
	v_mov_b32_e32 v83, s12
	v_add_u32_e32 v147, 20, v80
	v_cndmask_b32_e64 v67, v82, v67, s[10:11]
	v_cndmask_b32_e64 v66, v83, v66, s[10:11]
	v_lshl_add_u64 v[66:67], v[66:67], 0, v[98:99]
	v_add_u32_e32 v146, 24, v80
	v_add_u32_e32 v145, 28, v80
	global_load_dwordx4 v[94:97], v[66:67], off
	global_load_dwordx4 v[74:77], v[66:67], off offset:512
	v_subrev_u32_e32 v66, s14, v147
	v_subrev_u32_e32 v70, s14, v146
	v_subrev_u32_e32 v80, s14, v145
	v_ashrrev_i32_e32 v67, 31, v66
	v_ashrrev_i32_e32 v71, 31, v70
	v_ashrrev_i32_e32 v81, 31, v80
	v_lshlrev_b64 v[66:67], 10, v[66:67]
	v_lshlrev_b64 v[70:71], 10, v[70:71]
	v_lshlrev_b64 v[80:81], 10, v[80:81]
	v_lshl_add_u64 v[66:67], v[78:79], 0, v[66:67]
	v_lshl_add_u64 v[70:71], v[78:79], 0, v[70:71]
	v_lshl_add_u64 v[78:79], v[78:79], 0, v[80:81]
	s_waitcnt vmcnt(0) lgkmcnt(0)
	v_mul_f32_e32 v80, v11, v3
	v_fmac_f32_e32 v80, v10, v2
	v_fmac_f32_e32 v80, v12, v4
	v_fmac_f32_e32 v80, v13, v5
	v_cmp_gt_i32_e64 s[10:11], s44, v147
	v_mul_f32_e32 v148, v11, v27
	v_fmac_f32_e32 v148, v10, v26
	v_cndmask_b32_e64 v67, v82, v67, s[10:11]
	s_waitcnt lgkmcnt(0)
	v_add_f32_dpp v80, v80, v80 quad_perm:[1,0,3,2] row_mask:0xf bank_mask:0xf
	v_cndmask_b32_e64 v66, v83, v66, s[10:11]
	v_cmp_gt_i32_e64 s[10:11], s44, v146
	v_mul_f32_e32 v125, v23, v3
	v_cndmask_b32_e64 v71, v82, v71, s[10:11]
	v_cndmask_b32_e64 v70, v83, v70, s[10:11]
	v_cmp_gt_i32_e64 s[10:11], s44, v145
	s_waitcnt lgkmcnt(0)
	v_add_f32_dpp v80, v80, v80 quad_perm:[2,3,0,1] row_mask:0xf bank_mask:0xf
	v_cndmask_b32_e64 v79, v82, v79, s[10:11]
	v_mul_f32_e32 v82, v15, v3
	v_fmac_f32_e32 v82, v14, v2
	v_fmac_f32_e32 v82, v16, v4
	v_fmac_f32_e32 v82, v17, v5
	v_cndmask_b32_e64 v78, v83, v78, s[10:11]
	s_and_b32 s10, s48, 12
	s_waitcnt lgkmcnt(0)
	v_add_f32_dpp v118, v80, v80 row_half_mirror row_mask:0xf bank_mask:0xf
	s_cmp_eq_u32 s10, 4
	s_waitcnt lgkmcnt(0)
	v_add_f32_dpp v120, v82, v82 quad_perm:[1,0,3,2] row_mask:0xf bank_mask:0xf
	s_cselect_b32 s12, s27, s28
	s_and_b64 s[10:11], vcc, exec
	s_cselect_b32 s10, s26, s12
	s_or_b32 s10, s10, s15
	v_add_u32_e32 v156, s10, v100
	v_sub_u32_e32 v84, 0x800, v156
	s_waitcnt lgkmcnt(0)
	v_add_f32_dpp v118, v118, v118 row_mirror row_mask:0xf bank_mask:0xf
	s_waitcnt lgkmcnt(0)
	v_add_f32_dpp v119, v120, v120 quad_perm:[2,3,0,1] row_mask:0xf bank_mask:0xf
	v_cvt_f32_u32_e32 v124, v84
	v_cmp_gt_i32_e32 vcc, s2, v156
	v_fmac_f32_e32 v125, v22, v2
	v_fma_f32 v118, -v127, v124, v118
	v_cndmask_b32_e32 v169, v135, v118, vcc
	s_waitcnt lgkmcnt(0)
	v_add_f32_dpp v120, v119, v119 row_half_mirror row_mask:0xf bank_mask:0xf
	v_pk_mul_f32 v[118:119], v[12:13], v[28:29]
	v_fmac_f32_e32 v125, v24, v4
	v_add_f32_e32 v118, v118, v148
	v_add_f32_e32 v118, v119, v118
	v_fmac_f32_e32 v125, v25, v5
	v_mul_f32_e32 v150, v15, v27
	v_fmac_f32_e32 v150, v14, v26
	s_waitcnt lgkmcnt(0)
	v_add_f32_dpp v118, v118, v118 quad_perm:[1,0,3,2] row_mask:0xf bank_mask:0xf
	v_fmac_f32_e32 v150, v16, v28
	s_waitcnt lgkmcnt(0)
	v_add_f32_dpp v125, v125, v125 quad_perm:[1,0,3,2] row_mask:0xf bank_mask:0xf
	v_fmac_f32_e32 v150, v17, v29
	s_waitcnt lgkmcnt(0)
	v_add_f32_dpp v118, v118, v118 quad_perm:[2,3,0,1] row_mask:0xf bank_mask:0xf
	s_movk_i32 s10, 0x7fd
	s_waitcnt lgkmcnt(0)
	s_nop 1
	v_add_f32_dpp v148, v125, v125 quad_perm:[2,3,0,1] row_mask:0xf bank_mask:0xf
	v_sub_u32_e32 v125, 0x7fc, v156
	s_waitcnt lgkmcnt(0)
	v_add_f32_dpp v118, v118, v118 row_half_mirror row_mask:0xf bank_mask:0xf
	v_cvt_f32_u32_e32 v125, v125
	v_cmp_gt_i32_e64 s[10:11], s10, v156
	v_mul_f32_e32 v154, v11, v35
	v_fmac_f32_e32 v154, v10, v34
	s_waitcnt lgkmcnt(0)
	v_add_f32_dpp v118, v118, v118 row_mirror row_mask:0xf bank_mask:0xf
	v_add_f32_dpp v119, v150, v150 quad_perm:[1,0,3,2] row_mask:0xf bank_mask:0xf
	v_mul_f32_e32 v151, v19, v27
	v_fma_f32 v118, -v127, v125, v118
	v_fmac_f32_e32 v151, v18, v26
	v_fmac_f32_e32 v151, v20, v28
	v_cndmask_b32_e64 v172, v135, v118, s[10:11]
	s_waitcnt lgkmcnt(0)
	v_add_f32_dpp v118, v119, v119 quad_perm:[2,3,0,1] row_mask:0xf bank_mask:0xf
	v_fmac_f32_e32 v151, v21, v29
	v_lshl_add_u64 v[66:67], v[66:67], 0, v[98:99]
	v_lshl_add_u64 v[70:71], v[70:71], 0, v[98:99]
	v_lshl_add_u64 v[78:79], v[78:79], 0, v[98:99]
	s_waitcnt lgkmcnt(0)
	v_add_f32_dpp v164, v118, v118 row_half_mirror row_mask:0xf bank_mask:0xf
	v_pk_mul_f32 v[118:119], v[12:13], v[36:37]
	s_waitcnt lgkmcnt(0)
	v_add_f32_dpp v150, v151, v151 quad_perm:[1,0,3,2] row_mask:0xf bank_mask:0xf
	v_mul_f32_e32 v152, v23, v27
	v_add_f32_e32 v118, v118, v154
	v_fmac_f32_e32 v152, v22, v26
	v_add_f32_e32 v118, v119, v118
	v_fmac_f32_e32 v152, v24, v28
	v_fmac_f32_e32 v152, v25, v29
	global_load_dwordx4 v[90:93], v[66:67], off
	s_nop 0
	global_load_dwordx4 v[66:69], v[66:67], off offset:512
	s_waitcnt lgkmcnt(0)
	v_add_f32_dpp v118, v118, v118 quad_perm:[1,0,3,2] row_mask:0xf bank_mask:0xf
	v_add_f32_dpp v152, v152, v152 quad_perm:[1,0,3,2] row_mask:0xf bank_mask:0xf
	global_load_dwordx4 v[86:89], v[70:71], off
	s_nop 0
	global_load_dwordx4 v[70:73], v[70:71], off offset:512
	s_nop 0
	global_load_dwordx4 v[82:85], v[78:79], off
	s_nop 0
	global_load_dwordx4 v[78:81], v[78:79], off offset:512
	v_mul_f32_e32 v154, v15, v35
	s_waitcnt lgkmcnt(0)
	v_add_f32_dpp v118, v118, v118 quad_perm:[2,3,0,1] row_mask:0xf bank_mask:0xf
	v_fmac_f32_e32 v154, v14, v34
	v_fmac_f32_e32 v154, v16, v36
	v_add_f32_dpp v150, v150, v150 quad_perm:[2,3,0,1] row_mask:0xf bank_mask:0xf
	v_add_f32_dpp v152, v152, v152 quad_perm:[2,3,0,1] row_mask:0xf bank_mask:0xf
	v_fmac_f32_e32 v154, v17, v37
	s_waitcnt lgkmcnt(0)
	v_add_f32_dpp v118, v118, v118 row_half_mirror row_mask:0xf bank_mask:0xf
	v_add_f32_dpp v158, v150, v150 row_half_mirror row_mask:0xf bank_mask:0xf
	v_add_f32_dpp v150, v152, v152 row_half_mirror row_mask:0xf bank_mask:0xf
	v_sub_u32_e32 v152, 0x7f8, v156
	v_add_f32_dpp v154, v154, v154 quad_perm:[1,0,3,2] row_mask:0xf bank_mask:0xf
	v_cvt_f32_u32_e32 v152, v152
	v_or_b32_e32 v153, 8, v156
	s_waitcnt lgkmcnt(0)
	v_add_f32_dpp v118, v118, v118 row_mirror row_mask:0xf bank_mask:0xf
	v_fma_f32 v118, -v127, v152, v118
	v_cmp_gt_i32_e64 s[12:13], s2, v153
	v_mul_f32_e32 v153, v19, v35
	v_fmac_f32_e32 v153, v18, v34
	v_cndmask_b32_e64 v173, v135, v118, s[12:13]
	v_add_f32_dpp v118, v154, v154 quad_perm:[2,3,0,1] row_mask:0xf bank_mask:0xf
	v_mul_f32_e32 v155, v23, v35
	v_fmac_f32_e32 v155, v22, v34
	v_fmac_f32_e32 v153, v20, v36
	v_fmac_f32_e32 v155, v24, v36
	v_fmac_f32_e32 v153, v21, v37
	v_fmac_f32_e32 v155, v25, v37
	s_movk_i32 s14, 0x7f5
	v_cmp_gt_i32_e64 s[14:15], s14, v156
	s_waitcnt lgkmcnt(0)
	v_add_f32_dpp v153, v153, v153 quad_perm:[1,0,3,2] row_mask:0xf bank_mask:0xf
	s_nop 1
	v_add_f32_dpp v160, v155, v155 quad_perm:[1,0,3,2] row_mask:0xf bank_mask:0xf
	v_pk_mul_f32 v[154:155], v[10:11], v[46:47]
	v_add_f32_dpp v167, v118, v118 row_half_mirror row_mask:0xf bank_mask:0xf
	v_pk_mul_f32 v[118:119], v[12:13], v[48:49]
	v_add_f32_e32 v154, v154, v155
	v_add_f32_e32 v118, v118, v154
	v_add_f32_e32 v118, v119, v118
	v_mul_f32_e32 v122, v19, v3
	s_waitcnt lgkmcnt(0)
	v_add_f32_dpp v153, v153, v153 quad_perm:[2,3,0,1] row_mask:0xf bank_mask:0xf
	v_add_f32_dpp v155, v160, v160 quad_perm:[2,3,0,1] row_mask:0xf bank_mask:0xf
	v_add_f32_dpp v118, v118, v118 quad_perm:[1,0,3,2] row_mask:0xf bank_mask:0xf
	v_fmac_f32_e32 v122, v18, v2
	s_waitcnt lgkmcnt(0)
	v_add_f32_dpp v160, v153, v153 row_half_mirror row_mask:0xf bank_mask:0xf
	v_add_f32_dpp v153, v155, v155 row_half_mirror row_mask:0xf bank_mask:0xf
	v_mul_f32_e32 v162, v15, v47
	v_add_f32_dpp v118, v118, v118 quad_perm:[2,3,0,1] row_mask:0xf bank_mask:0xf
	v_fmac_f32_e32 v162, v14, v46
	v_fmac_f32_e32 v162, v16, v48
	v_fmac_f32_e32 v162, v17, v49
	v_sub_u32_e32 v155, 0x7f4, v156
	s_waitcnt lgkmcnt(0)
	v_add_f32_dpp v118, v118, v118 row_half_mirror row_mask:0xf bank_mask:0xf
	v_cvt_f32_u32_e32 v155, v155
	v_add_f32_dpp v162, v162, v162 quad_perm:[1,0,3,2] row_mask:0xf bank_mask:0xf
	v_mul_f32_e32 v156, v19, v47
	s_waitcnt lgkmcnt(0)
	v_add_f32_dpp v118, v118, v118 row_mirror row_mask:0xf bank_mask:0xf
	v_fma_f32 v118, -v127, v155, v118
	v_cndmask_b32_e64 v174, v135, v118, s[14:15]
	v_add_f32_dpp v118, v162, v162 quad_perm:[2,3,0,1] row_mask:0xf bank_mask:0xf
	v_mul_f32_e32 v163, v23, v47
	v_fmac_f32_e32 v156, v18, v46
	v_fmac_f32_e32 v163, v22, v46
	v_fmac_f32_e32 v122, v20, v4
	v_fmac_f32_e32 v156, v20, v48
	v_fmac_f32_e32 v163, v24, v48
	v_fmac_f32_e32 v122, v21, v5
	v_fmac_f32_e32 v156, v21, v49
	v_fmac_f32_e32 v163, v25, v49
	v_max3_f32 v157, v169, s33, v172
	s_waitcnt lgkmcnt(0)
	v_add_f32_dpp v122, v122, v122 quad_perm:[1,0,3,2] row_mask:0xf bank_mask:0xf
	v_add_f32_dpp v170, v118, v118 row_half_mirror row_mask:0xf bank_mask:0xf
	v_add_f32_dpp v118, v156, v156 quad_perm:[1,0,3,2] row_mask:0xf bank_mask:0xf
	v_add_f32_dpp v156, v163, v163 quad_perm:[1,0,3,2] row_mask:0xf bank_mask:0xf
	v_max3_f32 v157, v157, v173, v174
	ds_bpermute_b32 v163, v142, v157
	s_waitcnt lgkmcnt(0)
	v_add_f32_dpp v122, v122, v122 quad_perm:[2,3,0,1] row_mask:0xf bank_mask:0xf
	v_add_f32_dpp v118, v118, v118 quad_perm:[2,3,0,1] row_mask:0xf bank_mask:0xf
	v_add_f32_dpp v156, v156, v156 quad_perm:[2,3,0,1] row_mask:0xf bank_mask:0xf
	v_max_f32_e32 v162, v163, v163
	v_max_f32_e32 v176, v157, v162
	ds_bpermute_b32 v177, v143, v176
	s_waitcnt lgkmcnt(0)
	v_add_f32_dpp v122, v122, v122 row_half_mirror row_mask:0xf bank_mask:0xf
	v_add_f32_dpp v148, v148, v148 row_half_mirror row_mask:0xf bank_mask:0xf
	v_add_f32_dpp v162, v118, v118 row_half_mirror row_mask:0xf bank_mask:0xf
	v_add_f32_dpp v156, v156, v156 row_half_mirror row_mask:0xf bank_mask:0xf
	ds_bpermute_b32 v121, v141, v120
	ds_bpermute_b32 v123, v141, v122
	ds_bpermute_b32 v149, v141, v148
	ds_bpermute_b32 v165, v141, v164
	ds_bpermute_b32 v159, v141, v158
	ds_bpermute_b32 v151, v141, v150
	ds_bpermute_b32 v168, v141, v167
	ds_bpermute_b32 v161, v141, v160
	ds_bpermute_b32 v154, v141, v153
	ds_bpermute_b32 v171, v141, v170
	ds_bpermute_b32 v163, v141, v162
	ds_bpermute_b32 v157, v141, v156
	v_max_f32_e32 v118, v177, v177
	v_max_f32_e32 v175, v176, v118
	v_cmp_neq_f32_e64 s[16:17], s33, v175
	v_mov_b64_e32 v[118:119], v[112:113]
	s_and_saveexec_b64 s[22:23], s[16:17]
	s_cbranch_execz .LBB0_5343
	v_max_f32_e32 v118, v175, v175
	v_max_f32_e32 v119, v113, v113
	v_max_f32_e32 v119, v119, v118
	v_sub_f32_e32 v118, v169, v119
	v_mul_f32_e32 v118, 0x3fb8aa3b, v118
	v_exp_f32_e32 v118, v118
	v_sub_f32_e32 v113, v113, v119
	v_mul_f32_e32 v113, 0x3fb8aa3b, v113
	v_add_f32_e32 v169, 0, v118
	v_pk_fma_f32 v[176:177], v[8:9], v[118:119], 0 op_sel_hi:[1,0,0]
	v_pk_fma_f32 v[178:179], v[6:7], v[118:119], 0 op_sel_hi:[1,0,0]
	v_sub_f32_e32 v118, v172, v119
	v_mul_f32_e32 v118, 0x3fb8aa3b, v118
	v_exp_f32_e32 v118, v118
	s_nop 0
	v_add_f32_e32 v169, v118, v169
	v_pk_fma_f32 v[176:177], v[32:33], v[118:119], v[176:177] op_sel_hi:[1,0,1]
	v_pk_fma_f32 v[178:179], v[30:31], v[118:119], v[178:179] op_sel_hi:[1,0,1]
	v_sub_f32_e32 v118, v173, v119
	v_mul_f32_e32 v118, 0x3fb8aa3b, v118
	v_exp_f32_e32 v118, v118
	s_nop 0
	v_add_f32_e32 v169, v118, v169
	v_pk_fma_f32 v[172:173], v[38:39], v[118:119], v[178:179] op_sel_hi:[1,0,1]
	v_pk_fma_f32 v[176:177], v[40:41], v[118:119], v[176:177] op_sel_hi:[1,0,1]
	v_sub_f32_e32 v118, v174, v119
	v_mul_f32_e32 v118, 0x3fb8aa3b, v118
	v_exp_f32_e32 v118, v118
	s_nop 0
	v_add_f32_e32 v169, v118, v169
	v_pk_fma_f32 v[174:175], v[56:57], v[118:119], v[176:177] op_sel_hi:[1,0,1]
	v_exp_f32_e32 v176, v113
	ds_bpermute_b32 v113, v142, v169
	v_pk_fma_f32 v[172:173], v[54:55], v[118:119], v[172:173] op_sel_hi:[1,0,1]
	ds_bpermute_b32 v178, v142, v174
	ds_bpermute_b32 v179, v142, v175
	s_waitcnt lgkmcnt(0)
	v_add_f32_e32 v113, v169, v113
	ds_bpermute_b32 v118, v143, v113
	v_pk_add_f32 v[174:175], v[174:175], v[178:179]
	ds_bpermute_b32 v178, v143, v174
	ds_bpermute_b32 v179, v143, v175
	s_waitcnt lgkmcnt(0)
	v_add_f32_e32 v118, v113, v118
	v_fmac_f32_e32 v118, v112, v176
	ds_bpermute_b32 v112, v142, v172
	ds_bpermute_b32 v113, v142, v173
	s_waitcnt lgkmcnt(0)
	v_pk_add_f32 v[112:113], v[172:173], v[112:113]
	ds_bpermute_b32 v172, v143, v112
	ds_bpermute_b32 v173, v143, v113
	s_waitcnt lgkmcnt(0)
	v_pk_add_f32 v[112:113], v[112:113], v[172:173]
	v_pk_add_f32 v[172:173], v[174:175], v[178:179]
	v_pk_fma_f32 v[62:63], v[62:63], v[176:177], v[112:113] op_sel_hi:[1,0,1]
	v_pk_fma_f32 v[64:65], v[64:65], v[176:177], v[172:173] op_sel_hi:[1,0,1]
	v_mov_b32_e32 v112, v118
	v_mov_b32_e32 v113, v119

.LBB0_5351:
	v_mul_f32_e32 v149, v11, v95
	v_fmac_f32_e32 v149, v10, v94
	v_fmac_f32_e32 v149, v12, v96
	v_fmac_f32_e32 v149, v13, v97
	v_sub_u32_e32 v148, 0x800, v144
	v_cvt_f32_u32_e32 v148, v148
	v_cmp_gt_i32_e32 vcc, s2, v144
	s_waitcnt vmcnt(0)
	v_pk_mul_f32 v[154:155], v[12:13], v[92:93]
	s_waitcnt lgkmcnt(0)
	v_add_f32_dpp v149, v149, v149 quad_perm:[1,0,3,2] row_mask:0xf bank_mask:0xf
	v_cmp_gt_i32_e64 s[10:11], s2, v147
	v_pk_mul_f32 v[158:159], v[12:13], v[88:89]
	v_cmp_gt_i32_e64 s[12:13], s2, v146
	v_pk_mul_f32 v[160:161], v[10:11], v[82:83]
	s_waitcnt lgkmcnt(0)
	v_add_f32_dpp v149, v149, v149 quad_perm:[2,3,0,1] row_mask:0xf bank_mask:0xf
	v_cmp_gt_i32_e64 s[14:15], s2, v145
	s_waitcnt lgkmcnt(0)
	v_add_f32_dpp v149, v149, v149 row_half_mirror row_mask:0xf bank_mask:0xf
	s_waitcnt lgkmcnt(0)
	s_nop 0
	v_add_f32_dpp v149, v149, v149 row_mirror row_mask:0xf bank_mask:0xf
	v_fma_f32 v149, -v127, v148, v149
	v_cndmask_b32_e32 v153, v135, v149, vcc
	v_mul_f32_e32 v149, v15, v95
	v_fmac_f32_e32 v149, v14, v94
	v_fmac_f32_e32 v149, v16, v96
	v_fmac_f32_e32 v149, v17, v97
	s_waitcnt lgkmcnt(0)
	s_nop 0
	v_add_f32_dpp v149, v149, v149 quad_perm:[1,0,3,2] row_mask:0xf bank_mask:0xf
	s_waitcnt lgkmcnt(0)
	s_nop 0
	v_add_f32_dpp v149, v149, v149 quad_perm:[2,3,0,1] row_mask:0xf bank_mask:0xf
	s_waitcnt lgkmcnt(0)
	s_nop 0
	v_add_f32_dpp v151, v149, v149 row_half_mirror row_mask:0xf bank_mask:0xf
	v_mul_f32_e32 v149, v19, v95
	v_mul_f32_e32 v95, v23, v95
	v_fmac_f32_e32 v149, v18, v94
	v_fmac_f32_e32 v95, v22, v94
	v_fmac_f32_e32 v149, v20, v96
	v_fmac_f32_e32 v95, v24, v96
	v_fmac_f32_e32 v149, v21, v97
	v_fmac_f32_e32 v95, v25, v97
	v_mul_f32_e32 v97, v11, v91
	v_fmac_f32_e32 v97, v10, v90
	v_add_f32_e32 v97, v154, v97
	v_add_f32_e32 v97, v155, v97
	ds_bpermute_b32 v152, v141, v151
	s_waitcnt lgkmcnt(0)
	v_add_f32_dpp v97, v97, v97 quad_perm:[1,0,3,2] row_mask:0xf bank_mask:0xf
	s_waitcnt lgkmcnt(0)
	s_nop 1
	v_add_f32_dpp v94, v95, v95 quad_perm:[1,0,3,2] row_mask:0xf bank_mask:0xf
	s_waitcnt lgkmcnt(0)
	v_add_f32_dpp v149, v149, v149 quad_perm:[1,0,3,2] row_mask:0xf bank_mask:0xf
	s_waitcnt lgkmcnt(0)
	v_add_f32_dpp v97, v97, v97 quad_perm:[2,3,0,1] row_mask:0xf bank_mask:0xf
	s_waitcnt lgkmcnt(0)
	v_add_f32_dpp v94, v94, v94 quad_perm:[2,3,0,1] row_mask:0xf bank_mask:0xf
	s_waitcnt lgkmcnt(0)
	v_add_f32_dpp v149, v149, v149 quad_perm:[2,3,0,1] row_mask:0xf bank_mask:0xf
	s_waitcnt lgkmcnt(0)
	v_add_f32_dpp v97, v97, v97 row_half_mirror row_mask:0xf bank_mask:0xf
	s_waitcnt lgkmcnt(0)
	v_add_f32_dpp v94, v94, v94 row_half_mirror row_mask:0xf bank_mask:0xf
	v_sub_u32_e32 v95, 0x7fc, v144
	v_cvt_f32_u32_e32 v95, v95
	s_waitcnt lgkmcnt(0)
	v_add_f32_dpp v149, v149, v149 row_half_mirror row_mask:0xf bank_mask:0xf
	s_waitcnt lgkmcnt(0)
	v_add_f32_dpp v97, v97, v97 row_mirror row_mask:0xf bank_mask:0xf
	ds_bpermute_b32 v150, v141, v149
	v_fma_f32 v97, -v127, v95, v97
	v_cndmask_b32_e64 v156, v135, v97, s[10:11]
	v_mul_f32_e32 v97, v15, v91
	v_fmac_f32_e32 v97, v14, v90
	v_fmac_f32_e32 v97, v16, v92
	v_fmac_f32_e32 v97, v17, v93
	v_max3_f32 v162, v153, s33, v156
	ds_bpermute_b32 v96, v141, v94
	s_waitcnt lgkmcnt(0)
	v_add_f32_dpp v97, v97, v97 quad_perm:[1,0,3,2] row_mask:0xf bank_mask:0xf
	s_waitcnt lgkmcnt(0)
	s_nop 0
	v_add_f32_dpp v97, v97, v97 quad_perm:[2,3,0,1] row_mask:0xf bank_mask:0xf
	s_waitcnt lgkmcnt(0)
	s_nop 0
	v_add_f32_dpp v154, v97, v97 row_half_mirror row_mask:0xf bank_mask:0xf
	v_mul_f32_e32 v97, v19, v91
	v_mul_f32_e32 v91, v23, v91
	v_fmac_f32_e32 v97, v18, v90
	v_fmac_f32_e32 v91, v22, v90
	v_fmac_f32_e32 v97, v20, v92
	v_fmac_f32_e32 v91, v24, v92
	v_fmac_f32_e32 v97, v21, v93
	v_fmac_f32_e32 v91, v25, v93
	v_mul_f32_e32 v93, v11, v87
	v_fmac_f32_e32 v93, v10, v86
	v_add_f32_e32 v93, v158, v93
	v_add_f32_e32 v93, v159, v93
	ds_bpermute_b32 v155, v141, v154
	s_waitcnt lgkmcnt(0)
	v_add_f32_dpp v93, v93, v93 quad_perm:[1,0,3,2] row_mask:0xf bank_mask:0xf
	s_waitcnt lgkmcnt(0)
	s_nop 1
	v_add_f32_dpp v90, v91, v91 quad_perm:[1,0,3,2] row_mask:0xf bank_mask:0xf
	s_waitcnt lgkmcnt(0)
	v_add_f32_dpp v97, v97, v97 quad_perm:[1,0,3,2] row_mask:0xf bank_mask:0xf
	s_waitcnt lgkmcnt(0)
	v_add_f32_dpp v93, v93, v93 quad_perm:[2,3,0,1] row_mask:0xf bank_mask:0xf
	s_waitcnt lgkmcnt(0)
	v_add_f32_dpp v90, v90, v90 quad_perm:[2,3,0,1] row_mask:0xf bank_mask:0xf
	ds_bpermute_b32 v91, v140, v90
	s_waitcnt lgkmcnt(0)
	v_add_f32_dpp v97, v97, v97 quad_perm:[2,3,0,1] row_mask:0xf bank_mask:0xf
	s_waitcnt lgkmcnt(0)
	v_add_f32_dpp v93, v93, v93 row_half_mirror row_mask:0xf bank_mask:0xf
	s_waitcnt lgkmcnt(0)
	v_add_f32_e32 v91, v90, v91
	v_sub_u32_e32 v90, 0x7f8, v144
	v_cvt_f32_u32_e32 v90, v90
	s_waitcnt lgkmcnt(0)
	v_add_f32_dpp v97, v97, v97 row_half_mirror row_mask:0xf bank_mask:0xf
	s_waitcnt lgkmcnt(0)
	v_add_f32_dpp v93, v93, v93 row_mirror row_mask:0xf bank_mask:0xf
	ds_bpermute_b32 v147, v141, v97
	v_fma_f32 v93, -v127, v90, v93
	v_cndmask_b32_e64 v159, v135, v93, s[12:13]
	v_mul_f32_e32 v93, v15, v87
	v_fmac_f32_e32 v93, v14, v86
	v_fmac_f32_e32 v93, v16, v88
	v_fmac_f32_e32 v93, v17, v89
	ds_bpermute_b32 v92, v141, v91
	s_waitcnt lgkmcnt(0)
	v_add_f32_dpp v93, v93, v93 quad_perm:[1,0,3,2] row_mask:0xf bank_mask:0xf
	s_waitcnt lgkmcnt(0)
	s_nop 0
	v_add_f32_dpp v93, v93, v93 quad_perm:[2,3,0,1] row_mask:0xf bank_mask:0xf
	s_waitcnt lgkmcnt(0)
	s_nop 0
	v_add_f32_dpp v157, v93, v93 row_half_mirror row_mask:0xf bank_mask:0xf
	v_mul_f32_e32 v93, v19, v87
	v_mul_f32_e32 v87, v23, v87
	v_fmac_f32_e32 v87, v22, v86
	v_fmac_f32_e32 v87, v24, v88
	v_fmac_f32_e32 v87, v25, v89
	v_fmac_f32_e32 v93, v18, v86
	v_fmac_f32_e32 v93, v20, v88
	v_fmac_f32_e32 v93, v21, v89
	v_add_f32_e32 v89, v160, v161
	s_waitcnt lgkmcnt(0)
	s_nop 1
	v_add_f32_dpp v86, v87, v87 quad_perm:[1,0,3,2] row_mask:0xf bank_mask:0xf
	ds_bpermute_b32 v158, v141, v157
	s_waitcnt lgkmcnt(0)
	v_add_f32_dpp v93, v93, v93 quad_perm:[1,0,3,2] row_mask:0xf bank_mask:0xf
	s_waitcnt lgkmcnt(0)
	v_add_f32_dpp v86, v86, v86 quad_perm:[2,3,0,1] row_mask:0xf bank_mask:0xf
	s_waitcnt lgkmcnt(0)
	v_add_f32_dpp v93, v93, v93 quad_perm:[2,3,0,1] row_mask:0xf bank_mask:0xf
	s_waitcnt lgkmcnt(0)
	v_add_f32_dpp v86, v86, v86 row_half_mirror row_mask:0xf bank_mask:0xf
	v_sub_u32_e32 v87, 0x7f4, v144
	v_pk_mul_f32 v[144:145], v[12:13], v[84:85]
	v_cvt_f32_u32_e32 v87, v87
	v_add_f32_e32 v89, v144, v89
	v_add_f32_e32 v89, v145, v89
	s_waitcnt lgkmcnt(0)
	v_add_f32_dpp v93, v93, v93 row_half_mirror row_mask:0xf bank_mask:0xf
	ds_bpermute_b32 v146, v141, v93
	ds_bpermute_b32 v88, v141, v86
	s_waitcnt lgkmcnt(0)
	v_add_f32_dpp v89, v89, v89 quad_perm:[1,0,3,2] row_mask:0xf bank_mask:0xf
	s_waitcnt lgkmcnt(0)
	s_nop 0
	v_add_f32_dpp v89, v89, v89 quad_perm:[2,3,0,1] row_mask:0xf bank_mask:0xf
	s_waitcnt lgkmcnt(0)
	s_nop 0
	v_add_f32_dpp v89, v89, v89 row_half_mirror row_mask:0xf bank_mask:0xf
	s_waitcnt lgkmcnt(0)
	s_nop 0
	v_add_f32_dpp v89, v89, v89 row_mirror row_mask:0xf bank_mask:0xf
	v_fma_f32 v89, -v127, v87, v89
	v_cndmask_b32_e64 v161, v135, v89, s[14:15]
	v_mul_f32_e32 v89, v15, v83
	v_fmac_f32_e32 v89, v14, v82
	v_fmac_f32_e32 v89, v16, v84
	v_fmac_f32_e32 v89, v17, v85
	v_max3_f32 v162, v162, v159, v161
	s_waitcnt lgkmcnt(0)
	v_add_f32_dpp v89, v89, v89 quad_perm:[1,0,3,2] row_mask:0xf bank_mask:0xf
	s_waitcnt lgkmcnt(0)
	s_nop 0
	v_add_f32_dpp v89, v89, v89 quad_perm:[2,3,0,1] row_mask:0xf bank_mask:0xf
	s_waitcnt lgkmcnt(0)
	s_nop 0
	v_add_f32_dpp v145, v89, v89 row_half_mirror row_mask:0xf bank_mask:0xf
	v_mul_f32_e32 v89, v19, v83
	v_mul_f32_e32 v83, v23, v83
	v_fmac_f32_e32 v89, v18, v82
	v_fmac_f32_e32 v83, v22, v82
	v_fmac_f32_e32 v89, v20, v84
	v_fmac_f32_e32 v83, v24, v84
	v_fmac_f32_e32 v89, v21, v85
	v_fmac_f32_e32 v83, v25, v85
	ds_bpermute_b32 v84, v142, v162
	ds_bpermute_b32 v160, v141, v145
	s_waitcnt lgkmcnt(0)
	v_add_f32_dpp v89, v89, v89 quad_perm:[1,0,3,2] row_mask:0xf bank_mask:0xf
	s_waitcnt lgkmcnt(0)
	s_nop 1
	v_add_f32_dpp v82, v83, v83 quad_perm:[1,0,3,2] row_mask:0xf bank_mask:0xf
	s_waitcnt lgkmcnt(0)
	v_max_f32_e32 v84, v84, v84
	v_max_f32_e32 v84, v162, v84
	ds_bpermute_b32 v85, v143, v84
	s_waitcnt lgkmcnt(0)
	v_add_f32_dpp v89, v89, v89 quad_perm:[2,3,0,1] row_mask:0xf bank_mask:0xf
	s_waitcnt lgkmcnt(0)
	v_add_f32_dpp v82, v82, v82 quad_perm:[2,3,0,1] row_mask:0xf bank_mask:0xf
	s_waitcnt lgkmcnt(0)
	v_max_f32_e32 v85, v85, v85
	v_max_f32_e32 v84, v84, v85
	v_cmp_neq_f32_e64 s[16:17], s33, v84
	s_waitcnt lgkmcnt(0)
	v_add_f32_dpp v89, v89, v89 row_half_mirror row_mask:0xf bank_mask:0xf
	s_waitcnt lgkmcnt(0)
	v_add_f32_dpp v82, v82, v82 row_half_mirror row_mask:0xf bank_mask:0xf
	ds_bpermute_b32 v144, v141, v89
	ds_bpermute_b32 v83, v141, v82
	s_and_saveexec_b64 s[24:25], s[16:17]
	s_cbranch_execz .LBB0_5353
	v_max_f32_e32 v84, v84, v84
	v_max_f32_e32 v85, v113, v113
	v_max_f32_e32 v119, v85, v84
	v_sub_f32_e32 v84, v113, v119
	v_mul_f32_e32 v113, 0x3fb8aa3b, v84
	v_sub_f32_e32 v84, v153, v119
	v_mul_f32_e32 v84, 0x3fb8aa3b, v84
	v_sub_f32_e32 v118, v156, v119
	v_exp_f32_e32 v84, v84
	v_mul_f32_e32 v118, 0x3fb8aa3b, v118
	v_exp_f32_e32 v118, v118
	v_exp_f32_e32 v156, v113
	v_add_f32_e32 v153, 0, v84
	v_pk_fma_f32 v[162:163], v[76:77], v[84:85], 0 op_sel_hi:[1,0,0]
	v_pk_fma_f32 v[84:85], v[74:75], v[84:85], 0 op_sel_hi:[1,0,0]
	v_add_f32_e32 v153, v118, v153
	v_pk_fma_f32 v[162:163], v[68:69], v[118:119], v[162:163] op_sel_hi:[1,0,1]
	v_pk_fma_f32 v[84:85], v[66:67], v[118:119], v[84:85] op_sel_hi:[1,0,1]
	v_sub_f32_e32 v118, v159, v119
	v_mul_f32_e32 v118, 0x3fb8aa3b, v118
	v_exp_f32_e32 v118, v118
	s_nop 0
	v_add_f32_e32 v153, v118, v153
	v_pk_fma_f32 v[84:85], v[70:71], v[118:119], v[84:85] op_sel_hi:[1,0,1]
	v_pk_fma_f32 v[162:163], v[72:73], v[118:119], v[162:163] op_sel_hi:[1,0,1]
	v_sub_f32_e32 v118, v161, v119
	v_mul_f32_e32 v118, 0x3fb8aa3b, v118
	v_exp_f32_e32 v118, v118
	s_nop 0
	v_add_f32_e32 v153, v118, v153
	ds_bpermute_b32 v113, v142, v153
	v_pk_fma_f32 v[162:163], v[80:81], v[118:119], v[162:163] op_sel_hi:[1,0,1]
	v_pk_fma_f32 v[84:85], v[78:79], v[118:119], v[84:85] op_sel_hi:[1,0,1]
	ds_bpermute_b32 v164, v142, v162
	ds_bpermute_b32 v165, v142, v163
	s_waitcnt lgkmcnt(0)
	v_add_f32_e32 v113, v153, v113
	ds_bpermute_b32 v118, v143, v113
	s_waitcnt lgkmcnt(0)
	v_pk_add_f32 v[162:163], v[162:163], v[164:165]
	ds_bpermute_b32 v164, v143, v162
	s_waitcnt lgkmcnt(0)
	v_add_f32_e32 v118, v113, v118
	v_fmac_f32_e32 v118, v112, v156
	ds_bpermute_b32 v112, v142, v84
	ds_bpermute_b32 v113, v142, v85
	ds_bpermute_b32 v165, v143, v163
	s_waitcnt lgkmcnt(0)
	v_pk_add_f32 v[84:85], v[84:85], v[112:113]
	ds_bpermute_b32 v112, v143, v84
	ds_bpermute_b32 v113, v143, v85
	s_waitcnt lgkmcnt(0)
	v_pk_add_f32 v[84:85], v[84:85], v[112:113]
	v_pk_add_f32 v[112:113], v[162:163], v[164:165]
	v_pk_fma_f32 v[62:63], v[62:63], v[156:157], v[84:85] op_sel_hi:[1,0,1]
	v_pk_fma_f32 v[64:65], v[64:65], v[156:157], v[112:113] op_sel_hi:[1,0,1]
	v_mov_b32_e32 v112, v118
	v_mov_b32_e32 v113, v119

.LBB0_5544:
	v_lshl_add_u64 v[18:19], s[68:69], 0, v[94:95]
	v_lshl_add_u64 v[22:23], s[68:69], 0, v[92:93]
	v_add_co_u32_e32 v20, vcc, 0x7800000, v18
	v_add_co_u32_e64 v102, s[6:7], s24, v22
	s_nop 0
	v_addc_co_u32_e32 v21, vcc, 0, v19, vcc
	v_addc_co_u32_e64 v103, s[6:7], 0, v23, s[6:7]
	v_add_co_u32_e64 v104, s[6:7], s25, v22
	v_add_co_u32_e32 v22, vcc, 0x7801000, v18
	s_nop 0
	v_addc_co_u32_e64 v105, s[6:7], 0, v23, s[6:7]
	global_load_dwordx4 v[78:81], v[20:21], off
	global_load_dwordx4 v[74:77], v[20:21], off offset:1024
	global_load_dwordx4 v[70:73], v[20:21], off offset:2048
	global_load_dwordx4 v[66:69], v[20:21], off offset:3072
	v_addc_co_u32_e32 v23, vcc, 0, v19, vcc
	v_add_co_u32_e32 v20, vcc, 0x7802000, v18
	global_load_dwordx4 v[62:65], v[22:23], off
	global_load_dwordx4 v[58:61], v[22:23], off offset:1024
	global_load_dwordx4 v[54:57], v[22:23], off offset:2048
	global_load_dwordx4 v[50:53], v[22:23], off offset:3072
	v_addc_co_u32_e32 v21, vcc, 0, v19, vcc
	v_add_co_u32_e32 v82, vcc, 0x7803000, v18
	global_load_dwordx4 v[46:49], v[20:21], off
	global_load_dwordx4 v[42:45], v[20:21], off offset:1024
	global_load_dwordx4 v[38:41], v[20:21], off offset:2048
	global_load_dwordx4 v[34:37], v[20:21], off offset:3072
	v_addc_co_u32_e32 v83, vcc, 0, v19, vcc
	global_load_dwordx4 v[30:33], v[82:83], off
	global_load_dwordx4 v[26:29], v[82:83], off offset:1024
	global_load_dwordx4 v[22:25], v[82:83], off offset:2048
	global_load_dwordx4 v[18:21], v[82:83], off offset:3072
	s_ashr_i32 s8, s12, 13
	s_add_i32 s9, s12, 0xffffc002
	s_cmpk_lt_i32 s12, 0x4000
	s_cselect_b32 s6, s8, s9
	s_addk_i32 s6, 0x82
	s_mul_hi_i32 s7, s6, 0x9000
	s_mul_i32 s6, s6, 0x9000
	s_add_u32 s9, s3, s6
	s_addc_u32 s11, s4, s7
	s_add_u32 s6, s9, 0x6000
	s_addc_u32 s7, s11, 0
	s_add_u32 s10, s9, 0x7000
	s_addc_u32 s11, s11, 0
	v_lshl_add_u64 v[82:83], s[6:7], 0, v[90:91]
	v_lshl_add_u64 v[86:87], s[10:11], 0, v[90:91]
	global_load_dwordx4 v[82:85], v[82:83], off
	v_lshl_add_u64 v[148:149], s[6:7], 0, v[96:97]
	global_load_dwordx4 v[86:89], v[86:87], off
	v_lshl_add_u64 v[142:143], s[6:7], 0, v[98:99]
	v_lshl_add_u64 v[132:133], s[6:7], 0, v[100:101]
	s_add_i32 s6, s12, 0xffffc003
	s_cmpk_lt_i32 s12, 0x3fff
	s_cselect_b32 s6, s8, s6
	s_addk_i32 s6, 0x82
	s_mul_hi_i32 s7, s6, 0x9000
	s_mul_i32 s6, s6, 0x9000
	s_add_u32 s9, s3, s6
	v_lshl_add_u64 v[152:153], s[10:11], 0, v[96:97]
	v_lshl_add_u64 v[146:147], s[10:11], 0, v[98:99]
	v_lshl_add_u64 v[140:141], s[10:11], 0, v[100:101]
	s_addc_u32 s11, s4, s7
	s_add_u32 s6, s9, 0x6000
	s_addc_u32 s7, s11, 0
	s_add_u32 s10, s9, 0x7000
	v_lshl_add_u64 v[134:135], s[6:7], 0, v[90:91]
	v_lshl_add_u64 v[126:127], s[6:7], 0, v[96:97]
	v_lshl_add_u64 v[118:119], s[6:7], 0, v[98:99]
	v_lshl_add_u64 v[114:115], s[6:7], 0, v[100:101]
	s_addc_u32 s11, s11, 0
	s_add_i32 s6, s12, 0xffffc004
	s_cmpk_lt_i32 s12, 0x3ffe
	s_cselect_b32 s6, s8, s6
	s_addk_i32 s6, 0x82
	s_mul_hi_i32 s7, s6, 0x9000
	s_mul_i32 s6, s6, 0x9000
	s_add_u32 s6, s3, s6
	s_addc_u32 s7, s4, s7
	v_lshl_add_u64 v[136:137], s[10:11], 0, v[90:91]
	v_lshl_add_u64 v[130:131], s[10:11], 0, v[96:97]
	v_lshl_add_u64 v[122:123], s[10:11], 0, v[98:99]
	v_lshl_add_u64 v[116:117], s[10:11], 0, v[100:101]
	s_add_u32 s10, s6, 0x6000
	s_addc_u32 s11, s7, 0
	s_add_u32 s6, s6, 0x7000
	s_addc_u32 s7, s7, 0
	s_add_i32 s9, s12, 0xffffc005
	s_cmpk_lt_i32 s12, 0x3ffd
	v_lshl_add_u64 v[156:157], s[6:7], 0, v[90:91]
	v_lshl_add_u64 v[154:155], s[6:7], 0, v[96:97]
	v_lshl_add_u64 v[150:151], s[6:7], 0, v[98:99]
	v_lshl_add_u64 v[138:139], s[6:7], 0, v[100:101]
	s_cselect_b32 s6, s8, s9
	s_addk_i32 s6, 0x82
	s_waitcnt vmcnt(0) lgkmcnt(0)
	v_pk_mul_f32 v[158:159], v[80:81], v[80:81]
	v_pk_mul_f32 v[160:161], v[78:79], v[78:79]
	v_pk_mul_f32 v[162:163], v[76:77], v[76:77]
	v_pk_mul_f32 v[164:165], v[74:75], v[74:75]
	v_mul_f32_e32 v174, v71, v71
	v_mul_f32_e32 v176, v73, v73
	v_mul_f32_e32 v187, v68, v68
	v_mul_f32_e32 v189, v69, v69
	v_pk_mov_b32 v[178:179], v[160:161], v[158:159] op_sel:[1,0]
	v_mov_b32_e32 v161, v159
	v_pk_mov_b32 v[158:159], v[164:165], v[162:163] op_sel:[1,0]
	v_mov_b32_e32 v165, v163
	v_pk_fma_f32 v[162:163], v[70:71], v[70:71], v[174:175] op_sel_hi:[1,1,0]
	v_pk_fma_f32 v[174:175], v[72:73], v[72:73], v[176:177] op_sel_hi:[1,1,0]
	v_pk_mul_f32 v[176:177], v[64:65], v[64:65]
	v_pk_mul_f32 v[180:181], v[62:63], v[62:63]
	v_pk_mul_f32 v[182:183], v[60:61], v[60:61]
	v_pk_mul_f32 v[184:185], v[58:59], v[58:59]
	v_mul_f32_e32 v186, v55, v55
	v_mul_f32_e32 v188, v57, v57
	v_pk_add_f32 v[160:161], v[178:179], v[160:161]
	v_pk_add_f32 v[158:159], v[158:159], v[164:165]
	v_mov_b32_e32 v163, v187
	v_mov_b32_e32 v175, v189
	v_pk_mov_b32 v[164:165], v[180:181], v[176:177] op_sel:[1,0]
	v_mov_b32_e32 v181, v177
	v_pk_mov_b32 v[176:177], v[184:185], v[182:183] op_sel:[1,0]
	v_mov_b32_e32 v185, v183
	v_pk_fma_f32 v[178:179], v[54:55], v[54:55], v[186:187] op_sel_hi:[1,1,0]
	v_pk_fma_f32 v[182:183], v[56:57], v[56:57], v[188:189] op_sel_hi:[1,1,0]
	v_pk_mul_f32 v[186:187], v[48:49], v[48:49]
	v_pk_mul_f32 v[188:189], v[46:47], v[46:47]
	v_pk_mul_f32 v[190:191], v[44:45], v[44:45]
	v_pk_mul_f32 v[192:193], v[42:43], v[42:43]
	v_mul_f32_e32 v197, v66, v66
	v_mul_f32_e32 v203, v67, v67
	v_mul_f32_e32 v195, v52, v52
	v_mul_f32_e32 v202, v53, v53
	v_mul_f32_e32 v194, v39, v39
	v_mul_f32_e32 v196, v41, v41
	v_pk_add_f32 v[198:199], v[160:161], v[160:161] op_sel:[0,1] op_sel_hi:[1,0]
	v_pk_add_f32 v[200:201], v[158:159], v[158:159] op_sel:[0,1] op_sel_hi:[1,0]
	v_pk_add_f32 v[174:175], v[162:163], v[174:175]
	v_pk_add_f32 v[158:159], v[164:165], v[180:181]
	v_pk_add_f32 v[160:161], v[176:177], v[184:185]
	v_pk_mov_b32 v[162:163], v[188:189], v[186:187] op_sel:[1,0]
	v_mov_b32_e32 v189, v187
	v_pk_mov_b32 v[164:165], v[192:193], v[190:191] op_sel:[1,0]
	v_mov_b32_e32 v193, v191
	v_mul_f32_e32 v208, v50, v50
	v_mul_f32_e32 v209, v51, v51
	v_mul_f32_e32 v212, v36, v36
	v_mul_f32_e32 v213, v37, v37
	v_mov_b32_e32 v179, v195
	v_mov_b32_e32 v183, v202
	v_pk_fma_f32 v[176:177], v[38:39], v[38:39], v[194:195] op_sel_hi:[1,1,0]
	v_pk_fma_f32 v[180:181], v[40:41], v[40:41], v[196:197] op_sel_hi:[1,1,0]
	v_pk_mul_f32 v[184:185], v[32:33], v[32:33]
	v_pk_mul_f32 v[186:187], v[30:31], v[30:31]
	v_pk_mul_f32 v[190:191], v[28:29], v[28:29]
	v_pk_mul_f32 v[194:195], v[26:27], v[26:27]
	v_mov_b32_e32 v199, v197
	v_mov_b32_e32 v201, v203
	v_pk_add_f32 v[204:205], v[158:159], v[158:159] op_sel:[0,1] op_sel_hi:[1,0]
	v_pk_add_f32 v[206:207], v[160:161], v[160:161] op_sel:[0,1] op_sel_hi:[1,0]
	v_pk_add_f32 v[162:163], v[162:163], v[188:189]
	v_pk_add_f32 v[164:165], v[164:165], v[192:193]
	v_mul_f32_e32 v210, v34, v34
	v_mul_f32_e32 v211, v35, v35
	v_pk_add_f32 v[178:179], v[178:179], v[182:183]
	v_mov_b32_e32 v177, v212
	v_mov_b32_e32 v181, v213
	v_pk_mov_b32 v[182:183], v[186:187], v[184:185] op_sel:[1,0]
	v_mov_b32_e32 v187, v185
	v_pk_mov_b32 v[184:185], v[194:195], v[190:191] op_sel:[1,0]
	v_mov_b32_e32 v195, v191
	v_pk_add_f32 v[188:189], v[198:199], v[200:201]
	v_mov_b32_e32 v205, v208
	v_mov_b32_e32 v207, v209
	v_pk_add_f32 v[190:191], v[162:163], v[162:163] op_sel:[0,1] op_sel_hi:[1,0]
	v_pk_add_f32 v[192:193], v[164:165], v[164:165] op_sel:[0,1] op_sel_hi:[1,0]
	v_pk_add_f32 v[176:177], v[176:177], v[180:181]
	v_pk_add_f32 v[174:175], v[188:189], v[174:175]
	v_pk_add_f32 v[180:181], v[204:205], v[206:207]
	v_mov_b32_e32 v191, v210
	v_mov_b32_e32 v193, v211
	v_pk_add_f32 v[162:163], v[182:183], v[186:187]
	v_add_f32_e32 v182, v174, v175
	v_pk_add_f32 v[174:175], v[180:181], v[178:179]
	v_pk_add_f32 v[178:179], v[190:191], v[192:193]
	v_add_f32_e32 v180, v174, v175
	v_pk_add_f32 v[174:175], v[178:179], v[176:177]
	v_add_f32_e32 v174, v174, v175
	s_mul_hi_i32 s7, s6, 0x9000
	s_waitcnt lgkmcnt(0)
	s_nop 1
	v_add_f32_dpp v176, v182, v182 quad_perm:[1,0,3,2] row_mask:0xf bank_mask:0xf
	s_waitcnt lgkmcnt(0)
	s_nop 1
	v_add_f32_dpp v175, v180, v180 quad_perm:[1,0,3,2] row_mask:0xf bank_mask:0xf
	s_waitcnt lgkmcnt(0)
	s_nop 1
	v_add_f32_dpp v174, v174, v174 quad_perm:[1,0,3,2] row_mask:0xf bank_mask:0xf
	s_waitcnt lgkmcnt(0)
	s_nop 1
	v_add_f32_dpp v176, v176, v176 quad_perm:[2,3,0,1] row_mask:0xf bank_mask:0xf
	s_waitcnt lgkmcnt(0)
	s_nop 1
	v_add_f32_dpp v175, v175, v175 quad_perm:[2,3,0,1] row_mask:0xf bank_mask:0xf
	s_waitcnt lgkmcnt(0)
	s_nop 1
	v_add_f32_dpp v174, v174, v174 quad_perm:[2,3,0,1] row_mask:0xf bank_mask:0xf
	s_waitcnt lgkmcnt(0)
	s_nop 1
	v_add_f32_dpp v176, v176, v176 row_half_mirror row_mask:0xf bank_mask:0xf
	s_waitcnt lgkmcnt(0)
	s_nop 1
	v_add_f32_dpp v175, v175, v175 row_half_mirror row_mask:0xf bank_mask:0xf
	s_waitcnt lgkmcnt(0)
	s_nop 1
	v_add_f32_dpp v174, v174, v174 row_half_mirror row_mask:0xf bank_mask:0xf
	s_waitcnt lgkmcnt(0)
	s_nop 1
	v_add_f32_dpp v176, v176, v176 row_mirror row_mask:0xf bank_mask:0xf
	ds_bpermute_b32 v178, v170, v176
	s_waitcnt lgkmcnt(2)
	s_nop 1
	v_add_f32_dpp v175, v175, v175 row_mirror row_mask:0xf bank_mask:0xf
	ds_bpermute_b32 v179, v170, v175
	s_waitcnt lgkmcnt(2)
	s_nop 1
	v_add_f32_dpp v174, v174, v174 row_mirror row_mask:0xf bank_mask:0xf
	ds_bpermute_b32 v177, v170, v174
	s_waitcnt lgkmcnt(2)
	v_add_f32_e32 v176, v176, v178
	ds_bpermute_b32 v178, v171, v176
	s_waitcnt lgkmcnt(2)
	v_add_f32_e32 v175, v175, v179
	ds_bpermute_b32 v179, v171, v175
	s_mul_i32 s6, s6, 0x9000
	s_waitcnt lgkmcnt(2)
	v_add_f32_e32 v174, v174, v177
	s_add_u32 s6, s3, s6
	ds_bpermute_b32 v177, v171, v174
	s_addc_u32 s7, s4, s7
	s_waitcnt lgkmcnt(2)
	v_add_f32_e32 v176, v176, v178
	s_add_u32 s18, s6, 0x6000
	v_fmamk_f32 v176, v176, 0x3a800000, v172
	s_addc_u32 s19, s7, 0
	s_waitcnt lgkmcnt(1)
	v_add_f32_e32 v175, v175, v179
	v_mul_f32_e32 v178, 0x4f800000, v176
	v_cmp_gt_f32_e32 vcc, s13, v176
	s_add_u32 s20, s6, 0x7000
	v_fmamk_f32 v175, v175, 0x3a800000, v172
	v_cndmask_b32_e32 v176, v176, v178, vcc
	s_addc_u32 s21, s7, 0
	s_waitcnt lgkmcnt(0)
	v_add_f32_e32 v174, v174, v177
	v_mul_f32_e32 v177, 0x4f800000, v175
	v_cmp_gt_f32_e64 s[6:7], s13, v175
	v_sqrt_f32_e32 v178, v176
	v_fmamk_f32 v174, v174, 0x3a800000, v172
	v_cndmask_b32_e64 v175, v175, v177, s[6:7]
	v_mul_f32_e32 v177, 0x4f800000, v174
	v_cmp_gt_f32_e64 s[8:9], s13, v174
	v_sqrt_f32_e32 v179, v175
	v_add_u32_e32 v180, -1, v178
	v_cndmask_b32_e64 v174, v174, v177, s[8:9]
	v_sqrt_f32_e32 v177, v174
	v_add_u32_e32 v181, 1, v178
	v_fma_f32 v182, -v180, v178, v176
	v_lshl_add_u64 v[112:113], s[10:11], 0, v[90:91]
	v_lshl_add_u64 v[106:107], s[10:11], 0, v[96:97]
	v_lshl_add_u64 v[110:111], s[10:11], 0, v[98:99]
	v_lshl_add_u64 v[108:109], s[10:11], 0, v[100:101]
	v_pk_add_f32 v[164:165], v[184:185], v[194:195]
	v_fma_f32 v183, -v181, v178, v176
	v_add_u32_e32 v184, -1, v179
	v_cmp_ge_f32_e64 s[10:11], 0, v182
	v_add_u32_e32 v185, 1, v179
	v_fma_f32 v182, -v185, v179, v175
	v_cndmask_b32_e64 v178, v178, v180, s[10:11]
	v_fma_f32 v180, -v184, v179, v175
	v_cmp_lt_f32_e64 s[10:11], 0, v183
	v_add_u32_e32 v186, -1, v177
	v_add_u32_e32 v187, 1, v177
	v_cndmask_b32_e64 v178, v178, v181, s[10:11]
	v_cmp_ge_f32_e64 s[10:11], 0, v180
	v_fma_f32 v180, -v186, v177, v174
	v_fma_f32 v181, -v187, v177, v174
	v_cndmask_b32_e64 v179, v179, v184, s[10:11]
	v_cmp_lt_f32_e64 s[10:11], 0, v182
	v_mul_f32_e32 v182, 0x37800000, v178
	v_cndmask_b32_e32 v178, v178, v182, vcc
	v_cndmask_b32_e64 v179, v179, v185, s[10:11]
	v_cmp_ge_f32_e64 s[10:11], 0, v180
	v_cmp_class_f32_e32 vcc, v176, v173
	v_mul_f32_e32 v180, 0x37800000, v179
	v_cndmask_b32_e64 v177, v177, v186, s[10:11]
	v_cmp_lt_f32_e64 s[10:11], 0, v181
	v_cndmask_b32_e32 v176, v178, v176, vcc
	v_cndmask_b32_e64 v178, v179, v180, s[6:7]
	v_cndmask_b32_e64 v177, v177, v187, s[10:11]
	v_cmp_class_f32_e32 vcc, v175, v173
	v_mul_f32_e32 v179, 0x37800000, v177
	v_div_scale_f32 v180, s[6:7], v176, v176, 1.0
	v_cndmask_b32_e32 v175, v178, v175, vcc
	v_cndmask_b32_e64 v177, v177, v179, s[8:9]
	v_cmp_class_f32_e32 vcc, v174, v173
	v_rcp_f32_e32 v178, v180
	v_div_scale_f32 v179, s[8:9], v175, v175, 1.0
	v_cndmask_b32_e32 v177, v177, v174, vcc
	v_rcp_f32_e32 v183, v179
	v_div_scale_f32 v184, s[10:11], v177, v177, 1.0
	v_rcp_f32_e32 v186, v184
	v_fma_f32 v174, -v180, v178, 1.0
	v_div_scale_f32 v181, s[6:7], 1.0, v176, 1.0
	v_fmac_f32_e32 v178, v174, v178
	v_fma_f32 v174, -v179, v183, 1.0
	v_mul_f32_e32 v187, v181, v178
	v_div_scale_f32 v182, s[8:9], 1.0, v175, 1.0
	v_fmac_f32_e32 v183, v174, v183
	v_fma_f32 v174, -v184, v186, 1.0
	v_fma_f32 v188, -v180, v187, v181
	v_div_scale_f32 v185, s[10:11], 1.0, v177, 1.0
	v_mul_f32_e32 v189, v182, v183
	v_fmac_f32_e32 v186, v174, v186
	v_fmac_f32_e32 v187, v188, v178
	v_fma_f32 v174, -v179, v189, v182
	v_mul_f32_e32 v188, v185, v186
	v_fma_f32 v180, -v180, v187, v181
	s_mov_b64 vcc, s[6:7]
	v_fmac_f32_e32 v189, v174, v183
	v_fma_f32 v174, -v184, v188, v185
	v_div_fmas_f32 v178, v180, v178, v187
	v_fma_f32 v179, -v179, v189, v182
	v_fmac_f32_e32 v188, v174, v186
	v_div_fixup_f32 v174, v178, v176, 1.0
	s_mov_b64 vcc, s[8:9]
	v_div_fmas_f32 v176, v179, v183, v189
	v_fma_f32 v178, -v184, v188, v185
	v_pk_mul_f32 v[80:81], v[80:81], v[174:175] op_sel_hi:[1,0]
	v_pk_mul_f32 v[78:79], v[78:79], v[174:175] op_sel_hi:[1,0]
	s_mov_b64 vcc, s[10:11]
	v_pk_add_f32 v[88:89], v[88:89], 1.0 op_sel_hi:[1,0]
	v_pk_add_f32 v[86:87], v[86:87], 1.0 op_sel_hi:[1,0]
	v_pk_mul_f32 v[76:77], v[76:77], v[174:175] op_sel_hi:[1,0]
	v_pk_mul_f32 v[74:75], v[74:75], v[174:175] op_sel_hi:[1,0]
	v_pk_mul_f32 v[72:73], v[72:73], v[174:175] op_sel_hi:[1,0]
	v_pk_mul_f32 v[70:71], v[70:71], v[174:175] op_sel_hi:[1,0]
	v_pk_mul_f32 v[68:69], v[68:69], v[174:175] op_sel_hi:[1,0]
	v_pk_mul_f32 v[66:67], v[66:67], v[174:175] op_sel_hi:[1,0]
	v_div_fixup_f32 v174, v176, v175, 1.0
	v_div_fmas_f32 v176, v178, v186, v188
	v_pk_mul_f32 v[78:79], v[2:3], v[78:79]
	v_pk_mul_f32 v[80:81], v[4:5], v[80:81]
	v_pk_mul_f32 v[64:65], v[64:65], v[174:175] op_sel_hi:[1,0]
	v_pk_mul_f32 v[62:63], v[62:63], v[174:175] op_sel_hi:[1,0]
	v_pk_mul_f32 v[60:61], v[60:61], v[174:175] op_sel_hi:[1,0]
	v_pk_mul_f32 v[58:59], v[58:59], v[174:175] op_sel_hi:[1,0]
	v_pk_mul_f32 v[56:57], v[56:57], v[174:175] op_sel_hi:[1,0]
	v_pk_mul_f32 v[54:55], v[54:55], v[174:175] op_sel_hi:[1,0]
	v_pk_mul_f32 v[52:53], v[52:53], v[174:175] op_sel_hi:[1,0]
	v_pk_mul_f32 v[174:175], v[50:51], v[174:175] op_sel_hi:[1,0]
	v_div_fixup_f32 v50, v176, v177, 1.0
	v_pk_fma_f32 v[80:81], v[88:89], v[80:81], v[84:85]
	v_pk_fma_f32 v[78:79], v[86:87], v[78:79], v[82:83]
	v_pk_mul_f32 v[86:87], v[16:17], v[52:53]
	v_pk_mul_f32 v[48:49], v[48:49], v[50:51] op_sel_hi:[1,0]
	v_pk_mul_f32 v[46:47], v[46:47], v[50:51] op_sel_hi:[1,0]
	v_pk_mul_f32 v[82:83], v[10:11], v[54:55]
	v_pk_mul_f32 v[84:85], v[14:15], v[174:175]
	v_pk_mul_f32 v[88:89], v[2:3], v[46:47]
	v_pk_mul_f32 v[174:175], v[4:5], v[48:49]
	v_cvt_pk_bf16_f32 v46, v78, v79
	v_cvt_pk_bf16_f32 v47, v80, v81
	global_store_dwordx2 v[102:103], v[46:47], off
	global_load_dwordx4 v[46:49], v[152:153], off
	s_nop 0
	global_load_dwordx4 v[52:55], v[148:149], off
	v_pk_mul_f32 v[74:75], v[6:7], v[74:75]
	v_pk_mul_f32 v[76:77], v[8:9], v[76:77]
	v_pk_mul_f32 v[70:71], v[10:11], v[70:71]
	v_pk_mul_f32 v[72:73], v[12:13], v[72:73]
	v_pk_mul_f32 v[66:67], v[66:67], v[14:15]
	v_pk_mul_f32 v[68:69], v[68:69], v[16:17]
	v_pk_mul_f32 v[62:63], v[2:3], v[62:63]
	v_pk_mul_f32 v[64:65], v[4:5], v[64:65]
	v_pk_mul_f32 v[58:59], v[6:7], v[58:59]
	v_pk_mul_f32 v[60:61], v[8:9], v[60:61]
	v_pk_mul_f32 v[56:57], v[12:13], v[56:57]
	v_mul_f32_e32 v196, v23, v23
	v_mul_f32_e32 v202, v25, v25
	v_mul_f32_e32 v214, v18, v18
	v_mul_f32_e32 v215, v19, v19
	v_mul_f32_e32 v216, v20, v20
	v_mul_f32_e32 v217, v21, v21
	v_pk_fma_f32 v[158:159], v[22:23], v[22:23], v[196:197] op_sel_hi:[1,1,0]
	v_pk_fma_f32 v[160:161], v[24:25], v[24:25], v[202:203] op_sel_hi:[1,1,0]
	v_mov_b32_e32 v159, v216
	v_mov_b32_e32 v161, v217
	v_lshl_add_u64 v[144:145], s[20:21], 0, v[90:91]
	v_lshl_add_u64 v[128:129], s[18:19], 0, v[90:91]
	v_lshl_add_u64 v[124:125], s[20:21], 0, v[96:97]
	v_lshl_add_u64 v[120:121], s[18:19], 0, v[96:97]
	s_add_i32 s12, s12, 32
	v_lshl_add_u64 v[92:93], v[92:93], 0, s[14:15]
	v_lshl_add_u64 v[94:95], v[94:95], 0, s[16:17]
	s_cmp_lt_i32 s12, s2
	s_waitcnt vmcnt(0) lgkmcnt(0)
	v_pk_add_f32 v[48:49], v[48:49], 1.0 op_sel_hi:[1,0]
	v_pk_add_f32 v[46:47], v[46:47], 1.0 op_sel_hi:[1,0]
	v_pk_fma_f32 v[48:49], v[48:49], v[76:77], v[54:55]
	v_pk_fma_f32 v[46:47], v[46:47], v[74:75], v[52:53]
	v_cvt_pk_bf16_f32 v46, v46, v47
	v_cvt_pk_bf16_f32 v47, v48, v49
	global_store_dwordx2 v[102:103], v[46:47], off offset:512
	global_load_dwordx4 v[46:49], v[146:147], off
	s_nop 0
	global_load_dwordx4 v[52:55], v[142:143], off
	s_waitcnt vmcnt(0) lgkmcnt(0)
	v_pk_add_f32 v[48:49], v[48:49], 1.0 op_sel_hi:[1,0]
	v_pk_add_f32 v[46:47], v[46:47], 1.0 op_sel_hi:[1,0]
	v_pk_fma_f32 v[48:49], v[72:73], v[48:49], v[54:55]
	v_pk_fma_f32 v[46:47], v[70:71], v[46:47], v[52:53]
	v_cvt_pk_bf16_f32 v46, v46, v47
	v_cvt_pk_bf16_f32 v47, v48, v49
	global_store_dwordx2 v[102:103], v[46:47], off offset:1024
	global_load_dwordx4 v[46:49], v[140:141], off
	s_nop 0
	global_load_dwordx4 v[52:55], v[132:133], off
	s_waitcnt vmcnt(0) lgkmcnt(0)
	v_pk_add_f32 v[48:49], v[48:49], 1.0 op_sel_hi:[1,0]
	v_pk_add_f32 v[46:47], v[46:47], 1.0 op_sel_hi:[1,0]
	v_pk_fma_f32 v[48:49], v[68:69], v[48:49], v[54:55]
	v_pk_fma_f32 v[46:47], v[66:67], v[46:47], v[52:53]
	v_cvt_pk_bf16_f32 v46, v46, v47
	v_cvt_pk_bf16_f32 v47, v48, v49
	global_store_dwordx2 v[102:103], v[46:47], off offset:1536
	global_load_dwordx4 v[46:49], v[136:137], off
	s_nop 0
	global_load_dwordx4 v[52:55], v[134:135], off
	s_waitcnt vmcnt(0) lgkmcnt(0)
	v_pk_add_f32 v[48:49], v[48:49], 1.0 op_sel_hi:[1,0]
	v_pk_add_f32 v[46:47], v[46:47], 1.0 op_sel_hi:[1,0]
	v_pk_fma_f32 v[48:49], v[48:49], v[64:65], v[54:55]
	v_pk_fma_f32 v[46:47], v[46:47], v[62:63], v[52:53]
	v_cvt_pk_bf16_f32 v46, v46, v47
	v_cvt_pk_bf16_f32 v47, v48, v49
	global_store_dwordx2 v[102:103], v[46:47], off offset:2048
	global_load_dwordx4 v[46:49], v[130:131], off
	s_nop 0
	global_load_dwordx4 v[52:55], v[126:127], off
	s_waitcnt vmcnt(0) lgkmcnt(0)
	v_pk_add_f32 v[48:49], v[48:49], 1.0 op_sel_hi:[1,0]
	v_pk_add_f32 v[46:47], v[46:47], 1.0 op_sel_hi:[1,0]
	v_pk_fma_f32 v[48:49], v[48:49], v[60:61], v[54:55]
	v_pk_fma_f32 v[46:47], v[46:47], v[58:59], v[52:53]
	v_cvt_pk_bf16_f32 v46, v46, v47
	v_cvt_pk_bf16_f32 v47, v48, v49
	global_store_dwordx2 v[102:103], v[46:47], off offset:2560
	global_load_dwordx4 v[46:49], v[122:123], off
	s_nop 0
	global_load_dwordx4 v[52:55], v[118:119], off
	v_pk_add_f32 v[58:59], v[164:165], v[164:165] op_sel:[0,1] op_sel_hi:[1,0]
	v_pk_add_f32 v[60:61], v[158:159], v[160:161]
	v_mov_b32_e32 v59, v215
	s_waitcnt vmcnt(0) lgkmcnt(0)
	v_pk_add_f32 v[48:49], v[48:49], 1.0 op_sel_hi:[1,0]
	v_pk_add_f32 v[46:47], v[46:47], 1.0 op_sel_hi:[1,0]
	v_pk_fma_f32 v[48:49], v[48:49], v[56:57], v[54:55]
	v_pk_fma_f32 v[46:47], v[46:47], v[82:83], v[52:53]
	v_cvt_pk_bf16_f32 v46, v46, v47
	v_cvt_pk_bf16_f32 v47, v48, v49
	global_store_dwordx2 v[102:103], v[46:47], off offset:3072
	global_load_dwordx4 v[46:49], v[116:117], off
	s_nop 0
	global_load_dwordx4 v[52:55], v[114:115], off
	v_pk_add_f32 v[56:57], v[162:163], v[162:163] op_sel:[0,1] op_sel_hi:[1,0]
	s_waitcnt vmcnt(0) lgkmcnt(0)
	v_pk_add_f32 v[48:49], v[48:49], 1.0 op_sel_hi:[1,0]
	v_pk_add_f32 v[46:47], v[46:47], 1.0 op_sel_hi:[1,0]
	v_pk_fma_f32 v[48:49], v[86:87], v[48:49], v[54:55]
	v_pk_fma_f32 v[46:47], v[84:85], v[46:47], v[52:53]
	v_cvt_pk_bf16_f32 v46, v46, v47
	v_cvt_pk_bf16_f32 v47, v48, v49
	global_store_dwordx2 v[102:103], v[46:47], off offset:3584
	global_load_dwordx4 v[46:49], v[156:157], off
	s_nop 0
	global_load_dwordx4 v[52:55], v[112:113], off
	v_mov_b32_e32 v57, v214
	s_waitcnt vmcnt(0) lgkmcnt(0)
	v_pk_add_f32 v[48:49], v[48:49], 1.0 op_sel_hi:[1,0]
	v_pk_add_f32 v[46:47], v[46:47], 1.0 op_sel_hi:[1,0]
	v_pk_fma_f32 v[48:49], v[48:49], v[174:175], v[54:55]
	v_pk_fma_f32 v[46:47], v[46:47], v[88:89], v[52:53]
	v_bfe_u32 v51, v46, 16, 1
	v_bfe_u32 v52, v47, 16, 1
	v_add3_u32 v46, v46, v51, s22
	v_add3_u32 v47, v47, v52, s22
	v_lshrrev_b32_e32 v46, 16, v46
	v_and_or_b32 v46, v47, s23, v46
	v_cvt_pk_bf16_f32 v47, v48, v49
	global_store_dwordx2 v[104:105], v[46:47], off
	global_load_dwordx4 v[46:49], v[154:155], off
	s_nop 0
	global_load_dwordx4 v[52:55], v[106:107], off
	v_pk_mul_f32 v[44:45], v[44:45], v[50:51] op_sel_hi:[1,0]
	v_pk_mul_f32 v[42:43], v[42:43], v[50:51] op_sel_hi:[1,0]
	v_pk_mul_f32 v[44:45], v[8:9], v[44:45]
	v_pk_mul_f32 v[42:43], v[6:7], v[42:43]
	s_waitcnt vmcnt(0) lgkmcnt(0)
	v_pk_add_f32 v[48:49], v[48:49], 1.0 op_sel_hi:[1,0]
	v_pk_add_f32 v[46:47], v[46:47], 1.0 op_sel_hi:[1,0]
	v_pk_fma_f32 v[44:45], v[48:49], v[44:45], v[54:55]
	v_pk_fma_f32 v[42:43], v[46:47], v[42:43], v[52:53]
	v_cvt_pk_bf16_f32 v42, v42, v43
	v_cvt_pk_bf16_f32 v43, v44, v45
	global_store_dwordx2 v[104:105], v[42:43], off offset:512
	global_load_dwordx4 v[42:45], v[150:151], off
	s_nop 0
	global_load_dwordx4 v[46:49], v[110:111], off
	v_pk_add_f32 v[52:53], v[56:57], v[58:59]
	s_waitcnt vmcnt(0) lgkmcnt(0)
	v_pk_add_f32 v[44:45], v[44:45], 1.0 op_sel_hi:[1,0]
	v_pk_add_f32 v[52:53], v[52:53], v[60:61]
	v_pk_add_f32 v[42:43], v[42:43], 1.0 op_sel_hi:[1,0]
	v_add_f32_e32 v51, v52, v53
	s_waitcnt lgkmcnt(0)
	s_nop 1
	v_add_f32_dpp v51, v51, v51 quad_perm:[1,0,3,2] row_mask:0xf bank_mask:0xf
	ds_bpermute_b32 v52, v167, v51
	s_waitcnt lgkmcnt(0)
	v_add_f32_e32 v51, v51, v52
	v_pk_mul_f32 v[40:41], v[40:41], v[50:51] op_sel_hi:[1,0]
	v_pk_mul_f32 v[38:39], v[38:39], v[50:51] op_sel_hi:[1,0]
	v_pk_mul_f32 v[40:41], v[12:13], v[40:41]
	v_pk_mul_f32 v[38:39], v[10:11], v[38:39]
	v_pk_fma_f32 v[40:41], v[44:45], v[40:41], v[48:49]
	v_pk_fma_f32 v[38:39], v[42:43], v[38:39], v[46:47]
	v_cvt_pk_bf16_f32 v38, v38, v39
	v_cvt_pk_bf16_f32 v39, v40, v41
	global_store_dwordx2 v[104:105], v[38:39], off offset:1024
	global_load_dwordx4 v[38:41], v[138:139], off
	s_nop 0
	global_load_dwordx4 v[42:45], v[108:109], off
	v_pk_mul_f32 v[36:37], v[36:37], v[50:51] op_sel_hi:[1,0]
	v_pk_mul_f32 v[34:35], v[34:35], v[50:51] op_sel_hi:[1,0]
	v_pk_mul_f32 v[36:37], v[16:17], v[36:37]
	v_pk_mul_f32 v[34:35], v[14:15], v[34:35]
	ds_bpermute_b32 v46, v168, v51
	s_waitcnt lgkmcnt(0)
	v_add_f32_e32 v46, v51, v46
	ds_bpermute_b32 v47, v169, v46
	s_waitcnt lgkmcnt(0)
	v_add_f32_e32 v46, v46, v47
	ds_bpermute_b32 v47, v170, v46
	s_waitcnt lgkmcnt(0)
	v_add_f32_e32 v46, v46, v47
	ds_bpermute_b32 v47, v171, v46
	s_waitcnt lgkmcnt(0)
	v_add_f32_e32 v46, v46, v47
	v_fmamk_f32 v46, v46, 0x3a800000, v172
	v_mul_f32_e32 v47, 0x4f800000, v46
	v_cmp_gt_f32_e32 vcc, s13, v46
	s_waitcnt vmcnt(0)
	v_pk_add_f32 v[40:41], v[40:41], 1.0 op_sel_hi:[1,0]
	v_pk_add_f32 v[38:39], v[38:39], 1.0 op_sel_hi:[1,0]
	v_pk_fma_f32 v[36:37], v[36:37], v[40:41], v[44:45]
	v_pk_fma_f32 v[34:35], v[34:35], v[38:39], v[42:43]
	v_cvt_pk_bf16_f32 v34, v34, v35
	v_cvt_pk_bf16_f32 v35, v36, v37
	global_store_dwordx2 v[104:105], v[34:35], off offset:1536
	global_load_dwordx4 v[34:37], v[144:145], off
	s_nop 0
	global_load_dwordx4 v[38:41], v[128:129], off
	v_cndmask_b32_e32 v42, v46, v47, vcc
	v_sqrt_f32_e32 v43, v42
	s_waitcnt vmcnt(0) lgkmcnt(0)
	v_pk_add_f32 v[36:37], v[36:37], 1.0 op_sel_hi:[1,0]
	v_add_u32_e32 v44, -1, v43
	v_add_u32_e32 v45, 1, v43
	v_fma_f32 v46, -v44, v43, v42
	v_fma_f32 v47, -v45, v43, v42
	v_cmp_ge_f32_e64 s[6:7], 0, v46
	v_pk_add_f32 v[34:35], v[34:35], 1.0 op_sel_hi:[1,0]
	s_nop 0
	v_cndmask_b32_e64 v43, v43, v44, s[6:7]
	v_cmp_lt_f32_e64 s[6:7], 0, v47
	s_nop 1
	v_cndmask_b32_e64 v43, v43, v45, s[6:7]
	v_mul_f32_e32 v44, 0x37800000, v43
	v_cndmask_b32_e32 v43, v43, v44, vcc
	v_cmp_class_f32_e32 vcc, v42, v173
	s_nop 1
	v_cndmask_b32_e32 v42, v43, v42, vcc
	v_div_scale_f32 v43, s[6:7], v42, v42, 1.0
	v_rcp_f32_e32 v45, v43
	v_div_scale_f32 v44, vcc, 1.0, v42, 1.0
	v_fma_f32 v46, -v43, v45, 1.0
	v_fmac_f32_e32 v45, v46, v45
	v_mul_f32_e32 v46, v44, v45
	v_fma_f32 v47, -v43, v46, v44
	v_fmac_f32_e32 v46, v47, v45
	v_fma_f32 v43, -v43, v46, v44
	v_div_fmas_f32 v43, v43, v45, v46
	v_div_fixup_f32 v42, v43, v42, 1.0
	v_pk_mul_f32 v[32:33], v[32:33], v[42:43] op_sel_hi:[1,0]
	v_pk_mul_f32 v[30:31], v[30:31], v[42:43] op_sel_hi:[1,0]
	v_pk_mul_f32 v[32:33], v[4:5], v[32:33]
	v_pk_mul_f32 v[30:31], v[2:3], v[30:31]
	v_pk_fma_f32 v[32:33], v[36:37], v[32:33], v[40:41]
	v_pk_fma_f32 v[30:31], v[34:35], v[30:31], v[38:39]
	v_cvt_pk_bf16_f32 v30, v30, v31
	v_cvt_pk_bf16_f32 v31, v32, v33
	global_store_dwordx2 v[104:105], v[30:31], off offset:2048
	global_load_dwordx4 v[30:33], v[124:125], off
	s_nop 0
	global_load_dwordx4 v[34:37], v[120:121], off
	v_pk_mul_f32 v[28:29], v[28:29], v[42:43] op_sel_hi:[1,0]
	v_pk_mul_f32 v[26:27], v[26:27], v[42:43] op_sel_hi:[1,0]
	v_pk_mul_f32 v[28:29], v[8:9], v[28:29]
	v_pk_mul_f32 v[26:27], v[6:7], v[26:27]
	v_lshl_add_u64 v[40:41], s[20:21], 0, v[98:99]
	v_lshl_add_u64 v[38:39], s[18:19], 0, v[98:99]
	v_pk_mul_f32 v[24:25], v[24:25], v[42:43] op_sel_hi:[1,0]
	v_pk_mul_f32 v[22:23], v[22:23], v[42:43] op_sel_hi:[1,0]
	v_pk_mul_f32 v[24:25], v[12:13], v[24:25]
	v_pk_mul_f32 v[22:23], v[10:11], v[22:23]
	v_pk_mul_f32 v[20:21], v[20:21], v[42:43] op_sel_hi:[1,0]
	v_pk_mul_f32 v[18:19], v[18:19], v[42:43] op_sel_hi:[1,0]
	v_pk_mul_f32 v[20:21], v[16:17], v[20:21]
	v_pk_mul_f32 v[18:19], v[14:15], v[18:19]
	s_waitcnt vmcnt(0) lgkmcnt(0)
	v_pk_add_f32 v[32:33], v[32:33], 1.0 op_sel_hi:[1,0]
	v_pk_add_f32 v[30:31], v[30:31], 1.0 op_sel_hi:[1,0]
	v_pk_fma_f32 v[28:29], v[32:33], v[28:29], v[36:37]
	v_pk_fma_f32 v[26:27], v[30:31], v[26:27], v[34:35]
	v_cvt_pk_bf16_f32 v26, v26, v27
	v_cvt_pk_bf16_f32 v27, v28, v29
	global_store_dwordx2 v[104:105], v[26:27], off offset:2560
	global_load_dwordx4 v[26:29], v[40:41], off
	s_nop 0
	global_load_dwordx4 v[30:33], v[38:39], off
	v_lshl_add_u64 v[36:37], s[20:21], 0, v[100:101]
	v_lshl_add_u64 v[34:35], s[18:19], 0, v[100:101]
	s_waitcnt vmcnt(0) lgkmcnt(0)
	v_pk_add_f32 v[28:29], v[28:29], 1.0 op_sel_hi:[1,0]
	v_pk_add_f32 v[26:27], v[26:27], 1.0 op_sel_hi:[1,0]
	v_pk_fma_f32 v[24:25], v[28:29], v[24:25], v[32:33]
	v_pk_fma_f32 v[22:23], v[26:27], v[22:23], v[30:31]
	v_cvt_pk_bf16_f32 v22, v22, v23
	v_cvt_pk_bf16_f32 v23, v24, v25
	global_store_dwordx2 v[104:105], v[22:23], off offset:3072
	global_load_dwordx4 v[22:25], v[36:37], off
	s_nop 0
	global_load_dwordx4 v[26:29], v[34:35], off
	s_waitcnt vmcnt(0) lgkmcnt(0)
	v_pk_add_f32 v[24:25], v[24:25], 1.0 op_sel_hi:[1,0]
	v_pk_add_f32 v[22:23], v[22:23], 1.0 op_sel_hi:[1,0]
	v_pk_fma_f32 v[20:21], v[20:21], v[24:25], v[28:29]
	v_pk_fma_f32 v[18:19], v[18:19], v[22:23], v[26:27]
	v_cvt_pk_bf16_f32 v18, v18, v19
	v_cvt_pk_bf16_f32 v19, v20, v21
	global_store_dwordx2 v[104:105], v[18:19], off offset:3584
	s_cbranch_scc1 .LBB0_5544

.LBB0_5572:
	ds_read2_b32 v[20:21], v18 offset1:2
	ds_read2st64_b32 v[22:23], v19 offset1:4
	s_add_i32 s8, s8, -8
	s_cmp_lg_u32 s8, 0
	s_waitcnt lgkmcnt(0)
	v_mfma_f32_32x32x2_f32 v[2:17], v20, v22, v[2:17]
	v_mfma_f32_32x32x2_f32 v[2:17], v21, v23, v[2:17]
	ds_read2_b32 v[20:21], v18 offset0:4 offset1:6
	ds_read2st64_b32 v[22:23], v19 offset0:8 offset1:12
	s_waitcnt lgkmcnt(0)
	v_mfma_f32_32x32x2_f32 v[2:17], v20, v22, v[2:17]
	v_mfma_f32_32x32x2_f32 v[2:17], v21, v23, v[2:17]
	ds_read2_b32 v[20:21], v18 offset0:8 offset1:10
	ds_read2st64_b32 v[22:23], v19 offset0:16 offset1:20
	s_waitcnt lgkmcnt(0)
	v_mfma_f32_32x32x2_f32 v[2:17], v20, v22, v[2:17]
	v_mfma_f32_32x32x2_f32 v[2:17], v21, v23, v[2:17]
	ds_read2_b32 v[20:21], v18 offset0:12 offset1:14
	ds_read2st64_b32 v[22:23], v19 offset0:24 offset1:28
	v_add_u32_e32 v19, 0x2000, v19
	v_add_u32_e32 v18, 64, v18
	s_waitcnt lgkmcnt(0)
	v_mfma_f32_32x32x2_f32 v[2:17], v20, v22, v[2:17]
	v_mfma_f32_32x32x2_f32 v[2:17], v21, v23, v[2:17]
	s_cbranch_scc1 .LBB0_5572
	v_add_u32_e32 v18, 0xc200, v103
	s_barrier
	s_nop 14
	ds_write2_b32 v18, v2, v3 offset0:64 offset1:196
	v_add_u32_e32 v2, 0xc600, v103
	ds_write2_b32 v2, v4, v5 offset0:72 offset1:204
	v_add_u32_e32 v2, 0xd200, v103
	ds_write2_b32 v2, v6, v7 offset0:96 offset1:228
	v_add_u32_e32 v2, 0xd600, v103
	ds_write2_b32 v2, v8, v9 offset0:104 offset1:236
	v_add_u32_e32 v2, 0xe400, v103
	ds_write2_b32 v2, v10, v11 offset1:132
	v_add_u32_e32 v2, 0xe800, v103
	ds_write2_b32 v2, v12, v13 offset0:8 offset1:140
	v_add_u32_e32 v2, 0xf400, v103
	ds_write2_b32 v2, v14, v15 offset0:32 offset1:164
	v_add_u32_e32 v2, 0xf800, v103
	v_mov_b64_e32 v[18:19], s[0:1]
	ds_write2_b32 v2, v16, v17 offset0:40 offset1:172
	s_waitcnt lgkmcnt(0)
	s_barrier
	ds_read_b128 v[14:17], v95 offset:49920
	ds_read_b128 v[10:13], v95 offset:49936
	ds_read_b128 v[6:9], v95 offset:49952
	ds_read_b128 v[2:5], v95 offset:49968
	s_load_dwordx2 s[98:99], s[0:1], 0xa8
	s_waitcnt vmcnt(0) lgkmcnt(0)
	v_mov_b32_e32 v22, s98
	v_mov_b32_e32 v23, s99
	v_mov_b32_e32 v1, v229
	v_add_u32_e32 v60, s36, v94
	v_mov_b64_e32 v[18:19], s[12:13]
	v_and_b32_e32 v21, 64, v166
	s_lshl_b32 s70, s35, 2
	v_mad_i64_i32 v[18:19], s[8:9], v60, s29, v[18:19]
	v_xor_b32_e32 v20, 1, v166
	v_lshlrev_b32_e32 v42, 2, v54
	v_add_u32_e32 v59, 64, v21
	v_lshl_add_u64 v[18:19], v[18:19], 0, s[70:71]
	v_cmp_lt_i32_e32 vcc, v20, v59
	v_lshl_add_u64 v[30:31], v[18:19], 0, v[42:43]
	s_waitcnt lgkmcnt(0)
	v_mov_b32_e32 v26, v15
	v_cndmask_b32_e32 v20, v166, v20, vcc
	v_add_co_u32_e32 v18, vcc, s28, v30
	v_lshlrev_b32_e32 v61, 2, v20
	s_nop 0
	v_addc_co_u32_e32 v19, vcc, 0, v31, vcc
	global_load_dwordx4 v[18:21], v[18:19], off offset:1184
	v_mov_b32_e32 v27, v11
	v_mov_b32_e32 v24, v14
	v_mov_b32_e32 v25, v10
	v_mov_b32_e32 v36, v7
	v_mov_b32_e32 v37, v3
	v_pk_mul_f32 v[26:27], v[26:27], v[26:27]
	v_mov_b32_e32 v28, v16
	v_mov_b32_e32 v29, v12
	v_mov_b32_e32 v34, v6
	v_mov_b32_e32 v35, v2
	v_pk_mul_f32 v[36:37], v[36:37], v[36:37]
	v_pk_fma_f32 v[24:25], v[24:25], v[24:25], v[26:27]
	v_mov_b32_e32 v32, v17
	v_mov_b32_e32 v33, v13
	v_mov_b32_e32 v38, v8
	v_mov_b32_e32 v39, v4
	v_pk_fma_f32 v[26:27], v[34:35], v[34:35], v[36:37]
	v_pk_fma_f32 v[24:25], v[28:29], v[28:29], v[24:25]
	v_mov_b32_e32 v40, v9
	v_mov_b32_e32 v41, v5
	v_pk_fma_f32 v[26:27], v[38:39], v[38:39], v[26:27]
	v_pk_fma_f32 v[24:25], v[32:33], v[32:33], v[24:25]
	v_pk_fma_f32 v[26:27], v[40:41], v[40:41], v[26:27]
	v_add_f32_e32 v24, v24, v25
	v_add_f32_e32 v24, v24, v26
	v_add_f32_e32 v24, v24, v27
	v_xor_b32_e32 v26, 2, v166
	v_cmp_lt_i32_e32 vcc, v26, v59
	v_lshl_add_u64 v[62:63], v[30:31], 0, s[72:73]
	v_mov_b32_e32 v38, v14
	v_cndmask_b32_e32 v26, v166, v26, vcc
	v_lshlrev_b32_e32 v26, 2, v26
	s_waitcnt lgkmcnt(0)
	s_nop 1
	v_add_f32_dpp v24, v24, v24 quad_perm:[1,0,3,2] row_mask:0xf bank_mask:0xf
	v_ashrrev_i32_e32 v61, 31, v60
	s_lshl_b32 s70, s35, 1
	s_mov_b64 s[76:77], 0
	s_waitcnt lgkmcnt(0)
	s_nop 1
	v_add_f32_dpp v32, v24, v24 quad_perm:[2,3,0,1] row_mask:0xf bank_mask:0xf
	v_lshl_add_u64 v[64:65], v[22:23], 0, v[42:43]
	global_load_dwordx4 v[26:29], v[64:65], off offset:512
	v_xor_b32_e32 v22, 4, v166
	v_cmp_lt_i32_e32 vcc, v22, v59
	s_nop 1
	v_cndmask_b32_e32 v22, v166, v22, vcc
	v_lshlrev_b32_e32 v22, 2, v22
	global_load_dwordx4 v[22:25], v[64:65], off offset:528
	s_waitcnt lgkmcnt(0)
	s_nop 1
	v_add_f32_dpp v30, v32, v32 row_half_mirror row_mask:0xf bank_mask:0xf
	v_fmamk_f32 v30, v30, 0x3c000000, v104
	v_mul_f32_e32 v31, 0x4f800000, v30
	v_cmp_gt_f32_e32 vcc, s31, v30
	s_nop 1
	v_cndmask_b32_e32 v39, v30, v31, vcc
	v_sqrt_f32_e32 v40, v39
	global_load_dwordx4 v[30:33], v[62:63], off offset:16
	global_load_dwordx4 v[34:37], v[62:63], off offset:48
	v_add_u32_e32 v14, -1, v40
	v_add_u32_e32 v41, 1, v40
	v_fma_f32 v42, -v14, v40, v39
	v_fma_f32 v59, -v41, v40, v39
	v_cmp_ge_f32_e64 s[8:9], 0, v42
	s_nop 1
	v_cndmask_b32_e64 v14, v40, v14, s[8:9]
	v_cmp_lt_f32_e64 s[8:9], 0, v59
	s_nop 1
	v_cndmask_b32_e64 v14, v14, v41, s[8:9]
	v_mul_f32_e32 v40, 0x37800000, v14
	v_cndmask_b32_e32 v14, v14, v40, vcc
	v_cmp_class_f32_e32 vcc, v39, v105
	s_nop 1
	v_cndmask_b32_e32 v14, v14, v39, vcc
	v_div_scale_f32 v40, s[8:9], v14, v14, 1.0
	v_rcp_f32_e32 v41, v40
	v_mov_b32_e32 v39, v16
	v_div_scale_f32 v16, vcc, 1.0, v14, 1.0
	v_fma_f32 v42, -v40, v41, 1.0
	v_fmac_f32_e32 v41, v42, v41
	v_mul_f32_e32 v42, v16, v41
	v_fma_f32 v59, -v40, v42, v16
	v_fmac_f32_e32 v42, v59, v41
	v_fma_f32 v16, -v40, v42, v16
	v_div_fmas_f32 v16, v16, v41, v42
	v_div_fixup_f32 v14, v16, v14, 1.0
	v_pk_mul_f32 v[110:111], v[38:39], v[14:15] op_sel_hi:[1,0]
	s_waitcnt vmcnt(0)
	v_mul_f32_e32 v16, 0xbfb8aa3b, v18
	v_mul_f32_e32 v38, 0xbfb8aa3b, v20
	v_exp_f32_e32 v112, v16
	v_exp_f32_e32 v113, v38
	v_mul_f32_e32 v16, 0xbfb8aa3b, v19
	global_load_dwordx4 v[38:41], v[64:65], off offset:560
	global_load_dwordx4 v[106:109], v[64:65], off offset:544
	v_exp_f32_e32 v64, v16
	v_pk_add_f32 v[112:113], v[112:113], 1.0 op_sel_hi:[1,0]
	s_nop 0
	v_div_scale_f32 v16, s[8:9], v113, v113, v20
	v_rcp_f32_e32 v65, v16
	v_div_scale_f32 v59, s[8:9], v112, v112, v18
	v_rcp_f32_e32 v116, v59
	v_fma_f32 v114, -v16, v65, 1.0
	v_div_scale_f32 v42, vcc, v20, v113, v20
	v_fmac_f32_e32 v65, v114, v65
	v_fma_f32 v115, -v59, v116, 1.0
	v_mul_f32_e32 v114, v42, v65
	v_fmac_f32_e32 v116, v115, v116
	v_fma_f32 v115, -v16, v114, v42
	v_fmac_f32_e32 v114, v115, v65
	v_fma_f32 v16, -v16, v114, v42
	v_div_fmas_f32 v16, v16, v65, v114
	v_div_scale_f32 v117, s[8:9], v18, v112, v18
	v_div_fixup_f32 v113, v16, v113, v20
	v_mul_f32_e32 v20, 0xbfb8aa3b, v21
	v_mul_f32_e32 v118, v117, v116
	v_exp_f32_e32 v65, v20
	v_fma_f32 v119, -v59, v118, v117
	v_fmac_f32_e32 v118, v119, v116
	v_fma_f32 v16, -v59, v118, v117
	s_mov_b64 vcc, s[8:9]
	v_div_fmas_f32 v16, v16, v116, v118
	v_pk_add_f32 v[64:65], v[64:65], 1.0 op_sel_hi:[1,0]
	v_div_fixup_f32 v112, v16, v112, v18
	v_mov_b32_e32 v16, v15
	v_div_scale_f32 v15, s[8:9], v65, v65, v21
	v_rcp_f32_e32 v18, v15
	v_mov_b32_e32 v114, v26
	v_mov_b32_e32 v115, v28
	v_mov_b32_e32 v28, v27
	v_fma_f32 v20, -v15, v18, 1.0
	v_fmac_f32_e32 v18, v20, v18
	v_div_scale_f32 v20, vcc, v21, v65, v21
	v_mul_f32_e32 v26, v20, v18
	v_fma_f32 v27, -v15, v26, v20
	v_fmac_f32_e32 v26, v27, v18
	v_pk_mul_f32 v[16:17], v[16:17], v[14:15] op_sel_hi:[1,0]
	v_fma_f32 v15, -v15, v26, v20
	v_div_scale_f32 v20, s[8:9], v64, v64, v19
	v_rcp_f32_e32 v27, v20
	v_div_fmas_f32 v15, v15, v18, v26
	v_div_fixup_f32 v21, v15, v65, v21
	v_pk_mul_f32 v[16:17], v[28:29], v[16:17]
	v_fma_f32 v15, -v20, v27, 1.0
	v_fmac_f32_e32 v27, v15, v27
	v_div_scale_f32 v15, vcc, v19, v64, v19
	v_mul_f32_e32 v18, v15, v27
	v_fma_f32 v26, -v20, v18, v15
	v_fmac_f32_e32 v18, v26, v27
	v_fma_f32 v15, -v20, v18, v15
	v_div_fmas_f32 v15, v15, v27, v18
	v_div_fixup_f32 v20, v15, v64, v19
	v_pk_mul_f32 v[20:21], v[20:21], v[16:17]
	global_load_dwordx4 v[16:19], v[62:63], off offset:32
	s_waitcnt lgkmcnt(0)
	v_mul_f32_e32 v15, 0xbfb8aa3b, v30
	v_exp_f32_e32 v26, v15
	v_mul_f32_e32 v15, 0xbfb8aa3b, v31
	v_exp_f32_e32 v28, v15
	v_mul_f32_e32 v15, 0xbfb8aa3b, v32
	v_exp_f32_e32 v27, v15
	v_mov_b32_e32 v62, v10
	v_mov_b32_e32 v63, v12
	v_pk_mul_f32 v[62:63], v[62:63], v[14:15] op_sel_hi:[1,0]
	v_pk_add_f32 v[26:27], v[26:27], 1.0 op_sel_hi:[1,0]
	v_mov_b32_e32 v64, v22
	v_div_scale_f32 v10, s[8:9], v27, v27, v32
	v_rcp_f32_e32 v12, v10
	v_mov_b32_e32 v65, v24
	v_pk_mul_f32 v[110:111], v[114:115], v[110:111]
	v_pk_mul_f32 v[62:63], v[62:63], v[64:65]
	v_fma_f32 v15, -v10, v12, 1.0
	v_fmac_f32_e32 v12, v15, v12
	v_div_scale_f32 v15, vcc, v32, v27, v32
	v_mul_f32_e32 v22, v15, v12
	v_fma_f32 v24, -v10, v22, v15
	v_fmac_f32_e32 v22, v24, v12
	v_fma_f32 v10, -v10, v22, v15
	v_div_scale_f32 v15, s[8:9], v26, v26, v30
	v_rcp_f32_e32 v24, v15
	v_div_fmas_f32 v10, v10, v12, v22
	v_div_fixup_f32 v27, v10, v27, v32
	v_pk_mul_f32 v[110:111], v[112:113], v[110:111]
	v_fma_f32 v10, -v15, v24, 1.0
	v_fmac_f32_e32 v24, v10, v24
	v_div_scale_f32 v10, vcc, v30, v26, v30
	v_mul_f32_e32 v12, v10, v24
	v_fma_f32 v22, -v15, v12, v10
	v_fmac_f32_e32 v12, v22, v24
	v_fma_f32 v10, -v15, v12, v10
	v_div_fmas_f32 v10, v10, v24, v12
	v_mul_f32_e32 v12, 0xbfb8aa3b, v33
	v_exp_f32_e32 v29, v12
	v_div_fixup_f32 v26, v10, v26, v30
	v_mov_b32_e32 v12, v11
	v_mov_b32_e32 v24, v23
	v_pk_add_f32 v[10:11], v[28:29], 1.0 op_sel_hi:[1,0]
	v_pk_mul_f32 v[26:27], v[62:63], v[26:27]
	v_div_scale_f32 v15, s[8:9], v11, v11, v33
	v_rcp_f32_e32 v22, v15
	v_pk_mul_f32 v[12:13], v[12:13], v[14:15] op_sel_hi:[1,0]
	v_lshlrev_b32_e32 v42, 1, v54
	v_pk_mul_f32 v[12:13], v[12:13], v[24:25]
	v_fma_f32 v23, -v15, v22, 1.0
	v_fmac_f32_e32 v22, v23, v22
	v_div_scale_f32 v23, vcc, v33, v11, v33
	v_mul_f32_e32 v24, v23, v22
	v_fma_f32 v25, -v15, v24, v23
	v_fmac_f32_e32 v24, v25, v22
	v_fma_f32 v15, -v15, v24, v23
	v_div_scale_f32 v23, s[8:9], v10, v10, v31
	v_rcp_f32_e32 v25, v23
	v_div_fmas_f32 v15, v15, v22, v24
	v_div_fixup_f32 v11, v15, v11, v33
	v_fma_f32 v15, -v23, v25, 1.0
	v_fmac_f32_e32 v25, v15, v25
	v_div_scale_f32 v15, vcc, v31, v10, v31
	v_mul_f32_e32 v22, v15, v25
	v_fma_f32 v24, -v23, v22, v15
	v_fmac_f32_e32 v22, v24, v25
	v_fma_f32 v15, -v23, v22, v15
	v_div_fmas_f32 v15, v15, v25, v22
	v_div_fixup_f32 v10, v15, v10, v31
	v_pk_mul_f32 v[10:11], v[12:13], v[10:11]
	v_cvt_pk_bf16_f32 v13, v27, v11
	v_cvt_pk_bf16_f32 v11, v111, v21
	s_waitcnt vmcnt(0)
	v_mul_f32_e32 v15, 0xbfb8aa3b, v16
	v_cvt_pk_bf16_f32 v12, v26, v10
	v_cvt_pk_bf16_f32 v10, v110, v20
	v_exp_f32_e32 v20, v15
	v_mul_f32_e32 v15, 0xbfb8aa3b, v17
	v_exp_f32_e32 v22, v15
	v_mul_f32_e32 v15, 0xbfb8aa3b, v18
	v_exp_f32_e32 v21, v15
	v_mov_b32_e32 v24, v6
	v_mov_b32_e32 v25, v8
	v_pk_mul_f32 v[24:25], v[24:25], v[14:15] op_sel_hi:[1,0]
	v_pk_add_f32 v[20:21], v[20:21], 1.0 op_sel_hi:[1,0]
	v_mov_b32_e32 v26, v106
	v_div_scale_f32 v6, s[8:9], v21, v21, v18
	v_rcp_f32_e32 v8, v6
	v_mov_b32_e32 v27, v108
	v_pk_mul_f32 v[24:25], v[24:25], v[26:27]
	v_mov_b32_e32 v108, v107
	v_fma_f32 v15, -v6, v8, 1.0
	v_fmac_f32_e32 v8, v15, v8
	v_div_scale_f32 v15, vcc, v18, v21, v18
	v_mul_f32_e32 v23, v15, v8
	v_fma_f32 v26, -v6, v23, v15
	v_fmac_f32_e32 v23, v26, v8
	v_fma_f32 v6, -v6, v23, v15
	v_div_scale_f32 v15, s[8:9], v20, v20, v16
	v_rcp_f32_e32 v26, v15
	v_div_fmas_f32 v6, v6, v8, v23
	v_div_fixup_f32 v21, v6, v21, v18
	v_fma_f32 v6, -v15, v26, 1.0
	v_fmac_f32_e32 v26, v6, v26
	v_div_scale_f32 v6, vcc, v16, v20, v16
	v_mul_f32_e32 v8, v6, v26
	v_fma_f32 v18, -v15, v8, v6
	v_fmac_f32_e32 v8, v18, v26
	v_fma_f32 v6, -v15, v8, v6
	v_div_fmas_f32 v6, v6, v26, v8
	v_mul_f32_e32 v8, 0xbfb8aa3b, v19
	v_exp_f32_e32 v23, v8
	v_div_fixup_f32 v20, v6, v20, v16
	v_mov_b32_e32 v8, v7
	v_pk_mul_f32 v[20:21], v[24:25], v[20:21]
	v_pk_add_f32 v[6:7], v[22:23], 1.0 op_sel_hi:[1,0]
	s_nop 0
	v_div_scale_f32 v15, s[8:9], v7, v7, v19
	v_rcp_f32_e32 v16, v15
	v_pk_mul_f32 v[8:9], v[8:9], v[14:15] op_sel_hi:[1,0]
	v_fma_f32 v18, -v15, v16, 1.0
	v_fmac_f32_e32 v16, v18, v16
	v_div_scale_f32 v18, vcc, v19, v7, v19
	v_mul_f32_e32 v22, v18, v16
	v_fma_f32 v23, -v15, v22, v18
	v_fmac_f32_e32 v22, v23, v16
	v_fma_f32 v15, -v15, v22, v18
	v_div_scale_f32 v18, s[8:9], v6, v6, v17
	v_rcp_f32_e32 v23, v18
	v_div_fmas_f32 v15, v15, v16, v22
	v_div_fixup_f32 v7, v15, v7, v19
	v_pk_mul_f32 v[8:9], v[8:9], v[108:109]
	v_fma_f32 v15, -v18, v23, 1.0
	v_fmac_f32_e32 v23, v15, v23
	v_div_scale_f32 v15, vcc, v17, v6, v17
	v_mul_f32_e32 v16, v15, v23
	v_fma_f32 v19, -v18, v16, v15
	v_fmac_f32_e32 v16, v19, v23
	v_fma_f32 v15, -v18, v16, v15
	v_div_fmas_f32 v15, v15, v23, v16
	v_div_fixup_f32 v6, v15, v6, v17
	v_pk_mul_f32 v[6:7], v[8:9], v[6:7]
	v_mul_f32_e32 v9, 0xbfb8aa3b, v35
	v_mul_f32_e32 v8, 0xbfb8aa3b, v34
	v_exp_f32_e32 v16, v9
	v_mul_f32_e32 v9, 0xbfb8aa3b, v36
	v_exp_f32_e32 v8, v8
	v_exp_f32_e32 v9, v9
	v_mov_b32_e32 v18, v2
	v_mov_b32_e32 v19, v4
	v_pk_mul_f32 v[18:19], v[18:19], v[14:15] op_sel_hi:[1,0]
	v_pk_add_f32 v[8:9], v[8:9], 1.0 op_sel_hi:[1,0]
	v_mov_b32_e32 v22, v38
	v_div_scale_f32 v2, s[8:9], v9, v9, v36
	v_rcp_f32_e32 v4, v2
	v_mov_b32_e32 v23, v40
	v_pk_mul_f32 v[18:19], v[18:19], v[22:23]
	v_mov_b32_e32 v40, v39
	v_fma_f32 v15, -v2, v4, 1.0
	v_fmac_f32_e32 v4, v15, v4
	v_div_scale_f32 v15, vcc, v36, v9, v36
	v_mul_f32_e32 v17, v15, v4
	v_fma_f32 v22, -v2, v17, v15
	v_fmac_f32_e32 v17, v22, v4
	v_fma_f32 v2, -v2, v17, v15
	v_div_scale_f32 v15, s[8:9], v8, v8, v34
	v_rcp_f32_e32 v22, v15
	v_div_fmas_f32 v2, v2, v4, v17
	v_div_fixup_f32 v9, v2, v9, v36
	v_fma_f32 v2, -v15, v22, 1.0
	v_fmac_f32_e32 v22, v2, v22
	v_div_scale_f32 v2, vcc, v34, v8, v34
	v_mul_f32_e32 v4, v2, v22
	v_fma_f32 v17, -v15, v4, v2
	v_fmac_f32_e32 v4, v17, v22
	v_fma_f32 v2, -v15, v4, v2
	v_div_fmas_f32 v2, v2, v22, v4
	v_mul_f32_e32 v4, 0xbfb8aa3b, v37
	v_exp_f32_e32 v17, v4
	v_div_fixup_f32 v8, v2, v8, v34
	v_mov_b32_e32 v4, v3
	v_pk_mul_f32 v[8:9], v[18:19], v[8:9]
	v_pk_add_f32 v[2:3], v[16:17], 1.0 op_sel_hi:[1,0]
	s_nop 0
	v_div_scale_f32 v15, s[8:9], v3, v3, v37
	v_rcp_f32_e32 v16, v15
	v_pk_mul_f32 v[4:5], v[4:5], v[14:15] op_sel_hi:[1,0]
	v_fma_f32 v14, -v15, v16, 1.0
	v_fmac_f32_e32 v16, v14, v16
	v_div_scale_f32 v14, vcc, v37, v3, v37
	v_mul_f32_e32 v17, v14, v16
	v_fma_f32 v18, -v15, v17, v14
	v_fmac_f32_e32 v17, v18, v16
	v_fma_f32 v14, -v15, v17, v14
	v_div_scale_f32 v15, s[8:9], v2, v2, v35
	v_rcp_f32_e32 v18, v15
	v_div_fmas_f32 v14, v14, v16, v17
	v_div_fixup_f32 v3, v14, v3, v37
	v_pk_mul_f32 v[4:5], v[4:5], v[40:41]
	v_fma_f32 v14, -v15, v18, 1.0
	v_fmac_f32_e32 v18, v14, v18
	v_div_scale_f32 v14, vcc, v35, v2, v35
	v_mul_f32_e32 v16, v14, v18
	v_fma_f32 v17, -v15, v16, v14
	v_fmac_f32_e32 v16, v17, v18
	v_fma_f32 v14, -v15, v16, v14
	v_div_fmas_f32 v14, v14, v18, v16
	v_div_fixup_f32 v2, v14, v2, v35
	v_pk_mul_f32 v[2:3], v[4:5], v[2:3]
	v_bfe_u32 v5, v2, 16, 1
	v_add3_u32 v2, v2, v5, s33
	v_bfe_u32 v14, v8, 16, 1
	v_add3_u32 v8, v8, v14, s33
	v_lshrrev_b32_e32 v4, 16, v8
	v_cvt_pk_bf16_f32 v5, v9, v3
	v_and_or_b32 v4, v2, s34, v4
	v_cvt_pk_bf16_f32 v3, v21, v7
	v_cvt_pk_bf16_f32 v2, v20, v6
	v_lshlrev_b64 v[6:7], 11, v[60:61]
	v_lshl_add_u64 v[6:7], s[68:69], 0, v[6:7]
	v_lshl_add_u64 v[6:7], v[6:7], 0, s[70:71]
	v_lshl_add_u64 v[6:7], v[6:7], 0, v[42:43]
	v_lshl_add_u64 v[8:9], v[6:7], 0, s[74:75]
	v_add_co_u32_e32 v6, vcc, 0xdc00000, v6
	s_nop 1
	v_addc_co_u32_e32 v7, vcc, 0, v7, vcc
	global_store_dwordx4 v[6:7], v[10:13], off offset:1024
	global_store_dwordx4 v[8:9], v[2:5], off offset:16
	s_branch .LBB0_5556

.LBB0_5693:
	v_lshl_add_u64 v[18:19], s[68:69], 0, v[94:95]
	v_lshl_add_u64 v[22:23], s[68:69], 0, v[92:93]
	v_add_co_u32_e32 v20, vcc, 0x7800000, v18
	v_add_co_u32_e64 v102, s[6:7], s22, v22
	s_nop 0
	v_addc_co_u32_e32 v21, vcc, 0, v19, vcc
	v_addc_co_u32_e64 v103, s[6:7], 0, v23, s[6:7]
	v_add_co_u32_e64 v104, s[6:7], s23, v22
	v_add_co_u32_e32 v22, vcc, 0x7801000, v18
	s_nop 0
	v_addc_co_u32_e64 v105, s[6:7], 0, v23, s[6:7]
	global_load_dwordx4 v[78:81], v[20:21], off
	global_load_dwordx4 v[74:77], v[20:21], off offset:1024
	global_load_dwordx4 v[70:73], v[20:21], off offset:2048
	global_load_dwordx4 v[66:69], v[20:21], off offset:3072
	v_addc_co_u32_e32 v23, vcc, 0, v19, vcc
	v_add_co_u32_e32 v20, vcc, 0x7802000, v18
	global_load_dwordx4 v[62:65], v[22:23], off
	global_load_dwordx4 v[58:61], v[22:23], off offset:1024
	global_load_dwordx4 v[54:57], v[22:23], off offset:2048
	global_load_dwordx4 v[50:53], v[22:23], off offset:3072
	v_addc_co_u32_e32 v21, vcc, 0, v19, vcc
	v_add_co_u32_e32 v82, vcc, 0x7803000, v18
	global_load_dwordx4 v[46:49], v[20:21], off
	global_load_dwordx4 v[42:45], v[20:21], off offset:1024
	global_load_dwordx4 v[38:41], v[20:21], off offset:2048
	global_load_dwordx4 v[34:37], v[20:21], off offset:3072
	v_addc_co_u32_e32 v83, vcc, 0, v19, vcc
	global_load_dwordx4 v[30:33], v[82:83], off
	global_load_dwordx4 v[26:29], v[82:83], off offset:1024
	global_load_dwordx4 v[22:25], v[82:83], off offset:2048
	global_load_dwordx4 v[18:21], v[82:83], off offset:3072
	s_add_i32 s24, s8, 32
	s_add_i32 s10, s8, 0xffffc022
	s_ashr_i32 s9, s24, 13
	s_cmpk_lt_i32 s24, 0x4000
	s_cselect_b32 s6, s9, s10
	s_addk_i32 s6, 0x82
	s_mul_hi_i32 s7, s6, 0x9000
	s_mul_i32 s6, s6, 0x9000
	s_add_u32 s10, s4, s6
	s_addc_u32 s11, s5, s7
	s_add_u32 s6, s10, 0x6000
	s_addc_u32 s7, s11, 0
	s_add_u32 s10, s10, 0x7000
	s_addc_u32 s11, s11, 0
	v_lshl_add_u64 v[82:83], s[6:7], 0, v[90:91]
	v_lshl_add_u64 v[86:87], s[10:11], 0, v[90:91]
	global_load_dwordx4 v[82:85], v[82:83], off
	v_lshl_add_u64 v[148:149], s[6:7], 0, v[96:97]
	global_load_dwordx4 v[86:89], v[86:87], off
	v_lshl_add_u64 v[142:143], s[6:7], 0, v[98:99]
	v_lshl_add_u64 v[132:133], s[6:7], 0, v[100:101]
	s_add_i32 s6, s8, 0xffffc023
	s_cmpk_lt_i32 s24, 0x3fff
	s_cselect_b32 s6, s9, s6
	s_addk_i32 s6, 0x82
	s_mul_hi_i32 s7, s6, 0x9000
	s_mul_i32 s6, s6, 0x9000
	v_lshl_add_u64 v[152:153], s[10:11], 0, v[96:97]
	v_lshl_add_u64 v[146:147], s[10:11], 0, v[98:99]
	v_lshl_add_u64 v[140:141], s[10:11], 0, v[100:101]
	s_add_u32 s10, s4, s6
	s_addc_u32 s11, s5, s7
	s_add_u32 s6, s10, 0x6000
	s_addc_u32 s7, s11, 0
	s_add_u32 s10, s10, 0x7000
	v_lshl_add_u64 v[134:135], s[6:7], 0, v[90:91]
	v_lshl_add_u64 v[126:127], s[6:7], 0, v[96:97]
	v_lshl_add_u64 v[118:119], s[6:7], 0, v[98:99]
	v_lshl_add_u64 v[114:115], s[6:7], 0, v[100:101]
	s_addc_u32 s11, s11, 0
	s_add_i32 s6, s8, 0xffffc024
	s_cmpk_lt_i32 s24, 0x3ffe
	s_cselect_b32 s6, s9, s6
	s_addk_i32 s6, 0x82
	s_mul_hi_i32 s7, s6, 0x9000
	s_mul_i32 s6, s6, 0x9000
	s_add_u32 s6, s4, s6
	s_addc_u32 s7, s5, s7
	v_lshl_add_u64 v[136:137], s[10:11], 0, v[90:91]
	v_lshl_add_u64 v[130:131], s[10:11], 0, v[96:97]
	v_lshl_add_u64 v[122:123], s[10:11], 0, v[98:99]
	v_lshl_add_u64 v[116:117], s[10:11], 0, v[100:101]
	s_add_u32 s10, s6, 0x6000
	s_addc_u32 s11, s7, 0
	s_add_u32 s6, s6, 0x7000
	s_addc_u32 s7, s7, 0
	s_addk_i32 s8, 0xc025
	s_cmpk_lt_i32 s24, 0x3ffd
	v_lshl_add_u64 v[156:157], s[6:7], 0, v[90:91]
	v_lshl_add_u64 v[154:155], s[6:7], 0, v[96:97]
	v_lshl_add_u64 v[150:151], s[6:7], 0, v[98:99]
	v_lshl_add_u64 v[138:139], s[6:7], 0, v[100:101]
	s_cselect_b32 s6, s9, s8
	s_waitcnt vmcnt(0) lgkmcnt(0)
	v_pk_mul_f32 v[158:159], v[80:81], v[80:81]
	v_pk_mul_f32 v[160:161], v[78:79], v[78:79]
	v_pk_mul_f32 v[162:163], v[76:77], v[76:77]
	v_pk_mul_f32 v[164:165], v[74:75], v[74:75]
	v_mul_f32_e32 v174, v71, v71
	v_mul_f32_e32 v176, v73, v73
	v_mul_f32_e32 v187, v68, v68
	v_mul_f32_e32 v189, v69, v69
	v_pk_mov_b32 v[178:179], v[160:161], v[158:159] op_sel:[1,0]
	v_mov_b32_e32 v161, v159
	v_pk_mov_b32 v[158:159], v[164:165], v[162:163] op_sel:[1,0]
	v_mov_b32_e32 v165, v163
	v_pk_fma_f32 v[162:163], v[70:71], v[70:71], v[174:175] op_sel_hi:[1,1,0]
	v_pk_fma_f32 v[174:175], v[72:73], v[72:73], v[176:177] op_sel_hi:[1,1,0]
	v_pk_mul_f32 v[176:177], v[64:65], v[64:65]
	v_pk_mul_f32 v[180:181], v[62:63], v[62:63]
	v_pk_mul_f32 v[182:183], v[60:61], v[60:61]
	v_pk_mul_f32 v[184:185], v[58:59], v[58:59]
	v_mul_f32_e32 v186, v55, v55
	v_mul_f32_e32 v188, v57, v57
	v_pk_add_f32 v[160:161], v[178:179], v[160:161]
	v_pk_add_f32 v[158:159], v[158:159], v[164:165]
	v_mov_b32_e32 v163, v187
	v_mov_b32_e32 v175, v189
	v_pk_mov_b32 v[164:165], v[180:181], v[176:177] op_sel:[1,0]
	v_mov_b32_e32 v181, v177
	v_pk_mov_b32 v[176:177], v[184:185], v[182:183] op_sel:[1,0]
	v_mov_b32_e32 v185, v183
	v_pk_fma_f32 v[178:179], v[54:55], v[54:55], v[186:187] op_sel_hi:[1,1,0]
	v_pk_fma_f32 v[182:183], v[56:57], v[56:57], v[188:189] op_sel_hi:[1,1,0]
	v_pk_mul_f32 v[186:187], v[48:49], v[48:49]
	v_pk_mul_f32 v[188:189], v[46:47], v[46:47]
	v_pk_mul_f32 v[190:191], v[44:45], v[44:45]
	v_pk_mul_f32 v[192:193], v[42:43], v[42:43]
	v_mul_f32_e32 v173, v66, v66
	v_mul_f32_e32 v197, v67, v67
	v_mul_f32_e32 v195, v52, v52
	v_mul_f32_e32 v202, v53, v53
	v_mul_f32_e32 v194, v39, v39
	v_mul_f32_e32 v196, v41, v41
	v_pk_add_f32 v[198:199], v[160:161], v[160:161] op_sel:[0,1] op_sel_hi:[1,0]
	v_pk_add_f32 v[200:201], v[158:159], v[158:159] op_sel:[0,1] op_sel_hi:[1,0]
	v_pk_add_f32 v[174:175], v[162:163], v[174:175]
	v_pk_add_f32 v[158:159], v[164:165], v[180:181]
	v_pk_add_f32 v[160:161], v[176:177], v[184:185]
	v_pk_mov_b32 v[162:163], v[188:189], v[186:187] op_sel:[1,0]
	v_mov_b32_e32 v189, v187
	v_pk_mov_b32 v[164:165], v[192:193], v[190:191] op_sel:[1,0]
	v_mov_b32_e32 v193, v191
	v_mul_f32_e32 v203, v50, v50
	v_mul_f32_e32 v208, v51, v51
	v_mul_f32_e32 v211, v36, v36
	v_mul_f32_e32 v212, v37, v37
	v_mov_b32_e32 v179, v195
	v_mov_b32_e32 v183, v202
	v_pk_fma_f32 v[176:177], v[38:39], v[38:39], v[194:195] op_sel_hi:[1,1,0]
	v_pk_fma_f32 v[180:181], v[40:41], v[40:41], v[196:197] op_sel_hi:[1,1,0]
	v_pk_mul_f32 v[184:185], v[32:33], v[32:33]
	v_pk_mul_f32 v[186:187], v[30:31], v[30:31]
	v_pk_mul_f32 v[190:191], v[28:29], v[28:29]
	v_pk_mul_f32 v[194:195], v[26:27], v[26:27]
	v_mov_b32_e32 v199, v173
	v_mov_b32_e32 v201, v197
	v_pk_add_f32 v[204:205], v[158:159], v[158:159] op_sel:[0,1] op_sel_hi:[1,0]
	v_pk_add_f32 v[206:207], v[160:161], v[160:161] op_sel:[0,1] op_sel_hi:[1,0]
	v_pk_add_f32 v[162:163], v[162:163], v[188:189]
	v_pk_add_f32 v[164:165], v[164:165], v[192:193]
	v_mul_f32_e32 v209, v34, v34
	v_mul_f32_e32 v210, v35, v35
	v_pk_add_f32 v[178:179], v[178:179], v[182:183]
	v_mov_b32_e32 v177, v211
	v_mov_b32_e32 v181, v212
	v_pk_mov_b32 v[182:183], v[186:187], v[184:185] op_sel:[1,0]
	v_mov_b32_e32 v187, v185
	v_pk_mov_b32 v[184:185], v[194:195], v[190:191] op_sel:[1,0]
	v_mov_b32_e32 v195, v191
	v_pk_add_f32 v[188:189], v[198:199], v[200:201]
	v_mov_b32_e32 v205, v203
	v_mov_b32_e32 v207, v208
	v_pk_add_f32 v[190:191], v[162:163], v[162:163] op_sel:[0,1] op_sel_hi:[1,0]
	v_pk_add_f32 v[192:193], v[164:165], v[164:165] op_sel:[0,1] op_sel_hi:[1,0]
	v_pk_add_f32 v[176:177], v[176:177], v[180:181]
	v_pk_add_f32 v[174:175], v[188:189], v[174:175]
	v_pk_add_f32 v[180:181], v[204:205], v[206:207]
	v_mov_b32_e32 v191, v209
	v_mov_b32_e32 v193, v210
	v_add_f32_e32 v173, v174, v175
	v_pk_add_f32 v[174:175], v[180:181], v[178:179]
	v_pk_add_f32 v[178:179], v[190:191], v[192:193]
	v_add_f32_e32 v180, v174, v175
	v_pk_add_f32 v[174:175], v[178:179], v[176:177]
	v_add_f32_e32 v174, v174, v175
	s_addk_i32 s6, 0x82
	s_waitcnt lgkmcnt(0)
	s_nop 1
	v_add_f32_dpp v173, v173, v173 quad_perm:[1,0,3,2] row_mask:0xf bank_mask:0xf
	s_waitcnt lgkmcnt(0)
	s_nop 1
	v_add_f32_dpp v175, v180, v180 quad_perm:[1,0,3,2] row_mask:0xf bank_mask:0xf
	s_waitcnt lgkmcnt(0)
	s_nop 1
	v_add_f32_dpp v174, v174, v174 quad_perm:[1,0,3,2] row_mask:0xf bank_mask:0xf
	s_waitcnt lgkmcnt(0)
	s_nop 1
	v_add_f32_dpp v173, v173, v173 quad_perm:[2,3,0,1] row_mask:0xf bank_mask:0xf
	s_waitcnt lgkmcnt(0)
	s_nop 1
	v_add_f32_dpp v175, v175, v175 quad_perm:[2,3,0,1] row_mask:0xf bank_mask:0xf
	s_waitcnt lgkmcnt(0)
	s_nop 1
	v_add_f32_dpp v174, v174, v174 quad_perm:[2,3,0,1] row_mask:0xf bank_mask:0xf
	s_waitcnt lgkmcnt(0)
	s_nop 1
	v_add_f32_dpp v173, v173, v173 row_half_mirror row_mask:0xf bank_mask:0xf
	s_waitcnt lgkmcnt(0)
	s_nop 1
	v_add_f32_dpp v175, v175, v175 row_half_mirror row_mask:0xf bank_mask:0xf
	s_waitcnt lgkmcnt(0)
	s_nop 1
	v_add_f32_dpp v174, v174, v174 row_half_mirror row_mask:0xf bank_mask:0xf
	s_waitcnt lgkmcnt(0)
	s_nop 1
	v_add_f32_dpp v173, v173, v173 row_mirror row_mask:0xf bank_mask:0xf
	ds_bpermute_b32 v176, v169, v173
	s_waitcnt lgkmcnt(2)
	s_nop 1
	v_add_f32_dpp v175, v175, v175 row_mirror row_mask:0xf bank_mask:0xf
	ds_bpermute_b32 v178, v169, v175
	s_waitcnt lgkmcnt(2)
	s_nop 1
	v_add_f32_dpp v174, v174, v174 row_mirror row_mask:0xf bank_mask:0xf
	ds_bpermute_b32 v177, v169, v174
	s_waitcnt lgkmcnt(2)
	v_add_f32_e32 v173, v173, v176
	ds_bpermute_b32 v176, v170, v173
	s_waitcnt lgkmcnt(2)
	v_add_f32_e32 v175, v175, v178
	ds_bpermute_b32 v178, v170, v175
	s_mul_hi_i32 s7, s6, 0x9000
	s_mul_i32 s6, s6, 0x9000
	s_waitcnt lgkmcnt(2)
	v_add_f32_e32 v174, v174, v177
	s_add_u32 s6, s4, s6
	ds_bpermute_b32 v177, v170, v174
	s_addc_u32 s7, s5, s7
	s_waitcnt lgkmcnt(2)
	v_add_f32_e32 v173, v173, v176
	s_add_u32 s16, s6, 0x6000
	v_fmamk_f32 v173, v173, 0x3a800000, v171
	s_addc_u32 s17, s7, 0
	s_waitcnt lgkmcnt(1)
	v_add_f32_e32 v175, v175, v178
	v_mul_f32_e32 v176, 0x4f800000, v173
	v_cmp_gt_f32_e32 vcc, s2, v173
	s_add_u32 s18, s6, 0x7000
	v_fmamk_f32 v175, v175, 0x3a800000, v171
	v_cndmask_b32_e32 v173, v173, v176, vcc
	s_addc_u32 s19, s7, 0
	s_waitcnt lgkmcnt(0)
	v_add_f32_e32 v174, v174, v177
	v_mul_f32_e32 v176, 0x4f800000, v175
	v_cmp_gt_f32_e64 s[6:7], s2, v175
	v_sqrt_f32_e32 v177, v173
	v_fmamk_f32 v174, v174, 0x3a800000, v171
	v_cndmask_b32_e64 v175, v175, v176, s[6:7]
	v_mul_f32_e32 v176, 0x4f800000, v174
	v_cmp_gt_f32_e64 s[8:9], s2, v174
	v_sqrt_f32_e32 v178, v175
	v_add_u32_e32 v179, -1, v177
	v_cndmask_b32_e64 v174, v174, v176, s[8:9]
	v_sqrt_f32_e32 v176, v174
	v_add_u32_e32 v180, 1, v177
	v_fma_f32 v181, -v179, v177, v173
	v_lshl_add_u64 v[112:113], s[10:11], 0, v[90:91]
	v_lshl_add_u64 v[106:107], s[10:11], 0, v[96:97]
	v_lshl_add_u64 v[110:111], s[10:11], 0, v[98:99]
	v_lshl_add_u64 v[108:109], s[10:11], 0, v[100:101]
	v_pk_add_f32 v[162:163], v[182:183], v[186:187]
	v_fma_f32 v182, -v180, v177, v173
	v_add_u32_e32 v183, -1, v178
	v_cmp_ge_f32_e64 s[10:11], 0, v181
	v_pk_add_f32 v[164:165], v[184:185], v[194:195]
	v_add_u32_e32 v184, 1, v178
	v_cndmask_b32_e64 v177, v177, v179, s[10:11]
	v_fma_f32 v179, -v183, v178, v175
	v_cmp_lt_f32_e64 s[10:11], 0, v182
	v_fma_f32 v181, -v184, v178, v175
	v_add_u32_e32 v185, -1, v176
	v_cndmask_b32_e64 v177, v177, v180, s[10:11]
	v_cmp_ge_f32_e64 s[10:11], 0, v179
	v_add_u32_e32 v186, 1, v176
	v_fma_f32 v179, -v185, v176, v174
	v_cndmask_b32_e64 v178, v178, v183, s[10:11]
	v_cmp_lt_f32_e64 s[10:11], 0, v181
	v_fma_f32 v180, -v186, v176, v174
	v_mul_f32_e32 v181, 0x37800000, v177
	v_cndmask_b32_e64 v178, v178, v184, s[10:11]
	v_cmp_ge_f32_e64 s[10:11], 0, v179
	v_cndmask_b32_e32 v177, v177, v181, vcc
	v_cmp_class_f32_e32 vcc, v173, v172
	v_cndmask_b32_e64 v176, v176, v185, s[10:11]
	v_cmp_lt_f32_e64 s[10:11], 0, v180
	v_mul_f32_e32 v179, 0x37800000, v178
	v_cndmask_b32_e32 v173, v177, v173, vcc
	v_cndmask_b32_e64 v176, v176, v186, s[10:11]
	v_cndmask_b32_e64 v177, v178, v179, s[6:7]
	v_cmp_class_f32_e32 vcc, v175, v172
	v_mul_f32_e32 v178, 0x37800000, v176
	v_div_scale_f32 v179, s[6:7], v173, v173, 1.0
	v_cndmask_b32_e32 v175, v177, v175, vcc
	v_cndmask_b32_e64 v176, v176, v178, s[8:9]
	v_cmp_class_f32_e32 vcc, v174, v172
	v_rcp_f32_e32 v177, v179
	v_div_scale_f32 v178, s[8:9], v175, v175, 1.0
	v_cndmask_b32_e32 v176, v176, v174, vcc
	v_rcp_f32_e32 v182, v178
	v_div_scale_f32 v183, s[10:11], v176, v176, 1.0
	v_rcp_f32_e32 v185, v183
	v_fma_f32 v174, -v179, v177, 1.0
	v_div_scale_f32 v180, s[6:7], 1.0, v173, 1.0
	v_fmac_f32_e32 v177, v174, v177
	v_fma_f32 v174, -v178, v182, 1.0
	v_mul_f32_e32 v186, v180, v177
	v_div_scale_f32 v181, s[8:9], 1.0, v175, 1.0
	v_fmac_f32_e32 v182, v174, v182
	v_fma_f32 v174, -v183, v185, 1.0
	v_fma_f32 v187, -v179, v186, v180
	v_div_scale_f32 v184, s[10:11], 1.0, v176, 1.0
	v_mul_f32_e32 v188, v181, v182
	v_fmac_f32_e32 v185, v174, v185
	v_fmac_f32_e32 v186, v187, v177
	v_fma_f32 v174, -v178, v188, v181
	v_mul_f32_e32 v187, v184, v185
	v_fma_f32 v179, -v179, v186, v180
	s_mov_b64 vcc, s[6:7]
	v_fmac_f32_e32 v188, v174, v182
	v_fma_f32 v174, -v183, v187, v184
	v_div_fmas_f32 v177, v179, v177, v186
	v_fma_f32 v178, -v178, v188, v181
	v_fmac_f32_e32 v187, v174, v185
	v_div_fixup_f32 v174, v177, v173, 1.0
	s_mov_b64 vcc, s[8:9]
	v_div_fmas_f32 v173, v178, v182, v188
	v_fma_f32 v177, -v183, v187, v184
	v_pk_mul_f32 v[80:81], v[80:81], v[174:175] op_sel_hi:[1,0]
	v_pk_mul_f32 v[78:79], v[78:79], v[174:175] op_sel_hi:[1,0]
	s_mov_b64 vcc, s[10:11]
	v_pk_add_f32 v[88:89], v[88:89], 1.0 op_sel_hi:[1,0]
	v_pk_add_f32 v[86:87], v[86:87], 1.0 op_sel_hi:[1,0]
	v_pk_mul_f32 v[76:77], v[76:77], v[174:175] op_sel_hi:[1,0]
	v_pk_mul_f32 v[74:75], v[74:75], v[174:175] op_sel_hi:[1,0]
	v_pk_mul_f32 v[72:73], v[72:73], v[174:175] op_sel_hi:[1,0]
	v_pk_mul_f32 v[70:71], v[70:71], v[174:175] op_sel_hi:[1,0]
	v_pk_mul_f32 v[68:69], v[68:69], v[174:175] op_sel_hi:[1,0]
	v_pk_mul_f32 v[66:67], v[66:67], v[174:175] op_sel_hi:[1,0]
	v_div_fixup_f32 v174, v173, v175, 1.0
	v_div_fmas_f32 v173, v177, v185, v187
	v_pk_mul_f32 v[78:79], v[2:3], v[78:79]
	v_pk_mul_f32 v[80:81], v[4:5], v[80:81]
	v_pk_mul_f32 v[64:65], v[64:65], v[174:175] op_sel_hi:[1,0]
	v_pk_mul_f32 v[62:63], v[62:63], v[174:175] op_sel_hi:[1,0]
	v_pk_mul_f32 v[60:61], v[60:61], v[174:175] op_sel_hi:[1,0]
	v_pk_mul_f32 v[58:59], v[58:59], v[174:175] op_sel_hi:[1,0]
	v_pk_mul_f32 v[56:57], v[56:57], v[174:175] op_sel_hi:[1,0]
	v_pk_mul_f32 v[54:55], v[54:55], v[174:175] op_sel_hi:[1,0]
	v_pk_mul_f32 v[52:53], v[52:53], v[174:175] op_sel_hi:[1,0]
	v_pk_mul_f32 v[174:175], v[50:51], v[174:175] op_sel_hi:[1,0]
	v_div_fixup_f32 v50, v173, v176, 1.0
	v_pk_fma_f32 v[80:81], v[88:89], v[80:81], v[84:85]
	v_pk_fma_f32 v[78:79], v[86:87], v[78:79], v[82:83]
	v_pk_mul_f32 v[86:87], v[16:17], v[52:53]
	v_pk_mul_f32 v[48:49], v[48:49], v[50:51] op_sel_hi:[1,0]
	v_pk_mul_f32 v[46:47], v[46:47], v[50:51] op_sel_hi:[1,0]
	v_pk_mul_f32 v[82:83], v[10:11], v[54:55]
	v_pk_mul_f32 v[84:85], v[14:15], v[174:175]
	v_pk_mul_f32 v[88:89], v[2:3], v[46:47]
	v_pk_mul_f32 v[174:175], v[4:5], v[48:49]
	v_cvt_pk_bf16_f32 v46, v78, v79
	v_cvt_pk_bf16_f32 v47, v80, v81
	global_store_dwordx2 v[102:103], v[46:47], off
	global_load_dwordx4 v[46:49], v[152:153], off
	s_nop 0
	global_load_dwordx4 v[52:55], v[148:149], off
	v_pk_mul_f32 v[74:75], v[6:7], v[74:75]
	v_pk_mul_f32 v[76:77], v[8:9], v[76:77]
	v_pk_mul_f32 v[70:71], v[10:11], v[70:71]
	v_pk_mul_f32 v[72:73], v[12:13], v[72:73]
	v_pk_mul_f32 v[66:67], v[66:67], v[14:15]
	v_pk_mul_f32 v[68:69], v[68:69], v[16:17]
	v_pk_mul_f32 v[62:63], v[2:3], v[62:63]
	v_pk_mul_f32 v[64:65], v[4:5], v[64:65]
	v_pk_mul_f32 v[58:59], v[6:7], v[58:59]
	v_pk_mul_f32 v[60:61], v[8:9], v[60:61]
	v_pk_mul_f32 v[56:57], v[12:13], v[56:57]
	v_mul_f32_e32 v196, v23, v23
	v_mul_f32_e32 v202, v25, v25
	v_mul_f32_e32 v213, v18, v18
	v_mul_f32_e32 v214, v19, v19
	v_mul_f32_e32 v215, v20, v20
	v_mul_f32_e32 v216, v21, v21
	v_pk_fma_f32 v[158:159], v[22:23], v[22:23], v[196:197] op_sel_hi:[1,1,0]
	v_pk_fma_f32 v[160:161], v[24:25], v[24:25], v[202:203] op_sel_hi:[1,1,0]
	v_mov_b32_e32 v159, v215
	v_mov_b32_e32 v161, v216
	v_lshl_add_u64 v[144:145], s[18:19], 0, v[90:91]
	v_lshl_add_u64 v[128:129], s[16:17], 0, v[90:91]
	v_lshl_add_u64 v[124:125], s[18:19], 0, v[96:97]
	v_lshl_add_u64 v[120:121], s[16:17], 0, v[96:97]
	v_lshl_add_u64 v[92:93], v[92:93], 0, s[12:13]
	v_lshl_add_u64 v[94:95], v[94:95], 0, s[14:15]
	s_mov_b32 s8, s24
	s_cmp_lt_i32 s24, s20
	s_waitcnt vmcnt(0) lgkmcnt(0)
	v_pk_add_f32 v[48:49], v[48:49], 1.0 op_sel_hi:[1,0]
	v_pk_add_f32 v[46:47], v[46:47], 1.0 op_sel_hi:[1,0]
	v_pk_fma_f32 v[48:49], v[48:49], v[76:77], v[54:55]
	v_pk_fma_f32 v[46:47], v[46:47], v[74:75], v[52:53]
	v_cvt_pk_bf16_f32 v46, v46, v47
	v_cvt_pk_bf16_f32 v47, v48, v49
	global_store_dwordx2 v[102:103], v[46:47], off offset:512
	global_load_dwordx4 v[46:49], v[146:147], off
	s_nop 0
	global_load_dwordx4 v[52:55], v[142:143], off
	s_waitcnt vmcnt(0) lgkmcnt(0)
	v_pk_add_f32 v[48:49], v[48:49], 1.0 op_sel_hi:[1,0]
	v_pk_add_f32 v[46:47], v[46:47], 1.0 op_sel_hi:[1,0]
	v_pk_fma_f32 v[48:49], v[72:73], v[48:49], v[54:55]
	v_pk_fma_f32 v[46:47], v[70:71], v[46:47], v[52:53]
	v_cvt_pk_bf16_f32 v46, v46, v47
	v_cvt_pk_bf16_f32 v47, v48, v49
	global_store_dwordx2 v[102:103], v[46:47], off offset:1024
	global_load_dwordx4 v[46:49], v[140:141], off
	s_nop 0
	global_load_dwordx4 v[52:55], v[132:133], off
	s_waitcnt vmcnt(0) lgkmcnt(0)
	v_pk_add_f32 v[48:49], v[48:49], 1.0 op_sel_hi:[1,0]
	v_pk_add_f32 v[46:47], v[46:47], 1.0 op_sel_hi:[1,0]
	v_pk_fma_f32 v[48:49], v[68:69], v[48:49], v[54:55]
	v_pk_fma_f32 v[46:47], v[66:67], v[46:47], v[52:53]
	v_cvt_pk_bf16_f32 v46, v46, v47
	v_cvt_pk_bf16_f32 v47, v48, v49
	global_store_dwordx2 v[102:103], v[46:47], off offset:1536
	global_load_dwordx4 v[46:49], v[136:137], off
	s_nop 0
	global_load_dwordx4 v[52:55], v[134:135], off
	s_waitcnt vmcnt(0) lgkmcnt(0)
	v_pk_add_f32 v[48:49], v[48:49], 1.0 op_sel_hi:[1,0]
	v_pk_add_f32 v[46:47], v[46:47], 1.0 op_sel_hi:[1,0]
	v_pk_fma_f32 v[48:49], v[48:49], v[64:65], v[54:55]
	v_pk_fma_f32 v[46:47], v[46:47], v[62:63], v[52:53]
	v_cvt_pk_bf16_f32 v46, v46, v47
	v_cvt_pk_bf16_f32 v47, v48, v49
	global_store_dwordx2 v[102:103], v[46:47], off offset:2048
	global_load_dwordx4 v[46:49], v[130:131], off
	s_nop 0
	global_load_dwordx4 v[52:55], v[126:127], off
	s_waitcnt vmcnt(0) lgkmcnt(0)
	v_pk_add_f32 v[48:49], v[48:49], 1.0 op_sel_hi:[1,0]
	v_pk_add_f32 v[46:47], v[46:47], 1.0 op_sel_hi:[1,0]
	v_pk_fma_f32 v[48:49], v[48:49], v[60:61], v[54:55]
	v_pk_fma_f32 v[46:47], v[46:47], v[58:59], v[52:53]
	v_cvt_pk_bf16_f32 v46, v46, v47
	v_cvt_pk_bf16_f32 v47, v48, v49
	global_store_dwordx2 v[102:103], v[46:47], off offset:2560
	global_load_dwordx4 v[46:49], v[122:123], off
	s_nop 0
	global_load_dwordx4 v[52:55], v[118:119], off
	v_pk_add_f32 v[58:59], v[164:165], v[164:165] op_sel:[0,1] op_sel_hi:[1,0]
	v_pk_add_f32 v[60:61], v[158:159], v[160:161]
	v_mov_b32_e32 v59, v214
	s_waitcnt vmcnt(0) lgkmcnt(0)
	v_pk_add_f32 v[48:49], v[48:49], 1.0 op_sel_hi:[1,0]
	v_pk_add_f32 v[46:47], v[46:47], 1.0 op_sel_hi:[1,0]
	v_pk_fma_f32 v[48:49], v[48:49], v[56:57], v[54:55]
	v_pk_fma_f32 v[46:47], v[46:47], v[82:83], v[52:53]
	v_cvt_pk_bf16_f32 v46, v46, v47
	v_cvt_pk_bf16_f32 v47, v48, v49
	global_store_dwordx2 v[102:103], v[46:47], off offset:3072
	global_load_dwordx4 v[46:49], v[116:117], off
	s_nop 0
	global_load_dwordx4 v[52:55], v[114:115], off
	v_pk_add_f32 v[56:57], v[162:163], v[162:163] op_sel:[0,1] op_sel_hi:[1,0]
	s_waitcnt vmcnt(0) lgkmcnt(0)
	v_pk_add_f32 v[48:49], v[48:49], 1.0 op_sel_hi:[1,0]
	v_pk_add_f32 v[46:47], v[46:47], 1.0 op_sel_hi:[1,0]
	v_pk_fma_f32 v[48:49], v[86:87], v[48:49], v[54:55]
	v_pk_fma_f32 v[46:47], v[84:85], v[46:47], v[52:53]
	v_cvt_pk_bf16_f32 v46, v46, v47
	v_cvt_pk_bf16_f32 v47, v48, v49
	global_store_dwordx2 v[102:103], v[46:47], off offset:3584
	global_load_dwordx4 v[46:49], v[156:157], off
	s_nop 0
	global_load_dwordx4 v[52:55], v[112:113], off
	v_mov_b32_e32 v57, v213
	s_waitcnt vmcnt(0) lgkmcnt(0)
	v_pk_add_f32 v[48:49], v[48:49], 1.0 op_sel_hi:[1,0]
	v_pk_add_f32 v[46:47], v[46:47], 1.0 op_sel_hi:[1,0]
	v_pk_fma_f32 v[48:49], v[48:49], v[174:175], v[54:55]
	v_pk_fma_f32 v[46:47], v[46:47], v[88:89], v[52:53]
	v_bfe_u32 v51, v46, 16, 1
	v_bfe_u32 v52, v47, 16, 1
	v_add3_u32 v46, v46, v51, s3
	v_add3_u32 v47, v47, v52, s3
	v_lshrrev_b32_e32 v46, 16, v46
	v_and_or_b32 v46, v47, s21, v46
	v_cvt_pk_bf16_f32 v47, v48, v49
	global_store_dwordx2 v[104:105], v[46:47], off
	global_load_dwordx4 v[46:49], v[154:155], off
	s_nop 0
	global_load_dwordx4 v[52:55], v[106:107], off
	v_pk_mul_f32 v[44:45], v[44:45], v[50:51] op_sel_hi:[1,0]
	v_pk_mul_f32 v[42:43], v[42:43], v[50:51] op_sel_hi:[1,0]
	v_pk_mul_f32 v[44:45], v[8:9], v[44:45]
	v_pk_mul_f32 v[42:43], v[6:7], v[42:43]
	s_waitcnt vmcnt(0) lgkmcnt(0)
	v_pk_add_f32 v[48:49], v[48:49], 1.0 op_sel_hi:[1,0]
	v_pk_add_f32 v[46:47], v[46:47], 1.0 op_sel_hi:[1,0]
	v_pk_fma_f32 v[44:45], v[48:49], v[44:45], v[54:55]
	v_pk_fma_f32 v[42:43], v[46:47], v[42:43], v[52:53]
	v_cvt_pk_bf16_f32 v42, v42, v43
	v_cvt_pk_bf16_f32 v43, v44, v45
	global_store_dwordx2 v[104:105], v[42:43], off offset:512
	global_load_dwordx4 v[42:45], v[150:151], off
	s_nop 0
	global_load_dwordx4 v[46:49], v[110:111], off
	v_pk_add_f32 v[52:53], v[56:57], v[58:59]
	s_waitcnt vmcnt(0) lgkmcnt(0)
	v_pk_add_f32 v[44:45], v[44:45], 1.0 op_sel_hi:[1,0]
	v_pk_add_f32 v[52:53], v[52:53], v[60:61]
	v_pk_add_f32 v[42:43], v[42:43], 1.0 op_sel_hi:[1,0]
	v_add_f32_e32 v51, v52, v53
	s_waitcnt lgkmcnt(0)
	s_nop 1
	v_add_f32_dpp v51, v51, v51 quad_perm:[1,0,3,2] row_mask:0xf bank_mask:0xf
	ds_bpermute_b32 v52, v166, v51
	s_waitcnt lgkmcnt(0)
	v_add_f32_e32 v51, v51, v52
	v_pk_mul_f32 v[40:41], v[40:41], v[50:51] op_sel_hi:[1,0]
	v_pk_mul_f32 v[38:39], v[38:39], v[50:51] op_sel_hi:[1,0]
	v_pk_mul_f32 v[40:41], v[12:13], v[40:41]
	v_pk_mul_f32 v[38:39], v[10:11], v[38:39]
	v_pk_fma_f32 v[40:41], v[44:45], v[40:41], v[48:49]
	v_pk_fma_f32 v[38:39], v[42:43], v[38:39], v[46:47]
	v_cvt_pk_bf16_f32 v38, v38, v39
	v_cvt_pk_bf16_f32 v39, v40, v41
	global_store_dwordx2 v[104:105], v[38:39], off offset:1024
	global_load_dwordx4 v[38:41], v[138:139], off
	s_nop 0
	global_load_dwordx4 v[42:45], v[108:109], off
	v_pk_mul_f32 v[36:37], v[36:37], v[50:51] op_sel_hi:[1,0]
	v_pk_mul_f32 v[34:35], v[34:35], v[50:51] op_sel_hi:[1,0]
	v_pk_mul_f32 v[36:37], v[16:17], v[36:37]
	v_pk_mul_f32 v[34:35], v[14:15], v[34:35]
	ds_bpermute_b32 v46, v167, v51
	s_waitcnt lgkmcnt(0)
	v_add_f32_e32 v46, v51, v46
	ds_bpermute_b32 v47, v168, v46
	s_waitcnt lgkmcnt(0)
	v_add_f32_e32 v46, v46, v47
	ds_bpermute_b32 v47, v169, v46
	s_waitcnt lgkmcnt(0)
	v_add_f32_e32 v46, v46, v47
	ds_bpermute_b32 v47, v170, v46
	s_waitcnt lgkmcnt(0)
	v_add_f32_e32 v46, v46, v47
	v_fmamk_f32 v46, v46, 0x3a800000, v171
	v_mul_f32_e32 v47, 0x4f800000, v46
	v_cmp_gt_f32_e32 vcc, s2, v46
	s_waitcnt vmcnt(0)
	v_pk_add_f32 v[40:41], v[40:41], 1.0 op_sel_hi:[1,0]
	v_pk_add_f32 v[38:39], v[38:39], 1.0 op_sel_hi:[1,0]
	v_pk_fma_f32 v[36:37], v[36:37], v[40:41], v[44:45]
	v_pk_fma_f32 v[34:35], v[34:35], v[38:39], v[42:43]
	v_cvt_pk_bf16_f32 v34, v34, v35
	v_cvt_pk_bf16_f32 v35, v36, v37
	global_store_dwordx2 v[104:105], v[34:35], off offset:1536
	global_load_dwordx4 v[34:37], v[144:145], off
	s_nop 0
	global_load_dwordx4 v[38:41], v[128:129], off
	v_cndmask_b32_e32 v42, v46, v47, vcc
	v_sqrt_f32_e32 v43, v42
	s_waitcnt vmcnt(0) lgkmcnt(0)
	v_pk_add_f32 v[36:37], v[36:37], 1.0 op_sel_hi:[1,0]
	v_add_u32_e32 v44, -1, v43
	v_add_u32_e32 v45, 1, v43
	v_fma_f32 v46, -v44, v43, v42
	v_fma_f32 v47, -v45, v43, v42
	v_cmp_ge_f32_e64 s[6:7], 0, v46
	v_pk_add_f32 v[34:35], v[34:35], 1.0 op_sel_hi:[1,0]
	s_nop 0
	v_cndmask_b32_e64 v43, v43, v44, s[6:7]
	v_cmp_lt_f32_e64 s[6:7], 0, v47
	s_nop 1
	v_cndmask_b32_e64 v43, v43, v45, s[6:7]
	v_mul_f32_e32 v44, 0x37800000, v43
	v_cndmask_b32_e32 v43, v43, v44, vcc
	v_cmp_class_f32_e32 vcc, v42, v172
	s_nop 1
	v_cndmask_b32_e32 v42, v43, v42, vcc
	v_div_scale_f32 v43, s[6:7], v42, v42, 1.0
	v_rcp_f32_e32 v45, v43
	v_div_scale_f32 v44, vcc, 1.0, v42, 1.0
	v_fma_f32 v46, -v43, v45, 1.0
	v_fmac_f32_e32 v45, v46, v45
	v_mul_f32_e32 v46, v44, v45
	v_fma_f32 v47, -v43, v46, v44
	v_fmac_f32_e32 v46, v47, v45
	v_fma_f32 v43, -v43, v46, v44
	v_div_fmas_f32 v43, v43, v45, v46
	v_div_fixup_f32 v42, v43, v42, 1.0
	v_pk_mul_f32 v[32:33], v[32:33], v[42:43] op_sel_hi:[1,0]
	v_pk_mul_f32 v[30:31], v[30:31], v[42:43] op_sel_hi:[1,0]
	v_pk_mul_f32 v[32:33], v[4:5], v[32:33]
	v_pk_mul_f32 v[30:31], v[2:3], v[30:31]
	v_pk_fma_f32 v[32:33], v[36:37], v[32:33], v[40:41]
	v_pk_fma_f32 v[30:31], v[34:35], v[30:31], v[38:39]
	v_cvt_pk_bf16_f32 v30, v30, v31
	v_cvt_pk_bf16_f32 v31, v32, v33
	global_store_dwordx2 v[104:105], v[30:31], off offset:2048
	global_load_dwordx4 v[30:33], v[124:125], off
	s_nop 0
	global_load_dwordx4 v[34:37], v[120:121], off
	v_pk_mul_f32 v[28:29], v[28:29], v[42:43] op_sel_hi:[1,0]
	v_pk_mul_f32 v[26:27], v[26:27], v[42:43] op_sel_hi:[1,0]
	v_pk_mul_f32 v[28:29], v[8:9], v[28:29]
	v_pk_mul_f32 v[26:27], v[6:7], v[26:27]
	v_lshl_add_u64 v[40:41], s[18:19], 0, v[98:99]
	v_lshl_add_u64 v[38:39], s[16:17], 0, v[98:99]
	v_pk_mul_f32 v[24:25], v[24:25], v[42:43] op_sel_hi:[1,0]
	v_pk_mul_f32 v[22:23], v[22:23], v[42:43] op_sel_hi:[1,0]
	v_pk_mul_f32 v[24:25], v[12:13], v[24:25]
	v_pk_mul_f32 v[22:23], v[10:11], v[22:23]
	v_pk_mul_f32 v[20:21], v[20:21], v[42:43] op_sel_hi:[1,0]
	v_pk_mul_f32 v[18:19], v[18:19], v[42:43] op_sel_hi:[1,0]
	v_pk_mul_f32 v[20:21], v[16:17], v[20:21]
	v_pk_mul_f32 v[18:19], v[14:15], v[18:19]
	s_waitcnt vmcnt(0) lgkmcnt(0)
	v_pk_add_f32 v[32:33], v[32:33], 1.0 op_sel_hi:[1,0]
	v_pk_add_f32 v[30:31], v[30:31], 1.0 op_sel_hi:[1,0]
	v_pk_fma_f32 v[28:29], v[32:33], v[28:29], v[36:37]
	v_pk_fma_f32 v[26:27], v[30:31], v[26:27], v[34:35]
	v_cvt_pk_bf16_f32 v26, v26, v27
	v_cvt_pk_bf16_f32 v27, v28, v29
	global_store_dwordx2 v[104:105], v[26:27], off offset:2560
	global_load_dwordx4 v[26:29], v[40:41], off
	s_nop 0
	global_load_dwordx4 v[30:33], v[38:39], off
	v_lshl_add_u64 v[36:37], s[18:19], 0, v[100:101]
	v_lshl_add_u64 v[34:35], s[16:17], 0, v[100:101]
	s_waitcnt vmcnt(0) lgkmcnt(0)
	v_pk_add_f32 v[28:29], v[28:29], 1.0 op_sel_hi:[1,0]
	v_pk_add_f32 v[26:27], v[26:27], 1.0 op_sel_hi:[1,0]
	v_pk_fma_f32 v[24:25], v[28:29], v[24:25], v[32:33]
	v_pk_fma_f32 v[22:23], v[26:27], v[22:23], v[30:31]
	v_cvt_pk_bf16_f32 v22, v22, v23
	v_cvt_pk_bf16_f32 v23, v24, v25
	global_store_dwordx2 v[104:105], v[22:23], off offset:3072
	global_load_dwordx4 v[22:25], v[36:37], off
	s_nop 0
	global_load_dwordx4 v[26:29], v[34:35], off
	s_waitcnt vmcnt(0) lgkmcnt(0)
	v_pk_add_f32 v[24:25], v[24:25], 1.0 op_sel_hi:[1,0]
	v_pk_add_f32 v[22:23], v[22:23], 1.0 op_sel_hi:[1,0]
	v_pk_fma_f32 v[20:21], v[20:21], v[24:25], v[28:29]
	v_pk_fma_f32 v[18:19], v[18:19], v[22:23], v[26:27]
	v_cvt_pk_bf16_f32 v18, v18, v19
	v_cvt_pk_bf16_f32 v19, v20, v21
	global_store_dwordx2 v[104:105], v[18:19], off offset:3584
	s_cbranch_scc1 .LBB0_5693

.LBB0_5801:
	v_lshl_add_u64 v[18:19], v[84:85], 0, s[24:25]
	v_add_co_u32_e32 v20, vcc, 0x7800000, v18
	s_add_u32 s6, s38, s24
	s_nop 0
	v_addc_co_u32_e32 v21, vcc, 0, v19, vcc
	v_add_co_u32_e32 v22, vcc, 0x7801000, v18
	global_load_dwordx4 v[78:81], v[20:21], off
	global_load_dwordx4 v[70:73], v[20:21], off offset:1024
	global_load_dwordx4 v[66:69], v[20:21], off offset:3072
	global_load_dwordx4 v[74:77], v[20:21], off offset:2048
	v_addc_co_u32_e32 v23, vcc, 0, v19, vcc
	v_add_co_u32_e32 v20, vcc, 0x7802000, v18
	global_load_dwordx4 v[62:65], v[22:23], off
	global_load_dwordx4 v[54:57], v[22:23], off offset:1024
	global_load_dwordx4 v[50:53], v[22:23], off offset:3072
	global_load_dwordx4 v[58:61], v[22:23], off offset:2048
	v_addc_co_u32_e32 v21, vcc, 0, v19, vcc
	v_add_co_u32_e32 v86, vcc, 0x7803000, v18
	global_load_dwordx4 v[46:49], v[20:21], off
	global_load_dwordx4 v[42:45], v[20:21], off offset:1024
	global_load_dwordx4 v[38:41], v[20:21], off offset:2048
	global_load_dwordx4 v[34:37], v[20:21], off offset:3072
	v_addc_co_u32_e32 v87, vcc, 0, v19, vcc
	global_load_dwordx4 v[30:33], v[86:87], off
	global_load_dwordx4 v[26:29], v[86:87], off offset:1024
	global_load_dwordx4 v[22:25], v[86:87], off offset:2048
	global_load_dwordx4 v[18:21], v[86:87], off offset:3072
	s_addc_u32 s7, s39, s25
	s_add_i32 s22, s20, 0xffffc000
	s_lshl_b64 s[8:9], s[22:23], 12
	s_add_u32 s8, s28, s8
	s_addc_u32 s9, s29, s9
	s_cmpk_lt_i32 s20, 0x4000
	s_cselect_b32 s9, s7, s9
	s_cselect_b32 s8, s6, s8
	s_add_u32 s10, s6, 0x1000
	s_addc_u32 s11, s7, 0
	s_add_i32 s22, s20, 0xffffc001
	v_lshl_add_u64 v[92:93], s[8:9], 0, v[82:83]
	s_lshl_b64 s[8:9], s[22:23], 12
	s_add_u32 s8, s28, s8
	s_addc_u32 s9, s29, s9
	s_cmpk_lt_i32 s20, 0x3fff
	s_cselect_b32 s9, s11, s9
	s_cselect_b32 s8, s10, s8
	s_add_u32 s10, s6, 0x2000
	s_addc_u32 s11, s7, 0
	s_add_i32 s22, s20, 0xffffc002
	v_lshl_add_u64 v[90:91], s[8:9], 0, v[82:83]
	s_lshl_b64 s[8:9], s[22:23], 12
	s_add_u32 s8, s28, s8
	s_addc_u32 s9, s29, s9
	s_cmpk_lt_i32 s20, 0x3ffe
	s_cselect_b32 s9, s11, s9
	s_cselect_b32 s8, s10, s8
	s_add_u32 s10, s6, 0x3000
	v_lshl_add_u64 v[88:89], s[8:9], 0, v[82:83]
	s_addc_u32 s8, s7, 0
	s_add_i32 s22, s20, 0xffffc003
	s_lshl_b64 s[6:7], s[22:23], 12
	s_add_u32 s6, s28, s6
	s_addc_u32 s7, s29, s7
	s_cmpk_lt_i32 s20, 0x3ffd
	s_cselect_b32 s7, s8, s7
	s_cselect_b32 s6, s10, s6
	v_lshl_add_u64 v[86:87], s[6:7], 0, v[82:83]
	s_add_i32 s20, s20, 32
	s_add_u32 s38, s38, 0x20000
	s_addc_u32 s39, s39, 0
	v_lshl_add_u64 v[84:85], v[84:85], 0, s[26:27]
	s_cmp_lt_i32 s20, s5
	s_waitcnt vmcnt(0) lgkmcnt(0)
	v_pk_mul_f32 v[102:103], v[80:81], v[80:81]
	v_pk_mul_f32 v[104:105], v[78:79], v[78:79]
	v_pk_mul_f32 v[106:107], v[72:73], v[72:73]
	v_pk_mul_f32 v[108:109], v[70:71], v[70:71]
	v_mul_f32_e32 v110, v75, v75
	v_mul_f32_e32 v112, v77, v77
	v_pk_mov_b32 v[114:115], v[104:105], v[102:103] op_sel:[1,0]
	v_mov_b32_e32 v105, v103
	v_pk_mov_b32 v[102:103], v[108:109], v[106:107] op_sel:[1,0]
	v_mov_b32_e32 v109, v107
	v_mul_f32_e32 v123, v68, v68
	v_mul_f32_e32 v125, v69, v69
	v_pk_fma_f32 v[106:107], v[74:75], v[74:75], v[110:111] op_sel_hi:[1,1,0]
	v_pk_fma_f32 v[110:111], v[76:77], v[76:77], v[112:113] op_sel_hi:[1,1,0]
	v_pk_mul_f32 v[112:113], v[64:65], v[64:65]
	v_pk_mul_f32 v[116:117], v[62:63], v[62:63]
	v_pk_mul_f32 v[118:119], v[56:57], v[56:57]
	v_pk_mul_f32 v[120:121], v[54:55], v[54:55]
	v_mul_f32_e32 v122, v59, v59
	v_mul_f32_e32 v124, v61, v61
	v_pk_add_f32 v[104:105], v[114:115], v[104:105]
	v_pk_add_f32 v[102:103], v[102:103], v[108:109]
	v_mul_f32_e32 v101, v66, v66
	v_mul_f32_e32 v137, v67, v67
	v_mul_f32_e32 v131, v52, v52
	v_mul_f32_e32 v133, v53, v53
	v_mov_b32_e32 v107, v123
	v_mov_b32_e32 v111, v125
	v_pk_mov_b32 v[108:109], v[116:117], v[112:113] op_sel:[1,0]
	v_mov_b32_e32 v117, v113
	v_pk_mov_b32 v[112:113], v[120:121], v[118:119] op_sel:[1,0]
	v_mov_b32_e32 v121, v119
	v_pk_fma_f32 v[114:115], v[58:59], v[58:59], v[122:123] op_sel_hi:[1,1,0]
	v_pk_fma_f32 v[118:119], v[60:61], v[60:61], v[124:125] op_sel_hi:[1,1,0]
	v_pk_mul_f32 v[122:123], v[48:49], v[48:49]
	v_pk_mul_f32 v[124:125], v[46:47], v[46:47]
	v_pk_mul_f32 v[126:127], v[44:45], v[44:45]
	v_pk_mul_f32 v[128:129], v[42:43], v[42:43]
	v_mul_f32_e32 v130, v39, v39
	v_mul_f32_e32 v132, v41, v41
	v_pk_add_f32 v[104:105], v[104:105], v[104:105] op_sel:[0,1] op_sel_hi:[1,0]
	v_pk_add_f32 v[102:103], v[102:103], v[102:103] op_sel:[0,1] op_sel_hi:[1,0]
	v_mul_f32_e32 v143, v36, v36
	v_mul_f32_e32 v144, v37, v37
	v_pk_add_f32 v[106:107], v[106:107], v[110:111]
	v_pk_add_f32 v[108:109], v[108:109], v[116:117]
	v_pk_add_f32 v[110:111], v[112:113], v[120:121]
	v_mov_b32_e32 v115, v131
	v_mov_b32_e32 v119, v133
	v_pk_mov_b32 v[112:113], v[124:125], v[122:123] op_sel:[1,0]
	v_mov_b32_e32 v125, v123
	v_pk_mov_b32 v[116:117], v[128:129], v[126:127] op_sel:[1,0]
	v_mov_b32_e32 v129, v127
	v_pk_fma_f32 v[120:121], v[38:39], v[38:39], v[130:131] op_sel_hi:[1,1,0]
	v_pk_fma_f32 v[122:123], v[40:41], v[40:41], v[132:133] op_sel_hi:[1,1,0]
	v_pk_mul_f32 v[126:127], v[32:33], v[32:33]
	v_pk_mul_f32 v[130:131], v[30:31], v[30:31]
	v_pk_mul_f32 v[132:133], v[28:29], v[28:29]
	v_pk_mul_f32 v[134:135], v[26:27], v[26:27]
	v_mov_b32_e32 v105, v101
	v_mov_b32_e32 v103, v137
	v_mul_f32_e32 v139, v50, v50
	v_mul_f32_e32 v140, v51, v51
	v_pk_add_f32 v[108:109], v[108:109], v[108:109] op_sel:[0,1] op_sel_hi:[1,0]
	v_pk_add_f32 v[110:111], v[110:111], v[110:111] op_sel:[0,1] op_sel_hi:[1,0]
	v_pk_add_f32 v[114:115], v[114:115], v[118:119]
	v_pk_add_f32 v[112:113], v[112:113], v[124:125]
	v_pk_add_f32 v[116:117], v[116:117], v[128:129]
	v_mov_b32_e32 v121, v143
	v_mov_b32_e32 v123, v144
	v_pk_mov_b32 v[118:119], v[130:131], v[126:127] op_sel:[1,0]
	v_mov_b32_e32 v131, v127
	v_pk_mov_b32 v[124:125], v[134:135], v[132:133] op_sel:[1,0]
	v_mov_b32_e32 v135, v133
	v_pk_add_f32 v[102:103], v[104:105], v[102:103]
	v_mul_f32_e32 v141, v34, v34
	v_mul_f32_e32 v142, v35, v35
	v_mul_f32_e32 v136, v23, v23
	v_mul_f32_e32 v138, v25, v25
	v_mov_b32_e32 v109, v139
	v_mov_b32_e32 v111, v140
	v_pk_add_f32 v[104:105], v[112:113], v[112:113] op_sel:[0,1] op_sel_hi:[1,0]
	v_pk_add_f32 v[112:113], v[116:117], v[116:117] op_sel:[0,1] op_sel_hi:[1,0]
	v_pk_add_f32 v[116:117], v[120:121], v[122:123]
	v_pk_add_f32 v[118:119], v[118:119], v[130:131]
	v_pk_add_f32 v[120:121], v[124:125], v[134:135]
	v_pk_add_f32 v[102:103], v[102:103], v[106:107]
	v_mul_f32_e32 v145, v18, v18
	v_mul_f32_e32 v146, v19, v19
	v_mul_f32_e32 v147, v20, v20
	v_mul_f32_e32 v148, v21, v21
	v_pk_fma_f32 v[126:127], v[22:23], v[22:23], v[136:137] op_sel_hi:[1,1,0]
	v_pk_fma_f32 v[128:129], v[24:25], v[24:25], v[138:139] op_sel_hi:[1,1,0]
	v_pk_add_f32 v[106:107], v[108:109], v[110:111]
	v_mov_b32_e32 v105, v141
	v_mov_b32_e32 v113, v142
	v_pk_add_f32 v[108:109], v[118:119], v[118:119] op_sel:[0,1] op_sel_hi:[1,0]
	v_pk_add_f32 v[110:111], v[120:121], v[120:121] op_sel:[0,1] op_sel_hi:[1,0]
	v_add_f32_e32 v101, v102, v103
	v_mov_b32_e32 v127, v147
	v_mov_b32_e32 v129, v148
	v_pk_add_f32 v[102:103], v[106:107], v[114:115]
	v_pk_add_f32 v[104:105], v[104:105], v[112:113]
	v_mov_b32_e32 v109, v145
	v_mov_b32_e32 v111, v146
	ds_bpermute_b32 v107, v1, v101
	v_pk_add_f32 v[118:119], v[126:127], v[128:129]
	v_add_f32_e32 v106, v102, v103
	v_pk_add_f32 v[102:103], v[104:105], v[116:117]
	v_pk_add_f32 v[104:105], v[108:109], v[110:111]
	v_add_f32_e32 v108, v102, v103
	v_pk_add_f32 v[102:103], v[104:105], v[118:119]
	v_add_f32_e32 v102, v102, v103
	s_waitcnt lgkmcnt(0)
	v_add_f32_e32 v101, v101, v107
	s_waitcnt lgkmcnt(0)
	s_nop 1
	v_add_f32_dpp v104, v106, v106 quad_perm:[1,0,3,2] row_mask:0xf bank_mask:0xf
	s_waitcnt lgkmcnt(0)
	s_nop 1
	v_add_f32_dpp v103, v108, v108 quad_perm:[1,0,3,2] row_mask:0xf bank_mask:0xf
	s_waitcnt lgkmcnt(2)
	s_nop 1
	v_add_f32_dpp v102, v102, v102 quad_perm:[1,0,3,2] row_mask:0xf bank_mask:0xf
	s_waitcnt lgkmcnt(0)
	s_nop 1
	v_add_f32_dpp v101, v101, v101 quad_perm:[2,3,0,1] row_mask:0xf bank_mask:0xf
	ds_bpermute_b32 v107, v95, v101
	s_waitcnt lgkmcnt(3)
	s_nop 1
	v_add_f32_dpp v104, v104, v104 quad_perm:[2,3,0,1] row_mask:0xf bank_mask:0xf
	s_waitcnt lgkmcnt(0)
	s_nop 1
	v_add_f32_dpp v103, v103, v103 quad_perm:[2,3,0,1] row_mask:0xf bank_mask:0xf
	s_waitcnt lgkmcnt(2)
	s_nop 1
	v_add_f32_dpp v102, v102, v102 quad_perm:[2,3,0,1] row_mask:0xf bank_mask:0xf
	s_waitcnt lgkmcnt(0)
	v_add_f32_e32 v101, v101, v107
	ds_bpermute_b32 v107, v96, v101
	s_waitcnt lgkmcnt(3)
	s_nop 1
	v_add_f32_dpp v104, v104, v104 row_half_mirror row_mask:0xf bank_mask:0xf
	s_waitcnt lgkmcnt(0)
	s_nop 1
	v_add_f32_dpp v103, v103, v103 row_half_mirror row_mask:0xf bank_mask:0xf
	s_waitcnt lgkmcnt(2)
	s_nop 1
	v_add_f32_dpp v102, v102, v102 row_half_mirror row_mask:0xf bank_mask:0xf
	s_waitcnt lgkmcnt(0)
	v_add_f32_e32 v101, v101, v107
	ds_bpermute_b32 v107, v97, v101
	s_waitcnt lgkmcnt(3)
	s_nop 1
	v_add_f32_dpp v104, v104, v104 row_mirror row_mask:0xf bank_mask:0xf
	ds_bpermute_b32 v106, v97, v104
	s_waitcnt lgkmcnt(3)
	s_nop 1
	v_add_f32_dpp v103, v103, v103 row_mirror row_mask:0xf bank_mask:0xf
	s_waitcnt lgkmcnt(2)
	s_nop 1
	v_add_f32_dpp v102, v102, v102 row_mirror row_mask:0xf bank_mask:0xf
	ds_bpermute_b32 v108, v97, v103
	ds_bpermute_b32 v105, v97, v102
	s_waitcnt lgkmcnt(3)
	v_add_f32_e32 v101, v101, v107
	ds_bpermute_b32 v107, v98, v101
	s_waitcnt lgkmcnt(3)
	v_add_f32_e32 v104, v104, v106
	ds_bpermute_b32 v106, v98, v104
	s_waitcnt lgkmcnt(3)
	v_add_f32_e32 v103, v103, v108
	s_waitcnt lgkmcnt(2)
	v_add_f32_e32 v102, v102, v105
	ds_bpermute_b32 v108, v98, v103
	ds_bpermute_b32 v105, v98, v102
	s_waitcnt lgkmcnt(3)
	v_add_f32_e32 v101, v101, v107
	v_fmamk_f32 v101, v101, 0x3a800000, v99
	s_waitcnt lgkmcnt(2)
	v_add_f32_e32 v104, v104, v106
	v_mul_f32_e32 v106, 0x4f800000, v101
	v_cmp_gt_f32_e32 vcc, s21, v101
	v_fmamk_f32 v104, v104, 0x3a800000, v99
	s_waitcnt lgkmcnt(1)
	v_add_f32_e32 v103, v103, v108
	v_cndmask_b32_e32 v101, v101, v106, vcc
	v_mul_f32_e32 v106, 0x4f800000, v104
	v_cmp_gt_f32_e64 s[6:7], s21, v104
	s_waitcnt lgkmcnt(0)
	v_add_f32_e32 v102, v102, v105
	v_sqrt_f32_e32 v105, v101
	v_fmamk_f32 v103, v103, 0x3a800000, v99
	v_cndmask_b32_e64 v104, v104, v106, s[6:7]
	v_mul_f32_e32 v106, 0x4f800000, v103
	v_cmp_gt_f32_e64 s[8:9], s21, v103
	v_fmamk_f32 v102, v102, 0x3a800000, v99
	v_sqrt_f32_e32 v107, v104
	v_cndmask_b32_e64 v103, v103, v106, s[8:9]
	v_mul_f32_e32 v106, 0x4f800000, v102
	v_cmp_gt_f32_e64 s[10:11], s21, v102
	v_sqrt_f32_e32 v108, v103
	v_add_u32_e32 v109, -1, v105
	v_cndmask_b32_e64 v102, v102, v106, s[10:11]
	v_sqrt_f32_e32 v106, v102
	v_add_u32_e32 v110, 1, v105
	v_fma_f32 v111, -v109, v105, v101
	v_fma_f32 v112, -v110, v105, v101
	v_add_u32_e32 v113, -1, v107
	v_cmp_ge_f32_e64 s[12:13], 0, v111
	v_add_u32_e32 v114, 1, v107
	v_fma_f32 v111, -v114, v107, v104
	v_cndmask_b32_e64 v105, v105, v109, s[12:13]
	v_fma_f32 v109, -v113, v107, v104
	v_cmp_lt_f32_e64 s[12:13], 0, v112
	v_add_u32_e32 v115, -1, v108
	v_add_u32_e32 v116, 1, v108
	v_cndmask_b32_e64 v105, v105, v110, s[12:13]
	v_cmp_ge_f32_e64 s[12:13], 0, v109
	v_fma_f32 v109, -v115, v108, v103
	v_fma_f32 v110, -v116, v108, v103
	v_cndmask_b32_e64 v107, v107, v113, s[12:13]
	v_cmp_lt_f32_e64 s[12:13], 0, v111
	v_add_u32_e32 v111, -1, v106
	v_add_u32_e32 v112, 1, v106
	v_mul_f32_e32 v113, 0x37800000, v105
	v_cndmask_b32_e64 v107, v107, v114, s[12:13]
	v_cmp_ge_f32_e64 s[12:13], 0, v109
	v_fma_f32 v109, -v111, v106, v102
	v_cndmask_b32_e32 v105, v105, v113, vcc
	v_cndmask_b32_e64 v108, v108, v115, s[12:13]
	v_cmp_lt_f32_e64 s[12:13], 0, v110
	v_fma_f32 v110, -v112, v106, v102
	v_cmp_ge_f32_e32 vcc, 0, v109
	v_mul_f32_e32 v113, 0x37800000, v107
	v_cndmask_b32_e64 v108, v108, v116, s[12:13]
	v_cndmask_b32_e32 v106, v106, v111, vcc
	v_cmp_lt_f32_e32 vcc, 0, v110
	v_cmp_class_f32_e64 s[12:13], v101, v100
	s_nop 0
	v_cndmask_b32_e32 v106, v106, v112, vcc
	v_cndmask_b32_e64 v101, v105, v101, s[12:13]
	v_cndmask_b32_e64 v105, v107, v113, s[6:7]
	v_cmp_class_f32_e64 s[6:7], v104, v100
	v_mul_f32_e32 v107, 0x37800000, v108
	v_div_scale_f32 v109, s[12:13], v101, v101, 1.0
	v_cndmask_b32_e64 v111, v105, v104, s[6:7]
	v_cndmask_b32_e64 v104, v108, v107, s[8:9]
	v_cmp_class_f32_e64 s[6:7], v103, v100
	v_mul_f32_e32 v105, 0x37800000, v106
	v_rcp_f32_e32 v107, v109
	v_div_scale_f32 v108, s[8:9], v111, v111, 1.0
	v_cndmask_b32_e64 v113, v104, v103, s[6:7]
	v_cndmask_b32_e64 v103, v106, v105, s[10:11]
	v_cmp_class_f32_e64 s[6:7], v102, v100
	v_rcp_f32_e32 v104, v108
	v_div_scale_f32 v105, s[10:11], v113, v113, 1.0
	v_cndmask_b32_e64 v114, v103, v102, s[6:7]
	v_rcp_f32_e32 v115, v105
	v_div_scale_f32 v116, s[6:7], v114, v114, 1.0
	v_rcp_f32_e32 v118, v116
	v_fma_f32 v102, -v109, v107, 1.0
	v_div_scale_f32 v110, vcc, 1.0, v101, 1.0
	v_fmac_f32_e32 v107, v102, v107
	v_fma_f32 v102, -v108, v104, 1.0
	v_div_scale_f32 v112, s[8:9], 1.0, v111, 1.0
	v_mul_f32_e32 v103, v110, v107
	v_fmac_f32_e32 v104, v102, v104
	v_fma_f32 v102, -v105, v115, 1.0
	v_div_scale_f32 v106, s[10:11], 1.0, v113, 1.0
	v_fma_f32 v119, -v109, v103, v110
	v_mul_f32_e32 v120, v112, v104
	v_fmac_f32_e32 v115, v102, v115
	v_fma_f32 v102, -v116, v118, 1.0
	v_div_scale_f32 v117, s[6:7], 1.0, v114, 1.0
	v_fmac_f32_e32 v103, v119, v107
	v_fma_f32 v119, -v108, v120, v112
	v_mul_f32_e32 v121, v106, v115
	v_fmac_f32_e32 v118, v102, v118
	v_fma_f32 v102, -v109, v103, v110
	v_fmac_f32_e32 v120, v119, v104
	v_fma_f32 v109, -v105, v121, v106
	v_mul_f32_e32 v110, v117, v118
	v_div_fmas_f32 v102, v102, v107, v103
	v_fma_f32 v103, -v108, v120, v112
	v_fmac_f32_e32 v121, v109, v115
	v_fma_f32 v107, -v116, v110, v117
	s_mov_b64 vcc, s[8:9]
	v_div_fixup_f32 v102, v102, v101, 1.0
	v_div_fmas_f32 v101, v103, v104, v120
	v_fma_f32 v108, -v105, v121, v106
	v_fmac_f32_e32 v110, v107, v118
	s_mov_b64 vcc, s[10:11]
	v_pk_mul_f32 v[78:79], v[78:79], v[102:103] op_sel_hi:[1,0]
	v_pk_mul_f32 v[80:81], v[80:81], v[102:103] op_sel_hi:[1,0]
	v_pk_mul_f32 v[70:71], v[70:71], v[102:103] op_sel_hi:[1,0]
	v_pk_mul_f32 v[72:73], v[72:73], v[102:103] op_sel_hi:[1,0]
	v_pk_mul_f32 v[74:75], v[74:75], v[102:103] op_sel_hi:[1,0]
	v_pk_mul_f32 v[76:77], v[76:77], v[102:103] op_sel_hi:[1,0]
	v_pk_mul_f32 v[104:105], v[66:67], v[102:103] op_sel_hi:[1,0]
	v_pk_mul_f32 v[102:103], v[68:69], v[102:103] op_sel_hi:[1,0]
	v_div_fixup_f32 v106, v101, v111, 1.0
	v_div_fmas_f32 v101, v108, v115, v121
	v_fma_f32 v107, -v116, v110, v117
	s_mov_b64 vcc, s[6:7]
	v_pk_mul_f32 v[68:69], v[80:81], v[4:5]
	v_pk_mul_f32 v[66:67], v[78:79], v[2:3]
	v_pk_mul_f32 v[74:75], v[74:75], v[10:11]
	v_pk_mul_f32 v[80:81], v[102:103], v[16:17]
	v_pk_mul_f32 v[78:79], v[104:105], v[14:15]
	v_pk_mul_f32 v[62:63], v[62:63], v[106:107] op_sel_hi:[1,0]
	v_pk_mul_f32 v[64:65], v[64:65], v[106:107] op_sel_hi:[1,0]
	v_pk_mul_f32 v[54:55], v[54:55], v[106:107] op_sel_hi:[1,0]
	v_pk_mul_f32 v[56:57], v[56:57], v[106:107] op_sel_hi:[1,0]
	v_pk_mul_f32 v[58:59], v[58:59], v[106:107] op_sel_hi:[1,0]
	v_pk_mul_f32 v[60:61], v[60:61], v[106:107] op_sel_hi:[1,0]
	v_pk_mul_f32 v[102:103], v[50:51], v[106:107] op_sel_hi:[1,0]
	v_pk_mul_f32 v[104:105], v[52:53], v[106:107] op_sel_hi:[1,0]
	v_div_fixup_f32 v106, v101, v113, 1.0
	v_div_fmas_f32 v101, v107, v118, v110
	v_pk_mul_f32 v[72:73], v[72:73], v[8:9]
	v_pk_mul_f32 v[70:71], v[70:71], v[6:7]
	v_pk_mul_f32 v[76:77], v[76:77], v[12:13]
	global_store_dwordx4 v[92:93], v[66:69], off
	global_store_dwordx4 v[92:93], v[70:73], off offset:1024
	global_store_dwordx4 v[92:93], v[74:77], off offset:2048
	global_store_dwordx4 v[92:93], v[78:81], off offset:3072
	v_pk_mul_f32 v[52:53], v[64:65], v[4:5]
	v_div_fixup_f32 v74, v101, v114, 1.0
	v_pk_mul_f32 v[50:51], v[62:63], v[2:3]
	v_pk_mul_f32 v[56:57], v[56:57], v[8:9]
	v_pk_mul_f32 v[54:55], v[54:55], v[6:7]
	v_pk_mul_f32 v[46:47], v[46:47], v[106:107] op_sel_hi:[1,0]
	v_pk_mul_f32 v[48:49], v[48:49], v[106:107] op_sel_hi:[1,0]
	v_pk_mul_f32 v[30:31], v[30:31], v[74:75] op_sel_hi:[1,0]
	v_pk_mul_f32 v[32:33], v[32:33], v[74:75] op_sel_hi:[1,0]
	v_pk_mul_f32 v[60:61], v[60:61], v[12:13]
	v_pk_mul_f32 v[58:59], v[58:59], v[10:11]
	v_pk_mul_f32 v[64:65], v[104:105], v[16:17]
	v_pk_mul_f32 v[62:63], v[102:103], v[14:15]
	v_pk_mul_f32 v[42:43], v[42:43], v[106:107] op_sel_hi:[1,0]
	v_pk_mul_f32 v[44:45], v[44:45], v[106:107] op_sel_hi:[1,0]
	v_pk_mul_f32 v[66:67], v[38:39], v[106:107] op_sel_hi:[1,0]
	v_pk_mul_f32 v[68:69], v[40:41], v[106:107] op_sel_hi:[1,0]
	v_pk_mul_f32 v[70:71], v[34:35], v[106:107] op_sel_hi:[1,0]
	v_pk_mul_f32 v[72:73], v[36:37], v[106:107] op_sel_hi:[1,0]
	global_store_dwordx4 v[90:91], v[50:53], off
	global_store_dwordx4 v[90:91], v[54:57], off offset:1024
	global_store_dwordx4 v[90:91], v[58:61], off offset:2048
	global_store_dwordx4 v[90:91], v[62:65], off offset:3072
	v_pk_mul_f32 v[36:37], v[48:49], v[4:5]
	v_pk_mul_f32 v[34:35], v[46:47], v[2:3]
	v_pk_mul_f32 v[26:27], v[26:27], v[74:75] op_sel_hi:[1,0]
	v_pk_mul_f32 v[28:29], v[28:29], v[74:75] op_sel_hi:[1,0]
	v_pk_mul_f32 v[50:51], v[22:23], v[74:75] op_sel_hi:[1,0]
	v_pk_mul_f32 v[52:53], v[24:25], v[74:75] op_sel_hi:[1,0]
	v_pk_mul_f32 v[54:55], v[18:19], v[74:75] op_sel_hi:[1,0]
	v_pk_mul_f32 v[56:57], v[20:21], v[74:75] op_sel_hi:[1,0]
	v_pk_mul_f32 v[20:21], v[32:33], v[4:5]
	v_pk_mul_f32 v[18:19], v[30:31], v[2:3]
	v_pk_mul_f32 v[40:41], v[44:45], v[8:9]
	v_pk_mul_f32 v[38:39], v[42:43], v[6:7]
	v_pk_mul_f32 v[44:45], v[68:69], v[12:13]
	v_pk_mul_f32 v[42:43], v[66:67], v[10:11]
	v_pk_mul_f32 v[48:49], v[72:73], v[16:17]
	v_pk_mul_f32 v[46:47], v[70:71], v[14:15]
	global_store_dwordx4 v[88:89], v[34:37], off
	global_store_dwordx4 v[88:89], v[38:41], off offset:1024
	global_store_dwordx4 v[88:89], v[42:45], off offset:2048
	global_store_dwordx4 v[88:89], v[46:49], off offset:3072
	v_pk_mul_f32 v[24:25], v[28:29], v[8:9]
	v_pk_mul_f32 v[22:23], v[26:27], v[6:7]
	v_pk_mul_f32 v[28:29], v[52:53], v[12:13]
	v_pk_mul_f32 v[26:27], v[50:51], v[10:11]
	v_pk_mul_f32 v[32:33], v[56:57], v[16:17]
	v_pk_mul_f32 v[30:31], v[54:55], v[14:15]
	global_store_dwordx4 v[86:87], v[18:21], off
	global_store_dwordx4 v[86:87], v[22:25], off offset:1024
	global_store_dwordx4 v[86:87], v[26:29], off offset:2048
	global_store_dwordx4 v[86:87], v[30:33], off offset:3072
	s_cbranch_scc1 .LBB0_5801

.LBB0_5948:
	v_lshl_add_u64 v[16:17], v[82:83], 0, s[10:11]
	v_add_co_u32_e32 v18, vcc, 0x7800000, v16
	s_add_i32 s0, s17, 32
	s_nop 0
	v_addc_co_u32_e32 v19, vcc, 0, v17, vcc
	v_add_co_u32_e32 v20, vcc, 0x7801000, v16
	global_load_dwordx4 v[76:79], v[18:19], off
	global_load_dwordx4 v[68:71], v[18:19], off offset:1024
	global_load_dwordx4 v[64:67], v[18:19], off offset:3072
	global_load_dwordx4 v[72:75], v[18:19], off offset:2048
	v_addc_co_u32_e32 v21, vcc, 0, v17, vcc
	v_add_co_u32_e32 v18, vcc, 0x7802000, v16
	global_load_dwordx4 v[60:63], v[20:21], off
	global_load_dwordx4 v[52:55], v[20:21], off offset:1024
	global_load_dwordx4 v[48:51], v[20:21], off offset:3072
	global_load_dwordx4 v[56:59], v[20:21], off offset:2048
	v_addc_co_u32_e32 v19, vcc, 0, v17, vcc
	v_add_co_u32_e32 v84, vcc, 0x7803000, v16
	global_load_dwordx4 v[44:47], v[18:19], off
	global_load_dwordx4 v[40:43], v[18:19], off offset:1024
	global_load_dwordx4 v[36:39], v[18:19], off offset:2048
	global_load_dwordx4 v[32:35], v[18:19], off offset:3072
	v_addc_co_u32_e32 v85, vcc, 0, v17, vcc
	global_load_dwordx4 v[28:31], v[84:85], off
	global_load_dwordx4 v[24:27], v[84:85], off offset:1024
	global_load_dwordx4 v[20:23], v[84:85], off offset:2048
	global_load_dwordx4 v[16:19], v[84:85], off offset:3072
	s_add_u32 s1, s68, s10
	s_addc_u32 s4, s69, s11
	s_add_i32 s8, s17, 0xffffc020
	s_lshl_b64 s[2:3], s[8:9], 12
	s_add_u32 s2, s15, s2
	s_addc_u32 s3, s16, s3
	s_cmpk_lt_i32 s0, 0x4000
	s_cselect_b32 s3, s4, s3
	s_cselect_b32 s2, s1, s2
	s_add_u32 s5, s1, 0x1000
	s_addc_u32 s6, s4, 0
	s_add_i32 s8, s17, 0xffffc021
	v_lshl_add_u64 v[90:91], s[2:3], 0, v[80:81]
	s_lshl_b64 s[2:3], s[8:9], 12
	s_add_u32 s2, s15, s2
	s_addc_u32 s3, s16, s3
	s_cmpk_lt_i32 s0, 0x3fff
	s_cselect_b32 s3, s6, s3
	s_cselect_b32 s2, s5, s2
	s_add_u32 s5, s1, 0x2000
	s_addc_u32 s6, s4, 0
	s_add_i32 s8, s17, 0xffffc022
	v_lshl_add_u64 v[88:89], s[2:3], 0, v[80:81]
	s_lshl_b64 s[2:3], s[8:9], 12
	s_add_u32 s2, s15, s2
	s_addc_u32 s3, s16, s3
	s_cmpk_lt_i32 s0, 0x3ffe
	s_cselect_b32 s3, s6, s3
	s_cselect_b32 s2, s5, s2
	s_add_u32 s1, s1, 0x3000
	s_addc_u32 s4, s4, 0
	s_add_i32 s8, s17, 0xffffc023
	v_lshl_add_u64 v[84:85], s[2:3], 0, v[80:81]
	s_lshl_b64 s[2:3], s[8:9], 12
	s_add_u32 s2, s15, s2
	s_addc_u32 s3, s16, s3
	s_cmpk_lt_i32 s0, 0x3ffd
	s_cselect_b32 s3, s4, s3
	s_cselect_b32 s2, s1, s2
	s_add_u32 s68, s68, 0x20000
	s_addc_u32 s69, s69, 0
	s_mov_b32 s17, s0
	s_cmp_lt_i32 s0, s14
	v_lshl_add_u64 v[86:87], s[2:3], 0, v[80:81]
	v_lshl_add_u64 v[82:83], v[82:83], 0, s[12:13]
	s_waitcnt vmcnt(0) lgkmcnt(0)
	v_pk_mul_f32 v[100:101], v[78:79], v[78:79]
	v_pk_mul_f32 v[102:103], v[76:77], v[76:77]
	v_pk_mul_f32 v[104:105], v[70:71], v[70:71]
	v_pk_mul_f32 v[106:107], v[68:69], v[68:69]
	v_mul_f32_e32 v108, v73, v73
	v_mul_f32_e32 v110, v75, v75
	v_pk_mov_b32 v[112:113], v[102:103], v[100:101] op_sel:[1,0]
	v_mov_b32_e32 v103, v101
	v_pk_mov_b32 v[100:101], v[106:107], v[104:105] op_sel:[1,0]
	v_mov_b32_e32 v107, v105
	v_mul_f32_e32 v121, v66, v66
	v_mul_f32_e32 v123, v67, v67
	v_pk_fma_f32 v[104:105], v[72:73], v[72:73], v[108:109] op_sel_hi:[1,1,0]
	v_pk_fma_f32 v[108:109], v[74:75], v[74:75], v[110:111] op_sel_hi:[1,1,0]
	v_pk_mul_f32 v[110:111], v[62:63], v[62:63]
	v_pk_mul_f32 v[114:115], v[60:61], v[60:61]
	v_pk_mul_f32 v[116:117], v[54:55], v[54:55]
	v_pk_mul_f32 v[118:119], v[52:53], v[52:53]
	v_mul_f32_e32 v120, v57, v57
	v_mul_f32_e32 v122, v59, v59
	v_pk_add_f32 v[102:103], v[112:113], v[102:103]
	v_pk_add_f32 v[100:101], v[100:101], v[106:107]
	v_mul_f32_e32 v135, v64, v64
	v_mul_f32_e32 v137, v65, v65
	v_mul_f32_e32 v129, v50, v50
	v_mul_f32_e32 v131, v51, v51
	v_mov_b32_e32 v105, v121
	v_mov_b32_e32 v109, v123
	v_pk_mov_b32 v[106:107], v[114:115], v[110:111] op_sel:[1,0]
	v_mov_b32_e32 v115, v111
	v_pk_mov_b32 v[110:111], v[118:119], v[116:117] op_sel:[1,0]
	v_mov_b32_e32 v119, v117
	v_pk_fma_f32 v[112:113], v[56:57], v[56:57], v[120:121] op_sel_hi:[1,1,0]
	v_pk_fma_f32 v[116:117], v[58:59], v[58:59], v[122:123] op_sel_hi:[1,1,0]
	v_pk_mul_f32 v[120:121], v[46:47], v[46:47]
	v_pk_mul_f32 v[122:123], v[44:45], v[44:45]
	v_pk_mul_f32 v[124:125], v[42:43], v[42:43]
	v_pk_mul_f32 v[126:127], v[40:41], v[40:41]
	v_mul_f32_e32 v128, v37, v37
	v_mul_f32_e32 v130, v39, v39
	v_pk_add_f32 v[102:103], v[102:103], v[102:103] op_sel:[0,1] op_sel_hi:[1,0]
	v_pk_add_f32 v[100:101], v[100:101], v[100:101] op_sel:[0,1] op_sel_hi:[1,0]
	v_mul_f32_e32 v142, v34, v34
	v_mul_f32_e32 v143, v35, v35
	v_pk_add_f32 v[104:105], v[104:105], v[108:109]
	v_pk_add_f32 v[106:107], v[106:107], v[114:115]
	v_pk_add_f32 v[108:109], v[110:111], v[118:119]
	v_mov_b32_e32 v113, v129
	v_mov_b32_e32 v117, v131
	v_pk_mov_b32 v[110:111], v[122:123], v[120:121] op_sel:[1,0]
	v_mov_b32_e32 v123, v121
	v_pk_mov_b32 v[114:115], v[126:127], v[124:125] op_sel:[1,0]
	v_mov_b32_e32 v127, v125
	v_pk_fma_f32 v[118:119], v[36:37], v[36:37], v[128:129] op_sel_hi:[1,1,0]
	v_pk_fma_f32 v[120:121], v[38:39], v[38:39], v[130:131] op_sel_hi:[1,1,0]
	v_pk_mul_f32 v[124:125], v[30:31], v[30:31]
	v_pk_mul_f32 v[128:129], v[28:29], v[28:29]
	v_pk_mul_f32 v[130:131], v[26:27], v[26:27]
	v_pk_mul_f32 v[132:133], v[24:25], v[24:25]
	v_mov_b32_e32 v103, v135
	v_mov_b32_e32 v101, v137
	v_mul_f32_e32 v138, v48, v48
	v_mul_f32_e32 v139, v49, v49
	v_pk_add_f32 v[106:107], v[106:107], v[106:107] op_sel:[0,1] op_sel_hi:[1,0]
	v_pk_add_f32 v[108:109], v[108:109], v[108:109] op_sel:[0,1] op_sel_hi:[1,0]
	v_pk_add_f32 v[112:113], v[112:113], v[116:117]
	v_pk_add_f32 v[110:111], v[110:111], v[122:123]
	v_pk_add_f32 v[114:115], v[114:115], v[126:127]
	v_mov_b32_e32 v119, v142
	v_mov_b32_e32 v121, v143
	v_pk_mov_b32 v[116:117], v[128:129], v[124:125] op_sel:[1,0]
	v_mov_b32_e32 v129, v125
	v_pk_mov_b32 v[122:123], v[132:133], v[130:131] op_sel:[1,0]
	v_mov_b32_e32 v133, v131
	v_pk_add_f32 v[100:101], v[102:103], v[100:101]
	v_mul_f32_e32 v140, v32, v32
	v_mul_f32_e32 v141, v33, v33
	v_mul_f32_e32 v134, v21, v21
	v_mul_f32_e32 v136, v23, v23
	v_mov_b32_e32 v107, v138
	v_mov_b32_e32 v109, v139
	v_pk_add_f32 v[102:103], v[110:111], v[110:111] op_sel:[0,1] op_sel_hi:[1,0]
	v_pk_add_f32 v[110:111], v[114:115], v[114:115] op_sel:[0,1] op_sel_hi:[1,0]
	v_pk_add_f32 v[114:115], v[118:119], v[120:121]
	v_pk_add_f32 v[116:117], v[116:117], v[128:129]
	v_pk_add_f32 v[118:119], v[122:123], v[132:133]
	v_pk_add_f32 v[100:101], v[100:101], v[104:105]
	v_mul_f32_e32 v144, v16, v16
	v_mul_f32_e32 v145, v17, v17
	v_mul_f32_e32 v146, v18, v18
	v_mul_f32_e32 v147, v19, v19
	v_pk_fma_f32 v[124:125], v[20:21], v[20:21], v[134:135] op_sel_hi:[1,1,0]
	v_pk_fma_f32 v[126:127], v[22:23], v[22:23], v[136:137] op_sel_hi:[1,1,0]
	v_pk_add_f32 v[104:105], v[106:107], v[108:109]
	v_mov_b32_e32 v103, v140
	v_mov_b32_e32 v111, v141
	v_pk_add_f32 v[106:107], v[116:117], v[116:117] op_sel:[0,1] op_sel_hi:[1,0]
	v_pk_add_f32 v[108:109], v[118:119], v[118:119] op_sel:[0,1] op_sel_hi:[1,0]
	v_add_f32_e32 v118, v100, v101
	v_mov_b32_e32 v125, v146
	v_mov_b32_e32 v127, v147
	v_pk_add_f32 v[100:101], v[104:105], v[112:113]
	v_pk_add_f32 v[102:103], v[102:103], v[110:111]
	v_mov_b32_e32 v107, v144
	v_mov_b32_e32 v109, v145
	ds_bpermute_b32 v105, v92, v118
	v_pk_add_f32 v[116:117], v[124:125], v[126:127]
	v_add_f32_e32 v104, v100, v101
	v_pk_add_f32 v[100:101], v[102:103], v[114:115]
	v_pk_add_f32 v[102:103], v[106:107], v[108:109]
	v_add_f32_e32 v106, v100, v101
	v_pk_add_f32 v[100:101], v[102:103], v[116:117]
	v_add_f32_e32 v100, v100, v101
	s_waitcnt lgkmcnt(0)
	v_add_f32_e32 v105, v118, v105
	s_waitcnt lgkmcnt(0)
	s_nop 1
	v_add_f32_dpp v102, v104, v104 quad_perm:[1,0,3,2] row_mask:0xf bank_mask:0xf
	s_waitcnt lgkmcnt(0)
	s_nop 1
	v_add_f32_dpp v101, v106, v106 quad_perm:[1,0,3,2] row_mask:0xf bank_mask:0xf
	s_waitcnt lgkmcnt(2)
	s_nop 1
	v_add_f32_dpp v100, v100, v100 quad_perm:[1,0,3,2] row_mask:0xf bank_mask:0xf
	s_waitcnt lgkmcnt(0)
	s_nop 1
	v_add_f32_dpp v105, v105, v105 quad_perm:[2,3,0,1] row_mask:0xf bank_mask:0xf
	ds_bpermute_b32 v107, v94, v105
	s_waitcnt lgkmcnt(3)
	s_nop 1
	v_add_f32_dpp v102, v102, v102 quad_perm:[2,3,0,1] row_mask:0xf bank_mask:0xf
	s_waitcnt lgkmcnt(0)
	s_nop 1
	v_add_f32_dpp v101, v101, v101 quad_perm:[2,3,0,1] row_mask:0xf bank_mask:0xf
	s_waitcnt lgkmcnt(2)
	s_nop 1
	v_add_f32_dpp v100, v100, v100 quad_perm:[2,3,0,1] row_mask:0xf bank_mask:0xf
	s_waitcnt lgkmcnt(0)
	v_add_f32_e32 v105, v105, v107
	ds_bpermute_b32 v107, v95, v105
	s_waitcnt lgkmcnt(3)
	s_nop 1
	v_add_f32_dpp v102, v102, v102 row_half_mirror row_mask:0xf bank_mask:0xf
	s_waitcnt lgkmcnt(0)
	s_nop 1
	v_add_f32_dpp v101, v101, v101 row_half_mirror row_mask:0xf bank_mask:0xf
	s_waitcnt lgkmcnt(2)
	s_nop 1
	v_add_f32_dpp v100, v100, v100 row_half_mirror row_mask:0xf bank_mask:0xf
	s_waitcnt lgkmcnt(0)
	v_add_f32_e32 v105, v105, v107
	ds_bpermute_b32 v107, v96, v105
	s_waitcnt lgkmcnt(3)
	s_nop 1
	v_add_f32_dpp v102, v102, v102 row_mirror row_mask:0xf bank_mask:0xf
	ds_bpermute_b32 v104, v96, v102
	s_waitcnt lgkmcnt(3)
	s_nop 1
	v_add_f32_dpp v101, v101, v101 row_mirror row_mask:0xf bank_mask:0xf
	s_waitcnt lgkmcnt(2)
	s_nop 1
	v_add_f32_dpp v100, v100, v100 row_mirror row_mask:0xf bank_mask:0xf
	ds_bpermute_b32 v106, v96, v101
	ds_bpermute_b32 v103, v96, v100
	s_waitcnt lgkmcnt(3)
	v_add_f32_e32 v105, v105, v107
	ds_bpermute_b32 v107, v97, v105
	s_waitcnt lgkmcnt(3)
	v_add_f32_e32 v102, v102, v104
	ds_bpermute_b32 v104, v97, v102
	s_waitcnt lgkmcnt(3)
	v_add_f32_e32 v101, v101, v106
	s_waitcnt lgkmcnt(2)
	v_add_f32_e32 v100, v100, v103
	ds_bpermute_b32 v106, v97, v101
	ds_bpermute_b32 v103, v97, v100
	s_waitcnt lgkmcnt(3)
	v_add_f32_e32 v105, v105, v107
	v_fmamk_f32 v105, v105, 0x3a800000, v98
	s_waitcnt lgkmcnt(2)
	v_add_f32_e32 v102, v102, v104
	v_mul_f32_e32 v104, 0x4f800000, v105
	v_cmp_gt_f32_e32 vcc, s18, v105
	v_fmamk_f32 v102, v102, 0x3a800000, v98
	s_waitcnt lgkmcnt(1)
	v_add_f32_e32 v101, v101, v106
	v_cndmask_b32_e32 v104, v105, v104, vcc
	v_mul_f32_e32 v105, 0x4f800000, v102
	v_cmp_gt_f32_e64 s[0:1], s18, v102
	s_waitcnt lgkmcnt(0)
	v_add_f32_e32 v100, v100, v103
	v_sqrt_f32_e32 v103, v104
	v_fmamk_f32 v101, v101, 0x3a800000, v98
	v_cndmask_b32_e64 v102, v102, v105, s[0:1]
	v_mul_f32_e32 v105, 0x4f800000, v101
	v_cmp_gt_f32_e64 s[2:3], s18, v101
	v_fmamk_f32 v100, v100, 0x3a800000, v98
	v_sqrt_f32_e32 v106, v102
	v_cndmask_b32_e64 v101, v101, v105, s[2:3]
	v_mul_f32_e32 v105, 0x4f800000, v100
	v_cmp_gt_f32_e64 s[4:5], s18, v100
	v_sqrt_f32_e32 v107, v101
	v_add_u32_e32 v108, -1, v103
	v_cndmask_b32_e64 v100, v100, v105, s[4:5]
	v_sqrt_f32_e32 v105, v100
	v_add_u32_e32 v109, 1, v103
	v_fma_f32 v110, -v108, v103, v104
	v_fma_f32 v111, -v109, v103, v104
	v_add_u32_e32 v112, -1, v106
	v_cmp_ge_f32_e64 s[6:7], 0, v110
	v_add_u32_e32 v113, 1, v106
	v_fma_f32 v110, -v113, v106, v102
	v_cndmask_b32_e64 v103, v103, v108, s[6:7]
	v_fma_f32 v108, -v112, v106, v102
	v_cmp_lt_f32_e64 s[6:7], 0, v111
	v_add_u32_e32 v114, -1, v107
	v_add_u32_e32 v115, 1, v107
	v_cndmask_b32_e64 v103, v103, v109, s[6:7]
	v_cmp_ge_f32_e64 s[6:7], 0, v108
	v_fma_f32 v108, -v114, v107, v101
	v_fma_f32 v109, -v115, v107, v101
	v_cndmask_b32_e64 v106, v106, v112, s[6:7]
	v_cmp_lt_f32_e64 s[6:7], 0, v110
	v_add_u32_e32 v110, -1, v105
	v_add_u32_e32 v111, 1, v105
	v_mul_f32_e32 v112, 0x37800000, v103
	v_cndmask_b32_e64 v106, v106, v113, s[6:7]
	v_cmp_ge_f32_e64 s[6:7], 0, v108
	v_fma_f32 v108, -v110, v105, v100
	v_cndmask_b32_e32 v103, v103, v112, vcc
	v_cndmask_b32_e64 v107, v107, v114, s[6:7]
	v_cmp_lt_f32_e64 s[6:7], 0, v109
	v_fma_f32 v109, -v111, v105, v100
	v_cmp_ge_f32_e32 vcc, 0, v108
	v_mul_f32_e32 v112, 0x37800000, v106
	v_cndmask_b32_e64 v107, v107, v115, s[6:7]
	v_cndmask_b32_e32 v105, v105, v110, vcc
	v_cmp_lt_f32_e32 vcc, 0, v109
	v_cmp_class_f32_e64 s[6:7], v104, v99
	s_nop 0
	v_cndmask_b32_e32 v105, v105, v111, vcc
	v_cndmask_b32_e64 v103, v103, v104, s[6:7]
	v_cndmask_b32_e64 v104, v106, v112, s[0:1]
	v_cmp_class_f32_e64 s[0:1], v102, v99
	v_mul_f32_e32 v106, 0x37800000, v107
	v_div_scale_f32 v108, s[6:7], v103, v103, 1.0
	v_cndmask_b32_e64 v104, v104, v102, s[0:1]
	v_cndmask_b32_e64 v102, v107, v106, s[2:3]
	v_cmp_class_f32_e64 s[0:1], v101, v99
	v_mul_f32_e32 v106, 0x37800000, v105
	v_rcp_f32_e32 v107, v108
	v_div_scale_f32 v110, s[2:3], v104, v104, 1.0
	v_cndmask_b32_e64 v112, v102, v101, s[0:1]
	v_cndmask_b32_e64 v101, v105, v106, s[4:5]
	v_cmp_class_f32_e64 s[0:1], v100, v99
	v_rcp_f32_e32 v102, v110
	v_div_scale_f32 v105, s[4:5], v112, v112, 1.0
	v_cndmask_b32_e64 v113, v101, v100, s[0:1]
	v_rcp_f32_e32 v114, v105
	v_div_scale_f32 v115, s[0:1], v113, v113, 1.0
	v_rcp_f32_e32 v117, v115
	v_fma_f32 v100, -v108, v107, 1.0
	v_div_scale_f32 v109, vcc, 1.0, v103, 1.0
	v_fmac_f32_e32 v107, v100, v107
	v_fma_f32 v100, -v110, v102, 1.0
	v_div_scale_f32 v111, s[2:3], 1.0, v104, 1.0
	v_mul_f32_e32 v101, v109, v107
	v_fmac_f32_e32 v102, v100, v102
	v_fma_f32 v100, -v105, v114, 1.0
	v_div_scale_f32 v106, s[4:5], 1.0, v112, 1.0
	v_fma_f32 v118, -v108, v101, v109
	v_mul_f32_e32 v119, v111, v102
	v_fmac_f32_e32 v114, v100, v114
	v_fma_f32 v100, -v115, v117, 1.0
	v_div_scale_f32 v116, s[0:1], 1.0, v113, 1.0
	v_fmac_f32_e32 v101, v118, v107
	v_fma_f32 v118, -v110, v119, v111
	v_mul_f32_e32 v120, v106, v114
	v_fmac_f32_e32 v117, v100, v117
	v_fma_f32 v100, -v108, v101, v109
	v_fmac_f32_e32 v119, v118, v102
	v_fma_f32 v108, -v105, v120, v106
	v_mul_f32_e32 v109, v116, v117
	v_div_fmas_f32 v100, v100, v107, v101
	v_fma_f32 v101, -v110, v119, v111
	v_fmac_f32_e32 v120, v108, v114
	v_fma_f32 v107, -v115, v109, v116
	s_mov_b64 vcc, s[2:3]
	v_div_fixup_f32 v100, v100, v103, 1.0
	v_div_fmas_f32 v108, v101, v102, v119
	v_fma_f32 v105, -v105, v120, v106
	v_fmac_f32_e32 v109, v107, v117
	s_mov_b64 vcc, s[4:5]
	v_pk_mul_f32 v[76:77], v[76:77], v[100:101] op_sel_hi:[1,0]
	v_pk_mul_f32 v[78:79], v[78:79], v[100:101] op_sel_hi:[1,0]
	v_pk_mul_f32 v[68:69], v[68:69], v[100:101] op_sel_hi:[1,0]
	v_pk_mul_f32 v[70:71], v[70:71], v[100:101] op_sel_hi:[1,0]
	v_pk_mul_f32 v[72:73], v[72:73], v[100:101] op_sel_hi:[1,0]
	v_pk_mul_f32 v[74:75], v[74:75], v[100:101] op_sel_hi:[1,0]
	v_pk_mul_f32 v[102:103], v[64:65], v[100:101] op_sel_hi:[1,0]
	v_pk_mul_f32 v[100:101], v[66:67], v[100:101] op_sel_hi:[1,0]
	v_div_fixup_f32 v104, v108, v104, 1.0
	v_div_fmas_f32 v105, v105, v114, v120
	v_fma_f32 v106, -v115, v109, v116
	s_mov_b64 vcc, s[0:1]
	v_pk_mul_f32 v[66:67], v[78:79], v[2:3]
	v_pk_mul_f32 v[64:65], v[76:77], v[0:1]
	v_pk_mul_f32 v[72:73], v[72:73], v[8:9]
	v_pk_mul_f32 v[78:79], v[100:101], v[14:15]
	v_pk_mul_f32 v[76:77], v[102:103], v[12:13]
	v_pk_mul_f32 v[60:61], v[60:61], v[104:105] op_sel_hi:[1,0]
	v_pk_mul_f32 v[62:63], v[62:63], v[104:105] op_sel_hi:[1,0]
	v_pk_mul_f32 v[52:53], v[52:53], v[104:105] op_sel_hi:[1,0]
	v_pk_mul_f32 v[54:55], v[54:55], v[104:105] op_sel_hi:[1,0]
	v_pk_mul_f32 v[56:57], v[56:57], v[104:105] op_sel_hi:[1,0]
	v_pk_mul_f32 v[58:59], v[58:59], v[104:105] op_sel_hi:[1,0]
	v_pk_mul_f32 v[100:101], v[48:49], v[104:105] op_sel_hi:[1,0]
	v_pk_mul_f32 v[102:103], v[50:51], v[104:105] op_sel_hi:[1,0]
	v_div_fixup_f32 v104, v105, v112, 1.0
	v_div_fmas_f32 v105, v106, v117, v109
	v_pk_mul_f32 v[70:71], v[70:71], v[6:7]
	v_pk_mul_f32 v[68:69], v[68:69], v[4:5]
	v_pk_mul_f32 v[74:75], v[74:75], v[10:11]
	global_store_dwordx4 v[90:91], v[64:67], off
	global_store_dwordx4 v[90:91], v[68:71], off offset:1024
	global_store_dwordx4 v[90:91], v[72:75], off offset:2048
	global_store_dwordx4 v[90:91], v[76:79], off offset:3072
	v_pk_mul_f32 v[50:51], v[62:63], v[2:3]
	v_div_fixup_f32 v72, v105, v113, 1.0
	v_pk_mul_f32 v[48:49], v[60:61], v[0:1]
	v_pk_mul_f32 v[54:55], v[54:55], v[6:7]
	v_pk_mul_f32 v[52:53], v[52:53], v[4:5]
	v_pk_mul_f32 v[44:45], v[44:45], v[104:105] op_sel_hi:[1,0]
	v_pk_mul_f32 v[46:47], v[46:47], v[104:105] op_sel_hi:[1,0]
	v_pk_mul_f32 v[28:29], v[28:29], v[72:73] op_sel_hi:[1,0]
	v_pk_mul_f32 v[30:31], v[30:31], v[72:73] op_sel_hi:[1,0]
	v_pk_mul_f32 v[58:59], v[58:59], v[10:11]
	v_pk_mul_f32 v[56:57], v[56:57], v[8:9]
	v_pk_mul_f32 v[62:63], v[102:103], v[14:15]
	v_pk_mul_f32 v[60:61], v[100:101], v[12:13]
	v_pk_mul_f32 v[40:41], v[40:41], v[104:105] op_sel_hi:[1,0]
	v_pk_mul_f32 v[42:43], v[42:43], v[104:105] op_sel_hi:[1,0]
	v_pk_mul_f32 v[64:65], v[36:37], v[104:105] op_sel_hi:[1,0]
	v_pk_mul_f32 v[66:67], v[38:39], v[104:105] op_sel_hi:[1,0]
	v_pk_mul_f32 v[68:69], v[32:33], v[104:105] op_sel_hi:[1,0]
	v_pk_mul_f32 v[70:71], v[34:35], v[104:105] op_sel_hi:[1,0]
	global_store_dwordx4 v[88:89], v[48:51], off
	global_store_dwordx4 v[88:89], v[52:55], off offset:1024
	global_store_dwordx4 v[88:89], v[56:59], off offset:2048
	global_store_dwordx4 v[88:89], v[60:63], off offset:3072
	v_pk_mul_f32 v[34:35], v[46:47], v[2:3]
	v_pk_mul_f32 v[32:33], v[44:45], v[0:1]
	v_pk_mul_f32 v[24:25], v[24:25], v[72:73] op_sel_hi:[1,0]
	v_pk_mul_f32 v[26:27], v[26:27], v[72:73] op_sel_hi:[1,0]
	v_pk_mul_f32 v[48:49], v[20:21], v[72:73] op_sel_hi:[1,0]
	v_pk_mul_f32 v[50:51], v[22:23], v[72:73] op_sel_hi:[1,0]
	v_pk_mul_f32 v[52:53], v[16:17], v[72:73] op_sel_hi:[1,0]
	v_pk_mul_f32 v[54:55], v[18:19], v[72:73] op_sel_hi:[1,0]
	v_pk_mul_f32 v[18:19], v[30:31], v[2:3]
	v_pk_mul_f32 v[16:17], v[28:29], v[0:1]
	v_pk_mul_f32 v[38:39], v[42:43], v[6:7]
	v_pk_mul_f32 v[36:37], v[40:41], v[4:5]
	v_pk_mul_f32 v[42:43], v[66:67], v[10:11]
	v_pk_mul_f32 v[40:41], v[64:65], v[8:9]
	v_pk_mul_f32 v[46:47], v[70:71], v[14:15]
	v_pk_mul_f32 v[44:45], v[68:69], v[12:13]
	global_store_dwordx4 v[84:85], v[32:35], off
	global_store_dwordx4 v[84:85], v[36:39], off offset:1024
	global_store_dwordx4 v[84:85], v[40:43], off offset:2048
	global_store_dwordx4 v[84:85], v[44:47], off offset:3072
	v_pk_mul_f32 v[22:23], v[26:27], v[6:7]
	v_pk_mul_f32 v[20:21], v[24:25], v[4:5]
	v_pk_mul_f32 v[26:27], v[50:51], v[10:11]
	v_pk_mul_f32 v[24:25], v[48:49], v[8:9]
	v_pk_mul_f32 v[30:31], v[54:55], v[14:15]
	v_pk_mul_f32 v[28:29], v[52:53], v[12:13]
	global_store_dwordx4 v[86:87], v[16:19], off
	global_store_dwordx4 v[86:87], v[20:23], off offset:1024
	global_store_dwordx4 v[86:87], v[24:27], off offset:2048
	global_store_dwordx4 v[86:87], v[28:31], off offset:3072
	s_cbranch_scc1 .LBB0_5948
